# packed ops kept as hipcc emitted; scan step regions list-rescheduled with merged lgkmcnt waits and fewer hazard nops; Mamba prefetch vmcnt waits moved to first consumer; steady-state vmcnt ladders in
# speedup vs baseline: 1.0113x; 1.0111x over previous
; DI float row16_sum(float v) { v += dppf(v, 0); v += dppf(v, 1); v += dppf(v, 2); v += dppf(v, 3); return v; }
; DI void mamba_scan(CP p, const Ptrs& w, int l, int item, float* sm) {
;     ...
;   auto load = [&](int c, MPre& P) {
; #pragma unroll
;     for (int i = 0; i < 2; ++i) {
;       int idx = tid + 256 * i, j = idx >> 5, q = idx & 31;
;       int ii = pos2i(c * 16 + j, dir);
;       P.pbq[i] = *(const uint4*)(mbc + ((size_t)b * TPB + ii) * 512 + (q < 16 ? 0 : 256) + gp * 128 + (q & 15) * 8);
;     }
;     {
;       int pos = c * 16 + xj, ii = pos2i(pos, dir);
;       size_t tok = (size_t)b * TPB + ii;
;       const bf16_t* prw = w.pC + tok * SPC;
;       bool hp = (ii != 0) && (ii != CTXL), hn = (ii != CTXL - 1) && (ii != TPB - 1);
;       P.px[0] = prw[chX + (hp ? -SPC : 0)]; P.px[1] = prw[chX]; P.px[2] = prw[chX + (hn ? SPC : 0)];
;       P.pxm[0] = hp ? 1.f : 0.f; P.pxm[1] = hn ? 1.f : 0.f;
;       float2 dd = *(const float2*)(w.mdt + (tok * 16 + dir * 8 + hd) * 2);
;       P.pdt[0] = dd.x; P.pdt[1] = dd.y; P.pdt[2] = w.mcb[tok * 2 + gp];
;     }
;   };
;     ...
;   auto run_chunk = [&](int c, const float* bf, float* sy) {
;     flush(max(c - 1, 0));
;     MStep cur = lds_step(bf, 0);
; #pragma unroll
;     for (int j = 0; j < 16; ++j) {
;       MStep nxt = cur;
;       if (j + 1 < 16) nxt = lds_step(bf, j + 1);
;       f2v ya = M0 * cur.C0.xy + M1 * cur.C0.zw, yb = M2 * cur.C1.xy + M3 * cur.C1.zw;
;       ya += yb;
;       float yp = row16_sum(ya.x + ya.y);
;       float y = cur.sc.x * yp + cur.xq * cur.sc.y + cur.ds;
;       const float dA = cur.sc.x, xq = cur.xq;
;       M0 = M0 * dA + xq * cur.B0.xy; M1 = M1 * dA + xq * cur.B0.zw;
;       M2 = M2 * dA + xq * cur.B1.xy; M3 = M3 * dA + xq * cur.B1.zw;
;       sy[(ng == 0 ? j * 16 : 0) + ysel] = y;
;       cur = nxt;
;     }
;   };
.LBB0_543:
	s_or_b64 exec, exec, s[4:5]
	v_pk_mul_f32 v[12:13], v[42:43], v[38:39] op_sel_hi:[1,0]
	s_addk_i32 s57, 0x200
	v_pk_fma_f32 v[26:27], v[26:27], v[8:9], v[12:13] op_sel_hi:[1,0,1]
	v_pk_mul_f32 v[12:13], v[44:45], v[38:39] op_sel_hi:[1,0]
	s_add_i32 s52, s52, 2
	v_pk_fma_f32 v[28:29], v[28:29], v[8:9], v[12:13] op_sel_hi:[1,0,1]
	v_pk_mul_f32 v[12:13], v[40:41], v[38:39] op_sel_hi:[1,0]
	v_cndmask_b32_e64 v87, 1.0, 0, s[42:43]
	v_pk_fma_f32 v[22:23], v[22:23], v[8:9], v[12:13] op_sel_hi:[1,0,1]
	v_pk_mul_f32 v[12:13], v[46:47], v[38:39] op_sel_hi:[1,0]
	v_cndmask_b32_e64 v86, 1.0, 0, s[44:45]
	v_pk_fma_f32 v[24:25], v[24:25], v[8:9], v[12:13] op_sel_hi:[1,0,1]
	v_add_u32_e32 v82, 32, v82
	s_cmpk_lt_u32 s7, 0x20e
	v_subrev_u32_e32 v81, 32, v81
	s_waitcnt lgkmcnt(0)
	s_barrier
	s_cbranch_scc0 .LBB0_548
.LBB0_544:
	s_min_u32 s4, s52, 1
	s_lshl_b32 s5, s4, 8
	s_lshl_b32 s54, s4, 4
	s_add_i32 s4, s7, 4
	s_min_u32 s4, s4, 0x20f
	s_lshl_b32 s42, s4, 4
	v_add_u32_e32 v8, s42, v55
	s_sub_i32 s53, s57, s5
	v_cmp_lt_i32_e64 s[4:5], s37, v8
	v_mov_b64_e32 v[38:39], s[48:49]
	v_mov_b32_e32 v41, v157
	v_cndmask_b32_e64 v12, v231, v232, s[4:5]
	v_sub_u32_e32 v12, v12, v8
	v_cndmask_b32_e64 v12, v12, v8, s[40:41]
	v_add_u32_e32 v8, s42, v56
	v_cmp_lt_i32_e64 s[4:5], s37, v8
	v_ashrrev_i32_e32 v13, 31, v12
	v_lshl_add_u64 v[12:13], v[12:13], 0, s[90:91]
	v_cndmask_b32_e64 v14, v231, v232, s[4:5]
	v_sub_u32_e32 v14, v14, v8
	v_cndmask_b32_e64 v14, v14, v8, s[40:41]
	v_add_u32_e32 v8, s42, v54
	v_cmp_lt_i32_e64 s[4:5], s37, v8
	v_ashrrev_i32_e32 v15, 31, v14
	v_lshl_add_u64 v[14:15], v[14:15], 0, s[90:91]
	v_cndmask_b32_e64 v16, v231, v232, s[4:5]
	v_sub_u32_e32 v16, v16, v8
	v_cndmask_b32_e64 v16, v16, v8, s[40:41]
	v_and_b32_e32 v8, 0xfffffeff, v16
	v_ashrrev_i32_e32 v17, 31, v16
	v_cmp_eq_u32_e64 s[42:43], 0, v8
	v_lshl_add_u64 v[36:37], v[16:17], 0, s[90:91]
	v_mad_u64_u32 v[38:39], s[4:5], v36, s92, v[38:39]
	v_cndmask_b32_e64 v8, v233, 0, s[42:43]
	v_and_b32_e32 v40, 0xffffdfff, v16
	v_add_u32_e32 v16, v8, v48
	v_lshlrev_b64 v[12:13], 10, v[12:13]
	v_lshlrev_b64 v[14:15], 10, v[14:15]
	v_mad_i32_i24 v39, v37, s92, v39
	v_ashrrev_i32_e32 v17, 31, v16
	v_cmp_eq_u32_e64 s[44:45], s37, v40
	v_lshlrev_b64 v[42:43], 7, v[36:37]
	v_lshl_add_u64 v[12:13], v[30:31], 0, v[12:13]
	v_lshl_add_u64 v[14:15], v[30:31], 0, v[14:15]
	v_lshl_add_u64 v[16:17], v[16:17], 1, v[38:39]
	v_lshl_add_u64 v[38:39], v[38:39], 0, v[156:157]
	v_cndmask_b32_e64 v40, v234, 0, s[44:45]
	v_lshl_or_b32 v42, s6, 3, v42
	global_load_dwordx4 v[18:21], v[12:13], off
	s_nop 0
	global_load_dwordx4 v[12:15], v[14:15], off
	v_lshl_add_u64 v[40:41], v[38:39], 0, v[40:41]
	v_lshl_add_u64 v[42:43], s[46:47], 0, v[42:43]
	v_lshl_add_u64 v[44:45], v[36:37], 3, s[50:51]
	global_load_ushort v84, v[16:17], off
	global_load_ushort v85, v[38:39], off
	global_load_ushort v83, v[40:41], off
	global_load_dwordx2 v[36:37], v[42:43], off
	s_nop 0
	global_load_dword v17, v[44:45], off
	v_subrev_u32_e32 v8, s54, v82
	s_and_b32 s4, s53, 0x100
	v_lshl_add_u32 v16, s4, 2, v57
	v_cmp_lt_i32_e64 s[4:5], s37, v8
	ds_read_b32 v16, v16 offset:37376
	s_nop 0
	v_cndmask_b32_e64 v38, v231, v232, s[4:5]
	v_add3_u32 v38, v38, v81, s54
	v_cndmask_b32_e64 v38, v38, v8, s[40:41]
	v_ashrrev_i32_e32 v39, 31, v38
	v_lshl_add_u64 v[38:39], v[38:39], 0, s[90:91]
	v_lshlrev_b64 v[38:39], 10, v[38:39]
	s_waitcnt lgkmcnt(0)
	v_cvt_pk_bf16_f32 v8, v16, s0
	v_lshl_add_u64 v[38:39], v[34:35], 0, v[38:39]
	global_store_short v[38:39], v8, off
	s_waitcnt lgkmcnt(0)
	ds_read_b128 v[38:41], v59
	ds_read_b128 v[42:45], v59 offset:16
	ds_read_b128 v[88:91], v59 offset:8192
	ds_read_b128 v[92:95], v59 offset:8208
	v_add_u32_e32 v8, 0x4000, v60
	s_movk_i32 s4, 0x4800
	ds_read2_b32 v[46:47], v8 offset1:16
	v_add_u32_e32 v8, 0x4400, v60
	ds_read2_b32 v[116:117], v8 offset1:16
	v_add_u32_e64 v8, s4, 0
	ds_read2_b64 v[96:99], v8 offset1:2
	ds_read_b128 v[100:103], v59 offset:512
	ds_read_b128 v[104:107], v59 offset:528
	ds_read_b128 v[108:111], v59 offset:8704
	ds_read_b128 v[112:115], v59 offset:8720
	s_waitcnt lgkmcnt(8)
	v_pk_mul_f32 v[90:91], v[28:29], v[90:91]
	v_pk_fma_f32 v[88:89], v[26:27], v[88:89], v[90:91]
	s_waitcnt lgkmcnt(7)
	v_pk_mul_f32 v[90:91], v[24:25], v[94:95]
	v_pk_fma_f32 v[90:91], v[22:23], v[92:93], v[90:91]
	v_pk_add_f32 v[88:89], v[88:89], v[90:91]
	v_add_f32_e32 v8, v88, v89
	s_waitcnt lgkmcnt(4)
	v_pk_mul_f32 v[22:23], v[22:23], v[96:97] op_sel_hi:[1,0]
	v_pk_mul_f32 v[26:27], v[26:27], v[96:97] op_sel_hi:[1,0]
	v_add_f32_dpp v8, v8, v8 quad_perm:[1,0,3,2] row_mask:0xf bank_mask:0xf bound_ctrl:1
	v_pk_fma_f32 v[92:93], v[42:43], v[46:47], v[22:23] op_sel_hi:[1,0,1]
	v_pk_mul_f32 v[22:23], v[24:25], v[96:97] op_sel_hi:[1,0]
	v_add_f32_dpp v8, v8, v8 quad_perm:[2,3,0,1] row_mask:0xf bank_mask:0xf bound_ctrl:1
	v_pk_fma_f32 v[88:89], v[38:39], v[46:47], v[26:27] op_sel_hi:[1,0,1]
	v_pk_mul_f32 v[26:27], v[28:29], v[96:97] op_sel_hi:[1,0]
	v_add_f32_dpp v8, v8, v8 row_half_mirror row_mask:0xf bank_mask:0xf bound_ctrl:1
	v_pk_fma_f32 v[94:95], v[44:45], v[46:47], v[22:23] op_sel_hi:[1,0,1]
	v_pk_fma_f32 v[90:91], v[40:41], v[46:47], v[26:27] op_sel_hi:[1,0,1]
	v_add_f32_dpp v8, v8, v8 row_mirror row_mask:0xf bank_mask:0xf bound_ctrl:1
	v_mul_f32_e32 v8, v96, v8
	v_fmac_f32_e32 v8, v46, v97
	s_waitcnt lgkmcnt(1)
	v_pk_mul_f32 v[96:97], v[90:91], v[110:111]
	v_add_f32_e32 v8, v116, v8
	v_pk_fma_f32 v[96:97], v[88:89], v[108:109], v[96:97]
	s_waitcnt lgkmcnt(0)
; DI float row16_sum(float v) { v += dppf(v, 0); v += dppf(v, 1); v += dppf(v, 2); v += dppf(v, 3); return v; }
; DI void mamba_scan(CP p, const Ptrs& w, int l, int item, float* sm) {
;     ...
;   auto run_chunk = [&](int c, const float* bf, float* sy) {
;     flush(max(c - 1, 0));
;     MStep cur = lds_step(bf, 0);
; #pragma unroll
;     for (int j = 0; j < 16; ++j) {
;       MStep nxt = cur;
;       if (j + 1 < 16) nxt = lds_step(bf, j + 1);
;       f2v ya = M0 * cur.C0.xy + M1 * cur.C0.zw, yb = M2 * cur.C1.xy + M3 * cur.C1.zw;
;       ya += yb;
;       float yp = row16_sum(ya.x + ya.y);
;       float y = cur.sc.x * yp + cur.xq * cur.sc.y + cur.ds;
;       const float dA = cur.sc.x, xq = cur.xq;
;       M0 = M0 * dA + xq * cur.B0.xy; M1 = M1 * dA + xq * cur.B0.zw;
;       M2 = M2 * dA + xq * cur.B1.xy; M3 = M3 * dA + xq * cur.B1.zw;
;       sy[(ng == 0 ? j * 16 : 0) + ysel] = y;
;       cur = nxt;
;     }
;   };
	v_pk_mul_f32 v[108:109], v[94:95], v[114:115]
	ds_write_b32 v61, v8 offset:37376
	ds_read_b128 v[22:25], v59 offset:1024
	ds_read_b128 v[26:29], v59 offset:1040
	ds_read_b128 v[38:41], v59 offset:9216
	ds_read_b128 v[42:45], v59 offset:9232
	v_pk_fma_f32 v[108:109], v[92:93], v[112:113], v[108:109]
	ds_read_b32 v8, v60 offset:16512
	v_pk_add_f32 v[96:97], v[96:97], v[108:109]
	ds_read_b32 v116, v60 offset:17536
	v_add_f32_e32 v16, v96, v97
	ds_read_b64 v[118:119], v157 offset:18464
	v_pk_mul_f32 v[88:89], v[88:89], v[98:99] op_sel_hi:[1,0]
	v_add_f32_dpp v16, v16, v16 quad_perm:[1,0,3,2] row_mask:0xf bank_mask:0xf bound_ctrl:1
	s_nop 1
	v_add_f32_dpp v16, v16, v16 quad_perm:[2,3,0,1] row_mask:0xf bank_mask:0xf bound_ctrl:1
	s_nop 1
	v_add_f32_dpp v16, v16, v16 row_half_mirror row_mask:0xf bank_mask:0xf bound_ctrl:1
	s_nop 1
	v_add_f32_dpp v16, v16, v16 row_mirror row_mask:0xf bank_mask:0xf bound_ctrl:1
	v_mul_f32_e32 v16, v98, v16
	v_fmac_f32_e32 v16, v47, v99
	v_add_f32_e32 v96, v117, v16
	v_mov_b32_e32 v16, v47
	ds_write_b32 v62, v96 offset:37376
	v_pk_fma_f32 v[46:47], v[100:101], v[16:17], v[88:89] op_sel_hi:[1,0,1]
	v_pk_mul_f32 v[88:89], v[90:91], v[98:99] op_sel_hi:[1,0]
	v_pk_fma_f32 v[108:109], v[102:103], v[16:17], v[88:89] op_sel_hi:[1,0,1]
	v_pk_mul_f32 v[88:89], v[92:93], v[98:99] op_sel_hi:[1,0]
	v_pk_fma_f32 v[104:105], v[104:105], v[16:17], v[88:89] op_sel_hi:[1,0,1]
	v_pk_mul_f32 v[88:89], v[94:95], v[98:99] op_sel_hi:[1,0]
	v_pk_fma_f32 v[106:107], v[106:107], v[16:17], v[88:89] op_sel_hi:[1,0,1]
	ds_read_b128 v[88:91], v59 offset:1536
	ds_read_b128 v[92:95], v59 offset:1552
	ds_read_b128 v[96:99], v59 offset:9728
	ds_read_b128 v[100:103], v59 offset:9744
	ds_read_b32 v16, v60 offset:16576
	ds_read_b32 v114, v60 offset:17600
	s_waitcnt lgkmcnt(14)
	ds_read_b64 v[110:111], v157 offset:18480
	s_waitcnt lgkmcnt(10)
	v_pk_mul_f32 v[40:41], v[108:109], v[40:41]
	v_pk_fma_f32 v[38:39], v[46:47], v[38:39], v[40:41]
	v_pk_mul_f32 v[40:41], v[106:107], v[44:45]
	v_pk_fma_f32 v[40:41], v[104:105], v[42:43], v[40:41]
	v_pk_add_f32 v[38:39], v[38:39], v[40:41]
	v_add_f32_e32 v38, v38, v39
	s_nop 1
	v_add_f32_dpp v38, v38, v38 quad_perm:[1,0,3,2] row_mask:0xf bank_mask:0xf bound_ctrl:1
	s_nop 1
	v_add_f32_dpp v38, v38, v38 quad_perm:[2,3,0,1] row_mask:0xf bank_mask:0xf bound_ctrl:1
	s_nop 1
	v_add_f32_dpp v38, v38, v38 row_half_mirror row_mask:0xf bank_mask:0xf bound_ctrl:1
	s_nop 1
	v_add_f32_dpp v38, v38, v38 row_mirror row_mask:0xf bank_mask:0xf bound_ctrl:1
	s_waitcnt lgkmcnt(8)
	v_mul_f32_e32 v38, v118, v38
	v_fmac_f32_e32 v38, v8, v119
	v_add_f32_e32 v40, v116, v38
	v_pk_mul_f32 v[38:39], v[46:47], v[118:119] op_sel_hi:[1,0]
	ds_write_b32 v63, v40 offset:37376
	v_pk_fma_f32 v[46:47], v[22:23], v[8:9], v[38:39] op_sel_hi:[1,0,1]
	v_pk_mul_f32 v[22:23], v[108:109], v[118:119] op_sel_hi:[1,0]
	v_pk_fma_f32 v[108:109], v[24:25], v[8:9], v[22:23] op_sel_hi:[1,0,1]
	v_pk_mul_f32 v[22:23], v[104:105], v[118:119] op_sel_hi:[1,0]
	v_pk_fma_f32 v[104:105], v[26:27], v[8:9], v[22:23] op_sel_hi:[1,0,1]
	v_pk_mul_f32 v[22:23], v[106:107], v[118:119] op_sel_hi:[1,0]
	v_pk_fma_f32 v[106:107], v[28:29], v[8:9], v[22:23] op_sel_hi:[1,0,1]
	ds_read_b128 v[22:25], v59 offset:2048
	ds_read_b128 v[26:29], v59 offset:2064
	ds_read_b128 v[38:41], v59 offset:10240
	ds_read_b128 v[42:45], v59 offset:10256
	ds_read_b32 v8, v60 offset:16640
	ds_read_b32 v115, v60 offset:17664
	s_waitcnt lgkmcnt(14)
	ds_read_b64 v[112:113], v157 offset:18496
	s_waitcnt lgkmcnt(8)
	v_pk_mul_f32 v[98:99], v[108:109], v[98:99]
	v_pk_fma_f32 v[96:97], v[46:47], v[96:97], v[98:99]
	v_pk_mul_f32 v[46:47], v[46:47], v[110:111] op_sel_hi:[1,0]
	v_pk_mul_f32 v[98:99], v[106:107], v[102:103]
	v_pk_fma_f32 v[46:47], v[88:89], v[16:17], v[46:47] op_sel_hi:[1,0,1]
	v_pk_mul_f32 v[88:89], v[108:109], v[110:111] op_sel_hi:[1,0]
	v_pk_fma_f32 v[98:99], v[104:105], v[100:101], v[98:99]
	v_pk_fma_f32 v[108:109], v[90:91], v[16:17], v[88:89] op_sel_hi:[1,0,1]
	v_pk_mul_f32 v[88:89], v[104:105], v[110:111] op_sel_hi:[1,0]
	v_pk_add_f32 v[96:97], v[96:97], v[98:99]
	v_pk_fma_f32 v[104:105], v[92:93], v[16:17], v[88:89] op_sel_hi:[1,0,1]
	v_pk_mul_f32 v[88:89], v[106:107], v[110:111] op_sel_hi:[1,0]
	v_add_f32_e32 v96, v96, v97
	v_pk_fma_f32 v[106:107], v[94:95], v[16:17], v[88:89] op_sel_hi:[1,0,1]
	s_waitcnt lgkmcnt(4)
	v_pk_mul_f32 v[40:41], v[108:109], v[40:41]
	v_add_f32_dpp v96, v96, v96 quad_perm:[1,0,3,2] row_mask:0xf bank_mask:0xf bound_ctrl:1
	v_pk_fma_f32 v[38:39], v[46:47], v[38:39], v[40:41]
	s_waitcnt lgkmcnt(3)
	v_pk_mul_f32 v[40:41], v[106:107], v[44:45]
	v_add_f32_dpp v96, v96, v96 quad_perm:[2,3,0,1] row_mask:0xf bank_mask:0xf bound_ctrl:1
	v_pk_fma_f32 v[40:41], v[104:105], v[42:43], v[40:41]
	v_pk_add_f32 v[38:39], v[38:39], v[40:41]
	v_add_f32_dpp v96, v96, v96 row_half_mirror row_mask:0xf bank_mask:0xf bound_ctrl:1
	v_add_f32_e32 v38, v38, v39
	s_nop 0
	v_add_f32_dpp v96, v96, v96 row_mirror row_mask:0xf bank_mask:0xf bound_ctrl:1
	v_add_f32_dpp v38, v38, v38 quad_perm:[1,0,3,2] row_mask:0xf bank_mask:0xf bound_ctrl:1
	v_mul_f32_e32 v96, v110, v96
	v_fmac_f32_e32 v96, v16, v111
	v_add_f32_dpp v38, v38, v38 quad_perm:[2,3,0,1] row_mask:0xf bank_mask:0xf bound_ctrl:1
	v_add_f32_e32 v96, v114, v96
	ds_write_b32 v65, v96 offset:37376
	v_add_f32_dpp v38, v38, v38 row_half_mirror row_mask:0xf bank_mask:0xf bound_ctrl:1
	ds_read_b128 v[88:91], v59 offset:2560
	ds_read_b128 v[92:95], v59 offset:2576
	v_add_f32_dpp v38, v38, v38 row_mirror row_mask:0xf bank_mask:0xf bound_ctrl:1
	ds_read_b128 v[96:99], v59 offset:10752
	s_waitcnt lgkmcnt(4)
; DI float row16_sum(float v) { v += dppf(v, 0); v += dppf(v, 1); v += dppf(v, 2); v += dppf(v, 3); return v; }
; DI void mamba_scan(CP p, const Ptrs& w, int l, int item, float* sm) {
;     ...
;   auto run_chunk = [&](int c, const float* bf, float* sy) {
;     flush(max(c - 1, 0));
;     MStep cur = lds_step(bf, 0);
; #pragma unroll
;     for (int j = 0; j < 16; ++j) {
;       MStep nxt = cur;
;       if (j + 1 < 16) nxt = lds_step(bf, j + 1);
;       f2v ya = M0 * cur.C0.xy + M1 * cur.C0.zw, yb = M2 * cur.C1.xy + M3 * cur.C1.zw;
;       ya += yb;
;       float yp = row16_sum(ya.x + ya.y);
;       float y = cur.sc.x * yp + cur.xq * cur.sc.y + cur.ds;
;       const float dA = cur.sc.x, xq = cur.xq;
;       M0 = M0 * dA + xq * cur.B0.xy; M1 = M1 * dA + xq * cur.B0.zw;
;       M2 = M2 * dA + xq * cur.B1.xy; M3 = M3 * dA + xq * cur.B1.zw;
;       sy[(ng == 0 ? j * 16 : 0) + ysel] = y;
;       cur = nxt;
;     }
;   };
	v_mul_f32_e32 v38, v112, v38
	ds_read_b128 v[100:103], v59 offset:10768
	v_fmac_f32_e32 v38, v8, v113
	ds_read_b32 v16, v60 offset:16704
	v_add_f32_e32 v40, v115, v38
	v_pk_mul_f32 v[38:39], v[46:47], v[112:113] op_sel_hi:[1,0]
	ds_read_b32 v114, v60 offset:17728
	v_pk_fma_f32 v[46:47], v[22:23], v[8:9], v[38:39] op_sel_hi:[1,0,1]
	v_pk_mul_f32 v[22:23], v[108:109], v[112:113] op_sel_hi:[1,0]
	ds_read_b64 v[110:111], v157 offset:18512
	v_pk_fma_f32 v[108:109], v[24:25], v[8:9], v[22:23] op_sel_hi:[1,0,1]
	v_pk_mul_f32 v[22:23], v[104:105], v[112:113] op_sel_hi:[1,0]
	ds_write_b32 v66, v40 offset:37376
	v_pk_fma_f32 v[104:105], v[26:27], v[8:9], v[22:23] op_sel_hi:[1,0,1]
	v_pk_mul_f32 v[22:23], v[106:107], v[112:113] op_sel_hi:[1,0]
	v_pk_fma_f32 v[106:107], v[28:29], v[8:9], v[22:23] op_sel_hi:[1,0,1]
	ds_read_b128 v[22:25], v59 offset:3072
	ds_read_b128 v[26:29], v59 offset:3088
	ds_read_b128 v[38:41], v59 offset:11264
	ds_read_b128 v[42:45], v59 offset:11280
	ds_read_b32 v8, v60 offset:16768
	ds_read_b32 v115, v60 offset:17792
	s_waitcnt lgkmcnt(14)
	ds_read_b64 v[112:113], v157 offset:18528
	s_waitcnt lgkmcnt(12)
	v_pk_mul_f32 v[98:99], v[108:109], v[98:99]
	v_pk_fma_f32 v[96:97], v[46:47], v[96:97], v[98:99]
	s_waitcnt lgkmcnt(11)
	v_pk_mul_f32 v[98:99], v[106:107], v[102:103]
	v_pk_fma_f32 v[98:99], v[104:105], v[100:101], v[98:99]
	v_pk_add_f32 v[96:97], v[96:97], v[98:99]
	v_add_f32_e32 v96, v96, v97
	s_waitcnt lgkmcnt(8)
	v_pk_mul_f32 v[46:47], v[46:47], v[110:111] op_sel_hi:[1,0]
	v_pk_fma_f32 v[46:47], v[88:89], v[16:17], v[46:47] op_sel_hi:[1,0,1]
	v_pk_mul_f32 v[88:89], v[108:109], v[110:111] op_sel_hi:[1,0]
	v_add_f32_dpp v96, v96, v96 quad_perm:[1,0,3,2] row_mask:0xf bank_mask:0xf bound_ctrl:1
	v_pk_fma_f32 v[108:109], v[90:91], v[16:17], v[88:89] op_sel_hi:[1,0,1]
	v_pk_mul_f32 v[88:89], v[104:105], v[110:111] op_sel_hi:[1,0]
	v_add_f32_dpp v96, v96, v96 quad_perm:[2,3,0,1] row_mask:0xf bank_mask:0xf bound_ctrl:1
	v_pk_fma_f32 v[104:105], v[92:93], v[16:17], v[88:89] op_sel_hi:[1,0,1]
	v_pk_mul_f32 v[88:89], v[106:107], v[110:111] op_sel_hi:[1,0]
	v_add_f32_dpp v96, v96, v96 row_half_mirror row_mask:0xf bank_mask:0xf bound_ctrl:1
	v_pk_fma_f32 v[106:107], v[94:95], v[16:17], v[88:89] op_sel_hi:[1,0,1]
	s_waitcnt lgkmcnt(4)
	v_pk_mul_f32 v[40:41], v[108:109], v[40:41]
	v_add_f32_dpp v96, v96, v96 row_mirror row_mask:0xf bank_mask:0xf bound_ctrl:1
	v_pk_fma_f32 v[38:39], v[46:47], v[38:39], v[40:41]
	s_waitcnt lgkmcnt(3)
	v_pk_mul_f32 v[40:41], v[106:107], v[44:45]
	v_mul_f32_e32 v96, v110, v96
	v_pk_fma_f32 v[40:41], v[104:105], v[42:43], v[40:41]
	v_fmac_f32_e32 v96, v16, v111
	v_pk_add_f32 v[38:39], v[38:39], v[40:41]
	v_add_f32_e32 v96, v114, v96
	v_add_f32_e32 v38, v38, v39
	ds_write_b32 v67, v96 offset:37376
	ds_read_b128 v[88:91], v59 offset:3584
	v_add_f32_dpp v38, v38, v38 quad_perm:[1,0,3,2] row_mask:0xf bank_mask:0xf bound_ctrl:1
	ds_read_b128 v[92:95], v59 offset:3600
	ds_read_b128 v[96:99], v59 offset:11776
	v_add_f32_dpp v38, v38, v38 quad_perm:[2,3,0,1] row_mask:0xf bank_mask:0xf bound_ctrl:1
	ds_read_b128 v[100:103], v59 offset:11792
	ds_read_b32 v16, v60 offset:16832
	v_add_f32_dpp v38, v38, v38 row_half_mirror row_mask:0xf bank_mask:0xf bound_ctrl:1
	ds_read_b32 v114, v60 offset:17856
	ds_read_b64 v[110:111], v157 offset:18544
	v_add_f32_dpp v38, v38, v38 row_mirror row_mask:0xf bank_mask:0xf bound_ctrl:1
	s_waitcnt lgkmcnt(8)
	v_mul_f32_e32 v38, v112, v38
	v_fmac_f32_e32 v38, v8, v113
	v_add_f32_e32 v40, v115, v38
	v_pk_mul_f32 v[38:39], v[46:47], v[112:113] op_sel_hi:[1,0]
	ds_write_b32 v68, v40 offset:37376
	v_pk_fma_f32 v[46:47], v[22:23], v[8:9], v[38:39] op_sel_hi:[1,0,1]
	v_pk_mul_f32 v[22:23], v[108:109], v[112:113] op_sel_hi:[1,0]
	v_pk_fma_f32 v[108:109], v[24:25], v[8:9], v[22:23] op_sel_hi:[1,0,1]
	v_pk_mul_f32 v[22:23], v[104:105], v[112:113] op_sel_hi:[1,0]
	v_pk_fma_f32 v[104:105], v[26:27], v[8:9], v[22:23] op_sel_hi:[1,0,1]
	v_pk_mul_f32 v[22:23], v[106:107], v[112:113] op_sel_hi:[1,0]
	v_pk_fma_f32 v[106:107], v[28:29], v[8:9], v[22:23] op_sel_hi:[1,0,1]
	ds_read_b128 v[22:25], v59 offset:4096
	ds_read_b128 v[26:29], v59 offset:4112
	ds_read_b128 v[38:41], v59 offset:12288
	ds_read_b128 v[42:45], v59 offset:12304
	ds_read_b32 v8, v60 offset:16896
	ds_read_b32 v115, v60 offset:17920
	s_waitcnt lgkmcnt(14)
	ds_read_b64 v[112:113], v157 offset:18560
	s_waitcnt lgkmcnt(12)
	v_pk_mul_f32 v[98:99], v[108:109], v[98:99]
	v_pk_fma_f32 v[96:97], v[46:47], v[96:97], v[98:99]
	s_waitcnt lgkmcnt(11)
	v_pk_mul_f32 v[98:99], v[106:107], v[102:103]
	v_pk_fma_f32 v[98:99], v[104:105], v[100:101], v[98:99]
	v_pk_add_f32 v[96:97], v[96:97], v[98:99]
	s_waitcnt lgkmcnt(8)
	v_pk_mul_f32 v[46:47], v[46:47], v[110:111] op_sel_hi:[1,0]
	v_add_f32_e32 v96, v96, v97
	v_pk_fma_f32 v[46:47], v[88:89], v[16:17], v[46:47] op_sel_hi:[1,0,1]
	v_pk_mul_f32 v[88:89], v[108:109], v[110:111] op_sel_hi:[1,0]
	v_add_f32_dpp v96, v96, v96 quad_perm:[1,0,3,2] row_mask:0xf bank_mask:0xf bound_ctrl:1
	v_pk_fma_f32 v[108:109], v[90:91], v[16:17], v[88:89] op_sel_hi:[1,0,1]
	v_pk_mul_f32 v[88:89], v[104:105], v[110:111] op_sel_hi:[1,0]
	v_add_f32_dpp v96, v96, v96 quad_perm:[2,3,0,1] row_mask:0xf bank_mask:0xf bound_ctrl:1
	v_pk_fma_f32 v[104:105], v[92:93], v[16:17], v[88:89] op_sel_hi:[1,0,1]
	v_pk_mul_f32 v[88:89], v[106:107], v[110:111] op_sel_hi:[1,0]
	v_add_f32_dpp v96, v96, v96 row_half_mirror row_mask:0xf bank_mask:0xf bound_ctrl:1
	v_pk_fma_f32 v[106:107], v[94:95], v[16:17], v[88:89] op_sel_hi:[1,0,1]
	s_waitcnt lgkmcnt(4)
; DI float row16_sum(float v) { v += dppf(v, 0); v += dppf(v, 1); v += dppf(v, 2); v += dppf(v, 3); return v; }
; DI void mamba_scan(CP p, const Ptrs& w, int l, int item, float* sm) {
;     ...
;   auto run_chunk = [&](int c, const float* bf, float* sy) {
;     flush(max(c - 1, 0));
;     MStep cur = lds_step(bf, 0);
; #pragma unroll
;     for (int j = 0; j < 16; ++j) {
;       MStep nxt = cur;
;       if (j + 1 < 16) nxt = lds_step(bf, j + 1);
;       f2v ya = M0 * cur.C0.xy + M1 * cur.C0.zw, yb = M2 * cur.C1.xy + M3 * cur.C1.zw;
;       ya += yb;
;       float yp = row16_sum(ya.x + ya.y);
;       float y = cur.sc.x * yp + cur.xq * cur.sc.y + cur.ds;
;       const float dA = cur.sc.x, xq = cur.xq;
;       M0 = M0 * dA + xq * cur.B0.xy; M1 = M1 * dA + xq * cur.B0.zw;
;       M2 = M2 * dA + xq * cur.B1.xy; M3 = M3 * dA + xq * cur.B1.zw;
;       sy[(ng == 0 ? j * 16 : 0) + ysel] = y;
;       cur = nxt;
;     }
;   };
	v_pk_mul_f32 v[40:41], v[108:109], v[40:41]
	v_add_f32_dpp v96, v96, v96 row_mirror row_mask:0xf bank_mask:0xf bound_ctrl:1
	v_pk_fma_f32 v[38:39], v[46:47], v[38:39], v[40:41]
	s_waitcnt lgkmcnt(3)
	v_pk_mul_f32 v[40:41], v[106:107], v[44:45]
	v_mul_f32_e32 v96, v110, v96
	v_pk_fma_f32 v[40:41], v[104:105], v[42:43], v[40:41]
	v_fmac_f32_e32 v96, v16, v111
	v_pk_add_f32 v[38:39], v[38:39], v[40:41]
	v_add_f32_e32 v96, v114, v96
	v_add_f32_e32 v38, v38, v39
	ds_write_b32 v70, v96 offset:37376
	ds_read_b128 v[88:91], v59 offset:4608
	v_add_f32_dpp v38, v38, v38 quad_perm:[1,0,3,2] row_mask:0xf bank_mask:0xf bound_ctrl:1
	ds_read_b128 v[92:95], v59 offset:4624
	ds_read_b128 v[96:99], v59 offset:12800
	v_add_f32_dpp v38, v38, v38 quad_perm:[2,3,0,1] row_mask:0xf bank_mask:0xf bound_ctrl:1
	ds_read_b128 v[100:103], v59 offset:12816
	ds_read_b32 v16, v60 offset:16960
	v_add_f32_dpp v38, v38, v38 row_half_mirror row_mask:0xf bank_mask:0xf bound_ctrl:1
	ds_read_b32 v114, v60 offset:17984
	ds_read_b64 v[110:111], v157 offset:18576
	v_add_f32_dpp v38, v38, v38 row_mirror row_mask:0xf bank_mask:0xf bound_ctrl:1
	s_waitcnt lgkmcnt(8)
	v_mul_f32_e32 v38, v112, v38
	v_fmac_f32_e32 v38, v8, v113
	v_add_f32_e32 v40, v115, v38
	v_pk_mul_f32 v[38:39], v[46:47], v[112:113] op_sel_hi:[1,0]
	ds_write_b32 v71, v40 offset:37376
	v_pk_fma_f32 v[46:47], v[22:23], v[8:9], v[38:39] op_sel_hi:[1,0,1]
	v_pk_mul_f32 v[22:23], v[108:109], v[112:113] op_sel_hi:[1,0]
	v_pk_fma_f32 v[108:109], v[24:25], v[8:9], v[22:23] op_sel_hi:[1,0,1]
	v_pk_mul_f32 v[22:23], v[104:105], v[112:113] op_sel_hi:[1,0]
	v_pk_fma_f32 v[104:105], v[26:27], v[8:9], v[22:23] op_sel_hi:[1,0,1]
	v_pk_mul_f32 v[22:23], v[106:107], v[112:113] op_sel_hi:[1,0]
	v_pk_fma_f32 v[106:107], v[28:29], v[8:9], v[22:23] op_sel_hi:[1,0,1]
	ds_read_b128 v[22:25], v59 offset:5120
	ds_read_b128 v[26:29], v59 offset:5136
	ds_read_b128 v[38:41], v59 offset:13312
	ds_read_b128 v[42:45], v59 offset:13328
	ds_read_b32 v8, v60 offset:17024
	ds_read_b32 v115, v60 offset:18048
	s_waitcnt lgkmcnt(14)
	ds_read_b64 v[112:113], v157 offset:18592
	s_waitcnt lgkmcnt(12)
	v_pk_mul_f32 v[98:99], v[108:109], v[98:99]
	v_pk_fma_f32 v[96:97], v[46:47], v[96:97], v[98:99]
	s_waitcnt lgkmcnt(11)
	v_pk_mul_f32 v[98:99], v[106:107], v[102:103]
	v_pk_fma_f32 v[98:99], v[104:105], v[100:101], v[98:99]
	v_pk_add_f32 v[96:97], v[96:97], v[98:99]
	s_waitcnt lgkmcnt(8)
	v_pk_mul_f32 v[46:47], v[46:47], v[110:111] op_sel_hi:[1,0]
	v_add_f32_e32 v96, v96, v97
	v_pk_fma_f32 v[46:47], v[88:89], v[16:17], v[46:47] op_sel_hi:[1,0,1]
	v_pk_mul_f32 v[88:89], v[108:109], v[110:111] op_sel_hi:[1,0]
	v_add_f32_dpp v96, v96, v96 quad_perm:[1,0,3,2] row_mask:0xf bank_mask:0xf bound_ctrl:1
	v_pk_fma_f32 v[108:109], v[90:91], v[16:17], v[88:89] op_sel_hi:[1,0,1]
	v_pk_mul_f32 v[88:89], v[104:105], v[110:111] op_sel_hi:[1,0]
	v_add_f32_dpp v96, v96, v96 quad_perm:[2,3,0,1] row_mask:0xf bank_mask:0xf bound_ctrl:1
	v_pk_fma_f32 v[104:105], v[92:93], v[16:17], v[88:89] op_sel_hi:[1,0,1]
	v_pk_mul_f32 v[88:89], v[106:107], v[110:111] op_sel_hi:[1,0]
	v_add_f32_dpp v96, v96, v96 row_half_mirror row_mask:0xf bank_mask:0xf bound_ctrl:1
	v_pk_fma_f32 v[106:107], v[94:95], v[16:17], v[88:89] op_sel_hi:[1,0,1]
	s_waitcnt lgkmcnt(4)
	v_pk_mul_f32 v[40:41], v[108:109], v[40:41]
	v_add_f32_dpp v96, v96, v96 row_mirror row_mask:0xf bank_mask:0xf bound_ctrl:1
	v_pk_fma_f32 v[38:39], v[46:47], v[38:39], v[40:41]
	v_mul_f32_e32 v96, v110, v96
	s_waitcnt lgkmcnt(3)
	v_pk_mul_f32 v[40:41], v[106:107], v[44:45]
	v_fmac_f32_e32 v96, v16, v111
	v_pk_fma_f32 v[40:41], v[104:105], v[42:43], v[40:41]
	v_add_f32_e32 v96, v114, v96
	v_pk_add_f32 v[38:39], v[38:39], v[40:41]
	ds_write_b32 v73, v96 offset:37376
	ds_read_b128 v[88:91], v59 offset:5632
	ds_read_b128 v[92:95], v59 offset:5648
	v_add_f32_e32 v38, v38, v39
	ds_read_b128 v[96:99], v59 offset:13824
	ds_read_b128 v[100:103], v59 offset:13840
	v_add_f32_dpp v38, v38, v38 quad_perm:[1,0,3,2] row_mask:0xf bank_mask:0xf bound_ctrl:1
	ds_read_b32 v16, v60 offset:17088
	ds_read_b32 v114, v60 offset:18112
	v_add_f32_dpp v38, v38, v38 quad_perm:[2,3,0,1] row_mask:0xf bank_mask:0xf bound_ctrl:1
	ds_read_b64 v[110:111], v157 offset:18608
	s_nop 0
	v_add_f32_dpp v38, v38, v38 row_half_mirror row_mask:0xf bank_mask:0xf bound_ctrl:1
	s_nop 1
	v_add_f32_dpp v38, v38, v38 row_mirror row_mask:0xf bank_mask:0xf bound_ctrl:1
	s_waitcnt lgkmcnt(8)
	v_mul_f32_e32 v38, v112, v38
	v_fmac_f32_e32 v38, v8, v113
	v_add_f32_e32 v40, v115, v38
	v_pk_mul_f32 v[38:39], v[46:47], v[112:113] op_sel_hi:[1,0]
	ds_write_b32 v74, v40 offset:37376
	v_pk_fma_f32 v[46:47], v[22:23], v[8:9], v[38:39] op_sel_hi:[1,0,1]
	v_pk_mul_f32 v[22:23], v[108:109], v[112:113] op_sel_hi:[1,0]
	v_pk_fma_f32 v[108:109], v[24:25], v[8:9], v[22:23] op_sel_hi:[1,0,1]
	v_pk_mul_f32 v[22:23], v[104:105], v[112:113] op_sel_hi:[1,0]
	v_pk_fma_f32 v[104:105], v[26:27], v[8:9], v[22:23] op_sel_hi:[1,0,1]
	v_pk_mul_f32 v[22:23], v[106:107], v[112:113] op_sel_hi:[1,0]
	v_pk_fma_f32 v[106:107], v[28:29], v[8:9], v[22:23] op_sel_hi:[1,0,1]
	ds_read_b128 v[22:25], v59 offset:6144
	ds_read_b128 v[26:29], v59 offset:6160
	ds_read_b128 v[38:41], v59 offset:14336
	ds_read_b128 v[42:45], v59 offset:14352
	ds_read_b32 v8, v60 offset:17152
	ds_read_b32 v115, v60 offset:18176
	s_waitcnt lgkmcnt(14)
	ds_read_b64 v[112:113], v157 offset:18624
	s_waitcnt lgkmcnt(12)
	v_pk_mul_f32 v[98:99], v[108:109], v[98:99]
	v_pk_fma_f32 v[96:97], v[46:47], v[96:97], v[98:99]
	s_waitcnt lgkmcnt(11)
	v_pk_mul_f32 v[98:99], v[106:107], v[102:103]
	v_pk_fma_f32 v[98:99], v[104:105], v[100:101], v[98:99]
	v_pk_add_f32 v[96:97], v[96:97], v[98:99]
	s_waitcnt lgkmcnt(8)
; DI float row16_sum(float v) { v += dppf(v, 0); v += dppf(v, 1); v += dppf(v, 2); v += dppf(v, 3); return v; }
; DI void mamba_scan(CP p, const Ptrs& w, int l, int item, float* sm) {
;     ...
;   auto run_chunk = [&](int c, const float* bf, float* sy) {
;     flush(max(c - 1, 0));
;     MStep cur = lds_step(bf, 0);
; #pragma unroll
;     for (int j = 0; j < 16; ++j) {
;       MStep nxt = cur;
;       if (j + 1 < 16) nxt = lds_step(bf, j + 1);
;       f2v ya = M0 * cur.C0.xy + M1 * cur.C0.zw, yb = M2 * cur.C1.xy + M3 * cur.C1.zw;
;       ya += yb;
;       float yp = row16_sum(ya.x + ya.y);
;       float y = cur.sc.x * yp + cur.xq * cur.sc.y + cur.ds;
;       const float dA = cur.sc.x, xq = cur.xq;
;       M0 = M0 * dA + xq * cur.B0.xy; M1 = M1 * dA + xq * cur.B0.zw;
;       M2 = M2 * dA + xq * cur.B1.xy; M3 = M3 * dA + xq * cur.B1.zw;
;       sy[(ng == 0 ? j * 16 : 0) + ysel] = y;
;       cur = nxt;
;     }
;   };
	v_pk_mul_f32 v[46:47], v[46:47], v[110:111] op_sel_hi:[1,0]
	v_add_f32_e32 v96, v96, v97
	v_pk_fma_f32 v[46:47], v[88:89], v[16:17], v[46:47] op_sel_hi:[1,0,1]
	v_pk_mul_f32 v[88:89], v[108:109], v[110:111] op_sel_hi:[1,0]
	v_add_f32_dpp v96, v96, v96 quad_perm:[1,0,3,2] row_mask:0xf bank_mask:0xf bound_ctrl:1
	v_pk_fma_f32 v[108:109], v[90:91], v[16:17], v[88:89] op_sel_hi:[1,0,1]
	v_pk_mul_f32 v[88:89], v[104:105], v[110:111] op_sel_hi:[1,0]
	v_add_f32_dpp v96, v96, v96 quad_perm:[2,3,0,1] row_mask:0xf bank_mask:0xf bound_ctrl:1
	v_pk_fma_f32 v[104:105], v[92:93], v[16:17], v[88:89] op_sel_hi:[1,0,1]
	v_pk_mul_f32 v[88:89], v[106:107], v[110:111] op_sel_hi:[1,0]
	v_add_f32_dpp v96, v96, v96 row_half_mirror row_mask:0xf bank_mask:0xf bound_ctrl:1
	v_pk_fma_f32 v[106:107], v[94:95], v[16:17], v[88:89] op_sel_hi:[1,0,1]
	s_waitcnt lgkmcnt(4)
	v_pk_mul_f32 v[40:41], v[108:109], v[40:41]
	v_add_f32_dpp v96, v96, v96 row_mirror row_mask:0xf bank_mask:0xf bound_ctrl:1
	v_pk_fma_f32 v[38:39], v[46:47], v[38:39], v[40:41]
	v_mul_f32_e32 v96, v110, v96
	s_waitcnt lgkmcnt(3)
	v_pk_mul_f32 v[40:41], v[106:107], v[44:45]
	v_fmac_f32_e32 v96, v16, v111
	v_pk_fma_f32 v[40:41], v[104:105], v[42:43], v[40:41]
	v_add_f32_e32 v96, v114, v96
	v_pk_add_f32 v[38:39], v[38:39], v[40:41]
	ds_write_b32 v75, v96 offset:37376
	ds_read_b128 v[88:91], v59 offset:6656
	ds_read_b128 v[92:95], v59 offset:6672
	ds_read_b128 v[96:99], v59 offset:14848
	ds_read_b128 v[100:103], v59 offset:14864
	v_add_f32_e32 v38, v38, v39
	ds_read_b32 v16, v60 offset:17216
	ds_read_b32 v118, v60 offset:18240
	v_add_f32_dpp v38, v38, v38 quad_perm:[1,0,3,2] row_mask:0xf bank_mask:0xf bound_ctrl:1
	ds_read_b64 v[116:117], v157 offset:18640
	s_nop 0
	v_add_f32_dpp v38, v38, v38 quad_perm:[2,3,0,1] row_mask:0xf bank_mask:0xf bound_ctrl:1
	s_nop 1
	v_add_f32_dpp v38, v38, v38 row_half_mirror row_mask:0xf bank_mask:0xf bound_ctrl:1
	s_nop 1
	v_add_f32_dpp v38, v38, v38 row_mirror row_mask:0xf bank_mask:0xf bound_ctrl:1
	s_waitcnt lgkmcnt(8)
	v_mul_f32_e32 v38, v112, v38
	v_fmac_f32_e32 v38, v8, v113
	v_add_f32_e32 v40, v115, v38
	v_pk_mul_f32 v[38:39], v[46:47], v[112:113] op_sel_hi:[1,0]
	ds_write_b32 v76, v40 offset:37376
	v_pk_fma_f32 v[22:23], v[22:23], v[8:9], v[38:39] op_sel_hi:[1,0,1]
	v_pk_mul_f32 v[38:39], v[108:109], v[112:113] op_sel_hi:[1,0]
	ds_read_b128 v[42:45], v59 offset:7168
	v_pk_fma_f32 v[24:25], v[24:25], v[8:9], v[38:39] op_sel_hi:[1,0,1]
	v_pk_mul_f32 v[38:39], v[104:105], v[112:113] op_sel_hi:[1,0]
	v_pk_fma_f32 v[26:27], v[26:27], v[8:9], v[38:39] op_sel_hi:[1,0,1]
	v_pk_mul_f32 v[38:39], v[106:107], v[112:113] op_sel_hi:[1,0]
	ds_read_b128 v[104:107], v59 offset:7184
	v_pk_fma_f32 v[28:29], v[28:29], v[8:9], v[38:39] op_sel_hi:[1,0,1]
	ds_read_b128 v[108:111], v59 offset:15360
	ds_read_b128 v[112:115], v59 offset:15376
	ds_read_b32 v8, v60 offset:17280
	ds_read_b32 v119, v60 offset:18304
	s_waitcnt lgkmcnt(14)
	ds_read_b64 v[46:47], v157 offset:18656
	s_waitcnt lgkmcnt(11)
	v_pk_mul_f32 v[38:39], v[24:25], v[98:99]
	v_pk_mul_f32 v[40:41], v[28:29], v[102:103]
	v_pk_fma_f32 v[38:39], v[22:23], v[96:97], v[38:39]
	v_pk_fma_f32 v[40:41], v[26:27], v[100:101], v[40:41]
	v_pk_add_f32 v[38:39], v[38:39], v[40:41]
	v_add_f32_e32 v38, v38, v39
	s_waitcnt lgkmcnt(8)
	v_pk_mul_f32 v[22:23], v[22:23], v[116:117] op_sel_hi:[1,0]
	v_pk_fma_f32 v[40:41], v[88:89], v[16:17], v[22:23] op_sel_hi:[1,0,1]
	v_add_f32_dpp v38, v38, v38 quad_perm:[1,0,3,2] row_mask:0xf bank_mask:0xf bound_ctrl:1
	v_pk_mul_f32 v[22:23], v[24:25], v[116:117] op_sel_hi:[1,0]
	v_pk_fma_f32 v[96:97], v[90:91], v[16:17], v[22:23] op_sel_hi:[1,0,1]
	v_add_f32_dpp v38, v38, v38 quad_perm:[2,3,0,1] row_mask:0xf bank_mask:0xf bound_ctrl:1
	v_pk_mul_f32 v[22:23], v[26:27], v[116:117] op_sel_hi:[1,0]
	v_pk_fma_f32 v[98:99], v[92:93], v[16:17], v[22:23] op_sel_hi:[1,0,1]
	v_add_f32_dpp v38, v38, v38 row_half_mirror row_mask:0xf bank_mask:0xf bound_ctrl:1
	v_pk_mul_f32 v[22:23], v[28:29], v[116:117] op_sel_hi:[1,0]
	v_pk_fma_f32 v[100:101], v[94:95], v[16:17], v[22:23] op_sel_hi:[1,0,1]
	v_add_f32_dpp v38, v38, v38 row_mirror row_mask:0xf bank_mask:0xf bound_ctrl:1
	v_mul_f32_e32 v38, v116, v38
	v_fmac_f32_e32 v38, v16, v117
	v_add_f32_e32 v38, v118, v38
	ds_write_b32 v77, v38 offset:37376
	ds_read_b128 v[26:29], v59 offset:7680
	ds_read_b128 v[22:25], v59 offset:7696
	ds_read_b128 v[88:91], v59 offset:15872
	ds_read_b128 v[92:95], v59 offset:15888
	s_waitcnt lgkmcnt(6)
	v_pk_mul_f32 v[102:103], v[96:97], v[110:111]
	ds_read_b32 v16, v60 offset:17344
	v_pk_fma_f32 v[102:103], v[40:41], v[108:109], v[102:103]
	v_pk_mul_f32 v[108:109], v[100:101], v[114:115]
	s_waitcnt lgkmcnt(6)
	v_pk_mul_f32 v[40:41], v[40:41], v[46:47] op_sel_hi:[1,0]
	ds_read_b32 v116, v60 offset:18368
	v_pk_fma_f32 v[108:109], v[98:99], v[112:113], v[108:109]
	v_pk_fma_f32 v[42:43], v[42:43], v[8:9], v[40:41] op_sel_hi:[1,0,1]
	v_pk_mul_f32 v[40:41], v[96:97], v[46:47] op_sel_hi:[1,0]
	v_pk_add_f32 v[102:103], v[102:103], v[108:109]
	ds_read_b64 v[38:39], v157 offset:18672
	v_add_f32_e32 v102, v102, v103
	v_pk_fma_f32 v[44:45], v[44:45], v[8:9], v[40:41] op_sel_hi:[1,0,1]
	v_pk_mul_f32 v[40:41], v[98:99], v[46:47] op_sel_hi:[1,0]
	v_add_f32_dpp v102, v102, v102 quad_perm:[1,0,3,2] row_mask:0xf bank_mask:0xf bound_ctrl:1
	v_pk_fma_f32 v[40:41], v[104:105], v[8:9], v[40:41] op_sel_hi:[1,0,1]
	s_waitcnt lgkmcnt(4)
; DI float bf2f(bf16_t h) { return __uint_as_float(((unsigned)h) << 16); }
; DI float siluf(float x) { return x * sigmf(x); }
; DI float row16_sum(float v) { v += dppf(v, 0); v += dppf(v, 1); v += dppf(v, 2); v += dppf(v, 3); return v; }
; DI void mamba_scan(CP p, const Ptrs& w, int l, int item, float* sm) {
;     ...
;   auto stage = [&](const MPre& P, float* bufp) {
; #pragma unroll
;     for (int i = 0; i < 2; ++i) {
;       int idx = tid + 256 * i, j = idx >> 5, q = idx & 31;
;       float f[8];
;       unpack8(P.pbq[i], f);
;       float* d = bufp + (q < 16 ? 0 : 2048) + j * 128 + (q & 15) * 8;
;       *(float4*)d = make_float4(f[0], f[1], f[2], f[3]);
;       *(float4*)(d + 4) = make_float4(f[4], f[5], f[6], f[7]);
;     }
;     {
;       float xs = siluf(wX0 * P.pxm[0] * bf2f(P.px[0]) + wX1 * bf2f(P.px[1]) + wX2 * P.pxm[1] * bf2f(P.px[2]) + bX);
;       bufp[4096 + xj * 16 + xp] = xs * P.pdt[0];
;       bufp[4096 + 256 + xj * 16 + xp] = Dsk * xs;
;       if (xp == 0) *(float4*)(bufp + 4096 + 512 + xj * 4) = make_float4(P.pdt[1], P.pdt[2], 0.f, 0.f);
;     }
;   };
;     ...
;   auto run_chunk = [&](int c, const float* bf, float* sy) {
;     flush(max(c - 1, 0));
;     MStep cur = lds_step(bf, 0);
; #pragma unroll
;     for (int j = 0; j < 16; ++j) {
;       MStep nxt = cur;
;       if (j + 1 < 16) nxt = lds_step(bf, j + 1);
;       f2v ya = M0 * cur.C0.xy + M1 * cur.C0.zw, yb = M2 * cur.C1.xy + M3 * cur.C1.zw;
;       ya += yb;
;       float yp = row16_sum(ya.x + ya.y);
;       float y = cur.sc.x * yp + cur.xq * cur.sc.y + cur.ds;
;       const float dA = cur.sc.x, xq = cur.xq;
;       M0 = M0 * dA + xq * cur.B0.xy; M1 = M1 * dA + xq * cur.B0.zw;
;       M2 = M2 * dA + xq * cur.B1.xy; M3 = M3 * dA + xq * cur.B1.zw;
;       sy[(ng == 0 ? j * 16 : 0) + ysel] = y;
;       cur = nxt;
;     }
;   };
	v_pk_mul_f32 v[90:91], v[44:45], v[90:91]
	v_add_f32_dpp v102, v102, v102 quad_perm:[2,3,0,1] row_mask:0xf bank_mask:0xf bound_ctrl:1
	v_pk_fma_f32 v[88:89], v[42:43], v[88:89], v[90:91]
	s_nop 0
	v_add_f32_dpp v102, v102, v102 row_half_mirror row_mask:0xf bank_mask:0xf bound_ctrl:1
	s_nop 1
	v_add_f32_dpp v102, v102, v102 row_mirror row_mask:0xf bank_mask:0xf bound_ctrl:1
	v_mul_f32_e32 v102, v46, v102
	v_fmac_f32_e32 v102, v8, v47
	v_pk_mul_f32 v[46:47], v[100:101], v[46:47] op_sel_hi:[1,0]
	v_add_f32_e32 v102, v119, v102
	v_pk_fma_f32 v[46:47], v[106:107], v[8:9], v[46:47] op_sel_hi:[1,0,1]
	ds_write_b32 v78, v102 offset:37376
	s_waitcnt lgkmcnt(4)
	v_pk_mul_f32 v[90:91], v[46:47], v[94:95]
	v_pk_fma_f32 v[90:91], v[40:41], v[92:93], v[90:91]
	v_pk_add_f32 v[88:89], v[88:89], v[90:91]
	s_waitcnt vmcnt(8)
	v_lshlrev_b32_e32 v90, 16, v5
	v_add_f32_e32 v8, v88, v89
	v_lshlrev_b32_e32 v88, 16, v4
	v_and_b32_e32 v89, 0xffff0000, v4
	v_add_f32_dpp v8, v8, v8 quad_perm:[1,0,3,2] row_mask:0xf bank_mask:0xf bound_ctrl:1
	v_and_b32_e32 v91, 0xffff0000, v5
	v_lshlrev_b32_e32 v4, 16, v6
	v_add_f32_dpp v8, v8, v8 quad_perm:[2,3,0,1] row_mask:0xf bank_mask:0xf bound_ctrl:1
	v_and_b32_e32 v5, 0xffff0000, v6
	v_lshlrev_b32_e32 v6, 16, v7
	v_add_f32_dpp v8, v8, v8 row_half_mirror row_mask:0xf bank_mask:0xf bound_ctrl:1
	v_and_b32_e32 v7, 0xffff0000, v7
	s_nop 0
	v_add_f32_dpp v8, v8, v8 row_mirror row_mask:0xf bank_mask:0xf bound_ctrl:1
	s_waitcnt lgkmcnt(1)
	v_mul_f32_e32 v8, v38, v8
	v_fmac_f32_e32 v8, v16, v39
	v_add_f32_e32 v8, v116, v8
	ds_write_b32 v80, v8 offset:37376
	ds_write_b128 v58, v[88:91] offset:18688
	ds_write_b128 v58, v[4:7] offset:18704
	v_lshlrev_b32_e32 v4, 16, v0
	v_and_b32_e32 v5, 0xffff0000, v0
	v_lshlrev_b32_e32 v6, 16, v1
	v_and_b32_e32 v7, 0xffff0000, v1
	v_mul_f32_e32 v0, v49, v87
	v_lshlrev_b32_e32 v1, 16, v64
	v_mul_f32_e32 v0, v0, v1
	v_lshlrev_b32_e32 v1, 16, v69
	v_fmac_f32_e32 v0, v50, v1
	v_mul_f32_e32 v1, v51, v86
	v_lshlrev_b32_e32 v8, 16, v79
	v_fmac_f32_e32 v0, v1, v8
	v_add_f32_e32 v8, v52, v0
	v_mul_f32_e32 v0, 0xbfb8aa3b, v8
	v_exp_f32_e32 v39, v0
	v_lshlrev_b32_e32 v0, 16, v2
	v_and_b32_e32 v1, 0xffff0000, v2
	v_lshlrev_b32_e32 v2, 16, v3
	v_add_f32_e32 v39, 1.0, v39
	v_rcp_f32_e32 v39, v39
	v_and_b32_e32 v3, 0xffff0000, v3
	ds_write_b128 v58, v[4:7] offset:22784
	ds_write_b128 v58, v[0:3] offset:22800
	v_mul_f32_e32 v0, v8, v39
	v_mul_f32_e32 v1, v10, v0
	v_mul_f32_e32 v0, v53, v0
	ds_write2st64_b32 v57, v1, v0 offset0:137 offset1:141
	s_and_saveexec_b64 s[4:5], vcc
	v_mov_b32_e32 v8, v11
	v_mov_b32_e32 v10, v157
	v_mov_b32_e32 v11, v157
	ds_write_b128 v72, v[8:11] offset:37120
	s_or_b64 exec, exec, s[4:5]
	s_add_i32 s7, s7, 2
	v_pk_mul_f32 v[0:1], v[42:43], v[38:39] op_sel_hi:[1,0]
	s_min_u32 s4, s7, 0x20c
	v_pk_fma_f32 v[108:109], v[26:27], v[16:17], v[0:1] op_sel_hi:[1,0,1]
	v_pk_mul_f32 v[0:1], v[44:45], v[38:39] op_sel_hi:[1,0]
	s_lshl_b32 s4, s4, 4
	v_pk_fma_f32 v[110:111], v[28:29], v[16:17], v[0:1] op_sel_hi:[1,0,1]
	v_pk_mul_f32 v[0:1], v[40:41], v[38:39] op_sel_hi:[1,0]
	v_cndmask_b32_e64 v87, 1.0, 0, s[42:43]
	v_pk_fma_f32 v[112:113], v[22:23], v[16:17], v[0:1] op_sel_hi:[1,0,1]
	v_pk_mul_f32 v[0:1], v[46:47], v[38:39] op_sel_hi:[1,0]
	s_add_i32 s42, s4, 48
	v_pk_fma_f32 v[46:47], v[24:25], v[16:17], v[0:1] op_sel_hi:[1,0,1]
	v_add_u32_e32 v0, s42, v55
	v_cmp_lt_i32_e64 s[4:5], s37, v0
	v_add_u32_e32 v2, s42, v56
	v_add_u32_e32 v8, s42, v54
	v_cndmask_b32_e64 v1, v231, v232, s[4:5]
	v_cmp_lt_i32_e64 s[4:5], s37, v2
	v_sub_u32_e32 v1, v1, v0
	v_cndmask_b32_e64 v0, v1, v0, s[40:41]
	v_cndmask_b32_e64 v3, v231, v232, s[4:5]
	v_cmp_lt_i32_e64 s[4:5], s37, v8
	v_sub_u32_e32 v3, v3, v2
	v_cndmask_b32_e64 v2, v3, v2, s[40:41]
	v_cndmask_b32_e64 v9, v231, v232, s[4:5]
	v_sub_u32_e32 v9, v9, v8
	v_cndmask_b32_e64 v8, v9, v8, s[40:41]
	v_ashrrev_i32_e32 v9, 31, v8
	v_lshl_add_u64 v[10:11], v[8:9], 0, s[90:91]
	v_and_b32_e32 v9, 0xfffffeff, v8
	v_cmp_eq_u32_e64 s[42:43], 0, v9
	v_ashrrev_i32_e32 v1, 31, v0
	v_ashrrev_i32_e32 v3, 31, v2
	v_mov_b64_e32 v[22:23], s[48:49]
	v_and_b32_e32 v16, 0xffffdfff, v8
	v_cndmask_b32_e64 v8, v233, 0, s[42:43]
	v_lshl_add_u64 v[0:1], v[0:1], 0, s[90:91]
	v_lshl_add_u64 v[2:3], v[2:3], 0, s[90:91]
	v_mad_u64_u32 v[22:23], s[4:5], v10, s92, v[22:23]
	v_add_u32_e32 v8, v8, v48
	v_cndmask_b32_e64 v86, 1.0, 0, s[44:45]
	v_lshlrev_b64 v[0:1], 10, v[0:1]
	v_lshlrev_b64 v[2:3], 10, v[2:3]
	v_mad_i32_i24 v23, v11, s92, v23
	v_ashrrev_i32_e32 v9, 31, v8
	v_cmp_eq_u32_e64 s[44:45], s37, v16
	v_lshlrev_b64 v[26:27], 7, v[10:11]
	v_lshl_add_u64 v[0:1], v[30:31], 0, v[0:1]
	v_lshl_add_u64 v[2:3], v[30:31], 0, v[2:3]
	v_lshl_add_u64 v[8:9], v[8:9], 1, v[22:23]
	v_lshl_add_u64 v[22:23], v[22:23], 0, v[156:157]
	v_cndmask_b32_e64 v24, v234, 0, s[44:45]
	v_mov_b32_e32 v25, v157
	v_lshl_or_b32 v26, s6, 3, v26
	s_waitcnt lgkmcnt(0)
	s_barrier
; DI float row16_sum(float v) { v += dppf(v, 0); v += dppf(v, 1); v += dppf(v, 2); v += dppf(v, 3); return v; }
; DI void mamba_scan(CP p, const Ptrs& w, int l, int item, float* sm) {
;     ...
;   auto load = [&](int c, MPre& P) {
; #pragma unroll
;     for (int i = 0; i < 2; ++i) {
;       int idx = tid + 256 * i, j = idx >> 5, q = idx & 31;
;       int ii = pos2i(c * 16 + j, dir);
;       P.pbq[i] = *(const uint4*)(mbc + ((size_t)b * TPB + ii) * 512 + (q < 16 ? 0 : 256) + gp * 128 + (q & 15) * 8);
;     }
;     {
;       int pos = c * 16 + xj, ii = pos2i(pos, dir);
;       size_t tok = (size_t)b * TPB + ii;
;       const bf16_t* prw = w.pC + tok * SPC;
;       bool hp = (ii != 0) && (ii != CTXL), hn = (ii != CTXL - 1) && (ii != TPB - 1);
;       P.px[0] = prw[chX + (hp ? -SPC : 0)]; P.px[1] = prw[chX]; P.px[2] = prw[chX + (hn ? SPC : 0)];
;       P.pxm[0] = hp ? 1.f : 0.f; P.pxm[1] = hn ? 1.f : 0.f;
;       float2 dd = *(const float2*)(w.mdt + (tok * 16 + dir * 8 + hd) * 2);
;       P.pdt[0] = dd.x; P.pdt[1] = dd.y; P.pdt[2] = w.mcb[tok * 2 + gp];
;     }
;   };
;     ...
;   auto run_chunk = [&](int c, const float* bf, float* sy) {
;     flush(max(c - 1, 0));
;     MStep cur = lds_step(bf, 0);
; #pragma unroll
;     for (int j = 0; j < 16; ++j) {
;       MStep nxt = cur;
;       if (j + 1 < 16) nxt = lds_step(bf, j + 1);
;       f2v ya = M0 * cur.C0.xy + M1 * cur.C0.zw, yb = M2 * cur.C1.xy + M3 * cur.C1.zw;
;       ya += yb;
;       float yp = row16_sum(ya.x + ya.y);
;       float y = cur.sc.x * yp + cur.xq * cur.sc.y + cur.ds;
;       const float dA = cur.sc.x, xq = cur.xq;
;       M0 = M0 * dA + xq * cur.B0.xy; M1 = M1 * dA + xq * cur.B0.zw;
;       M2 = M2 * dA + xq * cur.B1.xy; M3 = M3 * dA + xq * cur.B1.zw;
;       sy[(ng == 0 ? j * 16 : 0) + ysel] = y;
;       cur = nxt;
;     }
;   };
	global_load_dwordx4 v[4:7], v[0:1], off
	s_nop 0
	global_load_dwordx4 v[0:3], v[2:3], off
	v_lshl_add_u64 v[24:25], v[22:23], 0, v[24:25]
	v_lshl_add_u64 v[26:27], s[46:47], 0, v[26:27]
	v_lshl_add_u64 v[28:29], v[10:11], 3, s[50:51]
	global_load_ushort v64, v[8:9], off
	global_load_ushort v69, v[22:23], off
	global_load_ushort v79, v[24:25], off
	global_load_dwordx2 v[10:11], v[26:27], off
	s_nop 0
	global_load_dword v9, v[28:29], off
	v_cmp_lt_i32_e64 s[4:5], s37, v82
	ds_read_b32 v8, v57 offset:37376
	ds_read_b128 v[22:25], v59 offset:18688
	v_cndmask_b32_e64 v16, v231, v232, s[4:5]
	v_add_u32_e32 v16, v16, v81
	v_cndmask_b32_e64 v26, v16, v82, s[40:41]
	v_ashrrev_i32_e32 v27, 31, v26
	v_lshl_add_u64 v[26:27], v[26:27], 0, s[90:91]
	v_lshlrev_b64 v[26:27], 10, v[26:27]
	s_waitcnt lgkmcnt(1)
	v_cvt_pk_bf16_f32 v8, v8, s0
	v_lshl_add_u64 v[26:27], v[34:35], 0, v[26:27]
	global_store_short v[26:27], v8, off
	s_waitcnt lgkmcnt(0)
	v_add_u32_e32 v8, 0x8800, v60
	s_mov_b32 s4, 0x9000
	ds_read2_b32 v[114:115], v8 offset0:64 offset1:80
	v_add_u32_e32 v8, 0x8c00, v60
	ds_read2_b32 v[116:117], v8 offset0:64 offset1:80
	v_add_u32_e64 v8, s4, 0
	ds_read2_b64 v[26:29], v8 offset0:32 offset1:34
	ds_read_b128 v[38:41], v59 offset:18704
	ds_read_b128 v[42:45], v59 offset:19200
	ds_read_b128 v[88:91], v59 offset:26880
	ds_read_b128 v[92:95], v59 offset:19216
	ds_read_b128 v[96:99], v59 offset:26896
	ds_read_b128 v[100:103], v59 offset:27392
	ds_read_b128 v[104:107], v59 offset:27408
	s_waitcnt lgkmcnt(4)
	v_pk_mul_f32 v[90:91], v[110:111], v[90:91]
	v_pk_fma_f32 v[88:89], v[108:109], v[88:89], v[90:91]
	s_waitcnt lgkmcnt(2)
	v_pk_mul_f32 v[90:91], v[46:47], v[98:99]
	v_pk_fma_f32 v[90:91], v[112:113], v[96:97], v[90:91]
	v_pk_add_f32 v[88:89], v[88:89], v[90:91]
	v_add_f32_e32 v8, v88, v89
	v_pk_mul_f32 v[88:89], v[108:109], v[26:27] op_sel_hi:[1,0]
	v_pk_fma_f32 v[108:109], v[22:23], v[114:115], v[88:89] op_sel_hi:[1,0,1]
	v_add_f32_dpp v8, v8, v8 quad_perm:[1,0,3,2] row_mask:0xf bank_mask:0xf bound_ctrl:1
	v_pk_mul_f32 v[22:23], v[110:111], v[26:27] op_sel_hi:[1,0]
	v_pk_fma_f32 v[110:111], v[24:25], v[114:115], v[22:23] op_sel_hi:[1,0,1]
	v_add_f32_dpp v8, v8, v8 quad_perm:[2,3,0,1] row_mask:0xf bank_mask:0xf bound_ctrl:1
	v_pk_mul_f32 v[22:23], v[112:113], v[26:27] op_sel_hi:[1,0]
	s_waitcnt lgkmcnt(1)
	v_pk_mul_f32 v[102:103], v[110:111], v[102:103]
	v_add_f32_dpp v8, v8, v8 row_half_mirror row_mask:0xf bank_mask:0xf bound_ctrl:1
	v_pk_fma_f32 v[112:113], v[38:39], v[114:115], v[22:23] op_sel_hi:[1,0,1]
	v_pk_mul_f32 v[22:23], v[46:47], v[26:27] op_sel_hi:[1,0]
	v_add_f32_dpp v8, v8, v8 row_mirror row_mask:0xf bank_mask:0xf bound_ctrl:1
	v_pk_fma_f32 v[100:101], v[108:109], v[100:101], v[102:103]
	v_mul_f32_e32 v8, v26, v8
	v_fmac_f32_e32 v8, v114, v27
	v_pk_fma_f32 v[26:27], v[40:41], v[114:115], v[22:23] op_sel_hi:[1,0,1]
	v_add_f32_e32 v8, v116, v8
	s_waitcnt lgkmcnt(0)
	v_pk_mul_f32 v[102:103], v[26:27], v[106:107]
	v_pk_mul_f32 v[26:27], v[26:27], v[28:29] op_sel_hi:[1,0]
	ds_write_b32 v61, v8 offset:38400
	ds_read_b128 v[22:25], v59 offset:19712
	ds_read_b128 v[38:41], v59 offset:19728
	ds_read_b128 v[88:91], v59 offset:27904
	ds_read_b128 v[96:99], v59 offset:27920
	v_pk_fma_f32 v[102:103], v[112:113], v[104:105], v[102:103]
	ds_read_b32 v8, v60 offset:35200
	v_pk_add_f32 v[100:101], v[100:101], v[102:103]
	ds_read_b32 v114, v60 offset:36224
	v_add_f32_e32 v16, v100, v101
	ds_read_b64 v[46:47], v157 offset:37152
	v_pk_mul_f32 v[100:101], v[108:109], v[28:29] op_sel_hi:[1,0]
	v_add_f32_dpp v16, v16, v16 quad_perm:[1,0,3,2] row_mask:0xf bank_mask:0xf bound_ctrl:1
	s_nop 1
	v_add_f32_dpp v16, v16, v16 quad_perm:[2,3,0,1] row_mask:0xf bank_mask:0xf bound_ctrl:1
	s_nop 1
	v_add_f32_dpp v16, v16, v16 row_half_mirror row_mask:0xf bank_mask:0xf bound_ctrl:1
	s_nop 1
	v_add_f32_dpp v16, v16, v16 row_mirror row_mask:0xf bank_mask:0xf bound_ctrl:1
	v_mul_f32_e32 v16, v28, v16
	v_fmac_f32_e32 v16, v115, v29
	v_add_f32_e32 v102, v117, v16
	v_mov_b32_e32 v16, v115
	ds_write_b32 v62, v102 offset:38400
	v_pk_fma_f32 v[104:105], v[42:43], v[16:17], v[100:101] op_sel_hi:[1,0,1]
	v_pk_mul_f32 v[42:43], v[110:111], v[28:29] op_sel_hi:[1,0]
	v_pk_fma_f32 v[110:111], v[94:95], v[16:17], v[26:27] op_sel_hi:[1,0,1]
	v_pk_fma_f32 v[106:107], v[44:45], v[16:17], v[42:43] op_sel_hi:[1,0,1]
	v_pk_mul_f32 v[42:43], v[112:113], v[28:29] op_sel_hi:[1,0]
	ds_read_b128 v[26:29], v59 offset:20224
	v_pk_fma_f32 v[108:109], v[92:93], v[16:17], v[42:43] op_sel_hi:[1,0,1]
	ds_read_b128 v[42:45], v59 offset:20240
	ds_read_b128 v[92:95], v59 offset:28416
	ds_read_b128 v[100:103], v59 offset:28432
	ds_read_b32 v16, v60 offset:35264
	ds_read_b32 v115, v60 offset:36288
	s_waitcnt lgkmcnt(14)
	ds_read_b64 v[112:113], v157 offset:37168
	s_waitcnt lgkmcnt(10)
	v_pk_mul_f32 v[90:91], v[106:107], v[90:91]
	v_pk_fma_f32 v[88:89], v[104:105], v[88:89], v[90:91]
	v_pk_mul_f32 v[90:91], v[110:111], v[98:99]
	v_pk_fma_f32 v[90:91], v[108:109], v[96:97], v[90:91]
	v_pk_add_f32 v[88:89], v[88:89], v[90:91]
	v_add_f32_e32 v88, v88, v89
	s_nop 1
	v_add_f32_dpp v88, v88, v88 quad_perm:[1,0,3,2] row_mask:0xf bank_mask:0xf bound_ctrl:1
	s_nop 1
	v_add_f32_dpp v88, v88, v88 quad_perm:[2,3,0,1] row_mask:0xf bank_mask:0xf bound_ctrl:1
	s_nop 1
	v_add_f32_dpp v88, v88, v88 row_half_mirror row_mask:0xf bank_mask:0xf bound_ctrl:1
	s_nop 1
	v_add_f32_dpp v88, v88, v88 row_mirror row_mask:0xf bank_mask:0xf bound_ctrl:1
	s_waitcnt lgkmcnt(8)
; DI float row16_sum(float v) { v += dppf(v, 0); v += dppf(v, 1); v += dppf(v, 2); v += dppf(v, 3); return v; }
; DI void mamba_scan(CP p, const Ptrs& w, int l, int item, float* sm) {
;     ...
;   auto run_chunk = [&](int c, const float* bf, float* sy) {
;     flush(max(c - 1, 0));
;     MStep cur = lds_step(bf, 0);
; #pragma unroll
;     for (int j = 0; j < 16; ++j) {
;       MStep nxt = cur;
;       if (j + 1 < 16) nxt = lds_step(bf, j + 1);
;       f2v ya = M0 * cur.C0.xy + M1 * cur.C0.zw, yb = M2 * cur.C1.xy + M3 * cur.C1.zw;
;       ya += yb;
;       float yp = row16_sum(ya.x + ya.y);
;       float y = cur.sc.x * yp + cur.xq * cur.sc.y + cur.ds;
;       const float dA = cur.sc.x, xq = cur.xq;
;       M0 = M0 * dA + xq * cur.B0.xy; M1 = M1 * dA + xq * cur.B0.zw;
;       M2 = M2 * dA + xq * cur.B1.xy; M3 = M3 * dA + xq * cur.B1.zw;
;       sy[(ng == 0 ? j * 16 : 0) + ysel] = y;
;       cur = nxt;
;     }
;   };
	v_mul_f32_e32 v88, v46, v88
	v_fmac_f32_e32 v88, v8, v47
	v_add_f32_e32 v90, v114, v88
	v_pk_mul_f32 v[88:89], v[104:105], v[46:47] op_sel_hi:[1,0]
	ds_write_b32 v63, v90 offset:38400
	v_pk_fma_f32 v[104:105], v[22:23], v[8:9], v[88:89] op_sel_hi:[1,0,1]
	v_pk_mul_f32 v[22:23], v[106:107], v[46:47] op_sel_hi:[1,0]
	v_pk_fma_f32 v[106:107], v[24:25], v[8:9], v[22:23] op_sel_hi:[1,0,1]
	v_pk_mul_f32 v[22:23], v[108:109], v[46:47] op_sel_hi:[1,0]
	v_pk_fma_f32 v[108:109], v[38:39], v[8:9], v[22:23] op_sel_hi:[1,0,1]
	v_pk_mul_f32 v[22:23], v[110:111], v[46:47] op_sel_hi:[1,0]
	s_waitcnt lgkmcnt(5)
	v_pk_mul_f32 v[94:95], v[106:107], v[94:95]
	v_pk_fma_f32 v[46:47], v[40:41], v[8:9], v[22:23] op_sel_hi:[1,0,1]
	ds_read_b128 v[22:25], v59 offset:20736
	v_pk_fma_f32 v[92:93], v[104:105], v[92:93], v[94:95]
	s_waitcnt lgkmcnt(4)
	v_pk_mul_f32 v[94:95], v[46:47], v[102:103]
	ds_read_b128 v[38:41], v59 offset:20752
	v_pk_fma_f32 v[94:95], v[108:109], v[100:101], v[94:95]
	ds_read_b128 v[88:91], v59 offset:28928
	v_pk_add_f32 v[92:93], v[92:93], v[94:95]
	ds_read_b128 v[96:99], v59 offset:28944
	v_add_f32_e32 v92, v92, v93
	ds_read_b32 v8, v60 offset:35328
	ds_read_b32 v114, v60 offset:36352
	v_add_f32_dpp v92, v92, v92 quad_perm:[1,0,3,2] row_mask:0xf bank_mask:0xf bound_ctrl:1
	ds_read_b64 v[110:111], v157 offset:37184
	s_nop 0
	v_add_f32_dpp v92, v92, v92 quad_perm:[2,3,0,1] row_mask:0xf bank_mask:0xf bound_ctrl:1
	s_nop 1
	v_add_f32_dpp v92, v92, v92 row_half_mirror row_mask:0xf bank_mask:0xf bound_ctrl:1
	s_nop 1
	v_add_f32_dpp v92, v92, v92 row_mirror row_mask:0xf bank_mask:0xf bound_ctrl:1
	s_waitcnt lgkmcnt(8)
	v_mul_f32_e32 v92, v112, v92
	v_fmac_f32_e32 v92, v16, v113
	v_add_f32_e32 v94, v115, v92
	v_pk_mul_f32 v[92:93], v[104:105], v[112:113] op_sel_hi:[1,0]
	ds_write_b32 v65, v94 offset:38400
	v_pk_fma_f32 v[104:105], v[26:27], v[16:17], v[92:93] op_sel_hi:[1,0,1]
	v_pk_mul_f32 v[26:27], v[106:107], v[112:113] op_sel_hi:[1,0]
	v_pk_fma_f32 v[106:107], v[28:29], v[16:17], v[26:27] op_sel_hi:[1,0,1]
	v_pk_mul_f32 v[26:27], v[108:109], v[112:113] op_sel_hi:[1,0]
	v_pk_fma_f32 v[108:109], v[42:43], v[16:17], v[26:27] op_sel_hi:[1,0,1]
	v_pk_mul_f32 v[26:27], v[46:47], v[112:113] op_sel_hi:[1,0]
	v_pk_fma_f32 v[46:47], v[44:45], v[16:17], v[26:27] op_sel_hi:[1,0,1]
	ds_read_b128 v[26:29], v59 offset:21248
	ds_read_b128 v[42:45], v59 offset:21264
	ds_read_b128 v[92:95], v59 offset:29440
	ds_read_b128 v[100:103], v59 offset:29456
	ds_read_b32 v16, v60 offset:35392
	ds_read_b32 v115, v60 offset:36416
	s_waitcnt lgkmcnt(14)
	ds_read_b64 v[112:113], v157 offset:37200
	s_waitcnt lgkmcnt(11)
	v_pk_mul_f32 v[90:91], v[106:107], v[90:91]
	v_pk_fma_f32 v[88:89], v[104:105], v[88:89], v[90:91]
	v_pk_mul_f32 v[90:91], v[46:47], v[98:99]
	v_pk_fma_f32 v[90:91], v[108:109], v[96:97], v[90:91]
	v_pk_add_f32 v[88:89], v[88:89], v[90:91]
	v_add_f32_e32 v88, v88, v89
	s_nop 1
	v_add_f32_dpp v88, v88, v88 quad_perm:[1,0,3,2] row_mask:0xf bank_mask:0xf bound_ctrl:1
	s_nop 1
	v_add_f32_dpp v88, v88, v88 quad_perm:[2,3,0,1] row_mask:0xf bank_mask:0xf bound_ctrl:1
	s_nop 1
	v_add_f32_dpp v88, v88, v88 row_half_mirror row_mask:0xf bank_mask:0xf bound_ctrl:1
	s_nop 1
	v_add_f32_dpp v88, v88, v88 row_mirror row_mask:0xf bank_mask:0xf bound_ctrl:1
	s_waitcnt lgkmcnt(8)
	v_mul_f32_e32 v88, v110, v88
	v_fmac_f32_e32 v88, v8, v111
	v_add_f32_e32 v90, v114, v88
	v_pk_mul_f32 v[88:89], v[104:105], v[110:111] op_sel_hi:[1,0]
	ds_write_b32 v66, v90 offset:38400
	v_pk_fma_f32 v[104:105], v[22:23], v[8:9], v[88:89] op_sel_hi:[1,0,1]
	v_pk_mul_f32 v[22:23], v[106:107], v[110:111] op_sel_hi:[1,0]
	v_pk_fma_f32 v[106:107], v[24:25], v[8:9], v[22:23] op_sel_hi:[1,0,1]
	v_pk_mul_f32 v[22:23], v[108:109], v[110:111] op_sel_hi:[1,0]
	v_pk_fma_f32 v[108:109], v[38:39], v[8:9], v[22:23] op_sel_hi:[1,0,1]
	v_pk_mul_f32 v[22:23], v[46:47], v[110:111] op_sel_hi:[1,0]
	v_pk_fma_f32 v[46:47], v[40:41], v[8:9], v[22:23] op_sel_hi:[1,0,1]
	ds_read_b128 v[22:25], v59 offset:21760
	s_waitcnt lgkmcnt(6)
	v_pk_mul_f32 v[94:95], v[106:107], v[94:95]
	ds_read_b128 v[38:41], v59 offset:21776
	v_pk_fma_f32 v[92:93], v[104:105], v[92:93], v[94:95]
	s_waitcnt lgkmcnt(4)
	v_pk_mul_f32 v[94:95], v[46:47], v[102:103]
	ds_read_b128 v[88:91], v59 offset:29952
	v_pk_fma_f32 v[94:95], v[108:109], v[100:101], v[94:95]
	ds_read_b128 v[96:99], v59 offset:29968
	v_pk_add_f32 v[92:93], v[92:93], v[94:95]
	ds_read_b32 v8, v60 offset:35456
	v_add_f32_e32 v92, v92, v93
	ds_read_b32 v114, v60 offset:36480
	ds_read_b64 v[110:111], v157 offset:37216
	v_add_f32_dpp v92, v92, v92 quad_perm:[1,0,3,2] row_mask:0xf bank_mask:0xf bound_ctrl:1
	s_nop 1
	v_add_f32_dpp v92, v92, v92 quad_perm:[2,3,0,1] row_mask:0xf bank_mask:0xf bound_ctrl:1
	s_nop 1
	v_add_f32_dpp v92, v92, v92 row_half_mirror row_mask:0xf bank_mask:0xf bound_ctrl:1
	s_nop 1
	v_add_f32_dpp v92, v92, v92 row_mirror row_mask:0xf bank_mask:0xf bound_ctrl:1
	s_waitcnt lgkmcnt(8)
	v_mul_f32_e32 v92, v112, v92
	v_fmac_f32_e32 v92, v16, v113
	v_add_f32_e32 v94, v115, v92
	v_pk_mul_f32 v[92:93], v[104:105], v[112:113] op_sel_hi:[1,0]
	ds_write_b32 v67, v94 offset:38400
	v_pk_fma_f32 v[104:105], v[26:27], v[16:17], v[92:93] op_sel_hi:[1,0,1]
	v_pk_mul_f32 v[26:27], v[106:107], v[112:113] op_sel_hi:[1,0]
	v_pk_fma_f32 v[106:107], v[28:29], v[16:17], v[26:27] op_sel_hi:[1,0,1]
	v_pk_mul_f32 v[26:27], v[108:109], v[112:113] op_sel_hi:[1,0]
	v_pk_fma_f32 v[108:109], v[42:43], v[16:17], v[26:27] op_sel_hi:[1,0,1]
	v_pk_mul_f32 v[26:27], v[46:47], v[112:113] op_sel_hi:[1,0]
	v_pk_fma_f32 v[46:47], v[44:45], v[16:17], v[26:27] op_sel_hi:[1,0,1]
	ds_read_b128 v[26:29], v59 offset:22272
	ds_read_b128 v[42:45], v59 offset:22288
	ds_read_b128 v[92:95], v59 offset:30464
	ds_read_b128 v[100:103], v59 offset:30480
	ds_read_b32 v16, v60 offset:35520
	ds_read_b32 v115, v60 offset:36544
	s_waitcnt lgkmcnt(14)
; DI float row16_sum(float v) { v += dppf(v, 0); v += dppf(v, 1); v += dppf(v, 2); v += dppf(v, 3); return v; }
; DI void mamba_scan(CP p, const Ptrs& w, int l, int item, float* sm) {
;     ...
;   auto run_chunk = [&](int c, const float* bf, float* sy) {
;     flush(max(c - 1, 0));
;     MStep cur = lds_step(bf, 0);
; #pragma unroll
;     for (int j = 0; j < 16; ++j) {
;       MStep nxt = cur;
;       if (j + 1 < 16) nxt = lds_step(bf, j + 1);
;       f2v ya = M0 * cur.C0.xy + M1 * cur.C0.zw, yb = M2 * cur.C1.xy + M3 * cur.C1.zw;
;       ya += yb;
;       float yp = row16_sum(ya.x + ya.y);
;       float y = cur.sc.x * yp + cur.xq * cur.sc.y + cur.ds;
;       const float dA = cur.sc.x, xq = cur.xq;
;       M0 = M0 * dA + xq * cur.B0.xy; M1 = M1 * dA + xq * cur.B0.zw;
;       M2 = M2 * dA + xq * cur.B1.xy; M3 = M3 * dA + xq * cur.B1.zw;
;       sy[(ng == 0 ? j * 16 : 0) + ysel] = y;
;       cur = nxt;
;     }
;   };
	ds_read_b64 v[112:113], v157 offset:37232
	s_waitcnt lgkmcnt(11)
	v_pk_mul_f32 v[90:91], v[106:107], v[90:91]
	v_pk_fma_f32 v[88:89], v[104:105], v[88:89], v[90:91]
	v_pk_mul_f32 v[90:91], v[46:47], v[98:99]
	v_pk_fma_f32 v[90:91], v[108:109], v[96:97], v[90:91]
	v_pk_add_f32 v[88:89], v[88:89], v[90:91]
	v_add_f32_e32 v88, v88, v89
	s_nop 1
	v_add_f32_dpp v88, v88, v88 quad_perm:[1,0,3,2] row_mask:0xf bank_mask:0xf bound_ctrl:1
	s_nop 1
	v_add_f32_dpp v88, v88, v88 quad_perm:[2,3,0,1] row_mask:0xf bank_mask:0xf bound_ctrl:1
	s_nop 1
	v_add_f32_dpp v88, v88, v88 row_half_mirror row_mask:0xf bank_mask:0xf bound_ctrl:1
	s_nop 1
	v_add_f32_dpp v88, v88, v88 row_mirror row_mask:0xf bank_mask:0xf bound_ctrl:1
	s_waitcnt lgkmcnt(8)
	v_mul_f32_e32 v88, v110, v88
	v_fmac_f32_e32 v88, v8, v111
	v_add_f32_e32 v90, v114, v88
	v_pk_mul_f32 v[88:89], v[104:105], v[110:111] op_sel_hi:[1,0]
	ds_write_b32 v68, v90 offset:38400
	v_pk_fma_f32 v[104:105], v[22:23], v[8:9], v[88:89] op_sel_hi:[1,0,1]
	v_pk_mul_f32 v[22:23], v[106:107], v[110:111] op_sel_hi:[1,0]
	v_pk_fma_f32 v[106:107], v[24:25], v[8:9], v[22:23] op_sel_hi:[1,0,1]
	v_pk_mul_f32 v[22:23], v[108:109], v[110:111] op_sel_hi:[1,0]
	v_pk_fma_f32 v[108:109], v[38:39], v[8:9], v[22:23] op_sel_hi:[1,0,1]
	v_pk_mul_f32 v[22:23], v[46:47], v[110:111] op_sel_hi:[1,0]
	v_pk_fma_f32 v[46:47], v[40:41], v[8:9], v[22:23] op_sel_hi:[1,0,1]
	ds_read_b128 v[22:25], v59 offset:22784
	ds_read_b128 v[38:41], v59 offset:22800
	s_waitcnt lgkmcnt(6)
	v_pk_mul_f32 v[94:95], v[106:107], v[94:95]
	ds_read_b128 v[88:91], v59 offset:30976
	v_pk_fma_f32 v[92:93], v[104:105], v[92:93], v[94:95]
	v_pk_mul_f32 v[94:95], v[46:47], v[102:103]
	ds_read_b128 v[96:99], v59 offset:30992
	v_pk_fma_f32 v[94:95], v[108:109], v[100:101], v[94:95]
	ds_read_b32 v8, v60 offset:35584
	v_pk_add_f32 v[92:93], v[92:93], v[94:95]
	ds_read_b32 v114, v60 offset:36608
	v_add_f32_e32 v92, v92, v93
	ds_read_b64 v[110:111], v157 offset:37248
	s_nop 0
	v_add_f32_dpp v92, v92, v92 quad_perm:[1,0,3,2] row_mask:0xf bank_mask:0xf bound_ctrl:1
	s_nop 1
	v_add_f32_dpp v92, v92, v92 quad_perm:[2,3,0,1] row_mask:0xf bank_mask:0xf bound_ctrl:1
	s_nop 1
	v_add_f32_dpp v92, v92, v92 row_half_mirror row_mask:0xf bank_mask:0xf bound_ctrl:1
	s_nop 1
	v_add_f32_dpp v92, v92, v92 row_mirror row_mask:0xf bank_mask:0xf bound_ctrl:1
	s_waitcnt lgkmcnt(8)
	v_mul_f32_e32 v92, v112, v92
	v_fmac_f32_e32 v92, v16, v113
	v_add_f32_e32 v94, v115, v92
	v_pk_mul_f32 v[92:93], v[104:105], v[112:113] op_sel_hi:[1,0]
	ds_write_b32 v70, v94 offset:38400
	v_pk_fma_f32 v[104:105], v[26:27], v[16:17], v[92:93] op_sel_hi:[1,0,1]
	v_pk_mul_f32 v[26:27], v[106:107], v[112:113] op_sel_hi:[1,0]
	v_pk_fma_f32 v[106:107], v[28:29], v[16:17], v[26:27] op_sel_hi:[1,0,1]
	v_pk_mul_f32 v[26:27], v[108:109], v[112:113] op_sel_hi:[1,0]
	v_pk_fma_f32 v[108:109], v[42:43], v[16:17], v[26:27] op_sel_hi:[1,0,1]
	v_pk_mul_f32 v[26:27], v[46:47], v[112:113] op_sel_hi:[1,0]
	v_pk_fma_f32 v[46:47], v[44:45], v[16:17], v[26:27] op_sel_hi:[1,0,1]
	ds_read_b128 v[26:29], v59 offset:23296
	ds_read_b128 v[42:45], v59 offset:23312
	ds_read_b128 v[92:95], v59 offset:31488
	ds_read_b128 v[100:103], v59 offset:31504
	ds_read_b32 v16, v60 offset:35648
	ds_read_b32 v115, v60 offset:36672
	s_waitcnt lgkmcnt(14)
	ds_read_b64 v[112:113], v157 offset:37264
	s_waitcnt lgkmcnt(10)
	v_pk_mul_f32 v[90:91], v[106:107], v[90:91]
	v_pk_fma_f32 v[88:89], v[104:105], v[88:89], v[90:91]
	v_pk_mul_f32 v[90:91], v[46:47], v[98:99]
	v_pk_fma_f32 v[90:91], v[108:109], v[96:97], v[90:91]
	v_pk_add_f32 v[88:89], v[88:89], v[90:91]
	v_add_f32_e32 v88, v88, v89
	s_nop 1
	v_add_f32_dpp v88, v88, v88 quad_perm:[1,0,3,2] row_mask:0xf bank_mask:0xf bound_ctrl:1
	s_nop 1
	v_add_f32_dpp v88, v88, v88 quad_perm:[2,3,0,1] row_mask:0xf bank_mask:0xf bound_ctrl:1
	s_nop 1
	v_add_f32_dpp v88, v88, v88 row_half_mirror row_mask:0xf bank_mask:0xf bound_ctrl:1
	s_nop 1
	v_add_f32_dpp v88, v88, v88 row_mirror row_mask:0xf bank_mask:0xf bound_ctrl:1
	s_waitcnt lgkmcnt(8)
	v_mul_f32_e32 v88, v110, v88
	v_fmac_f32_e32 v88, v8, v111
	v_add_f32_e32 v90, v114, v88
	v_pk_mul_f32 v[88:89], v[104:105], v[110:111] op_sel_hi:[1,0]
	ds_write_b32 v71, v90 offset:38400
	v_pk_fma_f32 v[104:105], v[22:23], v[8:9], v[88:89] op_sel_hi:[1,0,1]
	v_pk_mul_f32 v[22:23], v[106:107], v[110:111] op_sel_hi:[1,0]
	v_pk_fma_f32 v[106:107], v[24:25], v[8:9], v[22:23] op_sel_hi:[1,0,1]
	v_pk_mul_f32 v[22:23], v[108:109], v[110:111] op_sel_hi:[1,0]
	v_pk_fma_f32 v[108:109], v[38:39], v[8:9], v[22:23] op_sel_hi:[1,0,1]
	v_pk_mul_f32 v[22:23], v[46:47], v[110:111] op_sel_hi:[1,0]
	v_pk_fma_f32 v[46:47], v[40:41], v[8:9], v[22:23] op_sel_hi:[1,0,1]
	ds_read_b128 v[22:25], v59 offset:23808
	ds_read_b128 v[38:41], v59 offset:23824
	ds_read_b128 v[88:91], v59 offset:32000
	s_waitcnt lgkmcnt(6)
	v_pk_mul_f32 v[94:95], v[106:107], v[94:95]
	ds_read_b128 v[96:99], v59 offset:32016
	v_pk_fma_f32 v[92:93], v[104:105], v[92:93], v[94:95]
	v_pk_mul_f32 v[94:95], v[46:47], v[102:103]
	ds_read_b32 v8, v60 offset:35712
	v_pk_fma_f32 v[94:95], v[108:109], v[100:101], v[94:95]
	ds_read_b32 v114, v60 offset:36736
	v_pk_add_f32 v[92:93], v[92:93], v[94:95]
	ds_read_b64 v[110:111], v157 offset:37280
	v_add_f32_e32 v92, v92, v93
	s_nop 1
	v_add_f32_dpp v92, v92, v92 quad_perm:[1,0,3,2] row_mask:0xf bank_mask:0xf bound_ctrl:1
	s_nop 1
	v_add_f32_dpp v92, v92, v92 quad_perm:[2,3,0,1] row_mask:0xf bank_mask:0xf bound_ctrl:1
	s_nop 1
	v_add_f32_dpp v92, v92, v92 row_half_mirror row_mask:0xf bank_mask:0xf bound_ctrl:1
	s_nop 1
	v_add_f32_dpp v92, v92, v92 row_mirror row_mask:0xf bank_mask:0xf bound_ctrl:1
	s_waitcnt lgkmcnt(8)
; DI float row16_sum(float v) { v += dppf(v, 0); v += dppf(v, 1); v += dppf(v, 2); v += dppf(v, 3); return v; }
; DI void mamba_scan(CP p, const Ptrs& w, int l, int item, float* sm) {
;     ...
;   auto run_chunk = [&](int c, const float* bf, float* sy) {
;     flush(max(c - 1, 0));
;     MStep cur = lds_step(bf, 0);
; #pragma unroll
;     for (int j = 0; j < 16; ++j) {
;       MStep nxt = cur;
;       if (j + 1 < 16) nxt = lds_step(bf, j + 1);
;       f2v ya = M0 * cur.C0.xy + M1 * cur.C0.zw, yb = M2 * cur.C1.xy + M3 * cur.C1.zw;
;       ya += yb;
;       float yp = row16_sum(ya.x + ya.y);
;       float y = cur.sc.x * yp + cur.xq * cur.sc.y + cur.ds;
;       const float dA = cur.sc.x, xq = cur.xq;
;       M0 = M0 * dA + xq * cur.B0.xy; M1 = M1 * dA + xq * cur.B0.zw;
;       M2 = M2 * dA + xq * cur.B1.xy; M3 = M3 * dA + xq * cur.B1.zw;
;       sy[(ng == 0 ? j * 16 : 0) + ysel] = y;
;       cur = nxt;
;     }
;   };
	v_mul_f32_e32 v92, v112, v92
	v_fmac_f32_e32 v92, v16, v113
	v_add_f32_e32 v94, v115, v92
	v_pk_mul_f32 v[92:93], v[104:105], v[112:113] op_sel_hi:[1,0]
	ds_write_b32 v73, v94 offset:38400
	v_pk_fma_f32 v[104:105], v[26:27], v[16:17], v[92:93] op_sel_hi:[1,0,1]
	v_pk_mul_f32 v[26:27], v[106:107], v[112:113] op_sel_hi:[1,0]
	v_pk_fma_f32 v[106:107], v[28:29], v[16:17], v[26:27] op_sel_hi:[1,0,1]
	v_pk_mul_f32 v[26:27], v[108:109], v[112:113] op_sel_hi:[1,0]
	v_pk_fma_f32 v[108:109], v[42:43], v[16:17], v[26:27] op_sel_hi:[1,0,1]
	v_pk_mul_f32 v[26:27], v[46:47], v[112:113] op_sel_hi:[1,0]
	v_pk_fma_f32 v[46:47], v[44:45], v[16:17], v[26:27] op_sel_hi:[1,0,1]
	ds_read_b128 v[26:29], v59 offset:24320
	ds_read_b128 v[42:45], v59 offset:24336
	ds_read_b128 v[92:95], v59 offset:32512
	ds_read_b128 v[100:103], v59 offset:32528
	ds_read_b32 v16, v60 offset:35776
	ds_read_b32 v115, v60 offset:36800
	s_waitcnt lgkmcnt(9)
	v_pk_mul_f32 v[90:91], v[106:107], v[90:91]
	ds_read_b64 v[112:113], v157 offset:37296
	v_pk_fma_f32 v[88:89], v[104:105], v[88:89], v[90:91]
	v_pk_mul_f32 v[90:91], v[46:47], v[98:99]
	v_pk_fma_f32 v[90:91], v[108:109], v[96:97], v[90:91]
	v_pk_add_f32 v[88:89], v[88:89], v[90:91]
	v_add_f32_e32 v88, v88, v89
	s_nop 1
	v_add_f32_dpp v88, v88, v88 quad_perm:[1,0,3,2] row_mask:0xf bank_mask:0xf bound_ctrl:1
	s_nop 1
	v_add_f32_dpp v88, v88, v88 quad_perm:[2,3,0,1] row_mask:0xf bank_mask:0xf bound_ctrl:1
	s_nop 1
	v_add_f32_dpp v88, v88, v88 row_half_mirror row_mask:0xf bank_mask:0xf bound_ctrl:1
	s_nop 1
	v_add_f32_dpp v88, v88, v88 row_mirror row_mask:0xf bank_mask:0xf bound_ctrl:1
	s_waitcnt lgkmcnt(8)
	v_mul_f32_e32 v88, v110, v88
	v_fmac_f32_e32 v88, v8, v111
	v_add_f32_e32 v90, v114, v88
	v_pk_mul_f32 v[88:89], v[104:105], v[110:111] op_sel_hi:[1,0]
	ds_write_b32 v74, v90 offset:38400
	v_pk_fma_f32 v[104:105], v[22:23], v[8:9], v[88:89] op_sel_hi:[1,0,1]
	v_pk_mul_f32 v[22:23], v[106:107], v[110:111] op_sel_hi:[1,0]
	v_pk_fma_f32 v[106:107], v[24:25], v[8:9], v[22:23] op_sel_hi:[1,0,1]
	v_pk_mul_f32 v[22:23], v[108:109], v[110:111] op_sel_hi:[1,0]
	v_pk_fma_f32 v[108:109], v[38:39], v[8:9], v[22:23] op_sel_hi:[1,0,1]
	v_pk_mul_f32 v[22:23], v[46:47], v[110:111] op_sel_hi:[1,0]
	v_pk_fma_f32 v[46:47], v[40:41], v[8:9], v[22:23] op_sel_hi:[1,0,1]
	ds_read_b128 v[22:25], v59 offset:24832
	ds_read_b128 v[38:41], v59 offset:24848
	ds_read_b128 v[88:91], v59 offset:33024
	ds_read_b128 v[96:99], v59 offset:33040
	s_waitcnt lgkmcnt(6)
	v_pk_mul_f32 v[94:95], v[106:107], v[94:95]
	ds_read_b32 v8, v60 offset:35840
	v_pk_fma_f32 v[92:93], v[104:105], v[92:93], v[94:95]
	v_pk_mul_f32 v[94:95], v[46:47], v[102:103]
	ds_read_b32 v114, v60 offset:36864
	v_pk_fma_f32 v[94:95], v[108:109], v[100:101], v[94:95]
	ds_read_b64 v[110:111], v157 offset:37312
	v_pk_add_f32 v[92:93], v[92:93], v[94:95]
	v_add_f32_e32 v92, v92, v93
	s_nop 1
	v_add_f32_dpp v92, v92, v92 quad_perm:[1,0,3,2] row_mask:0xf bank_mask:0xf bound_ctrl:1
	s_nop 1
	v_add_f32_dpp v92, v92, v92 quad_perm:[2,3,0,1] row_mask:0xf bank_mask:0xf bound_ctrl:1
	s_nop 1
	v_add_f32_dpp v92, v92, v92 row_half_mirror row_mask:0xf bank_mask:0xf bound_ctrl:1
	s_nop 1
	v_add_f32_dpp v92, v92, v92 row_mirror row_mask:0xf bank_mask:0xf bound_ctrl:1
	s_waitcnt lgkmcnt(8)
	v_mul_f32_e32 v92, v112, v92
	v_fmac_f32_e32 v92, v16, v113
	v_add_f32_e32 v94, v115, v92
	v_pk_mul_f32 v[92:93], v[104:105], v[112:113] op_sel_hi:[1,0]
	ds_write_b32 v75, v94 offset:38400
	v_pk_fma_f32 v[104:105], v[26:27], v[16:17], v[92:93] op_sel_hi:[1,0,1]
	v_pk_mul_f32 v[26:27], v[106:107], v[112:113] op_sel_hi:[1,0]
	v_pk_fma_f32 v[106:107], v[28:29], v[16:17], v[26:27] op_sel_hi:[1,0,1]
	v_pk_mul_f32 v[26:27], v[108:109], v[112:113] op_sel_hi:[1,0]
	v_pk_fma_f32 v[108:109], v[42:43], v[16:17], v[26:27] op_sel_hi:[1,0,1]
	v_pk_mul_f32 v[26:27], v[46:47], v[112:113] op_sel_hi:[1,0]
	v_pk_fma_f32 v[46:47], v[44:45], v[16:17], v[26:27] op_sel_hi:[1,0,1]
	ds_read_b128 v[26:29], v59 offset:25344
	ds_read_b128 v[42:45], v59 offset:25360
	ds_read_b128 v[92:95], v59 offset:33536
	ds_read_b128 v[100:103], v59 offset:33552
	ds_read_b32 v16, v60 offset:35904
	ds_read_b32 v116, v60 offset:36928
	s_waitcnt lgkmcnt(9)
	v_pk_mul_f32 v[90:91], v[106:107], v[90:91]
	ds_read_b64 v[112:113], v157 offset:37328
	v_pk_fma_f32 v[88:89], v[104:105], v[88:89], v[90:91]
	v_pk_mul_f32 v[90:91], v[46:47], v[98:99]
	v_pk_fma_f32 v[90:91], v[108:109], v[96:97], v[90:91]
	v_pk_add_f32 v[88:89], v[88:89], v[90:91]
	s_waitcnt lgkmcnt(8)
	v_pk_mul_f32 v[46:47], v[46:47], v[110:111] op_sel_hi:[1,0]
	v_add_f32_e32 v88, v88, v89
	v_pk_fma_f32 v[40:41], v[40:41], v[8:9], v[46:47] op_sel_hi:[1,0,1]
	s_nop 0
	v_add_f32_dpp v88, v88, v88 quad_perm:[1,0,3,2] row_mask:0xf bank_mask:0xf bound_ctrl:1
	s_nop 1
	v_add_f32_dpp v88, v88, v88 quad_perm:[2,3,0,1] row_mask:0xf bank_mask:0xf bound_ctrl:1
	s_nop 1
	v_add_f32_dpp v88, v88, v88 row_half_mirror row_mask:0xf bank_mask:0xf bound_ctrl:1
	s_nop 1
	v_add_f32_dpp v88, v88, v88 row_mirror row_mask:0xf bank_mask:0xf bound_ctrl:1
	v_mul_f32_e32 v88, v110, v88
	v_fmac_f32_e32 v88, v8, v111
	v_add_f32_e32 v90, v114, v88
	v_pk_mul_f32 v[88:89], v[104:105], v[110:111] op_sel_hi:[1,0]
	ds_write_b32 v76, v90 offset:38400
	v_pk_fma_f32 v[22:23], v[22:23], v[8:9], v[88:89] op_sel_hi:[1,0,1]
	v_pk_mul_f32 v[88:89], v[106:107], v[110:111] op_sel_hi:[1,0]
	v_pk_fma_f32 v[24:25], v[24:25], v[8:9], v[88:89] op_sel_hi:[1,0,1]
	v_pk_mul_f32 v[88:89], v[108:109], v[110:111] op_sel_hi:[1,0]
	v_pk_fma_f32 v[38:39], v[38:39], v[8:9], v[88:89] op_sel_hi:[1,0,1]
	ds_read_b128 v[88:91], v59 offset:25856
	ds_read_b128 v[96:99], v59 offset:25872
	ds_read_b128 v[104:107], v59 offset:34048
	ds_read_b128 v[108:111], v59 offset:34064
	ds_read_b32 v46, v60 offset:35968
	ds_read_b32 v47, v60 offset:36992
	s_waitcnt lgkmcnt(7)
; DI float bf2f(bf16_t h) { return __uint_as_float(((unsigned)h) << 16); }
; DI float siluf(float x) { return x * sigmf(x); }
; DI float row16_sum(float v) { v += dppf(v, 0); v += dppf(v, 1); v += dppf(v, 2); v += dppf(v, 3); return v; }
; DI void mamba_scan(CP p, const Ptrs& w, int l, int item, float* sm) {
;     ...
;   auto stage = [&](const MPre& P, float* bufp) {
; #pragma unroll
;     for (int i = 0; i < 2; ++i) {
;       int idx = tid + 256 * i, j = idx >> 5, q = idx & 31;
;       float f[8];
;       unpack8(P.pbq[i], f);
;       float* d = bufp + (q < 16 ? 0 : 2048) + j * 128 + (q & 15) * 8;
;       *(float4*)d = make_float4(f[0], f[1], f[2], f[3]);
;       *(float4*)(d + 4) = make_float4(f[4], f[5], f[6], f[7]);
;     }
;     {
;       float xs = siluf(wX0 * P.pxm[0] * bf2f(P.px[0]) + wX1 * bf2f(P.px[1]) + wX2 * P.pxm[1] * bf2f(P.px[2]) + bX);
;       bufp[4096 + xj * 16 + xp] = xs * P.pdt[0];
;       bufp[4096 + 256 + xj * 16 + xp] = Dsk * xs;
;       if (xp == 0) *(float4*)(bufp + 4096 + 512 + xj * 4) = make_float4(P.pdt[1], P.pdt[2], 0.f, 0.f);
;     }
;   };
;     ...
;   auto run_chunk = [&](int c, const float* bf, float* sy) {
;     flush(max(c - 1, 0));
;     MStep cur = lds_step(bf, 0);
; #pragma unroll
;     for (int j = 0; j < 16; ++j) {
;       MStep nxt = cur;
;       if (j + 1 < 16) nxt = lds_step(bf, j + 1);
;       f2v ya = M0 * cur.C0.xy + M1 * cur.C0.zw, yb = M2 * cur.C1.xy + M3 * cur.C1.zw;
;       ya += yb;
;       float yp = row16_sum(ya.x + ya.y);
;       float y = cur.sc.x * yp + cur.xq * cur.sc.y + cur.ds;
;       const float dA = cur.sc.x, xq = cur.xq;
;       M0 = M0 * dA + xq * cur.B0.xy; M1 = M1 * dA + xq * cur.B0.zw;
;       M2 = M2 * dA + xq * cur.B1.xy; M3 = M3 * dA + xq * cur.B1.zw;
;       sy[(ng == 0 ? j * 16 : 0) + ysel] = y;
;       cur = nxt;
;     }
;   };
	v_pk_mul_f32 v[94:95], v[24:25], v[94:95]
	ds_read_b64 v[114:115], v157 offset:37344
	v_pk_fma_f32 v[92:93], v[22:23], v[92:93], v[94:95]
	v_pk_mul_f32 v[94:95], v[40:41], v[102:103]
	v_pk_fma_f32 v[94:95], v[38:39], v[100:101], v[94:95]
	v_pk_mul_f32 v[22:23], v[22:23], v[112:113] op_sel_hi:[1,0]
	v_pk_add_f32 v[92:93], v[92:93], v[94:95]
	v_add_f32_e32 v8, v92, v93
	s_nop 1
	v_add_f32_dpp v8, v8, v8 quad_perm:[1,0,3,2] row_mask:0xf bank_mask:0xf bound_ctrl:1
	s_nop 1
	v_add_f32_dpp v8, v8, v8 quad_perm:[2,3,0,1] row_mask:0xf bank_mask:0xf bound_ctrl:1
	s_nop 1
	v_add_f32_dpp v8, v8, v8 row_half_mirror row_mask:0xf bank_mask:0xf bound_ctrl:1
	s_nop 1
	v_add_f32_dpp v8, v8, v8 row_mirror row_mask:0xf bank_mask:0xf bound_ctrl:1
	v_mul_f32_e32 v8, v112, v8
	v_fmac_f32_e32 v8, v16, v113
	v_add_f32_e32 v8, v116, v8
	v_pk_fma_f32 v[116:117], v[26:27], v[16:17], v[22:23] op_sel_hi:[1,0,1]
	v_pk_mul_f32 v[22:23], v[24:25], v[112:113] op_sel_hi:[1,0]
	ds_write_b32 v77, v8 offset:38400
	v_pk_fma_f32 v[118:119], v[28:29], v[16:17], v[22:23] op_sel_hi:[1,0,1]
	v_pk_mul_f32 v[22:23], v[38:39], v[112:113] op_sel_hi:[1,0]
	ds_read_b128 v[26:29], v59 offset:26368
	v_pk_fma_f32 v[120:121], v[42:43], v[16:17], v[22:23] op_sel_hi:[1,0,1]
	v_pk_mul_f32 v[22:23], v[40:41], v[112:113] op_sel_hi:[1,0]
	v_pk_fma_f32 v[112:113], v[44:45], v[16:17], v[22:23] op_sel_hi:[1,0,1]
	ds_read_b128 v[22:25], v59 offset:26384
	ds_read_b128 v[92:95], v59 offset:34560
	ds_read_b128 v[100:103], v59 offset:34576
	ds_read_b32 v8, v60 offset:36032
	ds_read_b32 v16, v60 offset:37056
	s_waitcnt lgkmcnt(7)
	v_pk_mul_f32 v[40:41], v[118:119], v[106:107]
	ds_read_b64 v[38:39], v157 offset:37360
	v_pk_mul_f32 v[42:43], v[112:113], v[110:111]
	v_pk_fma_f32 v[40:41], v[116:117], v[104:105], v[40:41]
	v_pk_fma_f32 v[42:43], v[120:121], v[108:109], v[42:43]
	v_pk_add_f32 v[40:41], v[40:41], v[42:43]
	v_add_f32_e32 v40, v40, v41
	s_nop 1
	v_add_f32_dpp v40, v40, v40 quad_perm:[1,0,3,2] row_mask:0xf bank_mask:0xf bound_ctrl:1
	s_nop 1
	v_add_f32_dpp v40, v40, v40 quad_perm:[2,3,0,1] row_mask:0xf bank_mask:0xf bound_ctrl:1
	s_nop 1
	v_add_f32_dpp v40, v40, v40 row_half_mirror row_mask:0xf bank_mask:0xf bound_ctrl:1
	s_nop 1
	v_add_f32_dpp v40, v40, v40 row_mirror row_mask:0xf bank_mask:0xf bound_ctrl:1
	v_mul_f32_e32 v40, v114, v40
	v_fmac_f32_e32 v40, v46, v115
	v_add_f32_e32 v104, v47, v40
	v_pk_mul_f32 v[40:41], v[116:117], v[114:115] op_sel_hi:[1,0]
	ds_write_b32 v78, v104 offset:38400
	v_pk_fma_f32 v[42:43], v[88:89], v[46:47], v[40:41] op_sel_hi:[1,0,1]
	v_pk_mul_f32 v[40:41], v[118:119], v[114:115] op_sel_hi:[1,0]
	v_pk_mul_f32 v[88:89], v[112:113], v[114:115] op_sel_hi:[1,0]
	v_pk_fma_f32 v[44:45], v[90:91], v[46:47], v[40:41] op_sel_hi:[1,0,1]
	v_pk_mul_f32 v[40:41], v[120:121], v[114:115] op_sel_hi:[1,0]
	v_pk_fma_f32 v[40:41], v[96:97], v[46:47], v[40:41] op_sel_hi:[1,0,1]
	v_pk_fma_f32 v[46:47], v[98:99], v[46:47], v[88:89] op_sel_hi:[1,0,1]
	s_waitcnt lgkmcnt(5)
	v_pk_mul_f32 v[88:89], v[44:45], v[94:95]
	s_waitcnt lgkmcnt(4)
	v_pk_mul_f32 v[90:91], v[46:47], v[102:103]
	v_pk_fma_f32 v[88:89], v[42:43], v[92:93], v[88:89]
	v_pk_fma_f32 v[90:91], v[40:41], v[100:101], v[90:91]
	s_waitcnt vmcnt(8)
	v_lshlrev_b32_e32 v94, 16, v21
	v_pk_add_f32 v[88:89], v[88:89], v[90:91]
	v_and_b32_e32 v95, 0xffff0000, v21
	v_add_f32_e32 v88, v88, v89
	v_lshlrev_b32_e32 v21, 16, v85
	v_lshlrev_b32_e32 v90, 16, v19
	v_add_f32_dpp v88, v88, v88 quad_perm:[1,0,3,2] row_mask:0xf bank_mask:0xf bound_ctrl:1
	v_and_b32_e32 v91, 0xffff0000, v19
	v_lshlrev_b32_e32 v19, 16, v84
	v_add_f32_dpp v88, v88, v88 quad_perm:[2,3,0,1] row_mask:0xf bank_mask:0xf bound_ctrl:1
	v_mul_f32_e32 v21, v50, v21
	v_and_b32_e32 v89, 0xffff0000, v18
	v_add_f32_dpp v88, v88, v88 row_half_mirror row_mask:0xf bank_mask:0xf bound_ctrl:1
	v_lshlrev_b32_e32 v92, 16, v20
	v_and_b32_e32 v93, 0xffff0000, v20
	v_add_f32_dpp v88, v88, v88 row_mirror row_mask:0xf bank_mask:0xf bound_ctrl:1
	s_waitcnt lgkmcnt(1)
	v_mul_f32_e32 v88, v38, v88
	v_fmac_f32_e32 v88, v8, v39
	v_add_f32_e32 v16, v16, v88
	ds_write_b32 v80, v16 offset:38400
	v_mul_f32_e32 v16, v49, v87
	v_fmac_f32_e32 v21, v16, v19
	v_mul_f32_e32 v16, v51, v86
	v_lshlrev_b32_e32 v19, 16, v83
	v_fmac_f32_e32 v21, v16, v19
	v_add_f32_e32 v16, v52, v21
	v_mul_f32_e32 v19, 0xbfb8aa3b, v16
	v_exp_f32_e32 v39, v19
	v_lshlrev_b32_e32 v88, 16, v18
	v_lshlrev_b32_e32 v18, 16, v12
	v_and_b32_e32 v19, 0xffff0000, v12
	v_add_f32_e32 v12, 1.0, v39
	v_rcp_f32_e32 v12, v12
	ds_write_b128 v58, v[92:95] offset:16
	ds_write_b128 v58, v[88:91]
	v_lshlrev_b32_e32 v20, 16, v13
	v_lshlrev_b32_e32 v90, 16, v15
	v_mul_f32_e32 v12, v16, v12
	v_lshlrev_b32_e32 v88, 16, v14
	v_and_b32_e32 v21, 0xffff0000, v13
	v_and_b32_e32 v91, 0xffff0000, v15
	v_and_b32_e32 v89, 0xffff0000, v14
	v_mul_f32_e32 v13, v36, v12
	v_mul_f32_e32 v12, v53, v12
	ds_write_b128 v58, v[88:91] offset:4112
	ds_write_b128 v58, v[18:21] offset:4096
	ds_write2st64_b32 v57, v13, v12 offset0:64 offset1:68
	s_and_saveexec_b64 s[4:5], vcc
	s_cbranch_execz .LBB0_543
	v_mov_b32_e32 v16, v37
	v_mov_b32_e32 v18, v157
	v_mov_b32_e32 v19, v157
	ds_write_b128 v72, v[16:19] offset:18432
	s_branch .LBB0_543

; #define TIDX ltid()
; DI void rwkv_scan(CP p, const Ptrs& w, int l, int item, float* sm) {
;   const int tid = TIDX, lane = tid & 63, wid = tid >> 6;
;   const int chain = item >> 2, rq = item & 3, b = chain >> 4, hd = (chain >> 1) & 7, dir = chain & 1;
;   const int sj = tid >> 4, skq = (tid & 15) * 4, sc_ = hd * 64 + skq;
;   float mu_r[4], mu_k[4], mu_v[4], kk_c[4], ka_c[4];
; #pragma unroll
;   for (int j = 0; j < 4; ++j) {
;     mu_r[j] = p.in[11][l * 1792 + sc_ + j]; mu_k[j] = p.in[11][l * 1792 + 512 + sc_ + j]; mu_v[j] = p.in[11][l * 1792 + 1024 + sc_ + j];
;     kk_c[j] = p.in[16][l * 512 + sc_ + j]; ka_c[j] = p.in[17][l * 512 + sc_ + j];
;   }
;   const bf16_t* Wd = w.R1 + (size_t)(0 * 2 + dir) * T * 512;
;   const bf16_t* Ad = w.R1 + (size_t)(1 * 2 + dir) * T * 512;
;   bf16_t* yout = w.R2 + (size_t)dir * T * 512;
;   constexpr int BUF = 6 * 1024 + 32;
;   const int kg = lane & 15, rs = lane >> 4, row = rq * 16 + wid * 4 + rs;
;   f2v SA = {0.f, 0.f}, SB = {0.f, 0.f};
;   struct RPre { uint2 pq[3][3], pwd, pad_; float psc[3], pmk[2]; };
;   RPre PA, PB;
;   auto load = [&](int c, RPre& P) {
;     int ii = pos2i(c * 16 + sj, dir);
;     size_t tok = (size_t)b * TPB + ii;
;     const bf16_t* prow = w.pB + tok * SPB + sc_;
;     bool hp = (ii != 0) && (ii != CTXL), hn = (ii != CTXL - 1) && (ii != TPB - 1);
;     const int op = hp ? -SPB : 0, on = hn ? SPB : 0;
;     P.pmk[0] = hp ? 0.5f : 0.f; P.pmk[1] = hn ? 0.5f : 0.f;
; #pragma unroll
;     for (int q = 0; q < 3; ++q) {
;       P.pq[q][0] = *(const uint2*)(prow + q * 512);
;       P.pq[q][1] = *(const uint2*)(prow + q * 512 + op);
;       P.pq[q][2] = *(const uint2*)(prow + q * 512 + on);
;     }
;     P.pwd = *(const uint2*)(Wd + tok * 512 + sc_);
;     P.pad_ = *(const uint2*)(Ad + tok * 512 + sc_);
;     const float* sc = w.bonus + (tok * 8 + hd) * 8;
;     P.psc[0] = sc[0]; P.psc[1] = sc[1 + 3 * dir]; P.psc[2] = sc[2 + 3 * dir];
.LBB0_549:
	s_and_b64 vcc, exec, s[4:5]
	s_cbranch_vccz .LBB0_559
	s_add_u32 s42, s12, 0x33700
	s_addc_u32 s43, s13, 0
	s_add_u32 s44, s12, 0xa604700
	v_mov_b32_e32 v57, v214
	s_addc_u32 s45, s13, 0
	s_bfe_u32 s11, s16, 0x30003
	v_lshlrev_b32_e32 v83, 2, v57
	s_waitcnt vmcnt(2)
	v_and_b32_e32 v23, 60, v83
	s_lshl_b32 s10, s11, 6
	v_or_b32_e32 v22, s10, v23
	s_mul_i32 s2, s62, 0x700
	v_add_u32_e32 v156, s2, v22
	s_load_dwordx2 s[2:3], s[14:15], 0x58
	s_load_dwordx4 s[4:7], s[14:15], 0x80
	s_bfe_u32 s38, s16, 0x10002
	v_lshl_or_b32 v0, s62, 9, v22
	v_mov_b32_e32 v1, v157
	s_waitcnt lgkmcnt(0)
	v_lshl_add_u64 v[8:9], v[156:157], 2, s[2:3]
	s_movk_i32 s2, 0x1000
	v_add_co_u32_e32 v4, vcc, s2, v8
	s_ashr_i32 s2, s16, 6
	s_mul_i32 s14, s38, 0x1080000
	v_lshlrev_b64 v[0:1], 2, v[0:1]
	s_add_u32 s3, s12, s14
	v_lshl_add_u64 v[12:13], s[4:5], 0, v[0:1]
	s_addc_u32 s4, s13, 0
	s_add_u32 s46, s3, 0x17864700
	s_addc_u32 s47, s4, 0
	v_ashrrev_i32_e32 v97, 4, v57
	s_add_u32 s48, s3, 0x19964700
	s_addc_u32 s49, s4, 0
	v_cmp_lt_i32_e64 s[4:5], s37, v97
	v_addc_co_u32_e32 v5, vcc, 0, v9, vcc
	s_cmp_eq_u32 s38, 0
	v_cndmask_b32_e64 v20, v231, v232, s[4:5]
	s_cselect_b64 vcc, -1, 0
	v_sub_u32_e32 v20, v20, v97
	v_cndmask_b32_e32 v46, v20, v97, vcc
	v_ashrrev_i32_e32 v47, 31, v46
	v_mov_b32_e32 v20, 0x2100
	s_mul_hi_i32 s13, s2, 0x2100
	s_mul_i32 s12, s2, 0x2100
	v_mad_i64_i32 v[20:21], s[2:3], s2, v20, v[46:47]
	s_waitcnt vmcnt(1)
	v_mov_b64_e32 v[24:25], s[44:45]
	v_mad_u64_u32 v[24:25], s[2:3], v20, s20, v[24:25]
	s_waitcnt vmcnt(0)
	v_lshlrev_b64 v[30:31], 10, v[20:21]
	v_mad_i32_i24 v25, v21, s20, v25
	v_lshlrev_b32_e32 v156, 1, v22
	s_waitcnt vmcnt(0)
	v_lshl_add_u64 v[32:33], s[46:47], 0, v[30:31]
	v_lshl_add_u64 v[30:31], s[48:49], 0, v[30:31]
	v_lshl_add_u64 v[16:17], s[6:7], 0, v[0:1]
	v_lshl_add_u64 v[48:49], v[24:25], 0, v[156:157]
	v_lshl_add_u64 v[32:33], v[32:33], 0, v[156:157]
	v_lshl_add_u64 v[30:31], v[30:31], 0, v[156:157]
	global_load_dwordx4 v[0:3], v[8:9], off
	s_nop 0
	global_load_dwordx4 v[4:7], v[4:5], off
	s_nop 0
	global_load_dwordx4 v[8:11], v[8:9], off offset:2048
	s_nop 0
	global_load_dwordx4 v[12:15], v[12:13], off
	s_nop 0
	global_load_dwordx4 v[16:19], v[16:17], off
	s_barrier
; DI void rwkv_scan(CP p, const Ptrs& w, int l, int item, float* sm) {
;     ...
;   auto load = [&](int c, RPre& P) {
;     int ii = pos2i(c * 16 + sj, dir);
;     size_t tok = (size_t)b * TPB + ii;
;     const bf16_t* prow = w.pB + tok * SPB + sc_;
;     bool hp = (ii != 0) && (ii != CTXL), hn = (ii != CTXL - 1) && (ii != TPB - 1);
;     const int op = hp ? -SPB : 0, on = hn ? SPB : 0;
;     P.pmk[0] = hp ? 0.5f : 0.f; P.pmk[1] = hn ? 0.5f : 0.f;
; #pragma unroll
;     for (int q = 0; q < 3; ++q) {
;       P.pq[q][0] = *(const uint2*)(prow + q * 512);
;       P.pq[q][1] = *(const uint2*)(prow + q * 512 + op);
;       P.pq[q][2] = *(const uint2*)(prow + q * 512 + on);
;     }
;     P.pwd = *(const uint2*)(Wd + tok * 512 + sc_);
;     P.pad_ = *(const uint2*)(Ad + tok * 512 + sc_);
;     const float* sc = w.bonus + (tok * 8 + hd) * 8;
;     P.psc[0] = sc[0]; P.psc[1] = sc[1 + 3 * dir]; P.psc[2] = sc[2 + 3 * dir];
;   };
;   auto up4 = [](uint2 u, float* f) { f[0] = __uint_as_float(u.x << 16); f[1] = __uint_as_float(u.x & 0xffff0000u); f[2] = __uint_as_float(u.y << 16); f[3] = __uint_as_float(u.y & 0xffff0000u); };
;   auto stage = [&](const RPre& P, float* bufp) {
;     float rc[4], rp[4], rn[4], kc[4], kp[4], kn[4], vc[4], vp[4], vn[4], wd4[4], ad4[4];
;     up4(P.pq[0][0], rc); up4(P.pq[0][1], rp); up4(P.pq[0][2], rn);
;     up4(P.pq[1][0], kc); up4(P.pq[1][1], kp); up4(P.pq[1][2], kn);
;     up4(P.pq[2][0], vc); up4(P.pq[2][1], vp); up4(P.pq[2][2], vn);
;     up4(P.pwd, wd4); up4(P.pad_, ad4);
;     float o0[4], o1[4], o2[4], o3[4], o4[4], o5[4];
; #pragma unroll
;     for (int j = 0; j < 4; ++j) {
;       float r_s = rc[j] + ((P.pmk[0] * rp[j] + P.pmk[1] * rn[j]) - rc[j]) * mu_r[j];
;       float k_s = kc[j] + ((P.pmk[0] * kp[j] + P.pmk[1] * kn[j]) - kc[j]) * mu_k[j];
;       float v_s = vc[j] + ((P.pmk[0] * vp[j] + P.pmk[1] * vn[j]) - vc[j]) * mu_v[j];
;       float kk = k_s * kk_c[j] * P.psc[0];
;       float a = ad4[j], wv = 1.f - wd4[j];
;       o0[j] = -kk; o1[j] = wv * r_s; o2[j] = wv; o3[j] = kk * a; o4[j] = k_s * (1.f + (a - 1.f) * ka_c[j]); o5[j] = v_s;
;     }
;     float* d = bufp + sj * 64 + skq;
;     *(float4*)(d + 0 * 1024) = make_float4(o0[0], o0[1], o0[2], o0[3]);
;     *(float4*)(d + 1 * 1024) = make_float4(o1[0], o1[1], o1[2], o1[3]);
;     *(float4*)(d + 2 * 1024) = make_float4(o2[0], o2[1], o2[2], o2[3]);
	global_load_dwordx2 v[24:25], v[48:49], off
	global_load_dwordx2 v[26:27], v[48:49], off offset:1024
	global_load_dwordx2 v[28:29], v[48:49], off offset:2048
	global_load_dwordx2 v[36:37], v[32:33], off
	global_load_dwordx2 v[50:51], v[30:31], off
	v_lshlrev_b64 v[20:21], 8, v[20:21]
	v_lshl_add_u64 v[20:21], s[42:43], 0, v[20:21]
	s_lshl_b32 s50, s11, 5
	s_mov_b32 s51, s91
	v_and_b32_e32 v39, 0xfffffeff, v46
	v_and_b32_e32 v46, 0xffffdfff, v46
	v_lshl_add_u64 v[20:21], v[20:21], 0, s[50:51]
	v_cmp_eq_u32_e64 s[4:5], s37, v46
	v_cmp_eq_u32_e64 s[6:7], 0, v39
	global_load_dword v38, v[20:21], off
	v_cndmask_b32_e64 v52, v237, 0, s[4:5]
	v_mov_b32_e32 v53, v157
	v_lshl_add_u64 v[52:53], v[48:49], 0, v[52:53]
	v_cndmask_b32_e64 v46, 0.5, 0, s[4:5]
	v_cndmask_b32_e64 v47, 0.5, 0, s[6:7]
	v_lshlrev_b32_e32 v22, 8, v97
	v_lshl_or_b32 v103, v23, 2, v22
	s_mul_i32 s11, s38, 3
	v_cmp_eq_u32_e64 s[40:41], 0, v23
	s_waitcnt vmcnt(5)
	v_lshlrev_b32_e32 v34, 16, v24
	v_and_b32_e32 v35, 0xffff0000, v24
	v_lshlrev_b32_e32 v32, 16, v25
	v_and_b32_e32 v33, 0xffff0000, v25
	s_waitcnt vmcnt(4)
	v_lshlrev_b32_e32 v44, 16, v26
	v_and_b32_e32 v45, 0xffff0000, v26
	v_lshlrev_b32_e32 v42, 16, v27
	v_and_b32_e32 v43, 0xffff0000, v27
	s_waitcnt vmcnt(3)
	v_lshlrev_b32_e32 v26, 16, v28
	v_and_b32_e32 v27, 0xffff0000, v28
	v_lshlrev_b32_e32 v24, 16, v29
	v_and_b32_e32 v25, 0xffff0000, v29
	s_waitcnt vmcnt(1)
	v_lshlrev_b32_e32 v30, 16, v50
	v_and_b32_e32 v31, 0xffff0000, v50
	v_lshlrev_b32_e32 v28, 16, v51
	v_and_b32_e32 v29, 0xffff0000, v51
	v_cndmask_b32_e64 v51, -1, 0, s[6:7]
	v_cndmask_b32_e64 v50, v236, 0, s[6:7]
	v_lshl_add_u64 v[50:51], v[48:49], 0, v[50:51]
	global_load_dwordx2 v[54:55], v[50:51], off
	global_load_dwordx2 v[58:59], v[52:53], off
	global_load_dwordx2 v[60:61], v[50:51], off offset:1024
	global_load_dwordx2 v[62:63], v[52:53], off offset:1024
	global_load_dwordx2 v[48:49], v[50:51], off offset:2048
	global_load_dwordx2 v[64:65], v[52:53], off offset:2048
	v_lshlrev_b32_e32 v40, 16, v36
	v_and_b32_e32 v41, 0xffff0000, v36
	v_lshlrev_b32_e32 v36, 16, v37
	v_and_b32_e32 v37, 0xffff0000, v37
	s_waitcnt vmcnt(3)
	v_lshlrev_b32_e32 v52, 16, v60
	s_waitcnt vmcnt(2)
	v_and_b32_e32 v53, 0xffff0000, v62
	v_lshlrev_b32_e32 v50, 16, v62
	v_and_b32_e32 v51, 0xffff0000, v60
	v_pk_mul_f32 v[52:53], v[46:47], v[52:53] op_sel:[1,0] op_sel_hi:[0,1]
	v_pk_fma_f32 v[50:51], v[46:47], v[50:51], v[52:53]
	v_and_b32_e32 v53, 0xffff0000, v61
	v_lshlrev_b32_e32 v60, 16, v61
	v_and_b32_e32 v61, 0xffff0000, v63
	v_lshlrev_b32_e32 v52, 16, v63
	v_pk_mul_f32 v[60:61], v[46:47], v[60:61] op_sel:[1,0] op_sel_hi:[0,1]
	v_pk_fma_f32 v[52:53], v[46:47], v[52:53], v[60:61]
	v_pk_add_f32 v[50:51], v[50:51], v[44:45] neg_lo:[0,1] neg_hi:[0,1]
	v_pk_add_f32 v[52:53], v[52:53], v[42:43] neg_lo:[0,1] neg_hi:[0,1]
	v_pk_fma_f32 v[44:45], v[8:9], v[50:51], v[44:45]
	v_pk_fma_f32 v[42:43], v[10:11], v[52:53], v[42:43]
	v_pk_mul_f32 v[50:51], v[12:13], v[44:45]
	v_pk_mul_f32 v[52:53], v[14:15], v[42:43]
	v_pk_mul_f32 v[66:67], v[38:39], v[50:51] op_sel_hi:[0,1]
	v_pk_mul_f32 v[60:61], v[38:39], v[52:53] op_sel_hi:[0,1]
	v_xor_b32_e32 v51, 0x80000000, v67
	v_xor_b32_e32 v50, 0x80000000, v66
	v_xor_b32_e32 v53, 0x80000000, v61
	v_xor_b32_e32 v52, 0x80000000, v60
	ds_write_b128 v103, v[50:53]
	v_lshlrev_b32_e32 v50, 16, v54
	v_and_b32_e32 v51, 0xffff0000, v58
	v_pk_add_f32 v[38:39], v[40:41], 1.0 op_sel_hi:[1,0] neg_lo:[1,0] neg_hi:[1,0]
	v_lshlrev_b32_e32 v40, 16, v58
	v_and_b32_e32 v41, 0xffff0000, v54
	v_pk_mul_f32 v[50:51], v[46:47], v[50:51] op_sel:[1,0] op_sel_hi:[0,1]
	v_pk_fma_f32 v[40:41], v[46:47], v[40:41], v[50:51]
	v_lshlrev_b32_e32 v51, 16, v55
	v_and_b32_e32 v53, s0, v55
	v_and_b32_e32 v52, 0xffff0000, v59
	v_pk_add_f32 v[40:41], v[40:41], v[34:35] neg_lo:[0,1] neg_hi:[0,1]
	v_pk_mov_b32 v[50:51], v[50:51], v[52:53] op_sel:[1,0]
	v_pk_fma_f32 v[34:35], v[0:1], v[40:41], v[34:35]
	v_pk_add_f32 v[40:41], v[36:37], 1.0 op_sel_hi:[1,0] neg_lo:[1,0] neg_hi:[1,0]
	v_lshlrev_b32_e32 v36, 16, v59
	v_and_b32_e32 v37, 0xffff0000, v55
	v_pk_mul_f32 v[50:51], v[46:47], v[50:51] op_sel:[1,0] op_sel_hi:[0,1]
	v_pk_fma_f32 v[36:37], v[46:47], v[36:37], v[50:51]
	v_pk_mul_f32 v[34:35], v[34:35], v[38:39]
	v_pk_add_f32 v[36:37], v[36:37], v[32:33] neg_lo:[0,1] neg_hi:[0,1]
	s_nop 0
	v_pk_fma_f32 v[32:33], v[2:3], v[36:37], v[32:33]
	s_nop 0
	v_pk_mul_f32 v[36:37], v[32:33], v[40:41]
	ds_write_b128 v103, v[34:37] offset:4096
	ds_write_b128 v103, v[38:41] offset:8192
	v_pk_mul_f32 v[32:33], v[66:67], v[30:31]
	v_pk_mul_f32 v[34:35], v[60:61], v[28:29]
	v_pk_add_f32 v[30:31], v[30:31], -1.0 op_sel_hi:[1,0]
	v_pk_add_f32 v[28:29], v[28:29], -1.0 op_sel_hi:[1,0]
	v_pk_fma_f32 v[30:31], v[16:17], v[30:31], 1.0 op_sel_hi:[1,1,0]
	v_pk_fma_f32 v[28:29], v[18:19], v[28:29], 1.0 op_sel_hi:[1,1,0]
	ds_write_b128 v103, v[32:35] offset:12288
	v_pk_mul_f32 v[30:31], v[44:45], v[30:31]
	v_pk_mul_f32 v[32:33], v[42:43], v[28:29]
	ds_write_b128 v103, v[30:33] offset:16384
	s_waitcnt vmcnt(1)
	v_lshlrev_b32_e32 v30, 16, v48
	s_waitcnt vmcnt(0)
	v_and_b32_e32 v31, 0xffff0000, v64
	v_lshlrev_b32_e32 v28, 16, v64
	v_and_b32_e32 v29, 0xffff0000, v48
	v_pk_mul_f32 v[30:31], v[46:47], v[30:31] op_sel:[1,0] op_sel_hi:[0,1]
	v_pk_fma_f32 v[28:29], v[46:47], v[28:29], v[30:31]
	v_lshlrev_b32_e32 v31, 16, v49
	v_and_b32_e32 v33, s0, v49
	v_and_b32_e32 v32, 0xffff0000, v65
	v_pk_add_f32 v[28:29], v[28:29], v[26:27] neg_lo:[0,1] neg_hi:[0,1]
	v_pk_mov_b32 v[30:31], v[30:31], v[32:33] op_sel:[1,0]
	v_pk_fma_f32 v[26:27], v[4:5], v[28:29], v[26:27]
	v_lshlrev_b32_e32 v28, 16, v65
	v_and_b32_e32 v29, 0xffff0000, v49
	v_pk_mul_f32 v[30:31], v[46:47], v[30:31] op_sel:[1,0] op_sel_hi:[0,1]
	v_pk_fma_f32 v[28:29], v[46:47], v[28:29], v[30:31]
	s_nop 0
	v_pk_add_f32 v[28:29], v[28:29], v[24:25] neg_lo:[0,1] neg_hi:[0,1]
	s_nop 0
	v_pk_fma_f32 v[28:29], v[6:7], v[28:29], v[24:25]
	ds_write_b128 v103, v[26:29] offset:20480
	s_and_saveexec_b64 s[2:3], s[40:41]
	s_cbranch_execz .LBB0_552
	s_lshl_b32 s90, s11, 2
	v_lshl_add_u64 v[20:21], v[20:21], 0, s[90:91]
	global_load_dwordx2 v[20:21], v[20:21], off offset:4
	s_movk_i32 s4, 0xff08
	v_mad_u64_u32 v[22:23], s[4:5], v97, s4, v[22:23]
	s_waitcnt vmcnt(0)
	ds_write_b64 v22, v[20:21] offset:24576

; DI float row16_sum(float v) { v += dppf(v, 0); v += dppf(v, 1); v += dppf(v, 2); v += dppf(v, 3); return v; }
; DI void rwkv_scan(CP p, const Ptrs& w, int l, int item, float* sm) {
;     ...
;   auto lds_step = [&](const float* bf, int j) {
;     RStep q;
;     q.a4 = *(const f4v*)(bf + 0 * 1024 + j * 64 + 4 * kg);
;     q.wr4 = *(const f4v*)(bf + 1 * 1024 + j * 64 + 4 * kg);
;     q.w4 = *(const f4v*)(bf + 2 * 1024 + j * 64 + 4 * kg);
;     q.b4 = *(const f4v*)(bf + 3 * 1024 + j * 64 + 4 * kg);
;     q.k4 = *(const f4v*)(bf + 4 * 1024 + j * 64 + 4 * kg);
;     q.vv = bf[5 * 1024 + j * 64 + row];
;     q.sc = *(const float2*)(bf + 6 * 1024 + j * 2);
;     return q;
;   };
;   auto flush = [&](int c) {
;     {
;       int j = tid >> 4, rr = tid & 15;
;       int ii = pos2i(c * 16 + j, dir);
;       yout[((size_t)b * TPB + ii) * 512 + hd * 64 + rq * 16 + rr] = f2bf(sY[(c & 1) * 256 + j * 16 + rr]);
;     }
;   };
;   __syncthreads();
;   load(0, PA);
;   stage(PA, sm);
;   load(1, PB);
;   __syncthreads();
;   const int NCH = TPB / 16;
;   auto run_chunk = [&](int c, const float* bf, float* sy) {
;     flush(max(c - 1, 0));
;     RStep cur = lds_step(bf, 0);
; #pragma unroll
;     for (int j = 0; j < 16; ++j) {
;       RStep nxt = cur;
;       if (j + 1 < 16) nxt = lds_step(bf, j + 1);
;       f2v sa2 = SA * cur.a4.xy + SB * cur.a4.zw;
;       f2v yp2 = SA * cur.wr4.xy + SB * cur.wr4.zw;
;       float sa = sa2.x + sa2.y, yp = yp2.x + yp2.y;
;       sa = row16_sum(sa); yp = row16_sum(yp);
;       float y = yp + sa * cur.sc.x + cur.vv * cur.sc.y;
;       SA = SA * cur.w4.xy + (sa * cur.b4.xy + cur.vv * cur.k4.xy);
;       SB = SB * cur.w4.zw + (sa * cur.b4.zw + cur.vv * cur.k4.zw);
;       sy[(kg == 0 ? j * 16 : 0) + ysel - (c & 1) * 0] = y;
;       cur = nxt;
;     }
;   };
;   for (int c = 0; c < NCH; c += 2) {
;     load(min(c + 2, NCH - 1), PA);
;     run_chunk(c, sm, sY);
;     stage(PB, sm + BUF);
;     __syncthreads();
;     load(min(c + 3, NCH - 1), PB);
.LBB0_553:
	s_or_b64 exec, exec, s[4:5]
	v_pk_mul_f32 v[28:29], v[28:29], v[102:103] op_sel_hi:[1,0]
	s_addk_i32 s16, 0x200
	v_pk_fma_f32 v[24:25], v[24:25], v[96:97], v[28:29] op_sel_hi:[1,0,1]
	s_add_i32 s38, s38, 2
	v_pk_fma_f32 v[20:21], v[20:21], v[98:99], v[24:25]
	v_pk_mul_f32 v[24:25], v[30:31], v[102:103] op_sel_hi:[1,0]
	v_cndmask_b32_e64 v94, 0.5, 0, s[44:45]
	v_pk_fma_f32 v[24:25], v[26:27], v[96:97], v[24:25] op_sel_hi:[1,0,1]
	v_cndmask_b32_e64 v95, 0.5, 0, s[42:43]
	v_pk_fma_f32 v[22:23], v[22:23], v[100:101], v[24:25]
	v_add_u32_e32 v125, 32, v125
	s_cmpk_lt_u32 s17, 0x20e
	v_subrev_u32_e32 v124, 32, v124
	s_waitcnt lgkmcnt(0)
	s_barrier
	s_cbranch_scc0 .LBB0_558
.LBB0_554:
	s_min_u32 s4, s38, 1
	s_lshl_b32 s5, s4, 8
	s_lshl_b32 s46, s4, 4
	s_add_i32 s4, s17, 4
	s_min_u32 s4, s4, 0x20f
	v_lshl_add_u32 v24, s4, 4, v97
	s_sub_i32 s39, s16, s5
	v_cmp_lt_i32_e64 s[4:5], s37, v24
	s_nop 1
	v_cndmask_b32_e64 v25, v231, v232, s[4:5]
	v_sub_u32_e32 v25, v25, v24
	v_cndmask_b32_e32 v24, v25, v24, vcc
	v_ashrrev_i32_e32 v25, 31, v24
	v_lshl_add_u64 v[26:27], s[12:13], 0, v[24:25]
	v_mad_u64_u32 v[28:29], s[4:5], v26, s20, v[42:43]
	v_mov_b32_e32 v30, v29
	v_mad_u64_u32 v[30:31], s[4:5], v27, s20, v[30:31]
	v_and_b32_e32 v25, 0xfffffeff, v24
	v_mov_b32_e32 v29, v30
	v_and_b32_e32 v30, 0xffffdfff, v24
	v_cmp_eq_u32_e64 s[42:43], 0, v25
	v_cmp_eq_u32_e64 s[44:45], s37, v30
	s_and_b32 s4, s39, 0x100
	v_cndmask_b32_e64 v25, -1, 0, s[42:43]
	v_cndmask_b32_e64 v24, v236, 0, s[42:43]
	v_cndmask_b32_e64 v156, v237, 0, s[44:45]
	v_lshl_add_u64 v[24:25], v[28:29], 0, v[24:25]
	v_lshl_add_u64 v[30:31], v[28:29], 0, v[156:157]
	global_load_dwordx2 v[88:89], v[28:29], off
	global_load_dwordx2 v[86:87], v[28:29], off offset:1024
	global_load_dwordx2 v[84:85], v[28:29], off offset:2048
	global_load_dwordx2 v[74:75], v[24:25], off
	global_load_dwordx2 v[76:77], v[30:31], off
	global_load_dwordx2 v[78:79], v[24:25], off offset:1024
	global_load_dwordx2 v[70:71], v[24:25], off offset:2048
	v_lshlrev_b64 v[24:25], 10, v[26:27]
	v_lshl_add_u64 v[28:29], v[34:35], 0, v[24:25]
	v_lshl_add_u64 v[24:25], v[36:37], 0, v[24:25]
	global_load_dwordx2 v[80:81], v[30:31], off offset:1024
	global_load_dwordx2 v[72:73], v[30:31], off offset:2048
	global_load_dwordx2 v[92:93], v[28:29], off
	global_load_dwordx2 v[90:91], v[24:25], off
	v_lshlrev_b64 v[24:25], 8, v[26:27]
	v_lshl_add_u64 v[24:25], s[6:7], 0, v[24:25]
	v_lshl_add_u64 v[26:27], v[24:25], 0, s[90:91]
	global_load_dword v82, v[24:25], off
	global_load_dwordx2 v[68:69], v[26:27], off offset:4
	v_lshl_add_u32 v25, s4, 2, v83
	v_subrev_u32_e32 v24, s46, v125
	ds_read_b32 v25, v25 offset:49408
	v_cmp_lt_i32_e64 s[4:5], s37, v24
	ds_read2st64_b32 v[154:155], v106 offset0:80 offset1:81
	s_nop 0
	v_cndmask_b32_e64 v26, v231, v232, s[4:5]
	v_add3_u32 v26, v26, v124, s46
	v_cndmask_b32_e32 v24, v26, v24, vcc
	s_waitcnt lgkmcnt(1)
	v_cvt_pk_bf16_f32 v26, v25, s0
	v_ashrrev_i32_e32 v25, 31, v24
	v_lshl_add_u64 v[24:25], s[12:13], 0, v[24:25]
	v_lshlrev_b64 v[24:25], 10, v[24:25]
	v_lshl_add_u64 v[24:25], v[38:39], 0, v[24:25]
	global_store_short v[24:25], v26, off
	s_waitcnt lgkmcnt(0)
	v_add_u32_e64 v24, s21, 0
	ds_read2_b64 v[24:27], v24 offset1:1
	ds_read_b128 v[28:31], v105
	ds_read_b128 v[98:101], v105 offset:256
	ds_read_b128 v[126:129], v105 offset:4096
	ds_read_b128 v[130:133], v105 offset:4352
	ds_read_b128 v[134:137], v105 offset:8192
	ds_read_b128 v[138:141], v105 offset:8448
	ds_read_b128 v[142:145], v105 offset:12288
	ds_read_b128 v[146:149], v105 offset:12544
	ds_read_b128 v[150:153], v105 offset:16384
	ds_read_b128 v[168:171], v105 offset:16640
	s_waitcnt lgkmcnt(9)
	v_pk_mul_f32 v[30:31], v[22:23], v[30:31]
	v_pk_fma_f32 v[28:29], v[20:21], v[28:29], v[30:31]
	s_waitcnt lgkmcnt(7)
	v_pk_mul_f32 v[30:31], v[22:23], v[128:129]
	v_add_f32_e32 v28, v28, v29
	v_pk_fma_f32 v[30:31], v[20:21], v[126:127], v[30:31]
	v_add_f32_e32 v29, v30, v31
	v_add_f32_dpp v28, v28, v28 quad_perm:[1,0,3,2] row_mask:0xf bank_mask:0xf bound_ctrl:1
	s_nop 0
	v_add_f32_dpp v29, v29, v29 quad_perm:[1,0,3,2] row_mask:0xf bank_mask:0xf bound_ctrl:1
	v_add_f32_dpp v28, v28, v28 quad_perm:[2,3,0,1] row_mask:0xf bank_mask:0xf bound_ctrl:1
	s_nop 0
	v_add_f32_dpp v29, v29, v29 quad_perm:[2,3,0,1] row_mask:0xf bank_mask:0xf bound_ctrl:1
	v_add_f32_dpp v28, v28, v28 row_half_mirror row_mask:0xf bank_mask:0xf bound_ctrl:1
	s_nop 0
	v_add_f32_dpp v29, v29, v29 row_half_mirror row_mask:0xf bank_mask:0xf bound_ctrl:1
	v_add_f32_dpp v28, v28, v28 row_mirror row_mask:0xf bank_mask:0xf bound_ctrl:1
	s_nop 0
	v_add_f32_dpp v29, v29, v29 row_mirror row_mask:0xf bank_mask:0xf bound_ctrl:1
	v_fmac_f32_e32 v29, v24, v28
	v_fmac_f32_e32 v29, v154, v25
	s_waitcnt lgkmcnt(3)
	v_pk_mul_f32 v[24:25], v[142:143], v[28:29] op_sel_hi:[1,0]
	ds_write_b32 v107, v29 offset:49408
	s_waitcnt lgkmcnt(2)
; DI float row16_sum(float v) { v += dppf(v, 0); v += dppf(v, 1); v += dppf(v, 2); v += dppf(v, 3); return v; }
; DI void rwkv_scan(CP p, const Ptrs& w, int l, int item, float* sm) {
;     ...
;   auto lds_step = [&](const float* bf, int j) {
;     RStep q;
;     q.a4 = *(const f4v*)(bf + 0 * 1024 + j * 64 + 4 * kg);
;     q.wr4 = *(const f4v*)(bf + 1 * 1024 + j * 64 + 4 * kg);
;     q.w4 = *(const f4v*)(bf + 2 * 1024 + j * 64 + 4 * kg);
;     q.b4 = *(const f4v*)(bf + 3 * 1024 + j * 64 + 4 * kg);
;     q.k4 = *(const f4v*)(bf + 4 * 1024 + j * 64 + 4 * kg);
;     q.vv = bf[5 * 1024 + j * 64 + row];
;     q.sc = *(const float2*)(bf + 6 * 1024 + j * 2);
;     return q;
;   };
;   auto flush = [&](int c) {
;     {
;       int j = tid >> 4, rr = tid & 15;
;       int ii = pos2i(c * 16 + j, dir);
;       yout[((size_t)b * TPB + ii) * 512 + hd * 64 + rq * 16 + rr] = f2bf(sY[(c & 1) * 256 + j * 16 + rr]);
;     }
;   };
;   __syncthreads();
;   load(0, PA);
;   stage(PA, sm);
;   load(1, PB);
;   __syncthreads();
;   const int NCH = TPB / 16;
;   auto run_chunk = [&](int c, const float* bf, float* sy) {
;     flush(max(c - 1, 0));
;     RStep cur = lds_step(bf, 0);
; #pragma unroll
;     for (int j = 0; j < 16; ++j) {
;       RStep nxt = cur;
;       if (j + 1 < 16) nxt = lds_step(bf, j + 1);
;       f2v sa2 = SA * cur.a4.xy + SB * cur.a4.zw;
;       f2v yp2 = SA * cur.wr4.xy + SB * cur.wr4.zw;
;       float sa = sa2.x + sa2.y, yp = yp2.x + yp2.y;
;       sa = row16_sum(sa); yp = row16_sum(yp);
;       float y = yp + sa * cur.sc.x + cur.vv * cur.sc.y;
;       SA = SA * cur.w4.xy + (sa * cur.b4.xy + cur.vv * cur.k4.xy);
;       SB = SB * cur.w4.zw + (sa * cur.b4.zw + cur.vv * cur.k4.zw);
;       sy[(kg == 0 ? j * 16 : 0) + ysel - (c & 1) * 0] = y;
;       cur = nxt;
;     }
	v_pk_fma_f32 v[24:25], v[150:151], v[154:155], v[24:25] op_sel_hi:[1,0,1]
	v_pk_fma_f32 v[24:25], v[20:21], v[134:135], v[24:25]
	v_pk_mul_f32 v[20:21], v[144:145], v[28:29] op_sel_hi:[1,0]
	v_pk_fma_f32 v[20:21], v[152:153], v[154:155], v[20:21] op_sel_hi:[1,0,1]
	v_pk_fma_f32 v[150:151], v[22:23], v[136:137], v[20:21]
	ds_read_b128 v[20:23], v105 offset:512
	v_pk_mul_f32 v[100:101], v[100:101], v[150:151]
	ds_read_b128 v[28:31], v105 offset:4608
	v_pk_fma_f32 v[98:99], v[98:99], v[24:25], v[100:101]
	v_pk_mul_f32 v[100:101], v[132:133], v[150:151]
	ds_read_b128 v[126:129], v105 offset:8704
	v_pk_fma_f32 v[100:101], v[130:131], v[24:25], v[100:101]
	v_add_f32_e32 v98, v98, v99
	ds_read_b128 v[134:137], v105 offset:12800
	v_add_f32_e32 v99, v100, v101
	v_add_f32_dpp v98, v98, v98 quad_perm:[1,0,3,2] row_mask:0xf bank_mask:0xf bound_ctrl:1
	ds_read_b128 v[142:145], v105 offset:16896
	v_add_f32_dpp v99, v99, v99 quad_perm:[1,0,3,2] row_mask:0xf bank_mask:0xf bound_ctrl:1
	v_add_f32_dpp v98, v98, v98 quad_perm:[2,3,0,1] row_mask:0xf bank_mask:0xf bound_ctrl:1
	v_mov_b32_e32 v100, v155
	v_add_f32_dpp v99, v99, v99 quad_perm:[2,3,0,1] row_mask:0xf bank_mask:0xf bound_ctrl:1
	v_add_f32_dpp v98, v98, v98 row_half_mirror row_mask:0xf bank_mask:0xf bound_ctrl:1
	ds_read_b32 v96, v106 offset:20992
	v_add_f32_dpp v99, v99, v99 row_half_mirror row_mask:0xf bank_mask:0xf bound_ctrl:1
	v_add_f32_dpp v98, v98, v98 row_mirror row_mask:0xf bank_mask:0xf bound_ctrl:1
	ds_read_b64 v[152:153], v157 offset:24592
	v_add_f32_dpp v99, v99, v99 row_mirror row_mask:0xf bank_mask:0xf bound_ctrl:1
	v_fmac_f32_e32 v99, v98, v26
	v_fmac_f32_e32 v99, v155, v27
	v_pk_mul_f32 v[26:27], v[146:147], v[98:99] op_sel_hi:[1,0]
	ds_write_b32 v108, v99 offset:49408
	s_waitcnt lgkmcnt(8)
	v_pk_fma_f32 v[26:27], v[168:169], v[100:101], v[26:27] op_sel_hi:[1,0,1]
	v_pk_fma_f32 v[154:155], v[138:139], v[24:25], v[26:27]
	v_pk_mul_f32 v[24:25], v[148:149], v[98:99] op_sel_hi:[1,0]
	v_pk_fma_f32 v[24:25], v[170:171], v[100:101], v[24:25] op_sel_hi:[1,0,1]
	v_pk_fma_f32 v[150:151], v[140:141], v[150:151], v[24:25]
	ds_read_b128 v[24:27], v105 offset:768
	ds_read_b128 v[98:101], v105 offset:4864
	ds_read_b128 v[130:133], v105 offset:8960
	ds_read_b128 v[138:141], v105 offset:13056
	ds_read_b128 v[146:149], v105 offset:17152
	ds_read_b32 v102, v106 offset:21248
	ds_read_b64 v[168:169], v157 offset:24600
	s_waitcnt lgkmcnt(11)
	v_pk_mul_f32 v[22:23], v[22:23], v[150:151]
	v_pk_fma_f32 v[20:21], v[20:21], v[154:155], v[22:23]
	v_pk_mul_f32 v[22:23], v[30:31], v[150:151]
	v_add_f32_e32 v20, v20, v21
	v_pk_fma_f32 v[22:23], v[28:29], v[154:155], v[22:23]
	v_add_f32_e32 v21, v22, v23
	v_add_f32_dpp v20, v20, v20 quad_perm:[1,0,3,2] row_mask:0xf bank_mask:0xf bound_ctrl:1
	s_nop 0
	v_add_f32_dpp v21, v21, v21 quad_perm:[1,0,3,2] row_mask:0xf bank_mask:0xf bound_ctrl:1
	v_add_f32_dpp v20, v20, v20 quad_perm:[2,3,0,1] row_mask:0xf bank_mask:0xf bound_ctrl:1
	s_nop 0
	v_add_f32_dpp v21, v21, v21 quad_perm:[2,3,0,1] row_mask:0xf bank_mask:0xf bound_ctrl:1
	v_add_f32_dpp v20, v20, v20 row_half_mirror row_mask:0xf bank_mask:0xf bound_ctrl:1
	s_nop 0
	v_add_f32_dpp v21, v21, v21 row_half_mirror row_mask:0xf bank_mask:0xf bound_ctrl:1
	v_add_f32_dpp v20, v20, v20 row_mirror row_mask:0xf bank_mask:0xf bound_ctrl:1
	v_pk_mul_f32 v[22:23], v[134:135], v[20:21] op_sel_hi:[1,0]
	v_add_f32_dpp v28, v21, v21 row_mirror row_mask:0xf bank_mask:0xf bound_ctrl:1
	s_waitcnt lgkmcnt(7)
	v_pk_fma_f32 v[22:23], v[142:143], v[96:97], v[22:23] op_sel_hi:[1,0,1]
	v_fmac_f32_e32 v28, v20, v152
	v_pk_mul_f32 v[20:21], v[136:137], v[20:21] op_sel_hi:[1,0]
	v_fmac_f32_e32 v28, v96, v153
	v_pk_fma_f32 v[20:21], v[144:145], v[96:97], v[20:21] op_sel_hi:[1,0,1]
	v_pk_fma_f32 v[152:153], v[126:127], v[154:155], v[22:23]
	ds_write_b32 v109, v28 offset:49408
	v_pk_fma_f32 v[150:151], v[128:129], v[150:151], v[20:21]
	ds_read_b128 v[20:23], v105 offset:1024
	ds_read_b128 v[28:31], v105 offset:5120
	ds_read_b128 v[126:129], v105 offset:9216
	ds_read_b128 v[134:137], v105 offset:13312
	ds_read_b128 v[142:145], v105 offset:17408
	ds_read_b32 v96, v106 offset:21504
	ds_read_b64 v[154:155], v157 offset:24608
	s_waitcnt lgkmcnt(8)
	v_pk_mul_f32 v[26:27], v[26:27], v[150:151]
	v_pk_fma_f32 v[24:25], v[24:25], v[152:153], v[26:27]
	v_pk_mul_f32 v[26:27], v[100:101], v[150:151]
	v_add_f32_e32 v24, v24, v25
	v_pk_fma_f32 v[26:27], v[98:99], v[152:153], v[26:27]
	v_add_f32_e32 v25, v26, v27
	v_add_f32_dpp v24, v24, v24 quad_perm:[1,0,3,2] row_mask:0xf bank_mask:0xf bound_ctrl:1
	s_nop 0
	v_add_f32_dpp v25, v25, v25 quad_perm:[1,0,3,2] row_mask:0xf bank_mask:0xf bound_ctrl:1
	v_add_f32_dpp v24, v24, v24 quad_perm:[2,3,0,1] row_mask:0xf bank_mask:0xf bound_ctrl:1
	s_nop 0
	v_add_f32_dpp v25, v25, v25 quad_perm:[2,3,0,1] row_mask:0xf bank_mask:0xf bound_ctrl:1
	v_add_f32_dpp v24, v24, v24 row_half_mirror row_mask:0xf bank_mask:0xf bound_ctrl:1
	s_nop 0
	v_add_f32_dpp v25, v25, v25 row_half_mirror row_mask:0xf bank_mask:0xf bound_ctrl:1
	v_add_f32_dpp v24, v24, v24 row_mirror row_mask:0xf bank_mask:0xf bound_ctrl:1
	v_pk_mul_f32 v[26:27], v[138:139], v[24:25] op_sel_hi:[1,0]
	v_add_f32_dpp v98, v25, v25 row_mirror row_mask:0xf bank_mask:0xf bound_ctrl:1
	v_pk_fma_f32 v[26:27], v[146:147], v[102:103], v[26:27] op_sel_hi:[1,0,1]
	v_fmac_f32_e32 v98, v24, v168
	v_pk_mul_f32 v[24:25], v[140:141], v[24:25] op_sel_hi:[1,0]
	v_pk_fma_f32 v[152:153], v[130:131], v[152:153], v[26:27]
	v_fmac_f32_e32 v98, v102, v169
	v_pk_fma_f32 v[24:25], v[148:149], v[102:103], v[24:25] op_sel_hi:[1,0,1]
	ds_write_b32 v110, v98 offset:49408
	v_pk_fma_f32 v[150:151], v[132:133], v[150:151], v[24:25]
	ds_read_b128 v[24:27], v105 offset:1280
	ds_read_b128 v[98:101], v105 offset:5376
	ds_read_b128 v[130:133], v105 offset:9472
	ds_read_b128 v[138:141], v105 offset:13568
	ds_read_b128 v[146:149], v105 offset:17664
	ds_read_b32 v102, v106 offset:21760
	s_waitcnt lgkmcnt(14)
; DI float row16_sum(float v) { v += dppf(v, 0); v += dppf(v, 1); v += dppf(v, 2); v += dppf(v, 3); return v; }
; DI void rwkv_scan(CP p, const Ptrs& w, int l, int item, float* sm) {
;     ...
;   auto lds_step = [&](const float* bf, int j) {
;     RStep q;
;     q.a4 = *(const f4v*)(bf + 0 * 1024 + j * 64 + 4 * kg);
;     q.wr4 = *(const f4v*)(bf + 1 * 1024 + j * 64 + 4 * kg);
;     q.w4 = *(const f4v*)(bf + 2 * 1024 + j * 64 + 4 * kg);
;     q.b4 = *(const f4v*)(bf + 3 * 1024 + j * 64 + 4 * kg);
;     q.k4 = *(const f4v*)(bf + 4 * 1024 + j * 64 + 4 * kg);
;     q.vv = bf[5 * 1024 + j * 64 + row];
;     q.sc = *(const float2*)(bf + 6 * 1024 + j * 2);
;     return q;
;   };
;   auto flush = [&](int c) {
;     {
;       int j = tid >> 4, rr = tid & 15;
;       int ii = pos2i(c * 16 + j, dir);
;       yout[((size_t)b * TPB + ii) * 512 + hd * 64 + rq * 16 + rr] = f2bf(sY[(c & 1) * 256 + j * 16 + rr]);
;     }
;   };
;   __syncthreads();
;   load(0, PA);
;   stage(PA, sm);
;   load(1, PB);
;   __syncthreads();
;   const int NCH = TPB / 16;
;   auto run_chunk = [&](int c, const float* bf, float* sy) {
;     flush(max(c - 1, 0));
;     RStep cur = lds_step(bf, 0);
; #pragma unroll
;     for (int j = 0; j < 16; ++j) {
;       RStep nxt = cur;
;       if (j + 1 < 16) nxt = lds_step(bf, j + 1);
;       f2v sa2 = SA * cur.a4.xy + SB * cur.a4.zw;
;       f2v yp2 = SA * cur.wr4.xy + SB * cur.wr4.zw;
;       float sa = sa2.x + sa2.y, yp = yp2.x + yp2.y;
;       sa = row16_sum(sa); yp = row16_sum(yp);
;       float y = yp + sa * cur.sc.x + cur.vv * cur.sc.y;
;       SA = SA * cur.w4.xy + (sa * cur.b4.xy + cur.vv * cur.k4.xy);
;       SB = SB * cur.w4.zw + (sa * cur.b4.zw + cur.vv * cur.k4.zw);
;       sy[(kg == 0 ? j * 16 : 0) + ysel - (c & 1) * 0] = y;
;       cur = nxt;
;     }
	ds_read_b64 v[168:169], v157 offset:24616
	s_waitcnt lgkmcnt(8)
	v_pk_mul_f32 v[22:23], v[22:23], v[150:151]
	v_pk_fma_f32 v[20:21], v[20:21], v[152:153], v[22:23]
	v_pk_mul_f32 v[22:23], v[30:31], v[150:151]
	v_add_f32_e32 v20, v20, v21
	v_pk_fma_f32 v[22:23], v[28:29], v[152:153], v[22:23]
	v_add_f32_e32 v21, v22, v23
	v_add_f32_dpp v20, v20, v20 quad_perm:[1,0,3,2] row_mask:0xf bank_mask:0xf bound_ctrl:1
	s_nop 0
	v_add_f32_dpp v21, v21, v21 quad_perm:[1,0,3,2] row_mask:0xf bank_mask:0xf bound_ctrl:1
	v_add_f32_dpp v20, v20, v20 quad_perm:[2,3,0,1] row_mask:0xf bank_mask:0xf bound_ctrl:1
	s_nop 0
	v_add_f32_dpp v21, v21, v21 quad_perm:[2,3,0,1] row_mask:0xf bank_mask:0xf bound_ctrl:1
	v_add_f32_dpp v20, v20, v20 row_half_mirror row_mask:0xf bank_mask:0xf bound_ctrl:1
	s_nop 0
	v_add_f32_dpp v21, v21, v21 row_half_mirror row_mask:0xf bank_mask:0xf bound_ctrl:1
	v_add_f32_dpp v20, v20, v20 row_mirror row_mask:0xf bank_mask:0xf bound_ctrl:1
	v_pk_mul_f32 v[22:23], v[134:135], v[20:21] op_sel_hi:[1,0]
	v_add_f32_dpp v28, v21, v21 row_mirror row_mask:0xf bank_mask:0xf bound_ctrl:1
	v_pk_fma_f32 v[22:23], v[142:143], v[96:97], v[22:23] op_sel_hi:[1,0,1]
	v_fmac_f32_e32 v28, v20, v154
	v_pk_mul_f32 v[20:21], v[136:137], v[20:21] op_sel_hi:[1,0]
	v_pk_fma_f32 v[152:153], v[126:127], v[152:153], v[22:23]
	v_fmac_f32_e32 v28, v96, v155
	v_pk_fma_f32 v[20:21], v[144:145], v[96:97], v[20:21] op_sel_hi:[1,0,1]
	ds_write_b32 v111, v28 offset:49408
	v_pk_fma_f32 v[150:151], v[128:129], v[150:151], v[20:21]
	ds_read_b128 v[20:23], v105 offset:1536
	ds_read_b128 v[28:31], v105 offset:5632
	ds_read_b128 v[126:129], v105 offset:9728
	ds_read_b128 v[134:137], v105 offset:13824
	ds_read_b128 v[142:145], v105 offset:17920
	ds_read_b32 v96, v106 offset:22016
	s_waitcnt lgkmcnt(14)
	ds_read_b64 v[154:155], v157 offset:24624
	s_waitcnt lgkmcnt(8)
	v_pk_mul_f32 v[26:27], v[26:27], v[150:151]
	v_pk_fma_f32 v[24:25], v[24:25], v[152:153], v[26:27]
	v_pk_mul_f32 v[26:27], v[100:101], v[150:151]
	v_add_f32_e32 v24, v24, v25
	v_pk_fma_f32 v[26:27], v[98:99], v[152:153], v[26:27]
	v_add_f32_e32 v25, v26, v27
	v_add_f32_dpp v24, v24, v24 quad_perm:[1,0,3,2] row_mask:0xf bank_mask:0xf bound_ctrl:1
	s_nop 0
	v_add_f32_dpp v25, v25, v25 quad_perm:[1,0,3,2] row_mask:0xf bank_mask:0xf bound_ctrl:1
	v_add_f32_dpp v24, v24, v24 quad_perm:[2,3,0,1] row_mask:0xf bank_mask:0xf bound_ctrl:1
	s_nop 0
	v_add_f32_dpp v25, v25, v25 quad_perm:[2,3,0,1] row_mask:0xf bank_mask:0xf bound_ctrl:1
	v_add_f32_dpp v24, v24, v24 row_half_mirror row_mask:0xf bank_mask:0xf bound_ctrl:1
	s_nop 0
	v_add_f32_dpp v25, v25, v25 row_half_mirror row_mask:0xf bank_mask:0xf bound_ctrl:1
	v_add_f32_dpp v24, v24, v24 row_mirror row_mask:0xf bank_mask:0xf bound_ctrl:1
	v_pk_mul_f32 v[26:27], v[138:139], v[24:25] op_sel_hi:[1,0]
	v_add_f32_dpp v98, v25, v25 row_mirror row_mask:0xf bank_mask:0xf bound_ctrl:1
	v_pk_fma_f32 v[26:27], v[146:147], v[102:103], v[26:27] op_sel_hi:[1,0,1]
	v_fmac_f32_e32 v98, v24, v168
	v_pk_mul_f32 v[24:25], v[140:141], v[24:25] op_sel_hi:[1,0]
	v_pk_fma_f32 v[152:153], v[130:131], v[152:153], v[26:27]
	v_fmac_f32_e32 v98, v102, v169
	v_pk_fma_f32 v[24:25], v[148:149], v[102:103], v[24:25] op_sel_hi:[1,0,1]
	ds_write_b32 v112, v98 offset:49408
	v_pk_fma_f32 v[150:151], v[132:133], v[150:151], v[24:25]
	ds_read_b128 v[24:27], v105 offset:1792
	ds_read_b128 v[98:101], v105 offset:5888
	ds_read_b128 v[130:133], v105 offset:9984
	ds_read_b128 v[138:141], v105 offset:14080
	ds_read_b128 v[146:149], v105 offset:18176
	ds_read_b32 v102, v106 offset:22272
	s_waitcnt lgkmcnt(14)
	ds_read_b64 v[168:169], v157 offset:24632
	s_waitcnt lgkmcnt(8)
	v_pk_mul_f32 v[22:23], v[22:23], v[150:151]
	v_pk_fma_f32 v[20:21], v[20:21], v[152:153], v[22:23]
	v_pk_mul_f32 v[22:23], v[30:31], v[150:151]
	v_add_f32_e32 v20, v20, v21
	v_pk_fma_f32 v[22:23], v[28:29], v[152:153], v[22:23]
	v_add_f32_e32 v21, v22, v23
	v_add_f32_dpp v20, v20, v20 quad_perm:[1,0,3,2] row_mask:0xf bank_mask:0xf bound_ctrl:1
	s_nop 0
	v_add_f32_dpp v21, v21, v21 quad_perm:[1,0,3,2] row_mask:0xf bank_mask:0xf bound_ctrl:1
	v_add_f32_dpp v20, v20, v20 quad_perm:[2,3,0,1] row_mask:0xf bank_mask:0xf bound_ctrl:1
	s_nop 0
	v_add_f32_dpp v21, v21, v21 quad_perm:[2,3,0,1] row_mask:0xf bank_mask:0xf bound_ctrl:1
	v_add_f32_dpp v20, v20, v20 row_half_mirror row_mask:0xf bank_mask:0xf bound_ctrl:1
	s_nop 0
	v_add_f32_dpp v21, v21, v21 row_half_mirror row_mask:0xf bank_mask:0xf bound_ctrl:1
	v_add_f32_dpp v20, v20, v20 row_mirror row_mask:0xf bank_mask:0xf bound_ctrl:1
	v_pk_mul_f32 v[22:23], v[134:135], v[20:21] op_sel_hi:[1,0]
	v_add_f32_dpp v28, v21, v21 row_mirror row_mask:0xf bank_mask:0xf bound_ctrl:1
	v_pk_fma_f32 v[22:23], v[142:143], v[96:97], v[22:23] op_sel_hi:[1,0,1]
	v_fmac_f32_e32 v28, v20, v154
	v_pk_mul_f32 v[20:21], v[136:137], v[20:21] op_sel_hi:[1,0]
	v_pk_fma_f32 v[152:153], v[126:127], v[152:153], v[22:23]
	v_fmac_f32_e32 v28, v96, v155
	v_pk_fma_f32 v[20:21], v[144:145], v[96:97], v[20:21] op_sel_hi:[1,0,1]
	ds_write_b32 v113, v28 offset:49408
	v_pk_fma_f32 v[150:151], v[128:129], v[150:151], v[20:21]
	ds_read_b128 v[20:23], v105 offset:2048
	ds_read_b128 v[28:31], v105 offset:6144
	ds_read_b128 v[126:129], v105 offset:10240
	ds_read_b128 v[134:137], v105 offset:14336
	ds_read_b128 v[142:145], v105 offset:18432
	ds_read_b32 v96, v106 offset:22528
	s_waitcnt lgkmcnt(14)
	ds_read_b64 v[154:155], v157 offset:24640
	s_waitcnt lgkmcnt(8)
; DI float row16_sum(float v) { v += dppf(v, 0); v += dppf(v, 1); v += dppf(v, 2); v += dppf(v, 3); return v; }
; DI void rwkv_scan(CP p, const Ptrs& w, int l, int item, float* sm) {
;     ...
;   auto lds_step = [&](const float* bf, int j) {
;     RStep q;
;     q.a4 = *(const f4v*)(bf + 0 * 1024 + j * 64 + 4 * kg);
;     q.wr4 = *(const f4v*)(bf + 1 * 1024 + j * 64 + 4 * kg);
;     q.w4 = *(const f4v*)(bf + 2 * 1024 + j * 64 + 4 * kg);
;     q.b4 = *(const f4v*)(bf + 3 * 1024 + j * 64 + 4 * kg);
;     q.k4 = *(const f4v*)(bf + 4 * 1024 + j * 64 + 4 * kg);
;     q.vv = bf[5 * 1024 + j * 64 + row];
;     q.sc = *(const float2*)(bf + 6 * 1024 + j * 2);
;     return q;
;   };
;   auto flush = [&](int c) {
;     {
;       int j = tid >> 4, rr = tid & 15;
;       int ii = pos2i(c * 16 + j, dir);
;       yout[((size_t)b * TPB + ii) * 512 + hd * 64 + rq * 16 + rr] = f2bf(sY[(c & 1) * 256 + j * 16 + rr]);
;     }
;   };
;   __syncthreads();
;   load(0, PA);
;   stage(PA, sm);
;   load(1, PB);
;   __syncthreads();
;   const int NCH = TPB / 16;
;   auto run_chunk = [&](int c, const float* bf, float* sy) {
;     flush(max(c - 1, 0));
;     RStep cur = lds_step(bf, 0);
; #pragma unroll
;     for (int j = 0; j < 16; ++j) {
;       RStep nxt = cur;
;       if (j + 1 < 16) nxt = lds_step(bf, j + 1);
;       f2v sa2 = SA * cur.a4.xy + SB * cur.a4.zw;
;       f2v yp2 = SA * cur.wr4.xy + SB * cur.wr4.zw;
;       float sa = sa2.x + sa2.y, yp = yp2.x + yp2.y;
;       sa = row16_sum(sa); yp = row16_sum(yp);
;       float y = yp + sa * cur.sc.x + cur.vv * cur.sc.y;
;       SA = SA * cur.w4.xy + (sa * cur.b4.xy + cur.vv * cur.k4.xy);
;       SB = SB * cur.w4.zw + (sa * cur.b4.zw + cur.vv * cur.k4.zw);
;       sy[(kg == 0 ? j * 16 : 0) + ysel - (c & 1) * 0] = y;
;       cur = nxt;
;     }
	v_pk_mul_f32 v[26:27], v[26:27], v[150:151]
	v_pk_fma_f32 v[24:25], v[24:25], v[152:153], v[26:27]
	v_pk_mul_f32 v[26:27], v[100:101], v[150:151]
	v_add_f32_e32 v24, v24, v25
	v_pk_fma_f32 v[26:27], v[98:99], v[152:153], v[26:27]
	v_add_f32_e32 v25, v26, v27
	v_add_f32_dpp v24, v24, v24 quad_perm:[1,0,3,2] row_mask:0xf bank_mask:0xf bound_ctrl:1
	s_nop 0
	v_add_f32_dpp v25, v25, v25 quad_perm:[1,0,3,2] row_mask:0xf bank_mask:0xf bound_ctrl:1
	v_add_f32_dpp v24, v24, v24 quad_perm:[2,3,0,1] row_mask:0xf bank_mask:0xf bound_ctrl:1
	s_nop 0
	v_add_f32_dpp v25, v25, v25 quad_perm:[2,3,0,1] row_mask:0xf bank_mask:0xf bound_ctrl:1
	v_add_f32_dpp v24, v24, v24 row_half_mirror row_mask:0xf bank_mask:0xf bound_ctrl:1
	s_nop 0
	v_add_f32_dpp v25, v25, v25 row_half_mirror row_mask:0xf bank_mask:0xf bound_ctrl:1
	v_add_f32_dpp v24, v24, v24 row_mirror row_mask:0xf bank_mask:0xf bound_ctrl:1
	v_pk_mul_f32 v[26:27], v[138:139], v[24:25] op_sel_hi:[1,0]
	v_add_f32_dpp v98, v25, v25 row_mirror row_mask:0xf bank_mask:0xf bound_ctrl:1
	v_pk_fma_f32 v[26:27], v[146:147], v[102:103], v[26:27] op_sel_hi:[1,0,1]
	v_fmac_f32_e32 v98, v24, v168
	v_pk_mul_f32 v[24:25], v[140:141], v[24:25] op_sel_hi:[1,0]
	v_pk_fma_f32 v[152:153], v[130:131], v[152:153], v[26:27]
	v_fmac_f32_e32 v98, v102, v169
	v_pk_fma_f32 v[24:25], v[148:149], v[102:103], v[24:25] op_sel_hi:[1,0,1]
	ds_write_b32 v114, v98 offset:49408
	v_pk_fma_f32 v[150:151], v[132:133], v[150:151], v[24:25]
	ds_read_b128 v[24:27], v105 offset:2304
	ds_read_b128 v[98:101], v105 offset:6400
	ds_read_b128 v[130:133], v105 offset:10496
	ds_read_b128 v[138:141], v105 offset:14592
	ds_read_b128 v[146:149], v105 offset:18688
	ds_read_b32 v102, v106 offset:22784
	s_waitcnt lgkmcnt(14)
	ds_read_b64 v[168:169], v157 offset:24648
	s_waitcnt lgkmcnt(8)
	v_pk_mul_f32 v[22:23], v[22:23], v[150:151]
	v_pk_fma_f32 v[20:21], v[20:21], v[152:153], v[22:23]
	v_pk_mul_f32 v[22:23], v[30:31], v[150:151]
	v_add_f32_e32 v20, v20, v21
	v_pk_fma_f32 v[22:23], v[28:29], v[152:153], v[22:23]
	v_add_f32_e32 v21, v22, v23
	v_add_f32_dpp v20, v20, v20 quad_perm:[1,0,3,2] row_mask:0xf bank_mask:0xf bound_ctrl:1
	s_nop 0
	v_add_f32_dpp v21, v21, v21 quad_perm:[1,0,3,2] row_mask:0xf bank_mask:0xf bound_ctrl:1
	v_add_f32_dpp v20, v20, v20 quad_perm:[2,3,0,1] row_mask:0xf bank_mask:0xf bound_ctrl:1
	s_nop 0
	v_add_f32_dpp v21, v21, v21 quad_perm:[2,3,0,1] row_mask:0xf bank_mask:0xf bound_ctrl:1
	v_add_f32_dpp v20, v20, v20 row_half_mirror row_mask:0xf bank_mask:0xf bound_ctrl:1
	s_nop 0
	v_add_f32_dpp v21, v21, v21 row_half_mirror row_mask:0xf bank_mask:0xf bound_ctrl:1
	v_add_f32_dpp v20, v20, v20 row_mirror row_mask:0xf bank_mask:0xf bound_ctrl:1
	v_pk_mul_f32 v[22:23], v[134:135], v[20:21] op_sel_hi:[1,0]
	v_add_f32_dpp v28, v21, v21 row_mirror row_mask:0xf bank_mask:0xf bound_ctrl:1
	v_pk_fma_f32 v[22:23], v[142:143], v[96:97], v[22:23] op_sel_hi:[1,0,1]
	v_fmac_f32_e32 v28, v20, v154
	v_pk_mul_f32 v[20:21], v[136:137], v[20:21] op_sel_hi:[1,0]
	v_pk_fma_f32 v[152:153], v[126:127], v[152:153], v[22:23]
	v_fmac_f32_e32 v28, v96, v155
	v_pk_fma_f32 v[20:21], v[144:145], v[96:97], v[20:21] op_sel_hi:[1,0,1]
	ds_write_b32 v115, v28 offset:49408
	v_pk_fma_f32 v[150:151], v[128:129], v[150:151], v[20:21]
	ds_read_b128 v[20:23], v105 offset:2560
	ds_read_b128 v[28:31], v105 offset:6656
	ds_read_b128 v[126:129], v105 offset:10752
	ds_read_b128 v[134:137], v105 offset:14848
	ds_read_b128 v[142:145], v105 offset:18944
	ds_read_b32 v96, v106 offset:23040
	s_waitcnt lgkmcnt(14)
	ds_read_b64 v[154:155], v157 offset:24656
	s_waitcnt lgkmcnt(8)
	v_pk_mul_f32 v[26:27], v[26:27], v[150:151]
	v_pk_fma_f32 v[24:25], v[24:25], v[152:153], v[26:27]
	v_pk_mul_f32 v[26:27], v[100:101], v[150:151]
	v_add_f32_e32 v24, v24, v25
	v_pk_fma_f32 v[26:27], v[98:99], v[152:153], v[26:27]
	v_add_f32_e32 v25, v26, v27
	v_add_f32_dpp v24, v24, v24 quad_perm:[1,0,3,2] row_mask:0xf bank_mask:0xf bound_ctrl:1
	s_nop 0
	v_add_f32_dpp v25, v25, v25 quad_perm:[1,0,3,2] row_mask:0xf bank_mask:0xf bound_ctrl:1
	v_add_f32_dpp v24, v24, v24 quad_perm:[2,3,0,1] row_mask:0xf bank_mask:0xf bound_ctrl:1
	s_nop 0
	v_add_f32_dpp v25, v25, v25 quad_perm:[2,3,0,1] row_mask:0xf bank_mask:0xf bound_ctrl:1
	v_add_f32_dpp v24, v24, v24 row_half_mirror row_mask:0xf bank_mask:0xf bound_ctrl:1
	s_nop 0
	v_add_f32_dpp v25, v25, v25 row_half_mirror row_mask:0xf bank_mask:0xf bound_ctrl:1
	v_add_f32_dpp v24, v24, v24 row_mirror row_mask:0xf bank_mask:0xf bound_ctrl:1
	v_pk_mul_f32 v[26:27], v[138:139], v[24:25] op_sel_hi:[1,0]
	v_add_f32_dpp v98, v25, v25 row_mirror row_mask:0xf bank_mask:0xf bound_ctrl:1
	v_pk_fma_f32 v[26:27], v[146:147], v[102:103], v[26:27] op_sel_hi:[1,0,1]
	v_fmac_f32_e32 v98, v24, v168
	v_pk_mul_f32 v[24:25], v[140:141], v[24:25] op_sel_hi:[1,0]
	v_pk_fma_f32 v[152:153], v[130:131], v[152:153], v[26:27]
	v_fmac_f32_e32 v98, v102, v169
	v_pk_fma_f32 v[24:25], v[148:149], v[102:103], v[24:25] op_sel_hi:[1,0,1]
	ds_write_b32 v116, v98 offset:49408
	v_pk_fma_f32 v[150:151], v[132:133], v[150:151], v[24:25]
	ds_read_b128 v[24:27], v105 offset:2816
	ds_read_b128 v[98:101], v105 offset:6912
	ds_read_b128 v[130:133], v105 offset:11008
	ds_read_b128 v[138:141], v105 offset:15104
	ds_read_b128 v[146:149], v105 offset:19200
	ds_read_b32 v102, v106 offset:23296
	s_waitcnt lgkmcnt(14)
	ds_read_b64 v[168:169], v157 offset:24664
	s_waitcnt lgkmcnt(8)
; DI float row16_sum(float v) { v += dppf(v, 0); v += dppf(v, 1); v += dppf(v, 2); v += dppf(v, 3); return v; }
; DI void rwkv_scan(CP p, const Ptrs& w, int l, int item, float* sm) {
;     ...
;   auto lds_step = [&](const float* bf, int j) {
;     RStep q;
;     q.a4 = *(const f4v*)(bf + 0 * 1024 + j * 64 + 4 * kg);
;     q.wr4 = *(const f4v*)(bf + 1 * 1024 + j * 64 + 4 * kg);
;     q.w4 = *(const f4v*)(bf + 2 * 1024 + j * 64 + 4 * kg);
;     q.b4 = *(const f4v*)(bf + 3 * 1024 + j * 64 + 4 * kg);
;     q.k4 = *(const f4v*)(bf + 4 * 1024 + j * 64 + 4 * kg);
;     q.vv = bf[5 * 1024 + j * 64 + row];
;     q.sc = *(const float2*)(bf + 6 * 1024 + j * 2);
;     return q;
;   };
;   auto flush = [&](int c) {
;     {
;       int j = tid >> 4, rr = tid & 15;
;       int ii = pos2i(c * 16 + j, dir);
;       yout[((size_t)b * TPB + ii) * 512 + hd * 64 + rq * 16 + rr] = f2bf(sY[(c & 1) * 256 + j * 16 + rr]);
;     }
;   };
;   __syncthreads();
;   load(0, PA);
;   stage(PA, sm);
;   load(1, PB);
;   __syncthreads();
;   const int NCH = TPB / 16;
;   auto run_chunk = [&](int c, const float* bf, float* sy) {
;     flush(max(c - 1, 0));
;     RStep cur = lds_step(bf, 0);
; #pragma unroll
;     for (int j = 0; j < 16; ++j) {
;       RStep nxt = cur;
;       if (j + 1 < 16) nxt = lds_step(bf, j + 1);
;       f2v sa2 = SA * cur.a4.xy + SB * cur.a4.zw;
;       f2v yp2 = SA * cur.wr4.xy + SB * cur.wr4.zw;
;       float sa = sa2.x + sa2.y, yp = yp2.x + yp2.y;
;       sa = row16_sum(sa); yp = row16_sum(yp);
;       float y = yp + sa * cur.sc.x + cur.vv * cur.sc.y;
;       SA = SA * cur.w4.xy + (sa * cur.b4.xy + cur.vv * cur.k4.xy);
;       SB = SB * cur.w4.zw + (sa * cur.b4.zw + cur.vv * cur.k4.zw);
;       sy[(kg == 0 ? j * 16 : 0) + ysel - (c & 1) * 0] = y;
;       cur = nxt;
;     }
	v_pk_mul_f32 v[22:23], v[22:23], v[150:151]
	v_pk_fma_f32 v[20:21], v[20:21], v[152:153], v[22:23]
	v_pk_mul_f32 v[22:23], v[30:31], v[150:151]
	v_add_f32_e32 v20, v20, v21
	v_pk_fma_f32 v[22:23], v[28:29], v[152:153], v[22:23]
	v_add_f32_e32 v21, v22, v23
	v_add_f32_dpp v20, v20, v20 quad_perm:[1,0,3,2] row_mask:0xf bank_mask:0xf bound_ctrl:1
	s_nop 0
	v_add_f32_dpp v21, v21, v21 quad_perm:[1,0,3,2] row_mask:0xf bank_mask:0xf bound_ctrl:1
	v_add_f32_dpp v20, v20, v20 quad_perm:[2,3,0,1] row_mask:0xf bank_mask:0xf bound_ctrl:1
	s_nop 0
	v_add_f32_dpp v21, v21, v21 quad_perm:[2,3,0,1] row_mask:0xf bank_mask:0xf bound_ctrl:1
	v_add_f32_dpp v20, v20, v20 row_half_mirror row_mask:0xf bank_mask:0xf bound_ctrl:1
	s_nop 0
	v_add_f32_dpp v21, v21, v21 row_half_mirror row_mask:0xf bank_mask:0xf bound_ctrl:1
	v_add_f32_dpp v20, v20, v20 row_mirror row_mask:0xf bank_mask:0xf bound_ctrl:1
	v_pk_mul_f32 v[22:23], v[134:135], v[20:21] op_sel_hi:[1,0]
	v_add_f32_dpp v28, v21, v21 row_mirror row_mask:0xf bank_mask:0xf bound_ctrl:1
	v_pk_fma_f32 v[22:23], v[142:143], v[96:97], v[22:23] op_sel_hi:[1,0,1]
	v_fmac_f32_e32 v28, v20, v154
	v_pk_mul_f32 v[20:21], v[136:137], v[20:21] op_sel_hi:[1,0]
	v_pk_fma_f32 v[152:153], v[126:127], v[152:153], v[22:23]
	v_fmac_f32_e32 v28, v96, v155
	v_pk_fma_f32 v[20:21], v[144:145], v[96:97], v[20:21] op_sel_hi:[1,0,1]
	ds_write_b32 v117, v28 offset:49408
	v_pk_fma_f32 v[150:151], v[128:129], v[150:151], v[20:21]
	ds_read_b128 v[20:23], v105 offset:3072
	ds_read_b128 v[28:31], v105 offset:7168
	ds_read_b128 v[126:129], v105 offset:11264
	ds_read_b128 v[134:137], v105 offset:15360
	ds_read_b128 v[142:145], v105 offset:19456
	ds_read_b32 v96, v106 offset:23552
	s_waitcnt lgkmcnt(14)
	ds_read_b64 v[154:155], v157 offset:24672
	s_waitcnt lgkmcnt(8)
	v_pk_mul_f32 v[26:27], v[26:27], v[150:151]
	v_pk_fma_f32 v[24:25], v[24:25], v[152:153], v[26:27]
	v_pk_mul_f32 v[26:27], v[100:101], v[150:151]
	v_add_f32_e32 v24, v24, v25
	v_pk_fma_f32 v[26:27], v[98:99], v[152:153], v[26:27]
	v_add_f32_e32 v25, v26, v27
	v_add_f32_dpp v24, v24, v24 quad_perm:[1,0,3,2] row_mask:0xf bank_mask:0xf bound_ctrl:1
	s_nop 0
	v_add_f32_dpp v25, v25, v25 quad_perm:[1,0,3,2] row_mask:0xf bank_mask:0xf bound_ctrl:1
	v_add_f32_dpp v24, v24, v24 quad_perm:[2,3,0,1] row_mask:0xf bank_mask:0xf bound_ctrl:1
	s_nop 0
	v_add_f32_dpp v25, v25, v25 quad_perm:[2,3,0,1] row_mask:0xf bank_mask:0xf bound_ctrl:1
	v_add_f32_dpp v24, v24, v24 row_half_mirror row_mask:0xf bank_mask:0xf bound_ctrl:1
	s_nop 0
	v_add_f32_dpp v25, v25, v25 row_half_mirror row_mask:0xf bank_mask:0xf bound_ctrl:1
	v_add_f32_dpp v24, v24, v24 row_mirror row_mask:0xf bank_mask:0xf bound_ctrl:1
	v_pk_mul_f32 v[26:27], v[138:139], v[24:25] op_sel_hi:[1,0]
	v_add_f32_dpp v98, v25, v25 row_mirror row_mask:0xf bank_mask:0xf bound_ctrl:1
	v_pk_fma_f32 v[26:27], v[146:147], v[102:103], v[26:27] op_sel_hi:[1,0,1]
	v_fmac_f32_e32 v98, v24, v168
	v_pk_mul_f32 v[24:25], v[140:141], v[24:25] op_sel_hi:[1,0]
	v_pk_fma_f32 v[152:153], v[130:131], v[152:153], v[26:27]
	v_fmac_f32_e32 v98, v102, v169
	v_pk_fma_f32 v[24:25], v[148:149], v[102:103], v[24:25] op_sel_hi:[1,0,1]
	ds_write_b32 v118, v98 offset:49408
	v_pk_fma_f32 v[150:151], v[132:133], v[150:151], v[24:25]
	ds_read_b128 v[24:27], v105 offset:3328
	ds_read_b128 v[98:101], v105 offset:7424
	ds_read_b128 v[130:133], v105 offset:11520
	ds_read_b128 v[138:141], v105 offset:15616
	ds_read_b128 v[146:149], v105 offset:19712
	ds_read_b32 v102, v106 offset:23808
	s_waitcnt lgkmcnt(14)
	ds_read_b64 v[172:173], v157 offset:24680
	s_waitcnt lgkmcnt(8)
	v_pk_mul_f32 v[22:23], v[22:23], v[150:151]
	v_pk_fma_f32 v[20:21], v[20:21], v[152:153], v[22:23]
	v_pk_mul_f32 v[22:23], v[30:31], v[150:151]
	v_add_f32_e32 v20, v20, v21
	v_pk_fma_f32 v[22:23], v[28:29], v[152:153], v[22:23]
	v_add_f32_e32 v21, v22, v23
	v_add_f32_dpp v20, v20, v20 quad_perm:[1,0,3,2] row_mask:0xf bank_mask:0xf bound_ctrl:1
	s_nop 0
	v_add_f32_dpp v21, v21, v21 quad_perm:[1,0,3,2] row_mask:0xf bank_mask:0xf bound_ctrl:1
	v_add_f32_dpp v20, v20, v20 quad_perm:[2,3,0,1] row_mask:0xf bank_mask:0xf bound_ctrl:1
	s_nop 0
	v_add_f32_dpp v21, v21, v21 quad_perm:[2,3,0,1] row_mask:0xf bank_mask:0xf bound_ctrl:1
	v_add_f32_dpp v20, v20, v20 row_half_mirror row_mask:0xf bank_mask:0xf bound_ctrl:1
	s_nop 0
	v_add_f32_dpp v21, v21, v21 row_half_mirror row_mask:0xf bank_mask:0xf bound_ctrl:1
	v_add_f32_dpp v20, v20, v20 row_mirror row_mask:0xf bank_mask:0xf bound_ctrl:1
	v_pk_mul_f32 v[22:23], v[134:135], v[20:21] op_sel_hi:[1,0]
	v_add_f32_dpp v28, v21, v21 row_mirror row_mask:0xf bank_mask:0xf bound_ctrl:1
	v_pk_fma_f32 v[22:23], v[142:143], v[96:97], v[22:23] op_sel_hi:[1,0,1]
	v_fmac_f32_e32 v28, v20, v154
	v_pk_mul_f32 v[20:21], v[136:137], v[20:21] op_sel_hi:[1,0]
	v_pk_fma_f32 v[22:23], v[126:127], v[152:153], v[22:23]
	v_fmac_f32_e32 v28, v96, v155
	v_pk_fma_f32 v[20:21], v[144:145], v[96:97], v[20:21] op_sel_hi:[1,0,1]
	ds_write_b32 v119, v28 offset:49408
	v_pk_fma_f32 v[20:21], v[128:129], v[150:151], v[20:21]
	ds_read_b128 v[126:129], v105 offset:3584
	ds_read_b128 v[134:137], v105 offset:7680
	ds_read_b128 v[142:145], v105 offset:11776
	ds_read_b128 v[150:153], v105 offset:15872
	ds_read_b128 v[168:171], v105 offset:19968
	ds_read_b32 v154, v106 offset:24064
	s_waitcnt lgkmcnt(14)
	ds_read_b64 v[174:175], v157 offset:24688
	s_waitcnt lgkmcnt(8)
; DI float row16_sum(float v) { v += dppf(v, 0); v += dppf(v, 1); v += dppf(v, 2); v += dppf(v, 3); return v; }
; DI void rwkv_scan(CP p, const Ptrs& w, int l, int item, float* sm) {
;     ...
;   auto stage = [&](const RPre& P, float* bufp) {
;     float rc[4], rp[4], rn[4], kc[4], kp[4], kn[4], vc[4], vp[4], vn[4], wd4[4], ad4[4];
;     up4(P.pq[0][0], rc); up4(P.pq[0][1], rp); up4(P.pq[0][2], rn);
;     up4(P.pq[1][0], kc); up4(P.pq[1][1], kp); up4(P.pq[1][2], kn);
;     up4(P.pq[2][0], vc); up4(P.pq[2][1], vp); up4(P.pq[2][2], vn);
;     up4(P.pwd, wd4); up4(P.pad_, ad4);
;     float o0[4], o1[4], o2[4], o3[4], o4[4], o5[4];
; #pragma unroll
;     for (int j = 0; j < 4; ++j) {
;       float r_s = rc[j] + ((P.pmk[0] * rp[j] + P.pmk[1] * rn[j]) - rc[j]) * mu_r[j];
;       float k_s = kc[j] + ((P.pmk[0] * kp[j] + P.pmk[1] * kn[j]) - kc[j]) * mu_k[j];
;       float v_s = vc[j] + ((P.pmk[0] * vp[j] + P.pmk[1] * vn[j]) - vc[j]) * mu_v[j];
;       float kk = k_s * kk_c[j] * P.psc[0];
;       float a = ad4[j], wv = 1.f - wd4[j];
;       o0[j] = -kk; o1[j] = wv * r_s; o2[j] = wv; o3[j] = kk * a; o4[j] = k_s * (1.f + (a - 1.f) * ka_c[j]); o5[j] = v_s;
;     }
;     float* d = bufp + sj * 64 + skq;
;     *(float4*)(d + 0 * 1024) = make_float4(o0[0], o0[1], o0[2], o0[3]);
;     *(float4*)(d + 1 * 1024) = make_float4(o1[0], o1[1], o1[2], o1[3]);
;     *(float4*)(d + 2 * 1024) = make_float4(o2[0], o2[1], o2[2], o2[3]);
;     *(float4*)(d + 3 * 1024) = make_float4(o3[0], o3[1], o3[2], o3[3]);
;     *(float4*)(d + 4 * 1024) = make_float4(o4[0], o4[1], o4[2], o4[3]);
;     *(float4*)(d + 5 * 1024) = make_float4(o5[0], o5[1], o5[2], o5[3]);
;     if (skq == 0) *(float2*)(bufp + 6 * 1024 + sj * 2) = make_float2(P.psc[1], P.psc[2]);
;   };
;     ...
; #pragma unroll
;     for (int j = 0; j < 16; ++j) {
;       RStep nxt = cur;
;       if (j + 1 < 16) nxt = lds_step(bf, j + 1);
;       f2v sa2 = SA * cur.a4.xy + SB * cur.a4.zw;
;       f2v yp2 = SA * cur.wr4.xy + SB * cur.wr4.zw;
;       float sa = sa2.x + sa2.y, yp = yp2.x + yp2.y;
;       sa = row16_sum(sa); yp = row16_sum(yp);
;       float y = yp + sa * cur.sc.x + cur.vv * cur.sc.y;
;       SA = SA * cur.w4.xy + (sa * cur.b4.xy + cur.vv * cur.k4.xy);
;       SB = SB * cur.w4.zw + (sa * cur.b4.zw + cur.vv * cur.k4.zw);
;       sy[(kg == 0 ? j * 16 : 0) + ysel - (c & 1) * 0] = y;
;       cur = nxt;
;     }
	v_pk_mul_f32 v[26:27], v[26:27], v[20:21]
	v_pk_fma_f32 v[24:25], v[24:25], v[22:23], v[26:27]
	v_pk_mul_f32 v[26:27], v[100:101], v[20:21]
	v_add_f32_e32 v24, v24, v25
	v_pk_fma_f32 v[26:27], v[98:99], v[22:23], v[26:27]
	v_add_f32_e32 v25, v26, v27
	v_add_f32_dpp v24, v24, v24 quad_perm:[1,0,3,2] row_mask:0xf bank_mask:0xf bound_ctrl:1
	s_nop 0
	v_add_f32_dpp v25, v25, v25 quad_perm:[1,0,3,2] row_mask:0xf bank_mask:0xf bound_ctrl:1
	v_add_f32_dpp v24, v24, v24 quad_perm:[2,3,0,1] row_mask:0xf bank_mask:0xf bound_ctrl:1
	s_nop 0
	v_add_f32_dpp v25, v25, v25 quad_perm:[2,3,0,1] row_mask:0xf bank_mask:0xf bound_ctrl:1
	v_add_f32_dpp v24, v24, v24 row_half_mirror row_mask:0xf bank_mask:0xf bound_ctrl:1
	s_nop 0
	v_add_f32_dpp v25, v25, v25 row_half_mirror row_mask:0xf bank_mask:0xf bound_ctrl:1
	v_add_f32_dpp v24, v24, v24 row_mirror row_mask:0xf bank_mask:0xf bound_ctrl:1
	s_nop 0
	v_add_f32_dpp v25, v25, v25 row_mirror row_mask:0xf bank_mask:0xf bound_ctrl:1
	v_fmac_f32_e32 v25, v24, v172
	v_fmac_f32_e32 v25, v102, v173
	v_pk_mul_f32 v[26:27], v[138:139], v[24:25] op_sel_hi:[1,0]
	ds_write_b32 v120, v25 offset:49408
	v_pk_fma_f32 v[26:27], v[146:147], v[102:103], v[26:27] op_sel_hi:[1,0,1]
	v_pk_fma_f32 v[98:99], v[130:131], v[22:23], v[26:27]
	v_pk_mul_f32 v[22:23], v[140:141], v[24:25] op_sel_hi:[1,0]
	v_pk_fma_f32 v[22:23], v[148:149], v[102:103], v[22:23] op_sel_hi:[1,0,1]
	v_pk_fma_f32 v[100:101], v[132:133], v[20:21], v[22:23]
	ds_read_b128 v[130:133], v105 offset:3840
	ds_read_b128 v[138:141], v105 offset:7936
	ds_read_b128 v[20:23], v105 offset:12032
	ds_read_b128 v[28:31], v105 offset:16128
	s_waitcnt lgkmcnt(5)
	v_pk_mul_f32 v[128:129], v[128:129], v[100:101]
	ds_read_b128 v[24:27], v105 offset:20224
	v_pk_fma_f32 v[126:127], v[126:127], v[98:99], v[128:129]
	v_pk_mul_f32 v[128:129], v[136:137], v[100:101]
	ds_read_b32 v96, v106 offset:24320
	ds_read_b64 v[146:147], v157 offset:24696
	v_add_f32_e32 v102, v126, v127
	v_pk_fma_f32 v[128:129], v[134:135], v[98:99], v[128:129]
	s_waitcnt vmcnt(21)
	v_and_b32_e32 v137, 0xffff0000, v52
	v_add_f32_e32 v126, v128, v129
	v_add_f32_dpp v102, v102, v102 quad_perm:[1,0,3,2] row_mask:0xf bank_mask:0xf bound_ctrl:1
	s_waitcnt vmcnt(20)
	v_lshlrev_b32_e32 v136, 16, v54
	v_add_f32_dpp v126, v126, v126 quad_perm:[1,0,3,2] row_mask:0xf bank_mask:0xf bound_ctrl:1
	v_add_f32_dpp v102, v102, v102 quad_perm:[2,3,0,1] row_mask:0xf bank_mask:0xf bound_ctrl:1
	s_waitcnt vmcnt(16)
	v_lshlrev_b32_e32 v134, 16, v64
	v_add_f32_dpp v126, v126, v126 quad_perm:[2,3,0,1] row_mask:0xf bank_mask:0xf bound_ctrl:1
	v_add_f32_dpp v102, v102, v102 row_half_mirror row_mask:0xf bank_mask:0xf bound_ctrl:1
	v_and_b32_e32 v135, 0xffff0000, v64
	v_add_f32_dpp v126, v126, v126 row_half_mirror row_mask:0xf bank_mask:0xf bound_ctrl:1
	v_add_f32_dpp v102, v102, v102 row_mirror row_mask:0xf bank_mask:0xf bound_ctrl:1
	v_lshlrev_b32_e32 v64, 16, v65
	v_add_f32_dpp v128, v126, v126 row_mirror row_mask:0xf bank_mask:0xf bound_ctrl:1
	s_waitcnt lgkmcnt(11)
	v_pk_mul_f32 v[126:127], v[150:151], v[102:103] op_sel_hi:[1,0]
	s_waitcnt lgkmcnt(8)
	v_fmac_f32_e32 v128, v102, v174
	v_pk_fma_f32 v[126:127], v[168:169], v[154:155], v[126:127] op_sel_hi:[1,0,1]
	v_fmac_f32_e32 v128, v154, v175
	v_pk_fma_f32 v[98:99], v[142:143], v[98:99], v[126:127]
	v_pk_mul_f32 v[126:127], v[152:153], v[102:103] op_sel_hi:[1,0]
	ds_write_b32 v121, v128 offset:49408
	v_pk_fma_f32 v[126:127], v[170:171], v[154:155], v[126:127] op_sel_hi:[1,0,1]
	v_and_b32_e32 v65, 0xffff0000, v65
	v_pk_fma_f32 v[100:101], v[144:145], v[100:101], v[126:127]
	s_waitcnt lgkmcnt(7)
	v_pk_mul_f32 v[126:127], v[132:133], v[100:101]
	s_waitcnt lgkmcnt(6)
	v_pk_mul_f32 v[128:129], v[140:141], v[100:101]
	v_pk_fma_f32 v[126:127], v[130:131], v[98:99], v[126:127]
	v_pk_fma_f32 v[128:129], v[138:139], v[98:99], v[128:129]
	v_add_f32_e32 v102, v126, v127
	v_add_f32_e32 v126, v128, v129
	v_lshlrev_b32_e32 v138, 16, v52
	v_add_f32_dpp v102, v102, v102 quad_perm:[1,0,3,2] row_mask:0xf bank_mask:0xf bound_ctrl:1
	v_add_f32_dpp v126, v126, v126 quad_perm:[1,0,3,2] row_mask:0xf bank_mask:0xf bound_ctrl:1
	v_and_b32_e32 v139, 0xffff0000, v54
	v_add_f32_dpp v102, v102, v102 quad_perm:[2,3,0,1] row_mask:0xf bank_mask:0xf bound_ctrl:1
	v_add_f32_dpp v126, v126, v126 quad_perm:[2,3,0,1] row_mask:0xf bank_mask:0xf bound_ctrl:1
	v_and_b32_e32 v141, 0xffff0000, v53
	v_add_f32_dpp v102, v102, v102 row_half_mirror row_mask:0xf bank_mask:0xf bound_ctrl:1
	v_add_f32_dpp v126, v126, v126 row_half_mirror row_mask:0xf bank_mask:0xf bound_ctrl:1
	v_lshlrev_b32_e32 v52, 16, v53
	v_add_f32_dpp v102, v102, v102 row_mirror row_mask:0xf bank_mask:0xf bound_ctrl:1
	v_add_f32_dpp v126, v126, v126 row_mirror row_mask:0xf bank_mask:0xf bound_ctrl:1
	s_waitcnt lgkmcnt(1)
	v_fmac_f32_e32 v126, v102, v146
	v_and_b32_e32 v53, 0xffff0000, v55
	v_fmac_f32_e32 v126, v96, v147
	v_pk_mul_f32 v[138:139], v[94:95], v[138:139] op_sel:[1,0] op_sel_hi:[0,1]
	v_lshlrev_b32_e32 v140, 16, v55
	v_pk_mul_f32 v[52:53], v[94:95], v[52:53] op_sel:[1,0] op_sel_hi:[0,1]
	ds_write_b32 v122, v126 offset:49408
	v_lshlrev_b32_e32 v126, 16, v58
	v_and_b32_e32 v127, 0xffff0000, v58
	v_lshlrev_b32_e32 v128, 16, v59
	v_and_b32_e32 v129, 0xffff0000, v59
	v_lshlrev_b32_e32 v58, 16, v60
	v_and_b32_e32 v59, 0xffff0000, v60
	v_lshlrev_b32_e32 v60, 16, v61
	v_and_b32_e32 v61, 0xffff0000, v61
	v_pk_fma_f32 v[136:137], v[94:95], v[136:137], v[138:139]
	v_pk_fma_f32 v[52:53], v[94:95], v[140:141], v[52:53]
	v_pk_add_f32 v[136:137], v[136:137], v[58:59] neg_lo:[0,1] neg_hi:[0,1]
	v_pk_add_f32 v[52:53], v[52:53], v[60:61] neg_lo:[0,1] neg_hi:[0,1]
	v_pk_fma_f32 v[136:137], v[8:9], v[136:137], v[58:59]
	v_pk_fma_f32 v[140:141], v[10:11], v[52:53], v[60:61]
	v_pk_mul_f32 v[58:59], v[12:13], v[136:137]
	v_pk_mul_f32 v[52:53], v[14:15], v[140:141]
	s_waitcnt vmcnt(15)
; DI void rwkv_scan(CP p, const Ptrs& w, int l, int item, float* sm) {
;     ...
;   auto load = [&](int c, RPre& P) {
;     int ii = pos2i(c * 16 + sj, dir);
;     size_t tok = (size_t)b * TPB + ii;
;     const bf16_t* prow = w.pB + tok * SPB + sc_;
;     bool hp = (ii != 0) && (ii != CTXL), hn = (ii != CTXL - 1) && (ii != TPB - 1);
;     const int op = hp ? -SPB : 0, on = hn ? SPB : 0;
;     P.pmk[0] = hp ? 0.5f : 0.f; P.pmk[1] = hn ? 0.5f : 0.f;
; #pragma unroll
;     for (int q = 0; q < 3; ++q) {
;       P.pq[q][0] = *(const uint2*)(prow + q * 512);
;       P.pq[q][1] = *(const uint2*)(prow + q * 512 + op);
;       P.pq[q][2] = *(const uint2*)(prow + q * 512 + on);
;     }
;     P.pwd = *(const uint2*)(Wd + tok * 512 + sc_);
;     P.pad_ = *(const uint2*)(Ad + tok * 512 + sc_);
;     const float* sc = w.bonus + (tok * 8 + hd) * 8;
;     P.psc[0] = sc[0]; P.psc[1] = sc[1 + 3 * dir]; P.psc[2] = sc[2 + 3 * dir];
;   };
;   auto up4 = [](uint2 u, float* f) { f[0] = __uint_as_float(u.x << 16); f[1] = __uint_as_float(u.x & 0xffff0000u); f[2] = __uint_as_float(u.y << 16); f[3] = __uint_as_float(u.y & 0xffff0000u); };
;   auto stage = [&](const RPre& P, float* bufp) {
;     float rc[4], rp[4], rn[4], kc[4], kp[4], kn[4], vc[4], vp[4], vn[4], wd4[4], ad4[4];
;     up4(P.pq[0][0], rc); up4(P.pq[0][1], rp); up4(P.pq[0][2], rn);
;     up4(P.pq[1][0], kc); up4(P.pq[1][1], kp); up4(P.pq[1][2], kn);
;     up4(P.pq[2][0], vc); up4(P.pq[2][1], vp); up4(P.pq[2][2], vn);
;     up4(P.pwd, wd4); up4(P.pad_, ad4);
;     float o0[4], o1[4], o2[4], o3[4], o4[4], o5[4];
; #pragma unroll
;     for (int j = 0; j < 4; ++j) {
;       float r_s = rc[j] + ((P.pmk[0] * rp[j] + P.pmk[1] * rn[j]) - rc[j]) * mu_r[j];
;       float k_s = kc[j] + ((P.pmk[0] * kp[j] + P.pmk[1] * kn[j]) - kc[j]) * mu_k[j];
;       float v_s = vc[j] + ((P.pmk[0] * vp[j] + P.pmk[1] * vn[j]) - vc[j]) * mu_v[j];
;       float kk = k_s * kk_c[j] * P.psc[0];
;       float a = ad4[j], wv = 1.f - wd4[j];
;       o0[j] = -kk; o1[j] = wv * r_s; o2[j] = wv; o3[j] = kk * a; o4[j] = k_s * (1.f + (a - 1.f) * ka_c[j]); o5[j] = v_s;
;     }
;     float* d = bufp + sj * 64 + skq;
;     *(float4*)(d + 0 * 1024) = make_float4(o0[0], o0[1], o0[2], o0[3]);
;     *(float4*)(d + 1 * 1024) = make_float4(o1[0], o1[1], o1[2], o1[3]);
;     *(float4*)(d + 2 * 1024) = make_float4(o2[0], o2[1], o2[2], o2[3]);
	v_pk_mul_f32 v[138:139], v[56:57], v[58:59] op_sel_hi:[0,1]
	v_pk_mul_f32 v[142:143], v[56:57], v[52:53] op_sel_hi:[0,1]
	v_xor_b32_e32 v59, 0x80000000, v139
	v_xor_b32_e32 v58, 0x80000000, v138
	v_xor_b32_e32 v61, 0x80000000, v143
	v_xor_b32_e32 v60, 0x80000000, v142
	ds_write_b128 v103, v[58:61] offset:24704
	v_lshlrev_b32_e32 v59, 16, v48
	v_and_b32_e32 v61, s0, v48
	v_and_b32_e32 v60, 0xffff0000, v50
	v_pk_mov_b32 v[58:59], v[58:59], v[60:61] op_sel:[1,0]
	v_lshlrev_b32_e32 v54, 16, v50
	v_and_b32_e32 v55, 0xffff0000, v48
	v_pk_mul_f32 v[58:59], v[94:95], v[58:59] op_sel:[1,0] op_sel_hi:[0,1]
	v_pk_fma_f32 v[54:55], v[94:95], v[54:55], v[58:59]
	v_lshlrev_b32_e32 v132, 16, v66
	v_and_b32_e32 v133, 0xffff0000, v66
	v_pk_add_f32 v[54:55], v[54:55], v[126:127] neg_lo:[0,1] neg_hi:[0,1]
	v_lshlrev_b32_e32 v66, 16, v67
	v_and_b32_e32 v67, 0xffff0000, v67
	v_pk_add_f32 v[52:53], v[132:133], 1.0 op_sel_hi:[1,0] neg_lo:[1,0] neg_hi:[1,0]
	v_pk_fma_f32 v[54:55], v[0:1], v[54:55], v[126:127]
	v_and_b32_e32 v61, 0xffff0000, v49
	v_pk_mul_f32 v[58:59], v[54:55], v[52:53]
	v_pk_add_f32 v[54:55], v[66:67], 1.0 op_sel_hi:[1,0] neg_lo:[1,0] neg_hi:[1,0]
	v_lshlrev_b32_e32 v67, 16, v49
	v_and_b32_e32 v49, s0, v49
	v_and_b32_e32 v48, 0xffff0000, v51
	v_pk_mov_b32 v[48:49], v[66:67], v[48:49] op_sel:[1,0]
	v_lshlrev_b32_e32 v60, 16, v51
	v_pk_mul_f32 v[48:49], v[94:95], v[48:49] op_sel:[1,0] op_sel_hi:[0,1]
	v_pk_fma_f32 v[48:49], v[94:95], v[60:61], v[48:49]
	v_pk_mul_f32 v[50:51], v[142:143], v[64:65]
	v_pk_add_f32 v[48:49], v[48:49], v[128:129] neg_lo:[0,1] neg_hi:[0,1]
	v_lshlrev_b32_e32 v130, 16, v62
	v_pk_fma_f32 v[48:49], v[2:3], v[48:49], v[128:129]
	v_and_b32_e32 v131, 0xffff0000, v62
	v_pk_mul_f32 v[60:61], v[48:49], v[54:55]
	v_pk_mul_f32 v[48:49], v[138:139], v[134:135]
	ds_write_b128 v103, v[58:61] offset:28800
	ds_write_b128 v103, v[52:55] offset:32896
	ds_write_b128 v103, v[48:51] offset:36992
	v_pk_add_f32 v[48:49], v[134:135], -1.0 op_sel_hi:[1,0]
	v_pk_add_f32 v[50:51], v[64:65], -1.0 op_sel_hi:[1,0]
	v_pk_fma_f32 v[48:49], v[16:17], v[48:49], 1.0 op_sel_hi:[1,1,0]
	v_pk_fma_f32 v[50:51], v[18:19], v[50:51], 1.0 op_sel_hi:[1,1,0]
	v_pk_mul_f32 v[48:49], v[48:49], v[136:137]
	v_pk_mul_f32 v[50:51], v[50:51], v[140:141]
	ds_write_b128 v103, v[48:51] offset:41088
	v_lshlrev_b32_e32 v51, 16, v40
	v_and_b32_e32 v53, s0, v40
	v_and_b32_e32 v52, 0xffff0000, v46
	v_pk_mov_b32 v[50:51], v[50:51], v[52:53] op_sel:[1,0]
	v_lshlrev_b32_e32 v48, 16, v46
	v_and_b32_e32 v49, 0xffff0000, v40
	v_pk_mul_f32 v[50:51], v[94:95], v[50:51] op_sel:[1,0] op_sel_hi:[0,1]
	v_pk_fma_f32 v[48:49], v[94:95], v[48:49], v[50:51]
	v_and_b32_e32 v51, 0xffff0000, v41
	v_lshlrev_b32_e32 v53, 16, v41
	v_and_b32_e32 v41, s0, v41
	v_and_b32_e32 v40, 0xffff0000, v47
	v_pk_mov_b32 v[40:41], v[52:53], v[40:41] op_sel:[1,0]
	v_lshlrev_b32_e32 v50, 16, v47
	v_pk_mul_f32 v[40:41], v[94:95], v[40:41] op_sel:[1,0] op_sel_hi:[0,1]
	v_lshlrev_b32_e32 v62, 16, v63
	v_and_b32_e32 v63, 0xffff0000, v63
	v_pk_fma_f32 v[40:41], v[94:95], v[50:51], v[40:41]
	v_pk_add_f32 v[48:49], v[48:49], v[130:131] neg_lo:[0,1] neg_hi:[0,1]
	v_pk_add_f32 v[40:41], v[40:41], v[62:63] neg_lo:[0,1] neg_hi:[0,1]
	v_pk_fma_f32 v[48:49], v[4:5], v[48:49], v[130:131]
	v_pk_fma_f32 v[50:51], v[6:7], v[40:41], v[62:63]
	ds_write_b128 v103, v[48:51] offset:45184
	s_and_saveexec_b64 s[4:5], s[40:41]
	s_cbranch_execz .LBB0_556
	s_waitcnt vmcnt(14)
	ds_write_b64 v104, v[44:45] offset:49280
.LBB0_556:
	s_or_b64 exec, exec, s[4:5]
	v_pk_mul_f32 v[28:29], v[28:29], v[102:103] op_sel_hi:[1,0]
	s_add_i32 s17, s17, 2
	v_pk_fma_f32 v[24:25], v[24:25], v[96:97], v[28:29] op_sel_hi:[1,0,1]
	s_min_u32 s4, s17, 0x20c
	v_pk_fma_f32 v[154:155], v[20:21], v[98:99], v[24:25]
	v_pk_mul_f32 v[20:21], v[30:31], v[102:103] op_sel_hi:[1,0]
	v_cndmask_b32_e64 v95, 0.5, 0, s[42:43]
	v_pk_fma_f32 v[20:21], v[26:27], v[96:97], v[20:21] op_sel_hi:[1,0,1]
	v_cndmask_b32_e64 v94, 0.5, 0, s[44:45]
	v_pk_fma_f32 v[168:169], v[22:23], v[100:101], v[20:21]
	v_lshl_add_u32 v20, s4, 4, v123
	v_cmp_lt_i32_e64 s[4:5], s37, v20
	s_waitcnt lgkmcnt(0)
	s_barrier
	v_cndmask_b32_e64 v21, v231, v232, s[4:5]
	v_sub_u32_e32 v21, v21, v20
	v_cndmask_b32_e32 v20, v21, v20, vcc
	v_ashrrev_i32_e32 v21, 31, v20
	v_lshl_add_u64 v[22:23], s[12:13], 0, v[20:21]
	v_mad_u64_u32 v[24:25], s[4:5], v22, s20, v[42:43]
	v_mov_b32_e32 v26, v25
	v_mad_u64_u32 v[26:27], s[4:5], v23, s20, v[26:27]
	v_and_b32_e32 v21, 0xfffffeff, v20
	v_mov_b32_e32 v25, v26
	v_and_b32_e32 v26, 0xffffdfff, v20
	v_cmp_eq_u32_e64 s[42:43], 0, v21
	v_cmp_eq_u32_e64 s[44:45], s37, v26
	s_nop 0
	v_cndmask_b32_e64 v21, -1, 0, s[42:43]
	v_cndmask_b32_e64 v20, v236, 0, s[42:43]
	v_cndmask_b32_e64 v156, v237, 0, s[44:45]
	v_lshl_add_u64 v[20:21], v[24:25], 0, v[20:21]
	v_lshl_add_u64 v[26:27], v[24:25], 0, v[156:157]
	global_load_dwordx2 v[58:59], v[24:25], off
	global_load_dwordx2 v[60:61], v[24:25], off offset:1024
	global_load_dwordx2 v[62:63], v[24:25], off offset:2048
	global_load_dwordx2 v[48:49], v[20:21], off
	global_load_dwordx2 v[50:51], v[26:27], off
	global_load_dwordx2 v[52:53], v[20:21], off offset:1024
	global_load_dwordx2 v[40:41], v[20:21], off offset:2048
	v_lshlrev_b64 v[20:21], 10, v[22:23]
	v_lshl_add_u64 v[24:25], v[34:35], 0, v[20:21]
	v_lshl_add_u64 v[20:21], v[36:37], 0, v[20:21]
	global_load_dwordx2 v[54:55], v[26:27], off offset:1024
	global_load_dwordx2 v[46:47], v[26:27], off offset:2048
	global_load_dwordx2 v[66:67], v[24:25], off
	global_load_dwordx2 v[64:65], v[20:21], off
	v_lshlrev_b64 v[20:21], 8, v[22:23]
	v_lshl_add_u64 v[20:21], s[6:7], 0, v[20:21]
	v_lshl_add_u64 v[22:23], v[20:21], 0, s[90:91]
	global_load_dword v56, v[20:21], off
	global_load_dwordx2 v[44:45], v[22:23], off offset:4
	ds_read_b32 v21, v83 offset:49408
	v_cmp_lt_i32_e64 s[4:5], s37, v125
	s_waitcnt lgkmcnt(0)
; DI float row16_sum(float v) { v += dppf(v, 0); v += dppf(v, 1); v += dppf(v, 2); v += dppf(v, 3); return v; }
; DI void rwkv_scan(CP p, const Ptrs& w, int l, int item, float* sm) {
;     ...
;   auto lds_step = [&](const float* bf, int j) {
;     RStep q;
;     q.a4 = *(const f4v*)(bf + 0 * 1024 + j * 64 + 4 * kg);
;     q.wr4 = *(const f4v*)(bf + 1 * 1024 + j * 64 + 4 * kg);
;     q.w4 = *(const f4v*)(bf + 2 * 1024 + j * 64 + 4 * kg);
;     q.b4 = *(const f4v*)(bf + 3 * 1024 + j * 64 + 4 * kg);
;     q.k4 = *(const f4v*)(bf + 4 * 1024 + j * 64 + 4 * kg);
;     q.vv = bf[5 * 1024 + j * 64 + row];
;     q.sc = *(const float2*)(bf + 6 * 1024 + j * 2);
;     return q;
;   };
;   auto flush = [&](int c) {
;     {
;       int j = tid >> 4, rr = tid & 15;
;       int ii = pos2i(c * 16 + j, dir);
;       yout[((size_t)b * TPB + ii) * 512 + hd * 64 + rq * 16 + rr] = f2bf(sY[(c & 1) * 256 + j * 16 + rr]);
;     }
;   };
;   __syncthreads();
;   load(0, PA);
;   stage(PA, sm);
;   load(1, PB);
;   __syncthreads();
;   const int NCH = TPB / 16;
;   auto run_chunk = [&](int c, const float* bf, float* sy) {
;     flush(max(c - 1, 0));
;     RStep cur = lds_step(bf, 0);
; #pragma unroll
;     for (int j = 0; j < 16; ++j) {
;       RStep nxt = cur;
;       if (j + 1 < 16) nxt = lds_step(bf, j + 1);
;       f2v sa2 = SA * cur.a4.xy + SB * cur.a4.zw;
;       f2v yp2 = SA * cur.wr4.xy + SB * cur.wr4.zw;
;       float sa = sa2.x + sa2.y, yp = yp2.x + yp2.y;
;       sa = row16_sum(sa); yp = row16_sum(yp);
;       float y = yp + sa * cur.sc.x + cur.vv * cur.sc.y;
;       SA = SA * cur.w4.xy + (sa * cur.b4.xy + cur.vv * cur.k4.xy);
;       SB = SB * cur.w4.zw + (sa * cur.b4.zw + cur.vv * cur.k4.zw);
;       sy[(kg == 0 ? j * 16 : 0) + ysel - (c & 1) * 0] = y;
;       cur = nxt;
;     }
	v_cvt_pk_bf16_f32 v22, v21, s0
	v_cndmask_b32_e64 v20, v231, v232, s[4:5]
	v_add_u32_e32 v20, v20, v124
	v_cndmask_b32_e32 v20, v20, v125, vcc
	v_ashrrev_i32_e32 v21, 31, v20
	v_lshl_add_u64 v[20:21], s[12:13], 0, v[20:21]
	v_lshlrev_b64 v[20:21], 10, v[20:21]
	v_lshl_add_u64 v[20:21], v[38:39], 0, v[20:21]
	global_store_short v[20:21], v22, off
	s_waitcnt lgkmcnt(0)
	v_add_u32_e32 v20, 0x80, v106
	ds_read2st64_b32 v[170:171], v20 offset0:176 offset1:177
	v_add_u32_e64 v20, s22, 0
	ds_read2_b64 v[20:23], v20 offset0:16 offset1:17
	ds_read_b128 v[24:27], v105 offset:24704
	ds_read_b128 v[28:31], v105 offset:24960
	ds_read_b128 v[98:101], v105 offset:28800
	ds_read_b128 v[126:129], v105 offset:29056
	ds_read_b128 v[130:133], v105 offset:32896
	ds_read_b128 v[134:137], v105 offset:33152
	ds_read_b128 v[138:141], v105 offset:36992
	ds_read_b128 v[142:145], v105 offset:37248
	ds_read_b128 v[146:149], v105 offset:41088
	ds_read_b128 v[150:153], v105 offset:41344
	s_waitcnt lgkmcnt(9)
	v_pk_mul_f32 v[26:27], v[168:169], v[26:27]
	v_pk_fma_f32 v[24:25], v[154:155], v[24:25], v[26:27]
	s_waitcnt lgkmcnt(7)
	v_pk_mul_f32 v[26:27], v[168:169], v[100:101]
	v_add_f32_e32 v24, v24, v25
	v_pk_fma_f32 v[26:27], v[154:155], v[98:99], v[26:27]
	v_add_f32_e32 v25, v26, v27
	v_add_f32_dpp v24, v24, v24 quad_perm:[1,0,3,2] row_mask:0xf bank_mask:0xf bound_ctrl:1
	s_nop 0
	v_add_f32_dpp v25, v25, v25 quad_perm:[1,0,3,2] row_mask:0xf bank_mask:0xf bound_ctrl:1
	v_add_f32_dpp v24, v24, v24 quad_perm:[2,3,0,1] row_mask:0xf bank_mask:0xf bound_ctrl:1
	s_nop 0
	v_add_f32_dpp v25, v25, v25 quad_perm:[2,3,0,1] row_mask:0xf bank_mask:0xf bound_ctrl:1
	v_add_f32_dpp v24, v24, v24 row_half_mirror row_mask:0xf bank_mask:0xf bound_ctrl:1
	s_nop 0
	v_add_f32_dpp v25, v25, v25 row_half_mirror row_mask:0xf bank_mask:0xf bound_ctrl:1
	v_add_f32_dpp v24, v24, v24 row_mirror row_mask:0xf bank_mask:0xf bound_ctrl:1
	s_nop 0
	v_add_f32_dpp v26, v25, v25 row_mirror row_mask:0xf bank_mask:0xf bound_ctrl:1
	v_fmac_f32_e32 v26, v20, v24
	v_fmac_f32_e32 v26, v170, v21
	s_waitcnt lgkmcnt(3)
	v_pk_mul_f32 v[20:21], v[138:139], v[24:25] op_sel_hi:[1,0]
	v_pk_mul_f32 v[24:25], v[140:141], v[24:25] op_sel_hi:[1,0]
	ds_write_b32 v107, v26 offset:50432
	s_waitcnt lgkmcnt(2)
	v_pk_fma_f32 v[20:21], v[146:147], v[170:171], v[20:21] op_sel_hi:[1,0,1]
	v_pk_fma_f32 v[24:25], v[148:149], v[170:171], v[24:25] op_sel_hi:[1,0,1]
	v_pk_fma_f32 v[20:21], v[154:155], v[130:131], v[20:21]
	v_pk_fma_f32 v[154:155], v[168:169], v[132:133], v[24:25]
	ds_read_b128 v[24:27], v105 offset:33408
	ds_read_b128 v[98:101], v105 offset:37504
	ds_read_b128 v[130:133], v105 offset:25216
	ds_read_b128 v[138:141], v105 offset:41600
	ds_read_b128 v[146:149], v105 offset:29312
	v_pk_mul_f32 v[30:31], v[30:31], v[154:155]
	ds_read_b32 v96, v106 offset:45696
	v_pk_fma_f32 v[28:29], v[28:29], v[20:21], v[30:31]
	v_pk_mul_f32 v[30:31], v[128:129], v[154:155]
	ds_read_b64 v[168:169], v157 offset:49296
	v_pk_fma_f32 v[30:31], v[126:127], v[20:21], v[30:31]
	v_add_f32_e32 v28, v28, v29
	v_add_f32_e32 v29, v30, v31
	v_mov_b32_e32 v30, v171
	v_add_f32_dpp v28, v28, v28 quad_perm:[1,0,3,2] row_mask:0xf bank_mask:0xf bound_ctrl:1
	v_add_f32_dpp v29, v29, v29 quad_perm:[1,0,3,2] row_mask:0xf bank_mask:0xf bound_ctrl:1
	s_nop 0
	v_add_f32_dpp v28, v28, v28 quad_perm:[2,3,0,1] row_mask:0xf bank_mask:0xf bound_ctrl:1
	v_add_f32_dpp v29, v29, v29 quad_perm:[2,3,0,1] row_mask:0xf bank_mask:0xf bound_ctrl:1
	s_nop 0
	v_add_f32_dpp v28, v28, v28 row_half_mirror row_mask:0xf bank_mask:0xf bound_ctrl:1
	v_add_f32_dpp v29, v29, v29 row_half_mirror row_mask:0xf bank_mask:0xf bound_ctrl:1
	s_nop 0
	v_add_f32_dpp v28, v28, v28 row_mirror row_mask:0xf bank_mask:0xf bound_ctrl:1
	v_add_f32_dpp v29, v29, v29 row_mirror row_mask:0xf bank_mask:0xf bound_ctrl:1
	v_fmac_f32_e32 v29, v28, v22
	v_fmac_f32_e32 v29, v171, v23
	v_pk_mul_f32 v[22:23], v[142:143], v[28:29] op_sel_hi:[1,0]
	ds_write_b32 v108, v29 offset:50432
	s_waitcnt lgkmcnt(8)
	v_pk_fma_f32 v[22:23], v[150:151], v[30:31], v[22:23] op_sel_hi:[1,0,1]
	v_pk_fma_f32 v[150:151], v[134:135], v[20:21], v[22:23]
	v_pk_mul_f32 v[20:21], v[144:145], v[28:29] op_sel_hi:[1,0]
	v_pk_fma_f32 v[20:21], v[152:153], v[30:31], v[20:21] op_sel_hi:[1,0,1]
	v_pk_fma_f32 v[152:153], v[136:137], v[154:155], v[20:21]
	ds_read_b128 v[20:23], v105 offset:33664
	ds_read_b128 v[28:31], v105 offset:37760
	ds_read_b128 v[126:129], v105 offset:25472
	ds_read_b128 v[134:137], v105 offset:41856
	ds_read_b128 v[142:145], v105 offset:29568
	ds_read_b32 v102, v106 offset:45952
	ds_read_b64 v[154:155], v157 offset:49304
	s_waitcnt lgkmcnt(8)
	v_pk_mul_f32 v[132:133], v[132:133], v[152:153]
	v_pk_fma_f32 v[130:131], v[130:131], v[150:151], v[132:133]
	v_pk_mul_f32 v[132:133], v[148:149], v[152:153]
	v_add_f32_e32 v130, v130, v131
	v_pk_fma_f32 v[132:133], v[146:147], v[150:151], v[132:133]
	v_add_f32_e32 v131, v132, v133
	v_add_f32_dpp v130, v130, v130 quad_perm:[1,0,3,2] row_mask:0xf bank_mask:0xf bound_ctrl:1
	s_nop 0
	v_add_f32_dpp v131, v131, v131 quad_perm:[1,0,3,2] row_mask:0xf bank_mask:0xf bound_ctrl:1
	v_add_f32_dpp v130, v130, v130 quad_perm:[2,3,0,1] row_mask:0xf bank_mask:0xf bound_ctrl:1
	s_nop 0
	v_add_f32_dpp v131, v131, v131 quad_perm:[2,3,0,1] row_mask:0xf bank_mask:0xf bound_ctrl:1
	v_add_f32_dpp v130, v130, v130 row_half_mirror row_mask:0xf bank_mask:0xf bound_ctrl:1
	s_nop 0
	v_add_f32_dpp v131, v131, v131 row_half_mirror row_mask:0xf bank_mask:0xf bound_ctrl:1
	v_add_f32_dpp v130, v130, v130 row_mirror row_mask:0xf bank_mask:0xf bound_ctrl:1
	s_nop 0
	v_add_f32_dpp v131, v131, v131 row_mirror row_mask:0xf bank_mask:0xf bound_ctrl:1
	v_fmac_f32_e32 v131, v130, v168
	v_fmac_f32_e32 v131, v96, v169
	v_pk_mul_f32 v[98:99], v[98:99], v[130:131] op_sel_hi:[1,0]
	ds_write_b32 v109, v131 offset:50432
	v_pk_fma_f32 v[98:99], v[138:139], v[96:97], v[98:99] op_sel_hi:[1,0,1]
	v_pk_fma_f32 v[150:151], v[24:25], v[150:151], v[98:99]
	v_pk_mul_f32 v[24:25], v[100:101], v[130:131] op_sel_hi:[1,0]
	v_pk_fma_f32 v[24:25], v[140:141], v[96:97], v[24:25] op_sel_hi:[1,0,1]
	v_pk_fma_f32 v[152:153], v[26:27], v[152:153], v[24:25]
	ds_read_b128 v[24:27], v105 offset:33920
	ds_read_b128 v[98:101], v105 offset:38016
	ds_read_b128 v[130:133], v105 offset:25728
	ds_read_b128 v[138:141], v105 offset:42112
	ds_read_b128 v[146:149], v105 offset:29824
	ds_read_b32 v96, v106 offset:46208
	s_waitcnt lgkmcnt(7)
; DI float row16_sum(float v) { v += dppf(v, 0); v += dppf(v, 1); v += dppf(v, 2); v += dppf(v, 3); return v; }
; DI void rwkv_scan(CP p, const Ptrs& w, int l, int item, float* sm) {
;     ...
;   auto lds_step = [&](const float* bf, int j) {
;     RStep q;
;     q.a4 = *(const f4v*)(bf + 0 * 1024 + j * 64 + 4 * kg);
;     q.wr4 = *(const f4v*)(bf + 1 * 1024 + j * 64 + 4 * kg);
;     q.w4 = *(const f4v*)(bf + 2 * 1024 + j * 64 + 4 * kg);
;     q.b4 = *(const f4v*)(bf + 3 * 1024 + j * 64 + 4 * kg);
;     q.k4 = *(const f4v*)(bf + 4 * 1024 + j * 64 + 4 * kg);
;     q.vv = bf[5 * 1024 + j * 64 + row];
;     q.sc = *(const float2*)(bf + 6 * 1024 + j * 2);
;     return q;
;   };
;   auto flush = [&](int c) {
;     {
;       int j = tid >> 4, rr = tid & 15;
;       int ii = pos2i(c * 16 + j, dir);
;       yout[((size_t)b * TPB + ii) * 512 + hd * 64 + rq * 16 + rr] = f2bf(sY[(c & 1) * 256 + j * 16 + rr]);
;     }
;   };
;   __syncthreads();
;   load(0, PA);
;   stage(PA, sm);
;   load(1, PB);
;   __syncthreads();
;   const int NCH = TPB / 16;
;   auto run_chunk = [&](int c, const float* bf, float* sy) {
;     flush(max(c - 1, 0));
;     RStep cur = lds_step(bf, 0);
; #pragma unroll
;     for (int j = 0; j < 16; ++j) {
;       RStep nxt = cur;
;       if (j + 1 < 16) nxt = lds_step(bf, j + 1);
;       f2v sa2 = SA * cur.a4.xy + SB * cur.a4.zw;
;       f2v yp2 = SA * cur.wr4.xy + SB * cur.wr4.zw;
;       float sa = sa2.x + sa2.y, yp = yp2.x + yp2.y;
;       sa = row16_sum(sa); yp = row16_sum(yp);
;       float y = yp + sa * cur.sc.x + cur.vv * cur.sc.y;
;       SA = SA * cur.w4.xy + (sa * cur.b4.xy + cur.vv * cur.k4.xy);
;       SB = SB * cur.w4.zw + (sa * cur.b4.zw + cur.vv * cur.k4.zw);
;       sy[(kg == 0 ? j * 16 : 0) + ysel - (c & 1) * 0] = y;
;       cur = nxt;
;     }
	v_pk_mul_f32 v[128:129], v[128:129], v[152:153]
	ds_read_b64 v[168:169], v157 offset:49312
	v_pk_fma_f32 v[126:127], v[126:127], v[150:151], v[128:129]
	v_pk_mul_f32 v[128:129], v[144:145], v[152:153]
	v_add_f32_e32 v126, v126, v127
	v_pk_fma_f32 v[128:129], v[142:143], v[150:151], v[128:129]
	v_add_f32_e32 v127, v128, v129
	v_add_f32_dpp v126, v126, v126 quad_perm:[1,0,3,2] row_mask:0xf bank_mask:0xf bound_ctrl:1
	s_nop 0
	v_add_f32_dpp v127, v127, v127 quad_perm:[1,0,3,2] row_mask:0xf bank_mask:0xf bound_ctrl:1
	v_add_f32_dpp v126, v126, v126 quad_perm:[2,3,0,1] row_mask:0xf bank_mask:0xf bound_ctrl:1
	s_nop 0
	v_add_f32_dpp v127, v127, v127 quad_perm:[2,3,0,1] row_mask:0xf bank_mask:0xf bound_ctrl:1
	v_add_f32_dpp v126, v126, v126 row_half_mirror row_mask:0xf bank_mask:0xf bound_ctrl:1
	s_nop 0
	v_add_f32_dpp v127, v127, v127 row_half_mirror row_mask:0xf bank_mask:0xf bound_ctrl:1
	v_add_f32_dpp v126, v126, v126 row_mirror row_mask:0xf bank_mask:0xf bound_ctrl:1
	s_nop 0
	v_add_f32_dpp v127, v127, v127 row_mirror row_mask:0xf bank_mask:0xf bound_ctrl:1
	v_fmac_f32_e32 v127, v126, v154
	v_fmac_f32_e32 v127, v102, v155
	v_pk_mul_f32 v[28:29], v[28:29], v[126:127] op_sel_hi:[1,0]
	ds_write_b32 v110, v127 offset:50432
	v_pk_fma_f32 v[28:29], v[134:135], v[102:103], v[28:29] op_sel_hi:[1,0,1]
	v_pk_fma_f32 v[150:151], v[20:21], v[150:151], v[28:29]
	v_pk_mul_f32 v[20:21], v[30:31], v[126:127] op_sel_hi:[1,0]
	v_pk_fma_f32 v[20:21], v[136:137], v[102:103], v[20:21] op_sel_hi:[1,0,1]
	v_pk_fma_f32 v[152:153], v[22:23], v[152:153], v[20:21]
	ds_read_b128 v[20:23], v105 offset:34176
	ds_read_b128 v[28:31], v105 offset:38272
	ds_read_b128 v[126:129], v105 offset:25984
	ds_read_b128 v[134:137], v105 offset:42368
	ds_read_b128 v[142:145], v105 offset:30080
	ds_read_b32 v102, v106 offset:46464
	s_waitcnt lgkmcnt(14)
	ds_read_b64 v[154:155], v157 offset:49320
	s_waitcnt lgkmcnt(8)
	v_pk_mul_f32 v[132:133], v[132:133], v[152:153]
	v_pk_fma_f32 v[130:131], v[130:131], v[150:151], v[132:133]
	v_pk_mul_f32 v[132:133], v[148:149], v[152:153]
	v_add_f32_e32 v130, v130, v131
	v_pk_fma_f32 v[132:133], v[146:147], v[150:151], v[132:133]
	v_add_f32_e32 v131, v132, v133
	v_add_f32_dpp v130, v130, v130 quad_perm:[1,0,3,2] row_mask:0xf bank_mask:0xf bound_ctrl:1
	s_nop 0
	v_add_f32_dpp v131, v131, v131 quad_perm:[1,0,3,2] row_mask:0xf bank_mask:0xf bound_ctrl:1
	v_add_f32_dpp v130, v130, v130 quad_perm:[2,3,0,1] row_mask:0xf bank_mask:0xf bound_ctrl:1
	s_nop 0
	v_add_f32_dpp v131, v131, v131 quad_perm:[2,3,0,1] row_mask:0xf bank_mask:0xf bound_ctrl:1
	v_add_f32_dpp v130, v130, v130 row_half_mirror row_mask:0xf bank_mask:0xf bound_ctrl:1
	s_nop 0
	v_add_f32_dpp v131, v131, v131 row_half_mirror row_mask:0xf bank_mask:0xf bound_ctrl:1
	v_add_f32_dpp v130, v130, v130 row_mirror row_mask:0xf bank_mask:0xf bound_ctrl:1
	s_nop 0
	v_add_f32_dpp v131, v131, v131 row_mirror row_mask:0xf bank_mask:0xf bound_ctrl:1
	v_fmac_f32_e32 v131, v130, v168
	v_fmac_f32_e32 v131, v96, v169
	v_pk_mul_f32 v[98:99], v[98:99], v[130:131] op_sel_hi:[1,0]
	ds_write_b32 v111, v131 offset:50432
	v_pk_fma_f32 v[98:99], v[138:139], v[96:97], v[98:99] op_sel_hi:[1,0,1]
	v_pk_fma_f32 v[150:151], v[24:25], v[150:151], v[98:99]
	v_pk_mul_f32 v[24:25], v[100:101], v[130:131] op_sel_hi:[1,0]
	v_pk_fma_f32 v[24:25], v[140:141], v[96:97], v[24:25] op_sel_hi:[1,0,1]
	v_pk_fma_f32 v[152:153], v[26:27], v[152:153], v[24:25]
	ds_read_b128 v[24:27], v105 offset:34432
	ds_read_b128 v[98:101], v105 offset:38528
	ds_read_b128 v[130:133], v105 offset:26240
	ds_read_b128 v[138:141], v105 offset:42624
	ds_read_b128 v[146:149], v105 offset:30336
	ds_read_b32 v96, v106 offset:46720
	s_waitcnt lgkmcnt(7)
	v_pk_mul_f32 v[128:129], v[128:129], v[152:153]
	ds_read_b64 v[168:169], v157 offset:49328
	v_pk_fma_f32 v[126:127], v[126:127], v[150:151], v[128:129]
	v_pk_mul_f32 v[128:129], v[144:145], v[152:153]
	v_add_f32_e32 v126, v126, v127
	v_pk_fma_f32 v[128:129], v[142:143], v[150:151], v[128:129]
	v_add_f32_e32 v127, v128, v129
	v_add_f32_dpp v126, v126, v126 quad_perm:[1,0,3,2] row_mask:0xf bank_mask:0xf bound_ctrl:1
	s_nop 0
	v_add_f32_dpp v127, v127, v127 quad_perm:[1,0,3,2] row_mask:0xf bank_mask:0xf bound_ctrl:1
	v_add_f32_dpp v126, v126, v126 quad_perm:[2,3,0,1] row_mask:0xf bank_mask:0xf bound_ctrl:1
	s_nop 0
	v_add_f32_dpp v127, v127, v127 quad_perm:[2,3,0,1] row_mask:0xf bank_mask:0xf bound_ctrl:1
	v_add_f32_dpp v126, v126, v126 row_half_mirror row_mask:0xf bank_mask:0xf bound_ctrl:1
	s_nop 0
	v_add_f32_dpp v127, v127, v127 row_half_mirror row_mask:0xf bank_mask:0xf bound_ctrl:1
	v_add_f32_dpp v126, v126, v126 row_mirror row_mask:0xf bank_mask:0xf bound_ctrl:1
	s_nop 0
	v_add_f32_dpp v127, v127, v127 row_mirror row_mask:0xf bank_mask:0xf bound_ctrl:1
	v_fmac_f32_e32 v127, v126, v154
	v_fmac_f32_e32 v127, v102, v155
	v_pk_mul_f32 v[28:29], v[28:29], v[126:127] op_sel_hi:[1,0]
	ds_write_b32 v112, v127 offset:50432
	v_pk_fma_f32 v[28:29], v[134:135], v[102:103], v[28:29] op_sel_hi:[1,0,1]
	v_pk_fma_f32 v[150:151], v[20:21], v[150:151], v[28:29]
	v_pk_mul_f32 v[20:21], v[30:31], v[126:127] op_sel_hi:[1,0]
	v_pk_fma_f32 v[20:21], v[136:137], v[102:103], v[20:21] op_sel_hi:[1,0,1]
	v_pk_fma_f32 v[152:153], v[22:23], v[152:153], v[20:21]
	ds_read_b128 v[20:23], v105 offset:34688
	ds_read_b128 v[28:31], v105 offset:38784
	ds_read_b128 v[126:129], v105 offset:26496
	ds_read_b128 v[134:137], v105 offset:42880
	ds_read_b128 v[142:145], v105 offset:30592
	ds_read_b32 v102, v106 offset:46976
	s_waitcnt lgkmcnt(14)
	ds_read_b64 v[154:155], v157 offset:49336
	s_waitcnt lgkmcnt(8)
; DI float row16_sum(float v) { v += dppf(v, 0); v += dppf(v, 1); v += dppf(v, 2); v += dppf(v, 3); return v; }
; DI void rwkv_scan(CP p, const Ptrs& w, int l, int item, float* sm) {
;     ...
;   auto lds_step = [&](const float* bf, int j) {
;     RStep q;
;     q.a4 = *(const f4v*)(bf + 0 * 1024 + j * 64 + 4 * kg);
;     q.wr4 = *(const f4v*)(bf + 1 * 1024 + j * 64 + 4 * kg);
;     q.w4 = *(const f4v*)(bf + 2 * 1024 + j * 64 + 4 * kg);
;     q.b4 = *(const f4v*)(bf + 3 * 1024 + j * 64 + 4 * kg);
;     q.k4 = *(const f4v*)(bf + 4 * 1024 + j * 64 + 4 * kg);
;     q.vv = bf[5 * 1024 + j * 64 + row];
;     q.sc = *(const float2*)(bf + 6 * 1024 + j * 2);
;     return q;
;   };
;   auto flush = [&](int c) {
;     {
;       int j = tid >> 4, rr = tid & 15;
;       int ii = pos2i(c * 16 + j, dir);
;       yout[((size_t)b * TPB + ii) * 512 + hd * 64 + rq * 16 + rr] = f2bf(sY[(c & 1) * 256 + j * 16 + rr]);
;     }
;   };
;   __syncthreads();
;   load(0, PA);
;   stage(PA, sm);
;   load(1, PB);
;   __syncthreads();
;   const int NCH = TPB / 16;
;   auto run_chunk = [&](int c, const float* bf, float* sy) {
;     flush(max(c - 1, 0));
;     RStep cur = lds_step(bf, 0);
; #pragma unroll
;     for (int j = 0; j < 16; ++j) {
;       RStep nxt = cur;
;       if (j + 1 < 16) nxt = lds_step(bf, j + 1);
;       f2v sa2 = SA * cur.a4.xy + SB * cur.a4.zw;
;       f2v yp2 = SA * cur.wr4.xy + SB * cur.wr4.zw;
;       float sa = sa2.x + sa2.y, yp = yp2.x + yp2.y;
;       sa = row16_sum(sa); yp = row16_sum(yp);
;       float y = yp + sa * cur.sc.x + cur.vv * cur.sc.y;
;       SA = SA * cur.w4.xy + (sa * cur.b4.xy + cur.vv * cur.k4.xy);
;       SB = SB * cur.w4.zw + (sa * cur.b4.zw + cur.vv * cur.k4.zw);
;       sy[(kg == 0 ? j * 16 : 0) + ysel - (c & 1) * 0] = y;
;       cur = nxt;
;     }
	v_pk_mul_f32 v[132:133], v[132:133], v[152:153]
	v_pk_fma_f32 v[130:131], v[130:131], v[150:151], v[132:133]
	v_pk_mul_f32 v[132:133], v[148:149], v[152:153]
	v_add_f32_e32 v130, v130, v131
	v_pk_fma_f32 v[132:133], v[146:147], v[150:151], v[132:133]
	v_add_f32_e32 v131, v132, v133
	v_add_f32_dpp v130, v130, v130 quad_perm:[1,0,3,2] row_mask:0xf bank_mask:0xf bound_ctrl:1
	s_nop 0
	v_add_f32_dpp v131, v131, v131 quad_perm:[1,0,3,2] row_mask:0xf bank_mask:0xf bound_ctrl:1
	v_add_f32_dpp v130, v130, v130 quad_perm:[2,3,0,1] row_mask:0xf bank_mask:0xf bound_ctrl:1
	s_nop 0
	v_add_f32_dpp v131, v131, v131 quad_perm:[2,3,0,1] row_mask:0xf bank_mask:0xf bound_ctrl:1
	v_add_f32_dpp v130, v130, v130 row_half_mirror row_mask:0xf bank_mask:0xf bound_ctrl:1
	s_nop 0
	v_add_f32_dpp v131, v131, v131 row_half_mirror row_mask:0xf bank_mask:0xf bound_ctrl:1
	v_add_f32_dpp v130, v130, v130 row_mirror row_mask:0xf bank_mask:0xf bound_ctrl:1
	s_nop 0
	v_add_f32_dpp v131, v131, v131 row_mirror row_mask:0xf bank_mask:0xf bound_ctrl:1
	v_fmac_f32_e32 v131, v130, v168
	v_fmac_f32_e32 v131, v96, v169
	v_pk_mul_f32 v[98:99], v[98:99], v[130:131] op_sel_hi:[1,0]
	ds_write_b32 v113, v131 offset:50432
	v_pk_fma_f32 v[98:99], v[138:139], v[96:97], v[98:99] op_sel_hi:[1,0,1]
	v_pk_fma_f32 v[150:151], v[24:25], v[150:151], v[98:99]
	v_pk_mul_f32 v[24:25], v[100:101], v[130:131] op_sel_hi:[1,0]
	v_pk_fma_f32 v[24:25], v[140:141], v[96:97], v[24:25] op_sel_hi:[1,0,1]
	v_pk_fma_f32 v[152:153], v[26:27], v[152:153], v[24:25]
	ds_read_b128 v[24:27], v105 offset:34944
	ds_read_b128 v[98:101], v105 offset:39040
	ds_read_b128 v[130:133], v105 offset:26752
	ds_read_b128 v[138:141], v105 offset:43136
	ds_read_b128 v[146:149], v105 offset:30848
	ds_read_b32 v96, v106 offset:47232
	s_waitcnt lgkmcnt(7)
	v_pk_mul_f32 v[128:129], v[128:129], v[152:153]
	ds_read_b64 v[168:169], v157 offset:49344
	v_pk_fma_f32 v[126:127], v[126:127], v[150:151], v[128:129]
	v_pk_mul_f32 v[128:129], v[144:145], v[152:153]
	v_add_f32_e32 v126, v126, v127
	v_pk_fma_f32 v[128:129], v[142:143], v[150:151], v[128:129]
	v_add_f32_e32 v127, v128, v129
	v_add_f32_dpp v126, v126, v126 quad_perm:[1,0,3,2] row_mask:0xf bank_mask:0xf bound_ctrl:1
	s_nop 0
	v_add_f32_dpp v127, v127, v127 quad_perm:[1,0,3,2] row_mask:0xf bank_mask:0xf bound_ctrl:1
	v_add_f32_dpp v126, v126, v126 quad_perm:[2,3,0,1] row_mask:0xf bank_mask:0xf bound_ctrl:1
	s_nop 0
	v_add_f32_dpp v127, v127, v127 quad_perm:[2,3,0,1] row_mask:0xf bank_mask:0xf bound_ctrl:1
	v_add_f32_dpp v126, v126, v126 row_half_mirror row_mask:0xf bank_mask:0xf bound_ctrl:1
	s_nop 0
	v_add_f32_dpp v127, v127, v127 row_half_mirror row_mask:0xf bank_mask:0xf bound_ctrl:1
	v_add_f32_dpp v126, v126, v126 row_mirror row_mask:0xf bank_mask:0xf bound_ctrl:1
	s_nop 0
	v_add_f32_dpp v127, v127, v127 row_mirror row_mask:0xf bank_mask:0xf bound_ctrl:1
	v_fmac_f32_e32 v127, v126, v154
	v_fmac_f32_e32 v127, v102, v155
	v_pk_mul_f32 v[28:29], v[28:29], v[126:127] op_sel_hi:[1,0]
	ds_write_b32 v114, v127 offset:50432
	v_pk_fma_f32 v[28:29], v[134:135], v[102:103], v[28:29] op_sel_hi:[1,0,1]
	v_pk_fma_f32 v[150:151], v[20:21], v[150:151], v[28:29]
	v_pk_mul_f32 v[20:21], v[30:31], v[126:127] op_sel_hi:[1,0]
	v_pk_fma_f32 v[20:21], v[136:137], v[102:103], v[20:21] op_sel_hi:[1,0,1]
	v_pk_fma_f32 v[152:153], v[22:23], v[152:153], v[20:21]
	ds_read_b128 v[20:23], v105 offset:35200
	ds_read_b128 v[28:31], v105 offset:39296
	ds_read_b128 v[126:129], v105 offset:27008
	ds_read_b128 v[134:137], v105 offset:43392
	ds_read_b128 v[142:145], v105 offset:31104
	ds_read_b32 v102, v106 offset:47488
	s_waitcnt lgkmcnt(14)
	ds_read_b64 v[154:155], v157 offset:49352
	s_waitcnt lgkmcnt(8)
	v_pk_mul_f32 v[132:133], v[132:133], v[152:153]
	v_pk_fma_f32 v[130:131], v[130:131], v[150:151], v[132:133]
	v_pk_mul_f32 v[132:133], v[148:149], v[152:153]
	v_add_f32_e32 v130, v130, v131
	v_pk_fma_f32 v[132:133], v[146:147], v[150:151], v[132:133]
	v_add_f32_e32 v131, v132, v133
	v_add_f32_dpp v130, v130, v130 quad_perm:[1,0,3,2] row_mask:0xf bank_mask:0xf bound_ctrl:1
	s_nop 0
	v_add_f32_dpp v131, v131, v131 quad_perm:[1,0,3,2] row_mask:0xf bank_mask:0xf bound_ctrl:1
	v_add_f32_dpp v130, v130, v130 quad_perm:[2,3,0,1] row_mask:0xf bank_mask:0xf bound_ctrl:1
	s_nop 0
	v_add_f32_dpp v131, v131, v131 quad_perm:[2,3,0,1] row_mask:0xf bank_mask:0xf bound_ctrl:1
	v_add_f32_dpp v130, v130, v130 row_half_mirror row_mask:0xf bank_mask:0xf bound_ctrl:1
	s_nop 0
	v_add_f32_dpp v131, v131, v131 row_half_mirror row_mask:0xf bank_mask:0xf bound_ctrl:1
	v_add_f32_dpp v130, v130, v130 row_mirror row_mask:0xf bank_mask:0xf bound_ctrl:1
	s_nop 0
	v_add_f32_dpp v131, v131, v131 row_mirror row_mask:0xf bank_mask:0xf bound_ctrl:1
	v_fmac_f32_e32 v131, v130, v168
	v_fmac_f32_e32 v131, v96, v169
	v_pk_mul_f32 v[98:99], v[98:99], v[130:131] op_sel_hi:[1,0]
	ds_write_b32 v115, v131 offset:50432
	v_pk_fma_f32 v[98:99], v[138:139], v[96:97], v[98:99] op_sel_hi:[1,0,1]
	v_pk_fma_f32 v[150:151], v[24:25], v[150:151], v[98:99]
	v_pk_mul_f32 v[24:25], v[100:101], v[130:131] op_sel_hi:[1,0]
	v_pk_fma_f32 v[24:25], v[140:141], v[96:97], v[24:25] op_sel_hi:[1,0,1]
	v_pk_fma_f32 v[152:153], v[26:27], v[152:153], v[24:25]
	ds_read_b128 v[24:27], v105 offset:35456
	ds_read_b128 v[98:101], v105 offset:39552
	ds_read_b128 v[130:133], v105 offset:27264
	ds_read_b128 v[138:141], v105 offset:43648
	ds_read_b128 v[146:149], v105 offset:31360
	ds_read_b32 v96, v106 offset:47744
	s_waitcnt lgkmcnt(7)
; DI float row16_sum(float v) { v += dppf(v, 0); v += dppf(v, 1); v += dppf(v, 2); v += dppf(v, 3); return v; }
; DI void rwkv_scan(CP p, const Ptrs& w, int l, int item, float* sm) {
;     ...
;   auto lds_step = [&](const float* bf, int j) {
;     RStep q;
;     q.a4 = *(const f4v*)(bf + 0 * 1024 + j * 64 + 4 * kg);
;     q.wr4 = *(const f4v*)(bf + 1 * 1024 + j * 64 + 4 * kg);
;     q.w4 = *(const f4v*)(bf + 2 * 1024 + j * 64 + 4 * kg);
;     q.b4 = *(const f4v*)(bf + 3 * 1024 + j * 64 + 4 * kg);
;     q.k4 = *(const f4v*)(bf + 4 * 1024 + j * 64 + 4 * kg);
;     q.vv = bf[5 * 1024 + j * 64 + row];
;     q.sc = *(const float2*)(bf + 6 * 1024 + j * 2);
;     return q;
;   };
;   auto flush = [&](int c) {
;     {
;       int j = tid >> 4, rr = tid & 15;
;       int ii = pos2i(c * 16 + j, dir);
;       yout[((size_t)b * TPB + ii) * 512 + hd * 64 + rq * 16 + rr] = f2bf(sY[(c & 1) * 256 + j * 16 + rr]);
;     }
;   };
;   __syncthreads();
;   load(0, PA);
;   stage(PA, sm);
;   load(1, PB);
;   __syncthreads();
;   const int NCH = TPB / 16;
;   auto run_chunk = [&](int c, const float* bf, float* sy) {
;     flush(max(c - 1, 0));
;     RStep cur = lds_step(bf, 0);
; #pragma unroll
;     for (int j = 0; j < 16; ++j) {
;       RStep nxt = cur;
;       if (j + 1 < 16) nxt = lds_step(bf, j + 1);
;       f2v sa2 = SA * cur.a4.xy + SB * cur.a4.zw;
;       f2v yp2 = SA * cur.wr4.xy + SB * cur.wr4.zw;
;       float sa = sa2.x + sa2.y, yp = yp2.x + yp2.y;
;       sa = row16_sum(sa); yp = row16_sum(yp);
;       float y = yp + sa * cur.sc.x + cur.vv * cur.sc.y;
;       SA = SA * cur.w4.xy + (sa * cur.b4.xy + cur.vv * cur.k4.xy);
;       SB = SB * cur.w4.zw + (sa * cur.b4.zw + cur.vv * cur.k4.zw);
;       sy[(kg == 0 ? j * 16 : 0) + ysel - (c & 1) * 0] = y;
;       cur = nxt;
;     }
	v_pk_mul_f32 v[128:129], v[128:129], v[152:153]
	ds_read_b64 v[168:169], v157 offset:49360
	v_pk_fma_f32 v[126:127], v[126:127], v[150:151], v[128:129]
	v_pk_mul_f32 v[128:129], v[144:145], v[152:153]
	v_add_f32_e32 v126, v126, v127
	v_pk_fma_f32 v[128:129], v[142:143], v[150:151], v[128:129]
	v_add_f32_e32 v127, v128, v129
	v_add_f32_dpp v126, v126, v126 quad_perm:[1,0,3,2] row_mask:0xf bank_mask:0xf bound_ctrl:1
	s_nop 0
	v_add_f32_dpp v127, v127, v127 quad_perm:[1,0,3,2] row_mask:0xf bank_mask:0xf bound_ctrl:1
	v_add_f32_dpp v126, v126, v126 quad_perm:[2,3,0,1] row_mask:0xf bank_mask:0xf bound_ctrl:1
	s_nop 0
	v_add_f32_dpp v127, v127, v127 quad_perm:[2,3,0,1] row_mask:0xf bank_mask:0xf bound_ctrl:1
	v_add_f32_dpp v126, v126, v126 row_half_mirror row_mask:0xf bank_mask:0xf bound_ctrl:1
	s_nop 0
	v_add_f32_dpp v127, v127, v127 row_half_mirror row_mask:0xf bank_mask:0xf bound_ctrl:1
	v_add_f32_dpp v126, v126, v126 row_mirror row_mask:0xf bank_mask:0xf bound_ctrl:1
	s_nop 0
	v_add_f32_dpp v127, v127, v127 row_mirror row_mask:0xf bank_mask:0xf bound_ctrl:1
	v_fmac_f32_e32 v127, v126, v154
	v_fmac_f32_e32 v127, v102, v155
	v_pk_mul_f32 v[28:29], v[28:29], v[126:127] op_sel_hi:[1,0]
	ds_write_b32 v116, v127 offset:50432
	v_pk_fma_f32 v[28:29], v[134:135], v[102:103], v[28:29] op_sel_hi:[1,0,1]
	v_pk_fma_f32 v[150:151], v[20:21], v[150:151], v[28:29]
	v_pk_mul_f32 v[20:21], v[30:31], v[126:127] op_sel_hi:[1,0]
	v_pk_fma_f32 v[20:21], v[136:137], v[102:103], v[20:21] op_sel_hi:[1,0,1]
	v_pk_fma_f32 v[152:153], v[22:23], v[152:153], v[20:21]
	ds_read_b128 v[20:23], v105 offset:35712
	ds_read_b128 v[28:31], v105 offset:39808
	ds_read_b128 v[126:129], v105 offset:27520
	ds_read_b128 v[134:137], v105 offset:43904
	ds_read_b128 v[142:145], v105 offset:31616
	ds_read_b32 v102, v106 offset:48000
	s_waitcnt lgkmcnt(14)
	ds_read_b64 v[154:155], v157 offset:49368
	s_waitcnt lgkmcnt(8)
	v_pk_mul_f32 v[132:133], v[132:133], v[152:153]
	v_pk_fma_f32 v[130:131], v[130:131], v[150:151], v[132:133]
	v_pk_mul_f32 v[132:133], v[148:149], v[152:153]
	v_add_f32_e32 v130, v130, v131
	v_pk_fma_f32 v[132:133], v[146:147], v[150:151], v[132:133]
	v_add_f32_e32 v131, v132, v133
	v_add_f32_dpp v130, v130, v130 quad_perm:[1,0,3,2] row_mask:0xf bank_mask:0xf bound_ctrl:1
	s_nop 0
	v_add_f32_dpp v131, v131, v131 quad_perm:[1,0,3,2] row_mask:0xf bank_mask:0xf bound_ctrl:1
	v_add_f32_dpp v130, v130, v130 quad_perm:[2,3,0,1] row_mask:0xf bank_mask:0xf bound_ctrl:1
	s_nop 0
	v_add_f32_dpp v131, v131, v131 quad_perm:[2,3,0,1] row_mask:0xf bank_mask:0xf bound_ctrl:1
	v_add_f32_dpp v130, v130, v130 row_half_mirror row_mask:0xf bank_mask:0xf bound_ctrl:1
	s_nop 0
	v_add_f32_dpp v131, v131, v131 row_half_mirror row_mask:0xf bank_mask:0xf bound_ctrl:1
	v_add_f32_dpp v130, v130, v130 row_mirror row_mask:0xf bank_mask:0xf bound_ctrl:1
	s_nop 0
	v_add_f32_dpp v131, v131, v131 row_mirror row_mask:0xf bank_mask:0xf bound_ctrl:1
	v_fmac_f32_e32 v131, v130, v168
	v_fmac_f32_e32 v131, v96, v169
	v_pk_mul_f32 v[98:99], v[98:99], v[130:131] op_sel_hi:[1,0]
	ds_write_b32 v117, v131 offset:50432
	v_pk_fma_f32 v[98:99], v[138:139], v[96:97], v[98:99] op_sel_hi:[1,0,1]
	v_pk_fma_f32 v[150:151], v[24:25], v[150:151], v[98:99]
	v_pk_mul_f32 v[24:25], v[100:101], v[130:131] op_sel_hi:[1,0]
	v_pk_fma_f32 v[24:25], v[140:141], v[96:97], v[24:25] op_sel_hi:[1,0,1]
	v_pk_fma_f32 v[152:153], v[26:27], v[152:153], v[24:25]
	ds_read_b128 v[24:27], v105 offset:35968
	ds_read_b128 v[98:101], v105 offset:40064
	ds_read_b128 v[130:133], v105 offset:27776
	ds_read_b128 v[138:141], v105 offset:44160
	ds_read_b128 v[146:149], v105 offset:31872
	ds_read_b32 v96, v106 offset:48256
	s_waitcnt lgkmcnt(7)
	v_pk_mul_f32 v[128:129], v[128:129], v[152:153]
	ds_read_b64 v[168:169], v157 offset:49376
	v_pk_fma_f32 v[126:127], v[126:127], v[150:151], v[128:129]
	v_pk_mul_f32 v[128:129], v[144:145], v[152:153]
	v_add_f32_e32 v126, v126, v127
	v_pk_fma_f32 v[128:129], v[142:143], v[150:151], v[128:129]
	v_add_f32_e32 v127, v128, v129
	v_add_f32_dpp v126, v126, v126 quad_perm:[1,0,3,2] row_mask:0xf bank_mask:0xf bound_ctrl:1
	s_nop 0
	v_add_f32_dpp v127, v127, v127 quad_perm:[1,0,3,2] row_mask:0xf bank_mask:0xf bound_ctrl:1
	v_add_f32_dpp v126, v126, v126 quad_perm:[2,3,0,1] row_mask:0xf bank_mask:0xf bound_ctrl:1
	s_nop 0
	v_add_f32_dpp v127, v127, v127 quad_perm:[2,3,0,1] row_mask:0xf bank_mask:0xf bound_ctrl:1
	v_add_f32_dpp v126, v126, v126 row_half_mirror row_mask:0xf bank_mask:0xf bound_ctrl:1
	s_nop 0
	v_add_f32_dpp v127, v127, v127 row_half_mirror row_mask:0xf bank_mask:0xf bound_ctrl:1
	v_add_f32_dpp v126, v126, v126 row_mirror row_mask:0xf bank_mask:0xf bound_ctrl:1
	s_nop 0
	v_add_f32_dpp v127, v127, v127 row_mirror row_mask:0xf bank_mask:0xf bound_ctrl:1
	v_fmac_f32_e32 v127, v126, v154
	v_fmac_f32_e32 v127, v102, v155
	v_pk_mul_f32 v[28:29], v[28:29], v[126:127] op_sel_hi:[1,0]
	ds_write_b32 v118, v127 offset:50432
	v_pk_fma_f32 v[28:29], v[134:135], v[102:103], v[28:29] op_sel_hi:[1,0,1]
	v_pk_fma_f32 v[150:151], v[20:21], v[150:151], v[28:29]
	v_pk_mul_f32 v[20:21], v[30:31], v[126:127] op_sel_hi:[1,0]
	v_pk_fma_f32 v[20:21], v[136:137], v[102:103], v[20:21] op_sel_hi:[1,0,1]
	v_pk_fma_f32 v[152:153], v[22:23], v[152:153], v[20:21]
	ds_read_b128 v[20:23], v105 offset:36224
	ds_read_b128 v[28:31], v105 offset:40320
	ds_read_b128 v[126:129], v105 offset:28032
	ds_read_b128 v[134:137], v105 offset:44416
	ds_read_b128 v[142:145], v105 offset:32128
	ds_read_b32 v102, v106 offset:48512
	s_waitcnt lgkmcnt(14)
	ds_read_b64 v[154:155], v157 offset:49384
	s_waitcnt lgkmcnt(8)
; DI float row16_sum(float v) { v += dppf(v, 0); v += dppf(v, 1); v += dppf(v, 2); v += dppf(v, 3); return v; }
; DI void rwkv_scan(CP p, const Ptrs& w, int l, int item, float* sm) {
;     ...
;   auto stage = [&](const RPre& P, float* bufp) {
;     float rc[4], rp[4], rn[4], kc[4], kp[4], kn[4], vc[4], vp[4], vn[4], wd4[4], ad4[4];
;     up4(P.pq[0][0], rc); up4(P.pq[0][1], rp); up4(P.pq[0][2], rn);
;     up4(P.pq[1][0], kc); up4(P.pq[1][1], kp); up4(P.pq[1][2], kn);
;     up4(P.pq[2][0], vc); up4(P.pq[2][1], vp); up4(P.pq[2][2], vn);
;     up4(P.pwd, wd4); up4(P.pad_, ad4);
;     float o0[4], o1[4], o2[4], o3[4], o4[4], o5[4];
; #pragma unroll
;     for (int j = 0; j < 4; ++j) {
;       float r_s = rc[j] + ((P.pmk[0] * rp[j] + P.pmk[1] * rn[j]) - rc[j]) * mu_r[j];
;       float k_s = kc[j] + ((P.pmk[0] * kp[j] + P.pmk[1] * kn[j]) - kc[j]) * mu_k[j];
;       float v_s = vc[j] + ((P.pmk[0] * vp[j] + P.pmk[1] * vn[j]) - vc[j]) * mu_v[j];
;       float kk = k_s * kk_c[j] * P.psc[0];
;       float a = ad4[j], wv = 1.f - wd4[j];
;       o0[j] = -kk; o1[j] = wv * r_s; o2[j] = wv; o3[j] = kk * a; o4[j] = k_s * (1.f + (a - 1.f) * ka_c[j]); o5[j] = v_s;
;     }
;     float* d = bufp + sj * 64 + skq;
;     *(float4*)(d + 0 * 1024) = make_float4(o0[0], o0[1], o0[2], o0[3]);
;     *(float4*)(d + 1 * 1024) = make_float4(o1[0], o1[1], o1[2], o1[3]);
;     *(float4*)(d + 2 * 1024) = make_float4(o2[0], o2[1], o2[2], o2[3]);
;     *(float4*)(d + 3 * 1024) = make_float4(o3[0], o3[1], o3[2], o3[3]);
;     *(float4*)(d + 4 * 1024) = make_float4(o4[0], o4[1], o4[2], o4[3]);
;     *(float4*)(d + 5 * 1024) = make_float4(o5[0], o5[1], o5[2], o5[3]);
;     ...
; #pragma unroll
;     for (int j = 0; j < 16; ++j) {
;       RStep nxt = cur;
;       if (j + 1 < 16) nxt = lds_step(bf, j + 1);
;       f2v sa2 = SA * cur.a4.xy + SB * cur.a4.zw;
;       f2v yp2 = SA * cur.wr4.xy + SB * cur.wr4.zw;
;       float sa = sa2.x + sa2.y, yp = yp2.x + yp2.y;
;       sa = row16_sum(sa); yp = row16_sum(yp);
;       float y = yp + sa * cur.sc.x + cur.vv * cur.sc.y;
;       SA = SA * cur.w4.xy + (sa * cur.b4.xy + cur.vv * cur.k4.xy);
;       SB = SB * cur.w4.zw + (sa * cur.b4.zw + cur.vv * cur.k4.zw);
;       sy[(kg == 0 ? j * 16 : 0) + ysel - (c & 1) * 0] = y;
;       cur = nxt;
;     }
	v_pk_mul_f32 v[132:133], v[132:133], v[152:153]
	v_pk_fma_f32 v[130:131], v[130:131], v[150:151], v[132:133]
	v_pk_mul_f32 v[132:133], v[148:149], v[152:153]
	v_add_f32_e32 v130, v130, v131
	v_pk_fma_f32 v[132:133], v[146:147], v[150:151], v[132:133]
	v_add_f32_e32 v131, v132, v133
	v_add_f32_dpp v130, v130, v130 quad_perm:[1,0,3,2] row_mask:0xf bank_mask:0xf bound_ctrl:1
	s_nop 0
	v_add_f32_dpp v131, v131, v131 quad_perm:[1,0,3,2] row_mask:0xf bank_mask:0xf bound_ctrl:1
	v_add_f32_dpp v130, v130, v130 quad_perm:[2,3,0,1] row_mask:0xf bank_mask:0xf bound_ctrl:1
	s_nop 0
	v_add_f32_dpp v131, v131, v131 quad_perm:[2,3,0,1] row_mask:0xf bank_mask:0xf bound_ctrl:1
	v_add_f32_dpp v130, v130, v130 row_half_mirror row_mask:0xf bank_mask:0xf bound_ctrl:1
	s_nop 0
	v_add_f32_dpp v131, v131, v131 row_half_mirror row_mask:0xf bank_mask:0xf bound_ctrl:1
	v_add_f32_dpp v130, v130, v130 row_mirror row_mask:0xf bank_mask:0xf bound_ctrl:1
	s_nop 0
	v_add_f32_dpp v131, v131, v131 row_mirror row_mask:0xf bank_mask:0xf bound_ctrl:1
	v_fmac_f32_e32 v131, v130, v168
	v_fmac_f32_e32 v131, v96, v169
	v_pk_mul_f32 v[98:99], v[98:99], v[130:131] op_sel_hi:[1,0]
	ds_write_b32 v119, v131 offset:50432
	v_pk_fma_f32 v[98:99], v[138:139], v[96:97], v[98:99] op_sel_hi:[1,0,1]
	v_pk_fma_f32 v[24:25], v[24:25], v[150:151], v[98:99]
	v_pk_mul_f32 v[98:99], v[100:101], v[130:131] op_sel_hi:[1,0]
	v_pk_fma_f32 v[98:99], v[140:141], v[96:97], v[98:99] op_sel_hi:[1,0,1]
	v_pk_fma_f32 v[26:27], v[26:27], v[152:153], v[98:99]
	ds_read_b128 v[98:101], v105 offset:36480
	ds_read_b128 v[130:133], v105 offset:40576
	ds_read_b128 v[138:141], v105 offset:28288
	ds_read_b128 v[146:149], v105 offset:44672
	ds_read_b128 v[150:153], v105 offset:32384
	ds_read_b32 v156, v106 offset:48768
	s_waitcnt lgkmcnt(7)
	v_pk_mul_f32 v[128:129], v[128:129], v[26:27]
	ds_read_b64 v[168:169], v157 offset:49392
	v_pk_fma_f32 v[126:127], v[126:127], v[24:25], v[128:129]
	v_pk_mul_f32 v[128:129], v[144:145], v[26:27]
	v_add_f32_e32 v96, v126, v127
	v_pk_fma_f32 v[128:129], v[142:143], v[24:25], v[128:129]
	v_add_f32_e32 v126, v128, v129
	v_add_f32_dpp v96, v96, v96 quad_perm:[1,0,3,2] row_mask:0xf bank_mask:0xf bound_ctrl:1
	s_nop 0
	v_add_f32_dpp v126, v126, v126 quad_perm:[1,0,3,2] row_mask:0xf bank_mask:0xf bound_ctrl:1
	v_add_f32_dpp v96, v96, v96 quad_perm:[2,3,0,1] row_mask:0xf bank_mask:0xf bound_ctrl:1
	s_nop 0
	v_add_f32_dpp v126, v126, v126 quad_perm:[2,3,0,1] row_mask:0xf bank_mask:0xf bound_ctrl:1
	v_add_f32_dpp v96, v96, v96 row_half_mirror row_mask:0xf bank_mask:0xf bound_ctrl:1
	s_nop 0
	v_add_f32_dpp v126, v126, v126 row_half_mirror row_mask:0xf bank_mask:0xf bound_ctrl:1
	v_add_f32_dpp v96, v96, v96 row_mirror row_mask:0xf bank_mask:0xf bound_ctrl:1
	v_pk_mul_f32 v[28:29], v[28:29], v[96:97] op_sel_hi:[1,0]
	v_add_f32_dpp v126, v126, v126 row_mirror row_mask:0xf bank_mask:0xf bound_ctrl:1
	v_pk_fma_f32 v[28:29], v[134:135], v[102:103], v[28:29] op_sel_hi:[1,0,1]
	v_fmac_f32_e32 v126, v96, v154
	v_pk_fma_f32 v[142:143], v[20:21], v[24:25], v[28:29]
	v_pk_mul_f32 v[20:21], v[30:31], v[96:97] op_sel_hi:[1,0]
	v_fmac_f32_e32 v126, v102, v155
	v_pk_fma_f32 v[20:21], v[136:137], v[102:103], v[20:21] op_sel_hi:[1,0,1]
	ds_write_b32 v120, v126 offset:50432
	v_pk_fma_f32 v[144:145], v[22:23], v[26:27], v[20:21]
	ds_read_b128 v[20:23], v105 offset:36736
	ds_read_b128 v[28:31], v105 offset:40832
	ds_read_b128 v[126:129], v105 offset:28544
	ds_read_b128 v[24:27], v105 offset:44928
	ds_read_b128 v[134:137], v105 offset:32640
	ds_read_b32 v96, v106 offset:49024
	s_waitcnt lgkmcnt(14)
	ds_read_b64 v[154:155], v157 offset:49400
	s_waitcnt lgkmcnt(8)
	v_pk_mul_f32 v[140:141], v[140:141], v[144:145]
	v_pk_fma_f32 v[138:139], v[138:139], v[142:143], v[140:141]
	v_pk_mul_f32 v[140:141], v[152:153], v[144:145]
	v_add_f32_e32 v102, v138, v139
	v_pk_fma_f32 v[140:141], v[150:151], v[142:143], v[140:141]
	v_add_f32_e32 v138, v140, v141
	v_add_f32_dpp v102, v102, v102 quad_perm:[1,0,3,2] row_mask:0xf bank_mask:0xf bound_ctrl:1
	s_waitcnt vmcnt(20)
	v_and_b32_e32 v139, 0xffff0000, v80
	v_add_f32_dpp v102, v102, v102 quad_perm:[2,3,0,1] row_mask:0xf bank_mask:0xf bound_ctrl:1
	v_add_f32_dpp v138, v138, v138 quad_perm:[1,0,3,2] row_mask:0xf bank_mask:0xf bound_ctrl:1
	v_and_b32_e32 v141, 0xffff0000, v79
	v_add_f32_dpp v102, v102, v102 row_half_mirror row_mask:0xf bank_mask:0xf bound_ctrl:1
	v_add_f32_dpp v138, v138, v138 quad_perm:[2,3,0,1] row_mask:0xf bank_mask:0xf bound_ctrl:1
	v_lshlrev_b32_e32 v140, 16, v81
	v_add_f32_dpp v102, v102, v102 row_mirror row_mask:0xf bank_mask:0xf bound_ctrl:1
	v_pk_mul_f32 v[130:131], v[130:131], v[102:103] op_sel_hi:[1,0]
	v_add_f32_dpp v138, v138, v138 row_half_mirror row_mask:0xf bank_mask:0xf bound_ctrl:1
	s_waitcnt lgkmcnt(9)
	v_pk_fma_f32 v[130:131], v[146:147], v[156:157], v[130:131] op_sel_hi:[1,0,1]
	s_nop 0
	v_pk_fma_f32 v[98:99], v[98:99], v[142:143], v[130:131]
	v_pk_mul_f32 v[130:131], v[132:133], v[102:103] op_sel_hi:[1,0]
	v_add_f32_dpp v138, v138, v138 row_mirror row_mask:0xf bank_mask:0xf bound_ctrl:1
	v_pk_fma_f32 v[130:131], v[148:149], v[156:157], v[130:131] op_sel_hi:[1,0,1]
	s_waitcnt lgkmcnt(8)
	v_fmac_f32_e32 v138, v102, v168
	v_pk_fma_f32 v[100:101], v[100:101], v[144:145], v[130:131]
	v_fmac_f32_e32 v138, v156, v169
	s_waitcnt lgkmcnt(4)
	v_pk_mul_f32 v[128:129], v[128:129], v[100:101]
	ds_write_b32 v121, v138 offset:50432
	v_pk_fma_f32 v[126:127], v[126:127], v[98:99], v[128:129]
	s_waitcnt lgkmcnt(3)
; DI void rwkv_scan(CP p, const Ptrs& w, int l, int item, float* sm) {
;     ...
;   auto stage = [&](const RPre& P, float* bufp) {
;     float rc[4], rp[4], rn[4], kc[4], kp[4], kn[4], vc[4], vp[4], vn[4], wd4[4], ad4[4];
;     up4(P.pq[0][0], rc); up4(P.pq[0][1], rp); up4(P.pq[0][2], rn);
;     up4(P.pq[1][0], kc); up4(P.pq[1][1], kp); up4(P.pq[1][2], kn);
;     up4(P.pq[2][0], vc); up4(P.pq[2][1], vp); up4(P.pq[2][2], vn);
;     up4(P.pwd, wd4); up4(P.pad_, ad4);
;     float o0[4], o1[4], o2[4], o3[4], o4[4], o5[4];
; #pragma unroll
;     for (int j = 0; j < 4; ++j) {
;       float r_s = rc[j] + ((P.pmk[0] * rp[j] + P.pmk[1] * rn[j]) - rc[j]) * mu_r[j];
;       float k_s = kc[j] + ((P.pmk[0] * kp[j] + P.pmk[1] * kn[j]) - kc[j]) * mu_k[j];
;       float v_s = vc[j] + ((P.pmk[0] * vp[j] + P.pmk[1] * vn[j]) - vc[j]) * mu_v[j];
;       float kk = k_s * kk_c[j] * P.psc[0];
;       float a = ad4[j], wv = 1.f - wd4[j];
;       o0[j] = -kk; o1[j] = wv * r_s; o2[j] = wv; o3[j] = kk * a; o4[j] = k_s * (1.f + (a - 1.f) * ka_c[j]); o5[j] = v_s;
;     }
;     float* d = bufp + sj * 64 + skq;
;     *(float4*)(d + 0 * 1024) = make_float4(o0[0], o0[1], o0[2], o0[3]);
;     *(float4*)(d + 1 * 1024) = make_float4(o1[0], o1[1], o1[2], o1[3]);
;     *(float4*)(d + 2 * 1024) = make_float4(o2[0], o2[1], o2[2], o2[3]);
;     *(float4*)(d + 3 * 1024) = make_float4(o3[0], o3[1], o3[2], o3[3]);
;     *(float4*)(d + 4 * 1024) = make_float4(o4[0], o4[1], o4[2], o4[3]);
;     *(float4*)(d + 5 * 1024) = make_float4(o5[0], o5[1], o5[2], o5[3]);
;     if (skq == 0) *(float2*)(bufp + 6 * 1024 + sj * 2) = make_float2(P.psc[1], P.psc[2]);
;   };
;     ...
;     stage(PA, sm);
;     __syncthreads();
;   }
	v_pk_mul_f32 v[128:129], v[136:137], v[100:101]
	v_lshlrev_b32_e32 v132, 16, v85
	v_pk_fma_f32 v[128:129], v[134:135], v[98:99], v[128:129]
	v_and_b32_e32 v133, 0xffff0000, v85
	v_and_b32_e32 v85, 0xffff0000, v78
	v_lshlrev_b32_e32 v138, 16, v78
	v_lshlrev_b32_e32 v78, 16, v79
	v_and_b32_e32 v79, 0xffff0000, v81
	v_add_f32_e32 v102, v126, v127
	v_add_f32_e32 v126, v128, v129
	v_lshlrev_b32_e32 v130, 16, v84
	v_and_b32_e32 v131, 0xffff0000, v84
	v_lshlrev_b32_e32 v84, 16, v80
	v_pk_mul_f32 v[138:139], v[94:95], v[138:139] op_sel:[1,0] op_sel_hi:[0,1]
	v_pk_mul_f32 v[78:79], v[94:95], v[78:79] op_sel:[1,0] op_sel_hi:[0,1]
	v_add_f32_dpp v102, v102, v102 quad_perm:[1,0,3,2] row_mask:0xf bank_mask:0xf bound_ctrl:1
	v_add_f32_dpp v126, v126, v126 quad_perm:[1,0,3,2] row_mask:0xf bank_mask:0xf bound_ctrl:1
	v_lshlrev_b32_e32 v128, 16, v86
	v_and_b32_e32 v129, 0xffff0000, v86
	v_lshlrev_b32_e32 v86, 16, v87
	v_and_b32_e32 v87, 0xffff0000, v87
	v_pk_fma_f32 v[84:85], v[94:95], v[84:85], v[138:139]
	v_pk_fma_f32 v[78:79], v[94:95], v[140:141], v[78:79]
	v_add_f32_dpp v102, v102, v102 quad_perm:[2,3,0,1] row_mask:0xf bank_mask:0xf bound_ctrl:1
	v_add_f32_dpp v126, v126, v126 quad_perm:[2,3,0,1] row_mask:0xf bank_mask:0xf bound_ctrl:1
	v_pk_add_f32 v[84:85], v[84:85], v[128:129] neg_lo:[0,1] neg_hi:[0,1]
	v_pk_add_f32 v[78:79], v[78:79], v[86:87] neg_lo:[0,1] neg_hi:[0,1]
	v_add_f32_dpp v102, v102, v102 row_half_mirror row_mask:0xf bank_mask:0xf bound_ctrl:1
	v_add_f32_dpp v126, v126, v126 row_half_mirror row_mask:0xf bank_mask:0xf bound_ctrl:1
	v_pk_fma_f32 v[128:129], v[8:9], v[84:85], v[128:129]
	v_pk_fma_f32 v[140:141], v[10:11], v[78:79], v[86:87]
	v_add_f32_dpp v102, v102, v102 row_mirror row_mask:0xf bank_mask:0xf bound_ctrl:1
	v_add_f32_dpp v126, v126, v126 row_mirror row_mask:0xf bank_mask:0xf bound_ctrl:1
	v_pk_mul_f32 v[84:85], v[12:13], v[128:129]
	v_pk_mul_f32 v[78:79], v[14:15], v[140:141]
	s_waitcnt lgkmcnt(1)
	v_fmac_f32_e32 v126, v102, v154
	s_waitcnt vmcnt(16)
	v_pk_mul_f32 v[138:139], v[82:83], v[84:85] op_sel_hi:[0,1]
	v_pk_mul_f32 v[142:143], v[82:83], v[78:79] op_sel_hi:[0,1]
	v_fmac_f32_e32 v126, v96, v155
	v_xor_b32_e32 v85, 0x80000000, v139
	v_xor_b32_e32 v84, 0x80000000, v138
	v_xor_b32_e32 v87, 0x80000000, v143
	v_xor_b32_e32 v86, 0x80000000, v142
	ds_write_b32 v122, v126 offset:50432
	ds_write_b128 v103, v[84:87]
	v_lshlrev_b32_e32 v84, 16, v74
	v_and_b32_e32 v85, 0xffff0000, v76
	v_lshlrev_b32_e32 v80, 16, v76
	v_and_b32_e32 v81, 0xffff0000, v74
	v_pk_mul_f32 v[84:85], v[94:95], v[84:85] op_sel:[1,0] op_sel_hi:[0,1]
	v_lshlrev_b32_e32 v126, 16, v88
	v_and_b32_e32 v127, 0xffff0000, v88
	v_pk_fma_f32 v[80:81], v[94:95], v[80:81], v[84:85]
	v_lshlrev_b32_e32 v134, 16, v92
	v_and_b32_e32 v135, 0xffff0000, v92
	v_pk_add_f32 v[80:81], v[80:81], v[126:127] neg_lo:[0,1] neg_hi:[0,1]
	v_lshlrev_b32_e32 v92, 16, v93
	v_and_b32_e32 v93, 0xffff0000, v93
	v_pk_add_f32 v[78:79], v[134:135], 1.0 op_sel_hi:[1,0] neg_lo:[1,0] neg_hi:[1,0]
	v_pk_fma_f32 v[80:81], v[0:1], v[80:81], v[126:127]
	v_and_b32_e32 v87, 0xffff0000, v75
	v_pk_mul_f32 v[84:85], v[80:81], v[78:79]
	v_pk_add_f32 v[80:81], v[92:93], 1.0 op_sel_hi:[1,0] neg_lo:[1,0] neg_hi:[1,0]
	v_lshlrev_b32_e32 v93, 16, v75
	v_and_b32_e32 v75, s0, v75
	v_and_b32_e32 v74, 0xffff0000, v77
	v_pk_mov_b32 v[74:75], v[92:93], v[74:75] op_sel:[1,0]
	v_lshlrev_b32_e32 v86, 16, v77
	v_pk_mul_f32 v[74:75], v[94:95], v[74:75] op_sel:[1,0] op_sel_hi:[0,1]
	v_lshlrev_b32_e32 v88, 16, v89
	v_and_b32_e32 v89, 0xffff0000, v89
	v_pk_fma_f32 v[74:75], v[94:95], v[86:87], v[74:75]
	v_lshlrev_b32_e32 v136, 16, v90
	v_pk_add_f32 v[74:75], v[74:75], v[88:89] neg_lo:[0,1] neg_hi:[0,1]
	v_and_b32_e32 v137, 0xffff0000, v90
	v_lshlrev_b32_e32 v90, 16, v91
	v_and_b32_e32 v91, 0xffff0000, v91
	v_pk_fma_f32 v[74:75], v[2:3], v[74:75], v[88:89]
	v_pk_mul_f32 v[76:77], v[142:143], v[90:91]
	v_pk_mul_f32 v[86:87], v[74:75], v[80:81]
	v_pk_mul_f32 v[74:75], v[138:139], v[136:137]
	ds_write_b128 v103, v[84:87] offset:4096
	ds_write_b128 v103, v[78:81] offset:8192
	ds_write_b128 v103, v[74:77] offset:12288
	v_pk_add_f32 v[74:75], v[136:137], -1.0 op_sel_hi:[1,0]
	v_pk_add_f32 v[76:77], v[90:91], -1.0 op_sel_hi:[1,0]
	v_pk_fma_f32 v[74:75], v[16:17], v[74:75], 1.0 op_sel_hi:[1,1,0]
	v_pk_fma_f32 v[76:77], v[18:19], v[76:77], 1.0 op_sel_hi:[1,1,0]
	v_pk_mul_f32 v[74:75], v[128:129], v[74:75]
	v_pk_mul_f32 v[76:77], v[140:141], v[76:77]
	ds_write_b128 v103, v[74:77] offset:16384
	v_lshlrev_b32_e32 v76, 16, v70
	v_and_b32_e32 v77, 0xffff0000, v72
	v_lshlrev_b32_e32 v74, 16, v72
	v_and_b32_e32 v75, 0xffff0000, v70
	v_pk_mul_f32 v[76:77], v[94:95], v[76:77] op_sel:[1,0] op_sel_hi:[0,1]
	v_pk_fma_f32 v[74:75], v[94:95], v[74:75], v[76:77]
	v_and_b32_e32 v77, 0xffff0000, v71
	v_lshlrev_b32_e32 v79, 16, v71
	v_and_b32_e32 v71, s0, v71
	v_and_b32_e32 v70, 0xffff0000, v73
	v_pk_mov_b32 v[70:71], v[78:79], v[70:71] op_sel:[1,0]
	v_lshlrev_b32_e32 v76, 16, v73
	v_pk_mul_f32 v[70:71], v[94:95], v[70:71] op_sel:[1,0] op_sel_hi:[0,1]
	v_pk_fma_f32 v[70:71], v[94:95], v[76:77], v[70:71]
	v_pk_add_f32 v[74:75], v[74:75], v[130:131] neg_lo:[0,1] neg_hi:[0,1]
	v_pk_add_f32 v[70:71], v[70:71], v[132:133] neg_lo:[0,1] neg_hi:[0,1]
	v_pk_fma_f32 v[74:75], v[4:5], v[74:75], v[130:131]
	v_pk_fma_f32 v[76:77], v[6:7], v[70:71], v[132:133]
	ds_write_b128 v103, v[74:77] offset:20480
	s_and_saveexec_b64 s[4:5], s[40:41]
	s_cbranch_execz .LBB0_553
	s_waitcnt vmcnt(15)
	ds_write_b64 v104, v[68:69] offset:24576
	s_branch .LBB0_553

; DI void mamba_scan(CP p, const Ptrs& w, int l, int item, float* sm) {
;     ...
;   auto load = [&](int c, MPre& P) {
; #pragma unroll
;     for (int i = 0; i < 2; ++i) {
;       int idx = tid + 256 * i, j = idx >> 5, q = idx & 31;
;       int ii = pos2i(c * 16 + j, dir);
;       P.pbq[i] = *(const uint4*)(mbc + ((size_t)b * TPB + ii) * 512 + (q < 16 ? 0 : 256) + gp * 128 + (q & 15) * 8);
;     }
;     {
;       int pos = c * 16 + xj, ii = pos2i(pos, dir);
;       size_t tok = (size_t)b * TPB + ii;
;       const bf16_t* prw = w.pC + tok * SPC;
;       bool hp = (ii != 0) && (ii != CTXL), hn = (ii != CTXL - 1) && (ii != TPB - 1);
;       P.px[0] = prw[chX + (hp ? -SPC : 0)]; P.px[1] = prw[chX]; P.px[2] = prw[chX + (hn ? SPC : 0)];
;       P.pxm[0] = hp ? 1.f : 0.f; P.pxm[1] = hn ? 1.f : 0.f;
;       float2 dd = *(const float2*)(w.mdt + (tok * 16 + dir * 8 + hd) * 2);
;       P.pdt[0] = dd.x; P.pdt[1] = dd.y; P.pdt[2] = w.mcb[tok * 2 + gp];
;     }
;     ...
;   auto lds_step = [&](const float* bf, int j) {
;     MStep q;
;     q.B0 = *(const f4v*)(bf + j * 128 + 8 * ng); q.B1 = *(const f4v*)(bf + j * 128 + 8 * ng + 4);
;     q.C0 = *(const f4v*)(bf + 2048 + j * 128 + 8 * ng); q.C1 = *(const f4v*)(bf + 2048 + j * 128 + 8 * ng + 4);
;     q.xq = bf[4096 + j * 16 + prow]; q.ds = bf[4096 + 256 + j * 16 + prow];
;     q.sc = *(const float4*)(bf + 4096 + 512 + j * 4);
;     return q;
;   };
;   auto flush = [&](int c) {
;     {
;       int j = tid >> 4, rr = tid & 15;
;       int ii = pos2i(c * 16 + j, dir);
;       yout[((size_t)b * TPB + ii) * 512 + hd * 64 + pq * 16 + rr] = f2bf(sY[(c & 1) * 256 + j * 16 + rr]);
;     }
;   };
;   __syncthreads();
;   load(0, PA);
;   stage(PA, sm);
;   load(1, PB);
;   __syncthreads();
;   const int NCH = TPB / 16;
;   auto run_chunk = [&](int c, const float* bf, float* sy) {
;     flush(max(c - 1, 0));
;     MStep cur = lds_step(bf, 0);
; #pragma unroll
;     for (int j = 0; j < 16; ++j) {
;       MStep nxt = cur;
;       if (j + 1 < 16) nxt = lds_step(bf, j + 1);
;       f2v ya = M0 * cur.C0.xy + M1 * cur.C0.zw, yb = M2 * cur.C1.xy + M3 * cur.C1.zw;
;       ya += yb;
;       float yp = row16_sum(ya.x + ya.y);
;       float y = cur.sc.x * yp + cur.xq * cur.sc.y + cur.ds;
;       const float dA = cur.sc.x, xq = cur.xq;
;       M0 = M0 * dA + xq * cur.B0.xy; M1 = M1 * dA + xq * cur.B0.zw;
.LBB0_700:
	s_or_b64 exec, exec, s[4:5]
	v_pk_mul_f32 v[12:13], v[42:43], v[38:39] op_sel_hi:[1,0]
	s_addk_i32 s71, 0x200
	v_pk_fma_f32 v[26:27], v[26:27], v[8:9], v[12:13] op_sel_hi:[1,0,1]
	v_pk_mul_f32 v[12:13], v[44:45], v[38:39] op_sel_hi:[1,0]
	s_add_i32 s72, s72, 2
	v_pk_fma_f32 v[28:29], v[28:29], v[8:9], v[12:13] op_sel_hi:[1,0,1]
	v_pk_mul_f32 v[12:13], v[40:41], v[38:39] op_sel_hi:[1,0]
	v_cndmask_b32_e64 v87, 1.0, 0, s[42:43]
	v_pk_fma_f32 v[22:23], v[22:23], v[8:9], v[12:13] op_sel_hi:[1,0,1]
	v_pk_mul_f32 v[12:13], v[46:47], v[38:39] op_sel_hi:[1,0]
	v_cndmask_b32_e64 v86, 1.0, 0, s[44:45]
	v_pk_fma_f32 v[24:25], v[24:25], v[8:9], v[12:13] op_sel_hi:[1,0,1]
	v_add_u32_e32 v82, 32, v82
	s_cmpk_lt_u32 s7, 0x20e
	v_subrev_u32_e32 v81, 32, v81
	s_waitcnt lgkmcnt(0)
	s_barrier
	s_cbranch_scc0 .LBB0_705
.LBB0_701:
	s_min_u32 s4, s72, 1
	s_lshl_b32 s5, s4, 8
	s_lshl_b32 s17, s4, 4
	s_add_i32 s4, s7, 4
	s_min_u32 s4, s4, 0x20f
	s_lshl_b32 s42, s4, 4
	v_add_u32_e32 v8, s42, v55
	s_sub_i32 s16, s71, s5
	v_cmp_lt_i32_e64 s[4:5], s37, v8
	v_mov_b64_e32 v[38:39], s[52:53]
	v_mov_b32_e32 v41, v157
	v_cndmask_b32_e64 v12, v231, v232, s[4:5]
	v_sub_u32_e32 v12, v12, v8
	v_cndmask_b32_e64 v12, v12, v8, s[40:41]
	v_add_u32_e32 v8, s42, v56
	v_cmp_lt_i32_e64 s[4:5], s37, v8
	v_ashrrev_i32_e32 v13, 31, v12
	v_lshl_add_u64 v[12:13], v[12:13], 0, s[90:91]
	v_cndmask_b32_e64 v14, v231, v232, s[4:5]
	v_sub_u32_e32 v14, v14, v8
	v_cndmask_b32_e64 v14, v14, v8, s[40:41]
	v_add_u32_e32 v8, s42, v54
	v_cmp_lt_i32_e64 s[4:5], s37, v8
	v_ashrrev_i32_e32 v15, 31, v14
	v_lshl_add_u64 v[14:15], v[14:15], 0, s[90:91]
	v_cndmask_b32_e64 v16, v231, v232, s[4:5]
	v_sub_u32_e32 v16, v16, v8
	v_cndmask_b32_e64 v16, v16, v8, s[40:41]
	v_and_b32_e32 v8, 0xfffffeff, v16
	v_ashrrev_i32_e32 v17, 31, v16
	v_cmp_eq_u32_e64 s[42:43], 0, v8
	v_lshl_add_u64 v[36:37], v[16:17], 0, s[90:91]
	v_mad_u64_u32 v[38:39], s[4:5], v36, s92, v[38:39]
	v_cndmask_b32_e64 v8, v233, 0, s[42:43]
	v_and_b32_e32 v40, 0xffffdfff, v16
	v_add_u32_e32 v16, v8, v48
	v_lshlrev_b64 v[12:13], 10, v[12:13]
	v_lshlrev_b64 v[14:15], 10, v[14:15]
	v_mad_i32_i24 v39, v37, s92, v39
	v_ashrrev_i32_e32 v17, 31, v16
	v_cmp_eq_u32_e64 s[44:45], s37, v40
	v_lshlrev_b64 v[42:43], 7, v[36:37]
	v_lshl_add_u64 v[12:13], v[30:31], 0, v[12:13]
	v_lshl_add_u64 v[14:15], v[30:31], 0, v[14:15]
	v_lshl_add_u64 v[16:17], v[16:17], 1, v[38:39]
	v_lshl_add_u64 v[38:39], v[38:39], 0, v[156:157]
	v_cndmask_b32_e64 v40, v234, 0, s[44:45]
	v_lshl_or_b32 v42, s6, 3, v42
	global_load_dwordx4 v[18:21], v[12:13], off
	s_nop 0
	global_load_dwordx4 v[12:15], v[14:15], off
	v_lshl_add_u64 v[40:41], v[38:39], 0, v[40:41]
	v_lshl_add_u64 v[42:43], s[38:39], 0, v[42:43]
	v_lshl_add_u64 v[44:45], v[36:37], 3, s[68:69]
	global_load_ushort v84, v[16:17], off
	global_load_ushort v85, v[38:39], off
	global_load_ushort v83, v[40:41], off
	global_load_dwordx2 v[36:37], v[42:43], off
	s_nop 0
	global_load_dword v17, v[44:45], off
	v_subrev_u32_e32 v8, s17, v82
	s_and_b32 s4, s16, 0x100
	v_lshl_add_u32 v16, s4, 2, v57
	v_cmp_lt_i32_e64 s[4:5], s37, v8
	ds_read_b32 v16, v16 offset:37376
	s_nop 0
	v_cndmask_b32_e64 v38, v231, v232, s[4:5]
	v_add3_u32 v38, v38, v81, s17
	v_cndmask_b32_e64 v38, v38, v8, s[40:41]
	v_ashrrev_i32_e32 v39, 31, v38
	v_lshl_add_u64 v[38:39], v[38:39], 0, s[90:91]
	v_lshlrev_b64 v[38:39], 10, v[38:39]
	s_waitcnt lgkmcnt(0)
	v_cvt_pk_bf16_f32 v8, v16, s0
	v_lshl_add_u64 v[38:39], v[34:35], 0, v[38:39]
	global_store_short v[38:39], v8, off
	ds_read_b128 v[38:41], v59
	ds_read_b128 v[42:45], v59 offset:16
	ds_read_b128 v[88:91], v59 offset:8192
	ds_read_b128 v[92:95], v59 offset:8208
	v_add_u32_e32 v8, 0x4000, v60
	ds_read2_b32 v[46:47], v8 offset1:16
	v_add_u32_e32 v8, 0x4400, v60
	s_waitcnt lgkmcnt(2)
	v_pk_mul_f32 v[90:91], v[28:29], v[90:91]
	s_movk_i32 s4, 0x4800
	v_pk_fma_f32 v[88:89], v[26:27], v[88:89], v[90:91]
	s_waitcnt lgkmcnt(1)
	v_pk_mul_f32 v[90:91], v[24:25], v[94:95]
	ds_read2_b32 v[116:117], v8 offset1:16
	v_pk_fma_f32 v[90:91], v[22:23], v[92:93], v[90:91]
	v_add_u32_e64 v8, s4, 0
	v_pk_add_f32 v[88:89], v[88:89], v[90:91]
	ds_read2_b64 v[96:99], v8 offset1:2
	ds_read_b128 v[100:103], v59 offset:512
	ds_read_b128 v[104:107], v59 offset:528
	ds_read_b128 v[108:111], v59 offset:8704
	ds_read_b128 v[112:115], v59 offset:8720
	v_add_f32_e32 v8, v88, v89
	s_waitcnt lgkmcnt(4)
	v_pk_mul_f32 v[26:27], v[26:27], v[96:97] op_sel_hi:[1,0]
	v_pk_mul_f32 v[22:23], v[22:23], v[96:97] op_sel_hi:[1,0]
	v_add_f32_dpp v8, v8, v8 quad_perm:[1,0,3,2] row_mask:0xf bank_mask:0xf bound_ctrl:1
	v_pk_fma_f32 v[88:89], v[38:39], v[46:47], v[26:27] op_sel_hi:[1,0,1]
	v_pk_mul_f32 v[26:27], v[28:29], v[96:97] op_sel_hi:[1,0]
	v_add_f32_dpp v8, v8, v8 quad_perm:[2,3,0,1] row_mask:0xf bank_mask:0xf bound_ctrl:1
	v_pk_fma_f32 v[90:91], v[40:41], v[46:47], v[26:27] op_sel_hi:[1,0,1]
	v_pk_fma_f32 v[92:93], v[42:43], v[46:47], v[22:23] op_sel_hi:[1,0,1]
	v_add_f32_dpp v8, v8, v8 row_half_mirror row_mask:0xf bank_mask:0xf bound_ctrl:1
	v_pk_mul_f32 v[22:23], v[24:25], v[96:97] op_sel_hi:[1,0]
	s_nop 0
	v_add_f32_dpp v8, v8, v8 row_mirror row_mask:0xf bank_mask:0xf bound_ctrl:1
	v_mul_f32_e32 v8, v96, v8
	v_fmac_f32_e32 v8, v46, v97
	v_pk_fma_f32 v[94:95], v[44:45], v[46:47], v[22:23] op_sel_hi:[1,0,1]
	s_waitcnt lgkmcnt(1)
	v_pk_mul_f32 v[96:97], v[90:91], v[110:111]
	v_add_f32_e32 v8, v116, v8
	v_pk_fma_f32 v[96:97], v[88:89], v[108:109], v[96:97]
	s_waitcnt lgkmcnt(0)
; DI float row16_sum(float v) { v += dppf(v, 0); v += dppf(v, 1); v += dppf(v, 2); v += dppf(v, 3); return v; }
; DI void mamba_scan(CP p, const Ptrs& w, int l, int item, float* sm) {
;     ...
;   auto lds_step = [&](const float* bf, int j) {
;     MStep q;
;     q.B0 = *(const f4v*)(bf + j * 128 + 8 * ng); q.B1 = *(const f4v*)(bf + j * 128 + 8 * ng + 4);
;     q.C0 = *(const f4v*)(bf + 2048 + j * 128 + 8 * ng); q.C1 = *(const f4v*)(bf + 2048 + j * 128 + 8 * ng + 4);
;     q.xq = bf[4096 + j * 16 + prow]; q.ds = bf[4096 + 256 + j * 16 + prow];
;     q.sc = *(const float4*)(bf + 4096 + 512 + j * 4);
;     return q;
;     ...
;   auto run_chunk = [&](int c, const float* bf, float* sy) {
;     flush(max(c - 1, 0));
;     MStep cur = lds_step(bf, 0);
; #pragma unroll
;     for (int j = 0; j < 16; ++j) {
;       MStep nxt = cur;
;       if (j + 1 < 16) nxt = lds_step(bf, j + 1);
;       f2v ya = M0 * cur.C0.xy + M1 * cur.C0.zw, yb = M2 * cur.C1.xy + M3 * cur.C1.zw;
;       ya += yb;
;       float yp = row16_sum(ya.x + ya.y);
;       float y = cur.sc.x * yp + cur.xq * cur.sc.y + cur.ds;
;       const float dA = cur.sc.x, xq = cur.xq;
;       M0 = M0 * dA + xq * cur.B0.xy; M1 = M1 * dA + xq * cur.B0.zw;
;       M2 = M2 * dA + xq * cur.B1.xy; M3 = M3 * dA + xq * cur.B1.zw;
;       sy[(ng == 0 ? j * 16 : 0) + ysel] = y;
;       cur = nxt;
;     }
;   };
	v_pk_mul_f32 v[108:109], v[94:95], v[114:115]
	v_pk_mul_f32 v[88:89], v[88:89], v[98:99] op_sel_hi:[1,0]
	v_pk_fma_f32 v[108:109], v[92:93], v[112:113], v[108:109]
	ds_write_b32 v61, v8 offset:37376
	v_pk_add_f32 v[96:97], v[96:97], v[108:109]
	ds_read_b128 v[22:25], v59 offset:1024
	ds_read_b128 v[26:29], v59 offset:1040
	ds_read_b128 v[38:41], v59 offset:9216
	ds_read_b128 v[42:45], v59 offset:9232
	ds_read_b32 v8, v60 offset:16512
	ds_read_b32 v116, v60 offset:17536
	ds_read_b64 v[118:119], v157 offset:18464
	v_add_f32_e32 v16, v96, v97
	s_nop 1
	v_add_f32_dpp v16, v16, v16 quad_perm:[1,0,3,2] row_mask:0xf bank_mask:0xf bound_ctrl:1
	s_nop 1
	v_add_f32_dpp v16, v16, v16 quad_perm:[2,3,0,1] row_mask:0xf bank_mask:0xf bound_ctrl:1
	s_nop 1
	v_add_f32_dpp v16, v16, v16 row_half_mirror row_mask:0xf bank_mask:0xf bound_ctrl:1
	s_nop 1
	v_add_f32_dpp v16, v16, v16 row_mirror row_mask:0xf bank_mask:0xf bound_ctrl:1
	v_mul_f32_e32 v16, v98, v16
	v_fmac_f32_e32 v16, v47, v99
	v_add_f32_e32 v96, v117, v16
	v_mov_b32_e32 v16, v47
	ds_write_b32 v62, v96 offset:37376
	s_waitcnt vmcnt(1)
	v_pk_fma_f32 v[46:47], v[100:101], v[16:17], v[88:89] op_sel_hi:[1,0,1]
	v_pk_mul_f32 v[88:89], v[90:91], v[98:99] op_sel_hi:[1,0]
	s_nop 0
	v_pk_fma_f32 v[108:109], v[102:103], v[16:17], v[88:89] op_sel_hi:[1,0,1]
	v_pk_mul_f32 v[88:89], v[92:93], v[98:99] op_sel_hi:[1,0]
	s_waitcnt lgkmcnt(5)
	v_pk_mul_f32 v[40:41], v[108:109], v[40:41]
	v_pk_fma_f32 v[104:105], v[104:105], v[16:17], v[88:89] op_sel_hi:[1,0,1]
	v_pk_mul_f32 v[88:89], v[94:95], v[98:99] op_sel_hi:[1,0]
	v_pk_fma_f32 v[38:39], v[46:47], v[38:39], v[40:41]
	v_pk_fma_f32 v[106:107], v[106:107], v[16:17], v[88:89] op_sel_hi:[1,0,1]
	ds_read_b128 v[88:91], v59 offset:1536
	ds_read_b128 v[92:95], v59 offset:1552
	ds_read_b128 v[96:99], v59 offset:9728
	ds_read_b128 v[100:103], v59 offset:9744
	ds_read_b32 v16, v60 offset:16576
	ds_read_b32 v114, v60 offset:17600
	ds_read_b64 v[110:111], v157 offset:18480
	s_waitcnt lgkmcnt(11)
	v_pk_mul_f32 v[40:41], v[106:107], v[44:45]
	s_nop 0
	v_pk_fma_f32 v[40:41], v[104:105], v[42:43], v[40:41]
	s_nop 0
	v_pk_add_f32 v[38:39], v[38:39], v[40:41]
	s_nop 0
	v_add_f32_e32 v38, v38, v39
	s_nop 1
	v_add_f32_dpp v38, v38, v38 quad_perm:[1,0,3,2] row_mask:0xf bank_mask:0xf bound_ctrl:1
	s_nop 1
	v_add_f32_dpp v38, v38, v38 quad_perm:[2,3,0,1] row_mask:0xf bank_mask:0xf bound_ctrl:1
	s_nop 1
	v_add_f32_dpp v38, v38, v38 row_half_mirror row_mask:0xf bank_mask:0xf bound_ctrl:1
	s_nop 1
	v_add_f32_dpp v38, v38, v38 row_mirror row_mask:0xf bank_mask:0xf bound_ctrl:1
	s_waitcnt lgkmcnt(8)
	v_mul_f32_e32 v38, v118, v38
	v_fmac_f32_e32 v38, v8, v119
	v_add_f32_e32 v40, v116, v38
	v_pk_mul_f32 v[38:39], v[46:47], v[118:119] op_sel_hi:[1,0]
	ds_write_b32 v63, v40 offset:37376
	v_pk_fma_f32 v[46:47], v[22:23], v[8:9], v[38:39] op_sel_hi:[1,0,1]
	v_pk_mul_f32 v[22:23], v[108:109], v[118:119] op_sel_hi:[1,0]
	s_nop 0
	v_pk_fma_f32 v[108:109], v[24:25], v[8:9], v[22:23] op_sel_hi:[1,0,1]
	v_pk_mul_f32 v[22:23], v[104:105], v[118:119] op_sel_hi:[1,0]
	s_waitcnt lgkmcnt(5)
	v_pk_mul_f32 v[98:99], v[108:109], v[98:99]
	v_pk_fma_f32 v[104:105], v[26:27], v[8:9], v[22:23] op_sel_hi:[1,0,1]
	v_pk_mul_f32 v[22:23], v[106:107], v[118:119] op_sel_hi:[1,0]
	v_pk_fma_f32 v[96:97], v[46:47], v[96:97], v[98:99]
	s_waitcnt lgkmcnt(1)
	v_pk_mul_f32 v[46:47], v[46:47], v[110:111] op_sel_hi:[1,0]
	v_pk_fma_f32 v[106:107], v[28:29], v[8:9], v[22:23] op_sel_hi:[1,0,1]
	v_pk_fma_f32 v[46:47], v[88:89], v[16:17], v[46:47] op_sel_hi:[1,0,1]
	v_pk_mul_f32 v[88:89], v[108:109], v[110:111] op_sel_hi:[1,0]
	v_pk_mul_f32 v[98:99], v[106:107], v[102:103]
	v_pk_fma_f32 v[108:109], v[90:91], v[16:17], v[88:89] op_sel_hi:[1,0,1]
	v_pk_mul_f32 v[88:89], v[104:105], v[110:111] op_sel_hi:[1,0]
	ds_read_b128 v[22:25], v59 offset:2048
	ds_read_b128 v[26:29], v59 offset:2064
	ds_read_b128 v[38:41], v59 offset:10240
	ds_read_b128 v[42:45], v59 offset:10256
	ds_read_b32 v8, v60 offset:16640
	ds_read_b32 v115, v60 offset:17664
	ds_read_b64 v[112:113], v157 offset:18496
	v_pk_fma_f32 v[98:99], v[104:105], v[100:101], v[98:99]
	v_pk_fma_f32 v[104:105], v[92:93], v[16:17], v[88:89] op_sel_hi:[1,0,1]
	v_pk_mul_f32 v[88:89], v[106:107], v[110:111] op_sel_hi:[1,0]
	v_pk_add_f32 v[96:97], v[96:97], v[98:99]
	v_pk_fma_f32 v[106:107], v[94:95], v[16:17], v[88:89] op_sel_hi:[1,0,1]
	s_waitcnt lgkmcnt(4)
	v_pk_mul_f32 v[40:41], v[108:109], v[40:41]
	v_add_f32_e32 v96, v96, v97
	v_pk_fma_f32 v[38:39], v[46:47], v[38:39], v[40:41]
	s_waitcnt lgkmcnt(3)
	v_pk_mul_f32 v[40:41], v[106:107], v[44:45]
	v_add_f32_dpp v96, v96, v96 quad_perm:[1,0,3,2] row_mask:0xf bank_mask:0xf bound_ctrl:1
	v_pk_fma_f32 v[40:41], v[104:105], v[42:43], v[40:41]
	s_nop 0
	v_add_f32_dpp v96, v96, v96 quad_perm:[2,3,0,1] row_mask:0xf bank_mask:0xf bound_ctrl:1
	v_pk_add_f32 v[38:39], v[38:39], v[40:41]
	s_nop 0
	v_add_f32_dpp v96, v96, v96 row_half_mirror row_mask:0xf bank_mask:0xf bound_ctrl:1
	v_add_f32_e32 v38, v38, v39
	s_nop 0
	v_add_f32_dpp v96, v96, v96 row_mirror row_mask:0xf bank_mask:0xf bound_ctrl:1
	v_add_f32_dpp v38, v38, v38 quad_perm:[1,0,3,2] row_mask:0xf bank_mask:0xf bound_ctrl:1
	v_mul_f32_e32 v96, v110, v96
	v_fmac_f32_e32 v96, v16, v111
	v_add_f32_dpp v38, v38, v38 quad_perm:[2,3,0,1] row_mask:0xf bank_mask:0xf bound_ctrl:1
	v_add_f32_e32 v96, v114, v96
	ds_write_b32 v65, v96 offset:37376
	v_add_f32_dpp v38, v38, v38 row_half_mirror row_mask:0xf bank_mask:0xf bound_ctrl:1
	ds_read_b128 v[88:91], v59 offset:2560
	ds_read_b128 v[92:95], v59 offset:2576
	ds_read_b128 v[96:99], v59 offset:10752
	ds_read_b128 v[100:103], v59 offset:10768
	ds_read_b32 v16, v60 offset:16704
	ds_read_b32 v114, v60 offset:17728
	ds_read_b64 v[110:111], v157 offset:18512
	v_add_f32_dpp v38, v38, v38 row_mirror row_mask:0xf bank_mask:0xf bound_ctrl:1
	s_waitcnt lgkmcnt(8)
; DI float row16_sum(float v) { v += dppf(v, 0); v += dppf(v, 1); v += dppf(v, 2); v += dppf(v, 3); return v; }
; DI void mamba_scan(CP p, const Ptrs& w, int l, int item, float* sm) {
;     ...
;   auto lds_step = [&](const float* bf, int j) {
;     MStep q;
;     q.B0 = *(const f4v*)(bf + j * 128 + 8 * ng); q.B1 = *(const f4v*)(bf + j * 128 + 8 * ng + 4);
;     q.C0 = *(const f4v*)(bf + 2048 + j * 128 + 8 * ng); q.C1 = *(const f4v*)(bf + 2048 + j * 128 + 8 * ng + 4);
;     q.xq = bf[4096 + j * 16 + prow]; q.ds = bf[4096 + 256 + j * 16 + prow];
;     q.sc = *(const float4*)(bf + 4096 + 512 + j * 4);
;     return q;
;     ...
;   auto run_chunk = [&](int c, const float* bf, float* sy) {
;     flush(max(c - 1, 0));
;     MStep cur = lds_step(bf, 0);
; #pragma unroll
;     for (int j = 0; j < 16; ++j) {
;       MStep nxt = cur;
;       if (j + 1 < 16) nxt = lds_step(bf, j + 1);
;       f2v ya = M0 * cur.C0.xy + M1 * cur.C0.zw, yb = M2 * cur.C1.xy + M3 * cur.C1.zw;
;       ya += yb;
;       float yp = row16_sum(ya.x + ya.y);
;       float y = cur.sc.x * yp + cur.xq * cur.sc.y + cur.ds;
;       const float dA = cur.sc.x, xq = cur.xq;
;       M0 = M0 * dA + xq * cur.B0.xy; M1 = M1 * dA + xq * cur.B0.zw;
;       M2 = M2 * dA + xq * cur.B1.xy; M3 = M3 * dA + xq * cur.B1.zw;
;       sy[(ng == 0 ? j * 16 : 0) + ysel] = y;
;       cur = nxt;
;     }
;   };
	v_mul_f32_e32 v38, v112, v38
	v_fmac_f32_e32 v38, v8, v113
	v_add_f32_e32 v40, v115, v38
	v_pk_mul_f32 v[38:39], v[46:47], v[112:113] op_sel_hi:[1,0]
	ds_write_b32 v66, v40 offset:37376
	v_pk_fma_f32 v[46:47], v[22:23], v[8:9], v[38:39] op_sel_hi:[1,0,1]
	v_pk_mul_f32 v[22:23], v[108:109], v[112:113] op_sel_hi:[1,0]
	s_nop 0
	v_pk_fma_f32 v[108:109], v[24:25], v[8:9], v[22:23] op_sel_hi:[1,0,1]
	v_pk_mul_f32 v[22:23], v[104:105], v[112:113] op_sel_hi:[1,0]
	s_waitcnt lgkmcnt(5)
	v_pk_mul_f32 v[98:99], v[108:109], v[98:99]
	v_pk_fma_f32 v[104:105], v[26:27], v[8:9], v[22:23] op_sel_hi:[1,0,1]
	v_pk_mul_f32 v[22:23], v[106:107], v[112:113] op_sel_hi:[1,0]
	v_pk_fma_f32 v[96:97], v[46:47], v[96:97], v[98:99]
	s_waitcnt lgkmcnt(1)
	v_pk_mul_f32 v[46:47], v[46:47], v[110:111] op_sel_hi:[1,0]
	v_pk_fma_f32 v[106:107], v[28:29], v[8:9], v[22:23] op_sel_hi:[1,0,1]
	v_pk_fma_f32 v[46:47], v[88:89], v[16:17], v[46:47] op_sel_hi:[1,0,1]
	v_pk_mul_f32 v[88:89], v[108:109], v[110:111] op_sel_hi:[1,0]
	v_pk_mul_f32 v[98:99], v[106:107], v[102:103]
	v_pk_fma_f32 v[108:109], v[90:91], v[16:17], v[88:89] op_sel_hi:[1,0,1]
	v_pk_mul_f32 v[88:89], v[104:105], v[110:111] op_sel_hi:[1,0]
	ds_read_b128 v[22:25], v59 offset:3072
	ds_read_b128 v[26:29], v59 offset:3088
	ds_read_b128 v[38:41], v59 offset:11264
	ds_read_b128 v[42:45], v59 offset:11280
	ds_read_b32 v8, v60 offset:16768
	ds_read_b32 v115, v60 offset:17792
	ds_read_b64 v[112:113], v157 offset:18528
	v_pk_fma_f32 v[98:99], v[104:105], v[100:101], v[98:99]
	v_pk_fma_f32 v[104:105], v[92:93], v[16:17], v[88:89] op_sel_hi:[1,0,1]
	v_pk_mul_f32 v[88:89], v[106:107], v[110:111] op_sel_hi:[1,0]
	v_pk_add_f32 v[96:97], v[96:97], v[98:99]
	v_pk_fma_f32 v[106:107], v[94:95], v[16:17], v[88:89] op_sel_hi:[1,0,1]
	s_waitcnt lgkmcnt(4)
	v_pk_mul_f32 v[40:41], v[108:109], v[40:41]
	v_add_f32_e32 v96, v96, v97
	v_pk_fma_f32 v[38:39], v[46:47], v[38:39], v[40:41]
	s_waitcnt lgkmcnt(3)
	v_pk_mul_f32 v[40:41], v[106:107], v[44:45]
	v_add_f32_dpp v96, v96, v96 quad_perm:[1,0,3,2] row_mask:0xf bank_mask:0xf bound_ctrl:1
	v_pk_fma_f32 v[40:41], v[104:105], v[42:43], v[40:41]
	s_nop 0
	v_add_f32_dpp v96, v96, v96 quad_perm:[2,3,0,1] row_mask:0xf bank_mask:0xf bound_ctrl:1
	v_pk_add_f32 v[38:39], v[38:39], v[40:41]
	s_nop 0
	v_add_f32_dpp v96, v96, v96 row_half_mirror row_mask:0xf bank_mask:0xf bound_ctrl:1
	v_add_f32_e32 v38, v38, v39
	s_nop 0
	v_add_f32_dpp v96, v96, v96 row_mirror row_mask:0xf bank_mask:0xf bound_ctrl:1
	v_add_f32_dpp v38, v38, v38 quad_perm:[1,0,3,2] row_mask:0xf bank_mask:0xf bound_ctrl:1
	v_mul_f32_e32 v96, v110, v96
	v_fmac_f32_e32 v96, v16, v111
	v_add_f32_dpp v38, v38, v38 quad_perm:[2,3,0,1] row_mask:0xf bank_mask:0xf bound_ctrl:1
	v_add_f32_e32 v96, v114, v96
	ds_write_b32 v67, v96 offset:37376
	v_add_f32_dpp v38, v38, v38 row_half_mirror row_mask:0xf bank_mask:0xf bound_ctrl:1
	ds_read_b128 v[88:91], v59 offset:3584
	ds_read_b128 v[92:95], v59 offset:3600
	ds_read_b128 v[96:99], v59 offset:11776
	ds_read_b128 v[100:103], v59 offset:11792
	ds_read_b32 v16, v60 offset:16832
	ds_read_b32 v114, v60 offset:17856
	ds_read_b64 v[110:111], v157 offset:18544
	v_add_f32_dpp v38, v38, v38 row_mirror row_mask:0xf bank_mask:0xf bound_ctrl:1
	s_waitcnt lgkmcnt(8)
	v_mul_f32_e32 v38, v112, v38
	v_fmac_f32_e32 v38, v8, v113
	v_add_f32_e32 v40, v115, v38
	v_pk_mul_f32 v[38:39], v[46:47], v[112:113] op_sel_hi:[1,0]
	ds_write_b32 v68, v40 offset:37376
	v_pk_fma_f32 v[46:47], v[22:23], v[8:9], v[38:39] op_sel_hi:[1,0,1]
	v_pk_mul_f32 v[22:23], v[108:109], v[112:113] op_sel_hi:[1,0]
	s_nop 0
	v_pk_fma_f32 v[108:109], v[24:25], v[8:9], v[22:23] op_sel_hi:[1,0,1]
	v_pk_mul_f32 v[22:23], v[104:105], v[112:113] op_sel_hi:[1,0]
	s_waitcnt lgkmcnt(5)
	v_pk_mul_f32 v[98:99], v[108:109], v[98:99]
	v_pk_fma_f32 v[104:105], v[26:27], v[8:9], v[22:23] op_sel_hi:[1,0,1]
	v_pk_mul_f32 v[22:23], v[106:107], v[112:113] op_sel_hi:[1,0]
	v_pk_fma_f32 v[96:97], v[46:47], v[96:97], v[98:99]
	s_waitcnt lgkmcnt(1)
	v_pk_mul_f32 v[46:47], v[46:47], v[110:111] op_sel_hi:[1,0]
	v_pk_fma_f32 v[106:107], v[28:29], v[8:9], v[22:23] op_sel_hi:[1,0,1]
	v_pk_fma_f32 v[46:47], v[88:89], v[16:17], v[46:47] op_sel_hi:[1,0,1]
	v_pk_mul_f32 v[88:89], v[108:109], v[110:111] op_sel_hi:[1,0]
	v_pk_mul_f32 v[98:99], v[106:107], v[102:103]
	v_pk_fma_f32 v[108:109], v[90:91], v[16:17], v[88:89] op_sel_hi:[1,0,1]
	v_pk_mul_f32 v[88:89], v[104:105], v[110:111] op_sel_hi:[1,0]
	ds_read_b128 v[22:25], v59 offset:4096
	ds_read_b128 v[26:29], v59 offset:4112
	ds_read_b128 v[38:41], v59 offset:12288
	ds_read_b128 v[42:45], v59 offset:12304
	ds_read_b32 v8, v60 offset:16896
	ds_read_b32 v115, v60 offset:17920
	ds_read_b64 v[112:113], v157 offset:18560
	v_pk_fma_f32 v[98:99], v[104:105], v[100:101], v[98:99]
	v_pk_fma_f32 v[104:105], v[92:93], v[16:17], v[88:89] op_sel_hi:[1,0,1]
	v_pk_mul_f32 v[88:89], v[106:107], v[110:111] op_sel_hi:[1,0]
	v_pk_add_f32 v[96:97], v[96:97], v[98:99]
	v_pk_fma_f32 v[106:107], v[94:95], v[16:17], v[88:89] op_sel_hi:[1,0,1]
	s_waitcnt lgkmcnt(4)
	v_pk_mul_f32 v[40:41], v[108:109], v[40:41]
	v_add_f32_e32 v96, v96, v97
	v_pk_fma_f32 v[38:39], v[46:47], v[38:39], v[40:41]
	s_waitcnt lgkmcnt(3)
; DI float row16_sum(float v) { v += dppf(v, 0); v += dppf(v, 1); v += dppf(v, 2); v += dppf(v, 3); return v; }
; DI void mamba_scan(CP p, const Ptrs& w, int l, int item, float* sm) {
;     ...
;   auto lds_step = [&](const float* bf, int j) {
;     MStep q;
;     q.B0 = *(const f4v*)(bf + j * 128 + 8 * ng); q.B1 = *(const f4v*)(bf + j * 128 + 8 * ng + 4);
;     q.C0 = *(const f4v*)(bf + 2048 + j * 128 + 8 * ng); q.C1 = *(const f4v*)(bf + 2048 + j * 128 + 8 * ng + 4);
;     q.xq = bf[4096 + j * 16 + prow]; q.ds = bf[4096 + 256 + j * 16 + prow];
;     q.sc = *(const float4*)(bf + 4096 + 512 + j * 4);
;     return q;
;     ...
;   auto run_chunk = [&](int c, const float* bf, float* sy) {
;     flush(max(c - 1, 0));
;     MStep cur = lds_step(bf, 0);
; #pragma unroll
;     for (int j = 0; j < 16; ++j) {
;       MStep nxt = cur;
;       if (j + 1 < 16) nxt = lds_step(bf, j + 1);
;       f2v ya = M0 * cur.C0.xy + M1 * cur.C0.zw, yb = M2 * cur.C1.xy + M3 * cur.C1.zw;
;       ya += yb;
;       float yp = row16_sum(ya.x + ya.y);
;       float y = cur.sc.x * yp + cur.xq * cur.sc.y + cur.ds;
;       const float dA = cur.sc.x, xq = cur.xq;
;       M0 = M0 * dA + xq * cur.B0.xy; M1 = M1 * dA + xq * cur.B0.zw;
;       M2 = M2 * dA + xq * cur.B1.xy; M3 = M3 * dA + xq * cur.B1.zw;
;       sy[(ng == 0 ? j * 16 : 0) + ysel] = y;
;       cur = nxt;
;     }
;   };
	v_pk_mul_f32 v[40:41], v[106:107], v[44:45]
	v_add_f32_dpp v96, v96, v96 quad_perm:[1,0,3,2] row_mask:0xf bank_mask:0xf bound_ctrl:1
	v_pk_fma_f32 v[40:41], v[104:105], v[42:43], v[40:41]
	s_nop 0
	v_add_f32_dpp v96, v96, v96 quad_perm:[2,3,0,1] row_mask:0xf bank_mask:0xf bound_ctrl:1
	v_pk_add_f32 v[38:39], v[38:39], v[40:41]
	s_nop 0
	v_add_f32_dpp v96, v96, v96 row_half_mirror row_mask:0xf bank_mask:0xf bound_ctrl:1
	v_add_f32_e32 v38, v38, v39
	s_nop 0
	v_add_f32_dpp v96, v96, v96 row_mirror row_mask:0xf bank_mask:0xf bound_ctrl:1
	v_add_f32_dpp v38, v38, v38 quad_perm:[1,0,3,2] row_mask:0xf bank_mask:0xf bound_ctrl:1
	v_mul_f32_e32 v96, v110, v96
	v_fmac_f32_e32 v96, v16, v111
	v_add_f32_dpp v38, v38, v38 quad_perm:[2,3,0,1] row_mask:0xf bank_mask:0xf bound_ctrl:1
	v_add_f32_e32 v96, v114, v96
	ds_write_b32 v70, v96 offset:37376
	v_add_f32_dpp v38, v38, v38 row_half_mirror row_mask:0xf bank_mask:0xf bound_ctrl:1
	ds_read_b128 v[88:91], v59 offset:4608
	ds_read_b128 v[92:95], v59 offset:4624
	ds_read_b128 v[96:99], v59 offset:12800
	ds_read_b128 v[100:103], v59 offset:12816
	ds_read_b32 v16, v60 offset:16960
	ds_read_b32 v114, v60 offset:17984
	ds_read_b64 v[110:111], v157 offset:18576
	v_add_f32_dpp v38, v38, v38 row_mirror row_mask:0xf bank_mask:0xf bound_ctrl:1
	s_waitcnt lgkmcnt(8)
	v_mul_f32_e32 v38, v112, v38
	v_fmac_f32_e32 v38, v8, v113
	v_add_f32_e32 v40, v115, v38
	v_pk_mul_f32 v[38:39], v[46:47], v[112:113] op_sel_hi:[1,0]
	ds_write_b32 v71, v40 offset:37376
	v_pk_fma_f32 v[46:47], v[22:23], v[8:9], v[38:39] op_sel_hi:[1,0,1]
	v_pk_mul_f32 v[22:23], v[108:109], v[112:113] op_sel_hi:[1,0]
	s_nop 0
	v_pk_fma_f32 v[108:109], v[24:25], v[8:9], v[22:23] op_sel_hi:[1,0,1]
	v_pk_mul_f32 v[22:23], v[104:105], v[112:113] op_sel_hi:[1,0]
	s_waitcnt lgkmcnt(5)
	v_pk_mul_f32 v[98:99], v[108:109], v[98:99]
	v_pk_fma_f32 v[104:105], v[26:27], v[8:9], v[22:23] op_sel_hi:[1,0,1]
	v_pk_mul_f32 v[22:23], v[106:107], v[112:113] op_sel_hi:[1,0]
	v_pk_fma_f32 v[96:97], v[46:47], v[96:97], v[98:99]
	s_waitcnt lgkmcnt(1)
	v_pk_mul_f32 v[46:47], v[46:47], v[110:111] op_sel_hi:[1,0]
	v_pk_fma_f32 v[106:107], v[28:29], v[8:9], v[22:23] op_sel_hi:[1,0,1]
	v_pk_fma_f32 v[46:47], v[88:89], v[16:17], v[46:47] op_sel_hi:[1,0,1]
	v_pk_mul_f32 v[88:89], v[108:109], v[110:111] op_sel_hi:[1,0]
	v_pk_mul_f32 v[98:99], v[106:107], v[102:103]
	v_pk_fma_f32 v[108:109], v[90:91], v[16:17], v[88:89] op_sel_hi:[1,0,1]
	v_pk_mul_f32 v[88:89], v[104:105], v[110:111] op_sel_hi:[1,0]
	ds_read_b128 v[22:25], v59 offset:5120
	ds_read_b128 v[26:29], v59 offset:5136
	ds_read_b128 v[38:41], v59 offset:13312
	ds_read_b128 v[42:45], v59 offset:13328
	ds_read_b32 v8, v60 offset:17024
	ds_read_b32 v115, v60 offset:18048
	ds_read_b64 v[112:113], v157 offset:18592
	v_pk_fma_f32 v[98:99], v[104:105], v[100:101], v[98:99]
	v_pk_fma_f32 v[104:105], v[92:93], v[16:17], v[88:89] op_sel_hi:[1,0,1]
	v_pk_mul_f32 v[88:89], v[106:107], v[110:111] op_sel_hi:[1,0]
	v_pk_add_f32 v[96:97], v[96:97], v[98:99]
	v_pk_fma_f32 v[106:107], v[94:95], v[16:17], v[88:89] op_sel_hi:[1,0,1]
	s_waitcnt lgkmcnt(4)
	v_pk_mul_f32 v[40:41], v[108:109], v[40:41]
	v_add_f32_e32 v96, v96, v97
	v_pk_fma_f32 v[38:39], v[46:47], v[38:39], v[40:41]
	s_waitcnt lgkmcnt(3)
	v_pk_mul_f32 v[40:41], v[106:107], v[44:45]
	v_add_f32_dpp v96, v96, v96 quad_perm:[1,0,3,2] row_mask:0xf bank_mask:0xf bound_ctrl:1
	v_pk_fma_f32 v[40:41], v[104:105], v[42:43], v[40:41]
	s_nop 0
	v_add_f32_dpp v96, v96, v96 quad_perm:[2,3,0,1] row_mask:0xf bank_mask:0xf bound_ctrl:1
	v_pk_add_f32 v[38:39], v[38:39], v[40:41]
	s_nop 0
	v_add_f32_dpp v96, v96, v96 row_half_mirror row_mask:0xf bank_mask:0xf bound_ctrl:1
	v_add_f32_e32 v38, v38, v39
	s_nop 0
	v_add_f32_dpp v96, v96, v96 row_mirror row_mask:0xf bank_mask:0xf bound_ctrl:1
	v_add_f32_dpp v38, v38, v38 quad_perm:[1,0,3,2] row_mask:0xf bank_mask:0xf bound_ctrl:1
	v_mul_f32_e32 v96, v110, v96
	v_fmac_f32_e32 v96, v16, v111
	v_add_f32_dpp v38, v38, v38 quad_perm:[2,3,0,1] row_mask:0xf bank_mask:0xf bound_ctrl:1
	v_add_f32_e32 v96, v114, v96
	ds_write_b32 v73, v96 offset:37376
	v_add_f32_dpp v38, v38, v38 row_half_mirror row_mask:0xf bank_mask:0xf bound_ctrl:1
	ds_read_b128 v[88:91], v59 offset:5632
	ds_read_b128 v[92:95], v59 offset:5648
	ds_read_b128 v[96:99], v59 offset:13824
	ds_read_b128 v[100:103], v59 offset:13840
	ds_read_b32 v16, v60 offset:17088
	ds_read_b32 v114, v60 offset:18112
	ds_read_b64 v[110:111], v157 offset:18608
	v_add_f32_dpp v38, v38, v38 row_mirror row_mask:0xf bank_mask:0xf bound_ctrl:1
	s_waitcnt lgkmcnt(8)
	v_mul_f32_e32 v38, v112, v38
	v_fmac_f32_e32 v38, v8, v113
	v_add_f32_e32 v40, v115, v38
	v_pk_mul_f32 v[38:39], v[46:47], v[112:113] op_sel_hi:[1,0]
	ds_write_b32 v74, v40 offset:37376
	v_pk_fma_f32 v[46:47], v[22:23], v[8:9], v[38:39] op_sel_hi:[1,0,1]
	v_pk_mul_f32 v[22:23], v[108:109], v[112:113] op_sel_hi:[1,0]
	s_nop 0
	v_pk_fma_f32 v[108:109], v[24:25], v[8:9], v[22:23] op_sel_hi:[1,0,1]
	v_pk_mul_f32 v[22:23], v[104:105], v[112:113] op_sel_hi:[1,0]
	s_waitcnt lgkmcnt(5)
	v_pk_mul_f32 v[98:99], v[108:109], v[98:99]
	v_pk_fma_f32 v[104:105], v[26:27], v[8:9], v[22:23] op_sel_hi:[1,0,1]
	v_pk_mul_f32 v[22:23], v[106:107], v[112:113] op_sel_hi:[1,0]
	v_pk_fma_f32 v[96:97], v[46:47], v[96:97], v[98:99]
	s_waitcnt lgkmcnt(1)
; DI float row16_sum(float v) { v += dppf(v, 0); v += dppf(v, 1); v += dppf(v, 2); v += dppf(v, 3); return v; }
; DI void mamba_scan(CP p, const Ptrs& w, int l, int item, float* sm) {
;     ...
;   auto lds_step = [&](const float* bf, int j) {
;     MStep q;
;     q.B0 = *(const f4v*)(bf + j * 128 + 8 * ng); q.B1 = *(const f4v*)(bf + j * 128 + 8 * ng + 4);
;     q.C0 = *(const f4v*)(bf + 2048 + j * 128 + 8 * ng); q.C1 = *(const f4v*)(bf + 2048 + j * 128 + 8 * ng + 4);
;     q.xq = bf[4096 + j * 16 + prow]; q.ds = bf[4096 + 256 + j * 16 + prow];
;     q.sc = *(const float4*)(bf + 4096 + 512 + j * 4);
;     return q;
;     ...
;   auto run_chunk = [&](int c, const float* bf, float* sy) {
;     flush(max(c - 1, 0));
;     MStep cur = lds_step(bf, 0);
; #pragma unroll
;     for (int j = 0; j < 16; ++j) {
;       MStep nxt = cur;
;       if (j + 1 < 16) nxt = lds_step(bf, j + 1);
;       f2v ya = M0 * cur.C0.xy + M1 * cur.C0.zw, yb = M2 * cur.C1.xy + M3 * cur.C1.zw;
;       ya += yb;
;       float yp = row16_sum(ya.x + ya.y);
;       float y = cur.sc.x * yp + cur.xq * cur.sc.y + cur.ds;
;       const float dA = cur.sc.x, xq = cur.xq;
;       M0 = M0 * dA + xq * cur.B0.xy; M1 = M1 * dA + xq * cur.B0.zw;
;       M2 = M2 * dA + xq * cur.B1.xy; M3 = M3 * dA + xq * cur.B1.zw;
;       sy[(ng == 0 ? j * 16 : 0) + ysel] = y;
;       cur = nxt;
;     }
;   };
	v_pk_mul_f32 v[46:47], v[46:47], v[110:111] op_sel_hi:[1,0]
	v_pk_fma_f32 v[106:107], v[28:29], v[8:9], v[22:23] op_sel_hi:[1,0,1]
	v_pk_fma_f32 v[46:47], v[88:89], v[16:17], v[46:47] op_sel_hi:[1,0,1]
	v_pk_mul_f32 v[88:89], v[108:109], v[110:111] op_sel_hi:[1,0]
	v_pk_mul_f32 v[98:99], v[106:107], v[102:103]
	v_pk_fma_f32 v[108:109], v[90:91], v[16:17], v[88:89] op_sel_hi:[1,0,1]
	v_pk_mul_f32 v[88:89], v[104:105], v[110:111] op_sel_hi:[1,0]
	ds_read_b128 v[22:25], v59 offset:6144
	ds_read_b128 v[26:29], v59 offset:6160
	ds_read_b128 v[38:41], v59 offset:14336
	ds_read_b128 v[42:45], v59 offset:14352
	ds_read_b32 v8, v60 offset:17152
	ds_read_b32 v115, v60 offset:18176
	ds_read_b64 v[112:113], v157 offset:18624
	v_pk_fma_f32 v[98:99], v[104:105], v[100:101], v[98:99]
	v_pk_fma_f32 v[104:105], v[92:93], v[16:17], v[88:89] op_sel_hi:[1,0,1]
	v_pk_mul_f32 v[88:89], v[106:107], v[110:111] op_sel_hi:[1,0]
	s_waitcnt lgkmcnt(4)
	v_pk_mul_f32 v[40:41], v[108:109], v[40:41]
	v_pk_fma_f32 v[106:107], v[94:95], v[16:17], v[88:89] op_sel_hi:[1,0,1]
	v_pk_fma_f32 v[38:39], v[46:47], v[38:39], v[40:41]
	s_waitcnt lgkmcnt(3)
	v_pk_mul_f32 v[40:41], v[106:107], v[44:45]
	v_pk_add_f32 v[96:97], v[96:97], v[98:99]
	v_pk_fma_f32 v[40:41], v[104:105], v[42:43], v[40:41]
	v_add_f32_e32 v96, v96, v97
	v_pk_add_f32 v[38:39], v[38:39], v[40:41]
	s_nop 0
	v_add_f32_dpp v96, v96, v96 quad_perm:[1,0,3,2] row_mask:0xf bank_mask:0xf bound_ctrl:1
	v_add_f32_e32 v38, v38, v39
	s_nop 0
	v_add_f32_dpp v96, v96, v96 quad_perm:[2,3,0,1] row_mask:0xf bank_mask:0xf bound_ctrl:1
	v_add_f32_dpp v38, v38, v38 quad_perm:[1,0,3,2] row_mask:0xf bank_mask:0xf bound_ctrl:1
	s_nop 0
	v_add_f32_dpp v96, v96, v96 row_half_mirror row_mask:0xf bank_mask:0xf bound_ctrl:1
	v_add_f32_dpp v38, v38, v38 quad_perm:[2,3,0,1] row_mask:0xf bank_mask:0xf bound_ctrl:1
	s_nop 0
	v_add_f32_dpp v96, v96, v96 row_mirror row_mask:0xf bank_mask:0xf bound_ctrl:1
	v_add_f32_dpp v38, v38, v38 row_half_mirror row_mask:0xf bank_mask:0xf bound_ctrl:1
	v_mul_f32_e32 v96, v110, v96
	v_fmac_f32_e32 v96, v16, v111
	v_add_f32_dpp v38, v38, v38 row_mirror row_mask:0xf bank_mask:0xf bound_ctrl:1
	s_waitcnt lgkmcnt(0)
	v_mul_f32_e32 v38, v112, v38
	v_add_f32_e32 v96, v114, v96
	v_fmac_f32_e32 v38, v8, v113
	ds_write_b32 v75, v96 offset:37376
	v_add_f32_e32 v40, v115, v38
	v_pk_mul_f32 v[38:39], v[46:47], v[112:113] op_sel_hi:[1,0]
	ds_read_b128 v[88:91], v59 offset:6656
	ds_read_b128 v[92:95], v59 offset:6672
	ds_read_b128 v[96:99], v59 offset:14848
	ds_read_b128 v[100:103], v59 offset:14864
	ds_read_b32 v16, v60 offset:17216
	ds_read_b32 v118, v60 offset:18240
	ds_read_b64 v[116:117], v157 offset:18640
	v_pk_fma_f32 v[22:23], v[22:23], v[8:9], v[38:39] op_sel_hi:[1,0,1]
	v_pk_mul_f32 v[38:39], v[108:109], v[112:113] op_sel_hi:[1,0]
	ds_write_b32 v76, v40 offset:37376
	v_pk_fma_f32 v[24:25], v[24:25], v[8:9], v[38:39] op_sel_hi:[1,0,1]
	v_pk_mul_f32 v[38:39], v[104:105], v[112:113] op_sel_hi:[1,0]
	s_nop 0
	v_pk_fma_f32 v[26:27], v[26:27], v[8:9], v[38:39] op_sel_hi:[1,0,1]
	v_pk_mul_f32 v[38:39], v[106:107], v[112:113] op_sel_hi:[1,0]
	s_nop 0
	v_pk_fma_f32 v[28:29], v[28:29], v[8:9], v[38:39] op_sel_hi:[1,0,1]
	s_waitcnt lgkmcnt(5)
	v_pk_mul_f32 v[38:39], v[24:25], v[98:99]
	s_waitcnt lgkmcnt(4)
	v_pk_mul_f32 v[40:41], v[28:29], v[102:103]
	v_pk_fma_f32 v[38:39], v[22:23], v[96:97], v[38:39]
	v_pk_fma_f32 v[40:41], v[26:27], v[100:101], v[40:41]
	s_waitcnt lgkmcnt(1)
	v_pk_mul_f32 v[22:23], v[22:23], v[116:117] op_sel_hi:[1,0]
	v_pk_add_f32 v[38:39], v[38:39], v[40:41]
	v_pk_fma_f32 v[40:41], v[88:89], v[16:17], v[22:23] op_sel_hi:[1,0,1]
	v_pk_mul_f32 v[22:23], v[24:25], v[116:117] op_sel_hi:[1,0]
	ds_read_b128 v[42:45], v59 offset:7168
	ds_read_b128 v[104:107], v59 offset:7184
	ds_read_b128 v[108:111], v59 offset:15360
	ds_read_b128 v[112:115], v59 offset:15376
	ds_read_b32 v8, v60 offset:17280
	ds_read_b32 v119, v60 offset:18304
	ds_read_b64 v[46:47], v157 offset:18656
	v_pk_fma_f32 v[96:97], v[90:91], v[16:17], v[22:23] op_sel_hi:[1,0,1]
	v_pk_mul_f32 v[22:23], v[26:27], v[116:117] op_sel_hi:[1,0]
	s_waitcnt lgkmcnt(4)
	v_pk_mul_f32 v[102:103], v[96:97], v[110:111]
	v_pk_fma_f32 v[98:99], v[92:93], v[16:17], v[22:23] op_sel_hi:[1,0,1]
	v_pk_mul_f32 v[22:23], v[28:29], v[116:117] op_sel_hi:[1,0]
	v_add_f32_e32 v38, v38, v39
	v_pk_fma_f32 v[100:101], v[94:95], v[16:17], v[22:23] op_sel_hi:[1,0,1]
	v_pk_fma_f32 v[102:103], v[40:41], v[108:109], v[102:103]
	s_waitcnt lgkmcnt(3)
	v_pk_mul_f32 v[108:109], v[100:101], v[114:115]
	v_add_f32_dpp v38, v38, v38 quad_perm:[1,0,3,2] row_mask:0xf bank_mask:0xf bound_ctrl:1
	v_pk_fma_f32 v[108:109], v[98:99], v[112:113], v[108:109]
	s_waitcnt lgkmcnt(0)
	v_pk_mul_f32 v[40:41], v[40:41], v[46:47] op_sel_hi:[1,0]
	v_add_f32_dpp v38, v38, v38 quad_perm:[2,3,0,1] row_mask:0xf bank_mask:0xf bound_ctrl:1
	v_pk_add_f32 v[102:103], v[102:103], v[108:109]
	v_pk_fma_f32 v[42:43], v[42:43], v[8:9], v[40:41] op_sel_hi:[1,0,1]
	v_add_f32_dpp v38, v38, v38 row_half_mirror row_mask:0xf bank_mask:0xf bound_ctrl:1
	v_add_f32_e32 v102, v102, v103
	v_pk_mul_f32 v[40:41], v[96:97], v[46:47] op_sel_hi:[1,0]
	v_add_f32_dpp v38, v38, v38 row_mirror row_mask:0xf bank_mask:0xf bound_ctrl:1
	v_add_f32_dpp v102, v102, v102 quad_perm:[1,0,3,2] row_mask:0xf bank_mask:0xf bound_ctrl:1
	v_mul_f32_e32 v38, v116, v38
	v_fmac_f32_e32 v38, v16, v117
	v_add_f32_dpp v102, v102, v102 quad_perm:[2,3,0,1] row_mask:0xf bank_mask:0xf bound_ctrl:1
	v_add_f32_e32 v38, v118, v38
	ds_write_b32 v77, v38 offset:37376
	v_add_f32_dpp v102, v102, v102 row_half_mirror row_mask:0xf bank_mask:0xf bound_ctrl:1
	ds_read_b128 v[26:29], v59 offset:7680
	ds_read_b128 v[22:25], v59 offset:7696
	ds_read_b128 v[88:91], v59 offset:15872
	ds_read_b128 v[92:95], v59 offset:15888
	ds_read_b32 v16, v60 offset:17344
	ds_read_b32 v116, v60 offset:18368
	ds_read_b64 v[38:39], v157 offset:18672
	v_add_f32_dpp v102, v102, v102 row_mirror row_mask:0xf bank_mask:0xf bound_ctrl:1
	v_mul_f32_e32 v102, v46, v102
	v_fmac_f32_e32 v102, v8, v47
	v_pk_fma_f32 v[44:45], v[44:45], v[8:9], v[40:41] op_sel_hi:[1,0,1]
	v_pk_mul_f32 v[40:41], v[98:99], v[46:47] op_sel_hi:[1,0]
	v_pk_mul_f32 v[46:47], v[100:101], v[46:47] op_sel_hi:[1,0]
	s_waitcnt lgkmcnt(4)
; DI float bf2f(bf16_t h) { return __uint_as_float(((unsigned)h) << 16); }
; DI float siluf(float x) { return x * sigmf(x); }
; DI void mamba_scan(CP p, const Ptrs& w, int l, int item, float* sm) {
;     ...
;   auto load = [&](int c, MPre& P) {
; #pragma unroll
;     for (int i = 0; i < 2; ++i) {
;       int idx = tid + 256 * i, j = idx >> 5, q = idx & 31;
;       int ii = pos2i(c * 16 + j, dir);
;       P.pbq[i] = *(const uint4*)(mbc + ((size_t)b * TPB + ii) * 512 + (q < 16 ? 0 : 256) + gp * 128 + (q & 15) * 8);
;     }
;     {
;       int pos = c * 16 + xj, ii = pos2i(pos, dir);
;       size_t tok = (size_t)b * TPB + ii;
;       const bf16_t* prw = w.pC + tok * SPC;
;       bool hp = (ii != 0) && (ii != CTXL), hn = (ii != CTXL - 1) && (ii != TPB - 1);
;       P.px[0] = prw[chX + (hp ? -SPC : 0)]; P.px[1] = prw[chX]; P.px[2] = prw[chX + (hn ? SPC : 0)];
;       P.pxm[0] = hp ? 1.f : 0.f; P.pxm[1] = hn ? 1.f : 0.f;
;       float2 dd = *(const float2*)(w.mdt + (tok * 16 + dir * 8 + hd) * 2);
;       P.pdt[0] = dd.x; P.pdt[1] = dd.y; P.pdt[2] = w.mcb[tok * 2 + gp];
;     }
;     ...
;   auto stage = [&](const MPre& P, float* bufp) {
; #pragma unroll
;     for (int i = 0; i < 2; ++i) {
;       int idx = tid + 256 * i, j = idx >> 5, q = idx & 31;
;       float f[8];
;       unpack8(P.pbq[i], f);
;       float* d = bufp + (q < 16 ? 0 : 2048) + j * 128 + (q & 15) * 8;
;       *(float4*)d = make_float4(f[0], f[1], f[2], f[3]);
;       *(float4*)(d + 4) = make_float4(f[4], f[5], f[6], f[7]);
;     }
;     {
;       float xs = siluf(wX0 * P.pxm[0] * bf2f(P.px[0]) + wX1 * bf2f(P.px[1]) + wX2 * P.pxm[1] * bf2f(P.px[2]) + bX);
;       bufp[4096 + xj * 16 + xp] = xs * P.pdt[0];
;       bufp[4096 + 256 + xj * 16 + xp] = Dsk * xs;
;       if (xp == 0) *(float4*)(bufp + 4096 + 512 + xj * 4) = make_float4(P.pdt[1], P.pdt[2], 0.f, 0.f);
;     }
;   };
	v_pk_mul_f32 v[90:91], v[44:45], v[90:91]
	v_pk_fma_f32 v[46:47], v[106:107], v[8:9], v[46:47] op_sel_hi:[1,0,1]
	v_pk_fma_f32 v[40:41], v[104:105], v[8:9], v[40:41] op_sel_hi:[1,0,1]
	v_pk_fma_f32 v[88:89], v[42:43], v[88:89], v[90:91]
	s_waitcnt lgkmcnt(3)
	v_pk_mul_f32 v[90:91], v[46:47], v[94:95]
	v_add_f32_e32 v102, v119, v102
	v_pk_fma_f32 v[90:91], v[40:41], v[92:93], v[90:91]
	ds_write_b32 v78, v102 offset:37376
	v_pk_add_f32 v[88:89], v[88:89], v[90:91]
	v_lshlrev_b32_e32 v90, 16, v5
	v_add_f32_e32 v8, v88, v89
	v_lshlrev_b32_e32 v88, 16, v4
	v_and_b32_e32 v89, 0xffff0000, v4
	v_add_f32_dpp v8, v8, v8 quad_perm:[1,0,3,2] row_mask:0xf bank_mask:0xf bound_ctrl:1
	v_and_b32_e32 v91, 0xffff0000, v5
	v_lshlrev_b32_e32 v4, 16, v6
	v_add_f32_dpp v8, v8, v8 quad_perm:[2,3,0,1] row_mask:0xf bank_mask:0xf bound_ctrl:1
	v_and_b32_e32 v5, 0xffff0000, v6
	v_lshlrev_b32_e32 v6, 16, v7
	v_add_f32_dpp v8, v8, v8 row_half_mirror row_mask:0xf bank_mask:0xf bound_ctrl:1
	v_and_b32_e32 v7, 0xffff0000, v7
	s_nop 0
	v_add_f32_dpp v8, v8, v8 row_mirror row_mask:0xf bank_mask:0xf bound_ctrl:1
	s_waitcnt lgkmcnt(1)
	v_mul_f32_e32 v8, v38, v8
	v_fmac_f32_e32 v8, v16, v39
	v_add_f32_e32 v8, v116, v8
	ds_write_b32 v80, v8 offset:37376
	ds_write_b128 v58, v[88:91] offset:18688
	ds_write_b128 v58, v[4:7] offset:18704
	v_lshlrev_b32_e32 v4, 16, v0
	v_and_b32_e32 v5, 0xffff0000, v0
	v_lshlrev_b32_e32 v6, 16, v1
	v_and_b32_e32 v7, 0xffff0000, v1
	v_mul_f32_e32 v0, v49, v87
	v_lshlrev_b32_e32 v1, 16, v64
	v_mul_f32_e32 v0, v0, v1
	v_lshlrev_b32_e32 v1, 16, v69
	v_fmac_f32_e32 v0, v50, v1
	v_mul_f32_e32 v1, v51, v86
	v_lshlrev_b32_e32 v8, 16, v79
	v_fmac_f32_e32 v0, v1, v8
	v_add_f32_e32 v8, v52, v0
	v_mul_f32_e32 v0, 0xbfb8aa3b, v8
	v_exp_f32_e32 v39, v0
	v_lshlrev_b32_e32 v0, 16, v2
	v_and_b32_e32 v1, 0xffff0000, v2
	v_lshlrev_b32_e32 v2, 16, v3
	v_add_f32_e32 v39, 1.0, v39
	v_rcp_f32_e32 v39, v39
	v_and_b32_e32 v3, 0xffff0000, v3
	ds_write_b128 v58, v[4:7] offset:22784
	ds_write_b128 v58, v[0:3] offset:22800
	v_mul_f32_e32 v0, v8, v39
	v_mul_f32_e32 v1, v10, v0
	v_mul_f32_e32 v0, v53, v0
	ds_write2st64_b32 v57, v1, v0 offset0:137 offset1:141
	s_and_saveexec_b64 s[4:5], vcc
	v_mov_b32_e32 v8, v11
	v_mov_b32_e32 v10, v157
	v_mov_b32_e32 v11, v157
	ds_write_b128 v72, v[8:11] offset:37120
	s_or_b64 exec, exec, s[4:5]
	s_add_i32 s7, s7, 2
	v_pk_mul_f32 v[0:1], v[42:43], v[38:39] op_sel_hi:[1,0]
	s_min_u32 s4, s7, 0x20c
	v_pk_fma_f32 v[108:109], v[26:27], v[16:17], v[0:1] op_sel_hi:[1,0,1]
	v_pk_mul_f32 v[0:1], v[44:45], v[38:39] op_sel_hi:[1,0]
	s_lshl_b32 s4, s4, 4
	v_pk_fma_f32 v[110:111], v[28:29], v[16:17], v[0:1] op_sel_hi:[1,0,1]
	v_pk_mul_f32 v[0:1], v[40:41], v[38:39] op_sel_hi:[1,0]
	s_add_i32 s16, s4, 48
	v_pk_fma_f32 v[112:113], v[22:23], v[16:17], v[0:1] op_sel_hi:[1,0,1]
	v_pk_mul_f32 v[0:1], v[46:47], v[38:39] op_sel_hi:[1,0]
	v_add_u32_e32 v2, s16, v56
	v_pk_fma_f32 v[46:47], v[24:25], v[16:17], v[0:1] op_sel_hi:[1,0,1]
	v_add_u32_e32 v0, s16, v55
	v_cmp_lt_i32_e64 s[4:5], s37, v0
	v_add_u32_e32 v8, s16, v54
	v_cndmask_b32_e64 v87, 1.0, 0, s[42:43]
	v_cndmask_b32_e64 v1, v231, v232, s[4:5]
	v_cmp_lt_i32_e64 s[4:5], s37, v2
	v_sub_u32_e32 v1, v1, v0
	v_cndmask_b32_e64 v0, v1, v0, s[40:41]
	v_cndmask_b32_e64 v3, v231, v232, s[4:5]
	v_cmp_lt_i32_e64 s[4:5], s37, v8
	v_sub_u32_e32 v3, v3, v2
	v_cndmask_b32_e64 v2, v3, v2, s[40:41]
	v_cndmask_b32_e64 v9, v231, v232, s[4:5]
	v_sub_u32_e32 v9, v9, v8
	v_cndmask_b32_e64 v8, v9, v8, s[40:41]
	v_ashrrev_i32_e32 v9, 31, v8
	v_lshl_add_u64 v[10:11], v[8:9], 0, s[90:91]
	v_and_b32_e32 v9, 0xfffffeff, v8
	v_cmp_eq_u32_e64 s[42:43], 0, v9
	v_ashrrev_i32_e32 v1, 31, v0
	v_ashrrev_i32_e32 v3, 31, v2
	v_mov_b64_e32 v[22:23], s[52:53]
	v_and_b32_e32 v16, 0xffffdfff, v8
	v_cndmask_b32_e64 v8, v233, 0, s[42:43]
	v_lshl_add_u64 v[0:1], v[0:1], 0, s[90:91]
	v_lshl_add_u64 v[2:3], v[2:3], 0, s[90:91]
	v_mad_u64_u32 v[22:23], s[4:5], v10, s92, v[22:23]
	v_add_u32_e32 v8, v8, v48
	v_cndmask_b32_e64 v86, 1.0, 0, s[44:45]
	v_lshlrev_b64 v[0:1], 10, v[0:1]
	v_lshlrev_b64 v[2:3], 10, v[2:3]
	v_mad_i32_i24 v23, v11, s92, v23
	v_ashrrev_i32_e32 v9, 31, v8
	v_cmp_eq_u32_e64 s[44:45], s37, v16
	v_lshlrev_b64 v[26:27], 7, v[10:11]
	v_lshl_add_u64 v[0:1], v[30:31], 0, v[0:1]
	v_lshl_add_u64 v[2:3], v[30:31], 0, v[2:3]
	v_lshl_add_u64 v[8:9], v[8:9], 1, v[22:23]
	v_lshl_add_u64 v[22:23], v[22:23], 0, v[156:157]
	v_cndmask_b32_e64 v24, v234, 0, s[44:45]
	v_mov_b32_e32 v25, v157
	v_lshl_or_b32 v26, s6, 3, v26
	s_waitcnt lgkmcnt(0)
	s_barrier
; DI float row16_sum(float v) { v += dppf(v, 0); v += dppf(v, 1); v += dppf(v, 2); v += dppf(v, 3); return v; }
; DI void mamba_scan(CP p, const Ptrs& w, int l, int item, float* sm) {
;     ...
;   auto load = [&](int c, MPre& P) {
; #pragma unroll
;     for (int i = 0; i < 2; ++i) {
;       int idx = tid + 256 * i, j = idx >> 5, q = idx & 31;
;       int ii = pos2i(c * 16 + j, dir);
;       P.pbq[i] = *(const uint4*)(mbc + ((size_t)b * TPB + ii) * 512 + (q < 16 ? 0 : 256) + gp * 128 + (q & 15) * 8);
;     }
;     {
;       int pos = c * 16 + xj, ii = pos2i(pos, dir);
;       size_t tok = (size_t)b * TPB + ii;
;       const bf16_t* prw = w.pC + tok * SPC;
;       bool hp = (ii != 0) && (ii != CTXL), hn = (ii != CTXL - 1) && (ii != TPB - 1);
;       P.px[0] = prw[chX + (hp ? -SPC : 0)]; P.px[1] = prw[chX]; P.px[2] = prw[chX + (hn ? SPC : 0)];
;       P.pxm[0] = hp ? 1.f : 0.f; P.pxm[1] = hn ? 1.f : 0.f;
;       float2 dd = *(const float2*)(w.mdt + (tok * 16 + dir * 8 + hd) * 2);
;       P.pdt[0] = dd.x; P.pdt[1] = dd.y; P.pdt[2] = w.mcb[tok * 2 + gp];
;     }
;     ...
;   auto flush = [&](int c) {
;     {
;       int j = tid >> 4, rr = tid & 15;
;       int ii = pos2i(c * 16 + j, dir);
;       yout[((size_t)b * TPB + ii) * 512 + hd * 64 + pq * 16 + rr] = f2bf(sY[(c & 1) * 256 + j * 16 + rr]);
;     }
;   };
;   __syncthreads();
;   load(0, PA);
;   stage(PA, sm);
;   load(1, PB);
;   __syncthreads();
;   const int NCH = TPB / 16;
;   auto run_chunk = [&](int c, const float* bf, float* sy) {
;     flush(max(c - 1, 0));
;     MStep cur = lds_step(bf, 0);
; #pragma unroll
;     for (int j = 0; j < 16; ++j) {
;       MStep nxt = cur;
;       if (j + 1 < 16) nxt = lds_step(bf, j + 1);
;       f2v ya = M0 * cur.C0.xy + M1 * cur.C0.zw, yb = M2 * cur.C1.xy + M3 * cur.C1.zw;
;       ya += yb;
;       float yp = row16_sum(ya.x + ya.y);
;       float y = cur.sc.x * yp + cur.xq * cur.sc.y + cur.ds;
;       const float dA = cur.sc.x, xq = cur.xq;
;       M0 = M0 * dA + xq * cur.B0.xy; M1 = M1 * dA + xq * cur.B0.zw;
;       M2 = M2 * dA + xq * cur.B1.xy; M3 = M3 * dA + xq * cur.B1.zw;
;       sy[(ng == 0 ? j * 16 : 0) + ysel] = y;
;       cur = nxt;
;     }
;   };
	global_load_dwordx4 v[4:7], v[0:1], off
	s_nop 0
	global_load_dwordx4 v[0:3], v[2:3], off
	v_lshl_add_u64 v[24:25], v[22:23], 0, v[24:25]
	v_lshl_add_u64 v[26:27], s[38:39], 0, v[26:27]
	v_lshl_add_u64 v[28:29], v[10:11], 3, s[68:69]
	global_load_ushort v64, v[8:9], off
	global_load_ushort v69, v[22:23], off
	global_load_ushort v79, v[24:25], off
	global_load_dwordx2 v[10:11], v[26:27], off
	s_nop 0
	global_load_dword v9, v[28:29], off
	v_cmp_lt_i32_e64 s[4:5], s37, v82
	ds_read_b32 v8, v57 offset:37376
	ds_read_b128 v[22:25], v59 offset:18688
	v_cndmask_b32_e64 v16, v231, v232, s[4:5]
	v_add_u32_e32 v16, v16, v81
	v_cndmask_b32_e64 v26, v16, v82, s[40:41]
	v_ashrrev_i32_e32 v27, 31, v26
	v_lshl_add_u64 v[26:27], v[26:27], 0, s[90:91]
	v_lshlrev_b64 v[26:27], 10, v[26:27]
	s_waitcnt lgkmcnt(1)
	v_cvt_pk_bf16_f32 v8, v8, s0
	v_lshl_add_u64 v[26:27], v[34:35], 0, v[26:27]
	global_store_short v[26:27], v8, off
	v_add_u32_e32 v8, 0x8800, v60
	ds_read2_b32 v[114:115], v8 offset0:64 offset1:80
	v_add_u32_e32 v8, 0x8c00, v60
	s_mov_b32 s4, 0x9000
	ds_read2_b32 v[116:117], v8 offset0:64 offset1:80
	v_add_u32_e64 v8, s4, 0
	ds_read2_b64 v[26:29], v8 offset0:32 offset1:34
	ds_read_b128 v[38:41], v59 offset:18704
	ds_read_b128 v[42:45], v59 offset:19200
	ds_read_b128 v[88:91], v59 offset:26880
	ds_read_b128 v[92:95], v59 offset:19216
	ds_read_b128 v[96:99], v59 offset:26896
	ds_read_b128 v[100:103], v59 offset:27392
	ds_read_b128 v[104:107], v59 offset:27408
	s_waitcnt lgkmcnt(4)
	v_pk_mul_f32 v[90:91], v[110:111], v[90:91]
	s_nop 0
	v_pk_fma_f32 v[88:89], v[108:109], v[88:89], v[90:91]
	s_waitcnt lgkmcnt(2)
	v_pk_mul_f32 v[90:91], v[46:47], v[98:99]
	s_nop 0
	v_pk_fma_f32 v[90:91], v[112:113], v[96:97], v[90:91]
	s_nop 0
	v_pk_add_f32 v[88:89], v[88:89], v[90:91]
	s_nop 0
	v_add_f32_e32 v8, v88, v89
	v_pk_mul_f32 v[88:89], v[108:109], v[26:27] op_sel_hi:[1,0]
	s_nop 0
	v_add_f32_dpp v8, v8, v8 quad_perm:[1,0,3,2] row_mask:0xf bank_mask:0xf bound_ctrl:1
	v_pk_fma_f32 v[108:109], v[22:23], v[114:115], v[88:89] op_sel_hi:[1,0,1]
	v_pk_mul_f32 v[22:23], v[110:111], v[26:27] op_sel_hi:[1,0]
	v_add_f32_dpp v8, v8, v8 quad_perm:[2,3,0,1] row_mask:0xf bank_mask:0xf bound_ctrl:1
	v_pk_fma_f32 v[110:111], v[24:25], v[114:115], v[22:23] op_sel_hi:[1,0,1]
	v_pk_mul_f32 v[22:23], v[112:113], v[26:27] op_sel_hi:[1,0]
	v_add_f32_dpp v8, v8, v8 row_half_mirror row_mask:0xf bank_mask:0xf bound_ctrl:1
	v_pk_fma_f32 v[112:113], v[38:39], v[114:115], v[22:23] op_sel_hi:[1,0,1]
	v_pk_mul_f32 v[22:23], v[46:47], v[26:27] op_sel_hi:[1,0]
	v_add_f32_dpp v8, v8, v8 row_mirror row_mask:0xf bank_mask:0xf bound_ctrl:1
	v_mul_f32_e32 v8, v26, v8
	v_fmac_f32_e32 v8, v114, v27
	v_pk_fma_f32 v[26:27], v[40:41], v[114:115], v[22:23] op_sel_hi:[1,0,1]
	s_waitcnt lgkmcnt(1)
	v_pk_mul_f32 v[102:103], v[110:111], v[102:103]
	v_add_f32_e32 v8, v116, v8
	v_pk_fma_f32 v[100:101], v[108:109], v[100:101], v[102:103]
	s_waitcnt lgkmcnt(0)
	v_pk_mul_f32 v[102:103], v[26:27], v[106:107]
	ds_write_b32 v61, v8 offset:38400
	v_pk_fma_f32 v[102:103], v[112:113], v[104:105], v[102:103]
	ds_read_b128 v[22:25], v59 offset:19712
	ds_read_b128 v[38:41], v59 offset:19728
	ds_read_b128 v[88:91], v59 offset:27904
	ds_read_b128 v[96:99], v59 offset:27920
	ds_read_b32 v8, v60 offset:35200
	ds_read_b32 v114, v60 offset:36224
	ds_read_b64 v[46:47], v157 offset:37152
	v_pk_add_f32 v[100:101], v[100:101], v[102:103]
	v_pk_mul_f32 v[26:27], v[26:27], v[28:29] op_sel_hi:[1,0]
	v_add_f32_e32 v16, v100, v101
	v_pk_mul_f32 v[100:101], v[108:109], v[28:29] op_sel_hi:[1,0]
	s_nop 0
	v_add_f32_dpp v16, v16, v16 quad_perm:[1,0,3,2] row_mask:0xf bank_mask:0xf bound_ctrl:1
	s_nop 1
	v_add_f32_dpp v16, v16, v16 quad_perm:[2,3,0,1] row_mask:0xf bank_mask:0xf bound_ctrl:1
	s_nop 1
	v_add_f32_dpp v16, v16, v16 row_half_mirror row_mask:0xf bank_mask:0xf bound_ctrl:1
	s_nop 1
	v_add_f32_dpp v16, v16, v16 row_mirror row_mask:0xf bank_mask:0xf bound_ctrl:1
	v_mul_f32_e32 v16, v28, v16
	v_fmac_f32_e32 v16, v115, v29
	v_add_f32_e32 v102, v117, v16
	v_mov_b32_e32 v16, v115
	v_pk_fma_f32 v[104:105], v[42:43], v[16:17], v[100:101] op_sel_hi:[1,0,1]
	v_pk_mul_f32 v[42:43], v[110:111], v[28:29] op_sel_hi:[1,0]
	v_pk_fma_f32 v[110:111], v[94:95], v[16:17], v[26:27] op_sel_hi:[1,0,1]
	v_pk_fma_f32 v[106:107], v[44:45], v[16:17], v[42:43] op_sel_hi:[1,0,1]
	v_pk_mul_f32 v[42:43], v[112:113], v[28:29] op_sel_hi:[1,0]
	s_waitcnt lgkmcnt(4)
	v_pk_mul_f32 v[90:91], v[106:107], v[90:91]
	v_pk_fma_f32 v[108:109], v[92:93], v[16:17], v[42:43] op_sel_hi:[1,0,1]
	v_pk_fma_f32 v[88:89], v[104:105], v[88:89], v[90:91]
	s_waitcnt lgkmcnt(3)
	v_pk_mul_f32 v[90:91], v[110:111], v[98:99]
	ds_write_b32 v62, v102 offset:38400
	v_pk_fma_f32 v[90:91], v[108:109], v[96:97], v[90:91]
	ds_read_b128 v[26:29], v59 offset:20224
	ds_read_b128 v[42:45], v59 offset:20240
	ds_read_b128 v[92:95], v59 offset:28416
	ds_read_b128 v[100:103], v59 offset:28432
	ds_read_b32 v16, v60 offset:35264
	ds_read_b32 v115, v60 offset:36288
	ds_read_b64 v[112:113], v157 offset:37168
	v_pk_add_f32 v[88:89], v[88:89], v[90:91]
	s_nop 0
	v_add_f32_e32 v88, v88, v89
	s_nop 1
	v_add_f32_dpp v88, v88, v88 quad_perm:[1,0,3,2] row_mask:0xf bank_mask:0xf bound_ctrl:1
	s_nop 1
	v_add_f32_dpp v88, v88, v88 quad_perm:[2,3,0,1] row_mask:0xf bank_mask:0xf bound_ctrl:1
	s_nop 1
	v_add_f32_dpp v88, v88, v88 row_half_mirror row_mask:0xf bank_mask:0xf bound_ctrl:1
	s_nop 1
	v_add_f32_dpp v88, v88, v88 row_mirror row_mask:0xf bank_mask:0xf bound_ctrl:1
	s_waitcnt lgkmcnt(8)
	v_mul_f32_e32 v88, v46, v88
	v_fmac_f32_e32 v88, v8, v47
	v_add_f32_e32 v90, v114, v88
	v_pk_mul_f32 v[88:89], v[104:105], v[46:47] op_sel_hi:[1,0]
	ds_write_b32 v63, v90 offset:38400
	s_waitcnt vmcnt(1)
; DI float row16_sum(float v) { v += dppf(v, 0); v += dppf(v, 1); v += dppf(v, 2); v += dppf(v, 3); return v; }
; DI void mamba_scan(CP p, const Ptrs& w, int l, int item, float* sm) {
;     ...
;   auto lds_step = [&](const float* bf, int j) {
;     MStep q;
;     q.B0 = *(const f4v*)(bf + j * 128 + 8 * ng); q.B1 = *(const f4v*)(bf + j * 128 + 8 * ng + 4);
;     q.C0 = *(const f4v*)(bf + 2048 + j * 128 + 8 * ng); q.C1 = *(const f4v*)(bf + 2048 + j * 128 + 8 * ng + 4);
;     q.xq = bf[4096 + j * 16 + prow]; q.ds = bf[4096 + 256 + j * 16 + prow];
;     q.sc = *(const float4*)(bf + 4096 + 512 + j * 4);
;     return q;
;     ...
;   auto run_chunk = [&](int c, const float* bf, float* sy) {
;     flush(max(c - 1, 0));
;     MStep cur = lds_step(bf, 0);
; #pragma unroll
;     for (int j = 0; j < 16; ++j) {
;       MStep nxt = cur;
;       if (j + 1 < 16) nxt = lds_step(bf, j + 1);
;       f2v ya = M0 * cur.C0.xy + M1 * cur.C0.zw, yb = M2 * cur.C1.xy + M3 * cur.C1.zw;
;       ya += yb;
;       float yp = row16_sum(ya.x + ya.y);
;       float y = cur.sc.x * yp + cur.xq * cur.sc.y + cur.ds;
;       const float dA = cur.sc.x, xq = cur.xq;
;       M0 = M0 * dA + xq * cur.B0.xy; M1 = M1 * dA + xq * cur.B0.zw;
;       M2 = M2 * dA + xq * cur.B1.xy; M3 = M3 * dA + xq * cur.B1.zw;
;       sy[(ng == 0 ? j * 16 : 0) + ysel] = y;
;       cur = nxt;
;     }
;   };
	v_pk_fma_f32 v[104:105], v[22:23], v[8:9], v[88:89] op_sel_hi:[1,0,1]
	v_pk_mul_f32 v[22:23], v[106:107], v[46:47] op_sel_hi:[1,0]
	s_nop 0
	v_pk_fma_f32 v[106:107], v[24:25], v[8:9], v[22:23] op_sel_hi:[1,0,1]
	v_pk_mul_f32 v[22:23], v[108:109], v[46:47] op_sel_hi:[1,0]
	s_waitcnt lgkmcnt(5)
	v_pk_mul_f32 v[94:95], v[106:107], v[94:95]
	v_pk_fma_f32 v[108:109], v[38:39], v[8:9], v[22:23] op_sel_hi:[1,0,1]
	v_pk_mul_f32 v[22:23], v[110:111], v[46:47] op_sel_hi:[1,0]
	v_pk_fma_f32 v[92:93], v[104:105], v[92:93], v[94:95]
	v_pk_fma_f32 v[46:47], v[40:41], v[8:9], v[22:23] op_sel_hi:[1,0,1]
	ds_read_b128 v[22:25], v59 offset:20736
	ds_read_b128 v[38:41], v59 offset:20752
	ds_read_b128 v[88:91], v59 offset:28928
	ds_read_b128 v[96:99], v59 offset:28944
	ds_read_b32 v8, v60 offset:35328
	ds_read_b32 v114, v60 offset:36352
	ds_read_b64 v[110:111], v157 offset:37184
	s_waitcnt lgkmcnt(11)
	v_pk_mul_f32 v[94:95], v[46:47], v[102:103]
	s_nop 0
	v_pk_fma_f32 v[94:95], v[108:109], v[100:101], v[94:95]
	s_nop 0
	v_pk_add_f32 v[92:93], v[92:93], v[94:95]
	s_nop 0
	v_add_f32_e32 v92, v92, v93
	s_nop 1
	v_add_f32_dpp v92, v92, v92 quad_perm:[1,0,3,2] row_mask:0xf bank_mask:0xf bound_ctrl:1
	s_nop 1
	v_add_f32_dpp v92, v92, v92 quad_perm:[2,3,0,1] row_mask:0xf bank_mask:0xf bound_ctrl:1
	s_nop 1
	v_add_f32_dpp v92, v92, v92 row_half_mirror row_mask:0xf bank_mask:0xf bound_ctrl:1
	s_nop 1
	v_add_f32_dpp v92, v92, v92 row_mirror row_mask:0xf bank_mask:0xf bound_ctrl:1
	s_waitcnt lgkmcnt(8)
	v_mul_f32_e32 v92, v112, v92
	v_fmac_f32_e32 v92, v16, v113
	v_add_f32_e32 v94, v115, v92
	v_pk_mul_f32 v[92:93], v[104:105], v[112:113] op_sel_hi:[1,0]
	ds_write_b32 v65, v94 offset:38400
	v_pk_fma_f32 v[104:105], v[26:27], v[16:17], v[92:93] op_sel_hi:[1,0,1]
	v_pk_mul_f32 v[26:27], v[106:107], v[112:113] op_sel_hi:[1,0]
	s_nop 0
	v_pk_fma_f32 v[106:107], v[28:29], v[16:17], v[26:27] op_sel_hi:[1,0,1]
	v_pk_mul_f32 v[26:27], v[108:109], v[112:113] op_sel_hi:[1,0]
	s_waitcnt lgkmcnt(5)
	v_pk_mul_f32 v[90:91], v[106:107], v[90:91]
	v_pk_fma_f32 v[108:109], v[42:43], v[16:17], v[26:27] op_sel_hi:[1,0,1]
	v_pk_mul_f32 v[26:27], v[46:47], v[112:113] op_sel_hi:[1,0]
	v_pk_fma_f32 v[88:89], v[104:105], v[88:89], v[90:91]
	v_pk_fma_f32 v[46:47], v[44:45], v[16:17], v[26:27] op_sel_hi:[1,0,1]
	ds_read_b128 v[26:29], v59 offset:21248
	ds_read_b128 v[42:45], v59 offset:21264
	ds_read_b128 v[92:95], v59 offset:29440
	ds_read_b128 v[100:103], v59 offset:29456
	ds_read_b32 v16, v60 offset:35392
	ds_read_b32 v115, v60 offset:36416
	ds_read_b64 v[112:113], v157 offset:37200
	s_waitcnt lgkmcnt(11)
	v_pk_mul_f32 v[90:91], v[46:47], v[98:99]
	s_nop 0
	v_pk_fma_f32 v[90:91], v[108:109], v[96:97], v[90:91]
	s_nop 0
	v_pk_add_f32 v[88:89], v[88:89], v[90:91]
	s_nop 0
	v_add_f32_e32 v88, v88, v89
	s_nop 1
	v_add_f32_dpp v88, v88, v88 quad_perm:[1,0,3,2] row_mask:0xf bank_mask:0xf bound_ctrl:1
	s_nop 1
	v_add_f32_dpp v88, v88, v88 quad_perm:[2,3,0,1] row_mask:0xf bank_mask:0xf bound_ctrl:1
	s_nop 1
	v_add_f32_dpp v88, v88, v88 row_half_mirror row_mask:0xf bank_mask:0xf bound_ctrl:1
	s_nop 1
	v_add_f32_dpp v88, v88, v88 row_mirror row_mask:0xf bank_mask:0xf bound_ctrl:1
	s_waitcnt lgkmcnt(8)
	v_mul_f32_e32 v88, v110, v88
	v_fmac_f32_e32 v88, v8, v111
	v_add_f32_e32 v90, v114, v88
	v_pk_mul_f32 v[88:89], v[104:105], v[110:111] op_sel_hi:[1,0]
	ds_write_b32 v66, v90 offset:38400
	v_pk_fma_f32 v[104:105], v[22:23], v[8:9], v[88:89] op_sel_hi:[1,0,1]
	v_pk_mul_f32 v[22:23], v[106:107], v[110:111] op_sel_hi:[1,0]
	s_nop 0
	v_pk_fma_f32 v[106:107], v[24:25], v[8:9], v[22:23] op_sel_hi:[1,0,1]
	v_pk_mul_f32 v[22:23], v[108:109], v[110:111] op_sel_hi:[1,0]
	s_waitcnt lgkmcnt(5)
	v_pk_mul_f32 v[94:95], v[106:107], v[94:95]
	v_pk_fma_f32 v[108:109], v[38:39], v[8:9], v[22:23] op_sel_hi:[1,0,1]
	v_pk_mul_f32 v[22:23], v[46:47], v[110:111] op_sel_hi:[1,0]
	v_pk_fma_f32 v[92:93], v[104:105], v[92:93], v[94:95]
	v_pk_fma_f32 v[46:47], v[40:41], v[8:9], v[22:23] op_sel_hi:[1,0,1]
	ds_read_b128 v[22:25], v59 offset:21760
	ds_read_b128 v[38:41], v59 offset:21776
	ds_read_b128 v[88:91], v59 offset:29952
	ds_read_b128 v[96:99], v59 offset:29968
	ds_read_b32 v8, v60 offset:35456
	ds_read_b32 v114, v60 offset:36480
	ds_read_b64 v[110:111], v157 offset:37216
	s_waitcnt lgkmcnt(11)
	v_pk_mul_f32 v[94:95], v[46:47], v[102:103]
	s_nop 0
	v_pk_fma_f32 v[94:95], v[108:109], v[100:101], v[94:95]
	s_nop 0
	v_pk_add_f32 v[92:93], v[92:93], v[94:95]
	s_nop 0
	v_add_f32_e32 v92, v92, v93
	s_nop 1
	v_add_f32_dpp v92, v92, v92 quad_perm:[1,0,3,2] row_mask:0xf bank_mask:0xf bound_ctrl:1
	s_nop 1
	v_add_f32_dpp v92, v92, v92 quad_perm:[2,3,0,1] row_mask:0xf bank_mask:0xf bound_ctrl:1
	s_nop 1
	v_add_f32_dpp v92, v92, v92 row_half_mirror row_mask:0xf bank_mask:0xf bound_ctrl:1
	s_nop 1
	v_add_f32_dpp v92, v92, v92 row_mirror row_mask:0xf bank_mask:0xf bound_ctrl:1
	s_waitcnt lgkmcnt(8)
	v_mul_f32_e32 v92, v112, v92
	v_fmac_f32_e32 v92, v16, v113
	v_add_f32_e32 v94, v115, v92
	v_pk_mul_f32 v[92:93], v[104:105], v[112:113] op_sel_hi:[1,0]
	ds_write_b32 v67, v94 offset:38400
	v_pk_fma_f32 v[104:105], v[26:27], v[16:17], v[92:93] op_sel_hi:[1,0,1]
	v_pk_mul_f32 v[26:27], v[106:107], v[112:113] op_sel_hi:[1,0]
	s_nop 0
	v_pk_fma_f32 v[106:107], v[28:29], v[16:17], v[26:27] op_sel_hi:[1,0,1]
	v_pk_mul_f32 v[26:27], v[108:109], v[112:113] op_sel_hi:[1,0]
	s_waitcnt lgkmcnt(5)
; DI float row16_sum(float v) { v += dppf(v, 0); v += dppf(v, 1); v += dppf(v, 2); v += dppf(v, 3); return v; }
; DI void mamba_scan(CP p, const Ptrs& w, int l, int item, float* sm) {
;     ...
;   auto lds_step = [&](const float* bf, int j) {
;     MStep q;
;     q.B0 = *(const f4v*)(bf + j * 128 + 8 * ng); q.B1 = *(const f4v*)(bf + j * 128 + 8 * ng + 4);
;     q.C0 = *(const f4v*)(bf + 2048 + j * 128 + 8 * ng); q.C1 = *(const f4v*)(bf + 2048 + j * 128 + 8 * ng + 4);
;     q.xq = bf[4096 + j * 16 + prow]; q.ds = bf[4096 + 256 + j * 16 + prow];
;     q.sc = *(const float4*)(bf + 4096 + 512 + j * 4);
;     return q;
;     ...
;   auto run_chunk = [&](int c, const float* bf, float* sy) {
;     flush(max(c - 1, 0));
;     MStep cur = lds_step(bf, 0);
; #pragma unroll
;     for (int j = 0; j < 16; ++j) {
;       MStep nxt = cur;
;       if (j + 1 < 16) nxt = lds_step(bf, j + 1);
;       f2v ya = M0 * cur.C0.xy + M1 * cur.C0.zw, yb = M2 * cur.C1.xy + M3 * cur.C1.zw;
;       ya += yb;
;       float yp = row16_sum(ya.x + ya.y);
;       float y = cur.sc.x * yp + cur.xq * cur.sc.y + cur.ds;
;       const float dA = cur.sc.x, xq = cur.xq;
;       M0 = M0 * dA + xq * cur.B0.xy; M1 = M1 * dA + xq * cur.B0.zw;
;       M2 = M2 * dA + xq * cur.B1.xy; M3 = M3 * dA + xq * cur.B1.zw;
;       sy[(ng == 0 ? j * 16 : 0) + ysel] = y;
;       cur = nxt;
;     }
;   };
	v_pk_mul_f32 v[90:91], v[106:107], v[90:91]
	v_pk_fma_f32 v[108:109], v[42:43], v[16:17], v[26:27] op_sel_hi:[1,0,1]
	v_pk_mul_f32 v[26:27], v[46:47], v[112:113] op_sel_hi:[1,0]
	v_pk_fma_f32 v[88:89], v[104:105], v[88:89], v[90:91]
	v_pk_fma_f32 v[46:47], v[44:45], v[16:17], v[26:27] op_sel_hi:[1,0,1]
	ds_read_b128 v[26:29], v59 offset:22272
	ds_read_b128 v[42:45], v59 offset:22288
	ds_read_b128 v[92:95], v59 offset:30464
	ds_read_b128 v[100:103], v59 offset:30480
	ds_read_b32 v16, v60 offset:35520
	ds_read_b32 v115, v60 offset:36544
	ds_read_b64 v[112:113], v157 offset:37232
	s_waitcnt lgkmcnt(11)
	v_pk_mul_f32 v[90:91], v[46:47], v[98:99]
	s_nop 0
	v_pk_fma_f32 v[90:91], v[108:109], v[96:97], v[90:91]
	s_nop 0
	v_pk_add_f32 v[88:89], v[88:89], v[90:91]
	s_nop 0
	v_add_f32_e32 v88, v88, v89
	s_nop 1
	v_add_f32_dpp v88, v88, v88 quad_perm:[1,0,3,2] row_mask:0xf bank_mask:0xf bound_ctrl:1
	s_nop 1
	v_add_f32_dpp v88, v88, v88 quad_perm:[2,3,0,1] row_mask:0xf bank_mask:0xf bound_ctrl:1
	s_nop 1
	v_add_f32_dpp v88, v88, v88 row_half_mirror row_mask:0xf bank_mask:0xf bound_ctrl:1
	s_nop 1
	v_add_f32_dpp v88, v88, v88 row_mirror row_mask:0xf bank_mask:0xf bound_ctrl:1
	s_waitcnt lgkmcnt(8)
	v_mul_f32_e32 v88, v110, v88
	v_fmac_f32_e32 v88, v8, v111
	v_add_f32_e32 v90, v114, v88
	v_pk_mul_f32 v[88:89], v[104:105], v[110:111] op_sel_hi:[1,0]
	ds_write_b32 v68, v90 offset:38400
	v_pk_fma_f32 v[104:105], v[22:23], v[8:9], v[88:89] op_sel_hi:[1,0,1]
	v_pk_mul_f32 v[22:23], v[106:107], v[110:111] op_sel_hi:[1,0]
	s_nop 0
	v_pk_fma_f32 v[106:107], v[24:25], v[8:9], v[22:23] op_sel_hi:[1,0,1]
	v_pk_mul_f32 v[22:23], v[108:109], v[110:111] op_sel_hi:[1,0]
	s_waitcnt lgkmcnt(5)
	v_pk_mul_f32 v[94:95], v[106:107], v[94:95]
	v_pk_fma_f32 v[108:109], v[38:39], v[8:9], v[22:23] op_sel_hi:[1,0,1]
	v_pk_mul_f32 v[22:23], v[46:47], v[110:111] op_sel_hi:[1,0]
	v_pk_fma_f32 v[92:93], v[104:105], v[92:93], v[94:95]
	v_pk_fma_f32 v[46:47], v[40:41], v[8:9], v[22:23] op_sel_hi:[1,0,1]
	ds_read_b128 v[22:25], v59 offset:22784
	ds_read_b128 v[38:41], v59 offset:22800
	ds_read_b128 v[88:91], v59 offset:30976
	ds_read_b128 v[96:99], v59 offset:30992
	ds_read_b32 v8, v60 offset:35584
	ds_read_b32 v114, v60 offset:36608
	ds_read_b64 v[110:111], v157 offset:37248
	s_waitcnt lgkmcnt(11)
	v_pk_mul_f32 v[94:95], v[46:47], v[102:103]
	s_nop 0
	v_pk_fma_f32 v[94:95], v[108:109], v[100:101], v[94:95]
	s_nop 0
	v_pk_add_f32 v[92:93], v[92:93], v[94:95]
	s_nop 0
	v_add_f32_e32 v92, v92, v93
	s_nop 1
	v_add_f32_dpp v92, v92, v92 quad_perm:[1,0,3,2] row_mask:0xf bank_mask:0xf bound_ctrl:1
	s_nop 1
	v_add_f32_dpp v92, v92, v92 quad_perm:[2,3,0,1] row_mask:0xf bank_mask:0xf bound_ctrl:1
	s_nop 1
	v_add_f32_dpp v92, v92, v92 row_half_mirror row_mask:0xf bank_mask:0xf bound_ctrl:1
	s_nop 1
	v_add_f32_dpp v92, v92, v92 row_mirror row_mask:0xf bank_mask:0xf bound_ctrl:1
	s_waitcnt lgkmcnt(8)
	v_mul_f32_e32 v92, v112, v92
	v_fmac_f32_e32 v92, v16, v113
	v_add_f32_e32 v94, v115, v92
	v_pk_mul_f32 v[92:93], v[104:105], v[112:113] op_sel_hi:[1,0]
	ds_write_b32 v70, v94 offset:38400
	v_pk_fma_f32 v[104:105], v[26:27], v[16:17], v[92:93] op_sel_hi:[1,0,1]
	v_pk_mul_f32 v[26:27], v[106:107], v[112:113] op_sel_hi:[1,0]
	s_nop 0
	v_pk_fma_f32 v[106:107], v[28:29], v[16:17], v[26:27] op_sel_hi:[1,0,1]
	v_pk_mul_f32 v[26:27], v[108:109], v[112:113] op_sel_hi:[1,0]
	s_waitcnt lgkmcnt(5)
	v_pk_mul_f32 v[90:91], v[106:107], v[90:91]
	v_pk_fma_f32 v[108:109], v[42:43], v[16:17], v[26:27] op_sel_hi:[1,0,1]
	v_pk_mul_f32 v[26:27], v[46:47], v[112:113] op_sel_hi:[1,0]
	v_pk_fma_f32 v[88:89], v[104:105], v[88:89], v[90:91]
	v_pk_fma_f32 v[46:47], v[44:45], v[16:17], v[26:27] op_sel_hi:[1,0,1]
	ds_read_b128 v[26:29], v59 offset:23296
	ds_read_b128 v[42:45], v59 offset:23312
	ds_read_b128 v[92:95], v59 offset:31488
	ds_read_b128 v[100:103], v59 offset:31504
	ds_read_b32 v16, v60 offset:35648
	ds_read_b32 v115, v60 offset:36672
	ds_read_b64 v[112:113], v157 offset:37264
	s_waitcnt lgkmcnt(11)
	v_pk_mul_f32 v[90:91], v[46:47], v[98:99]
	s_nop 0
	v_pk_fma_f32 v[90:91], v[108:109], v[96:97], v[90:91]
	s_nop 0
	v_pk_add_f32 v[88:89], v[88:89], v[90:91]
	s_nop 0
	v_add_f32_e32 v88, v88, v89
	s_nop 1
	v_add_f32_dpp v88, v88, v88 quad_perm:[1,0,3,2] row_mask:0xf bank_mask:0xf bound_ctrl:1
	s_nop 1
	v_add_f32_dpp v88, v88, v88 quad_perm:[2,3,0,1] row_mask:0xf bank_mask:0xf bound_ctrl:1
	s_nop 1
	v_add_f32_dpp v88, v88, v88 row_half_mirror row_mask:0xf bank_mask:0xf bound_ctrl:1
	s_nop 1
	v_add_f32_dpp v88, v88, v88 row_mirror row_mask:0xf bank_mask:0xf bound_ctrl:1
	s_waitcnt lgkmcnt(8)
	v_mul_f32_e32 v88, v110, v88
	v_fmac_f32_e32 v88, v8, v111
	v_add_f32_e32 v90, v114, v88
	v_pk_mul_f32 v[88:89], v[104:105], v[110:111] op_sel_hi:[1,0]
	ds_write_b32 v71, v90 offset:38400
	v_pk_fma_f32 v[104:105], v[22:23], v[8:9], v[88:89] op_sel_hi:[1,0,1]
	v_pk_mul_f32 v[22:23], v[106:107], v[110:111] op_sel_hi:[1,0]
	s_nop 0
	v_pk_fma_f32 v[106:107], v[24:25], v[8:9], v[22:23] op_sel_hi:[1,0,1]
	v_pk_mul_f32 v[22:23], v[108:109], v[110:111] op_sel_hi:[1,0]
	s_waitcnt lgkmcnt(5)
	v_pk_mul_f32 v[94:95], v[106:107], v[94:95]
	v_pk_fma_f32 v[108:109], v[38:39], v[8:9], v[22:23] op_sel_hi:[1,0,1]
	v_pk_mul_f32 v[22:23], v[46:47], v[110:111] op_sel_hi:[1,0]
	v_pk_fma_f32 v[92:93], v[104:105], v[92:93], v[94:95]
	v_pk_fma_f32 v[46:47], v[40:41], v[8:9], v[22:23] op_sel_hi:[1,0,1]
	ds_read_b128 v[22:25], v59 offset:23808
	ds_read_b128 v[38:41], v59 offset:23824
	ds_read_b128 v[88:91], v59 offset:32000
	ds_read_b128 v[96:99], v59 offset:32016
	ds_read_b32 v8, v60 offset:35712
	ds_read_b32 v114, v60 offset:36736
	ds_read_b64 v[110:111], v157 offset:37280
	s_waitcnt lgkmcnt(11)
; DI float row16_sum(float v) { v += dppf(v, 0); v += dppf(v, 1); v += dppf(v, 2); v += dppf(v, 3); return v; }
; DI void mamba_scan(CP p, const Ptrs& w, int l, int item, float* sm) {
;     ...
;   auto lds_step = [&](const float* bf, int j) {
;     MStep q;
;     q.B0 = *(const f4v*)(bf + j * 128 + 8 * ng); q.B1 = *(const f4v*)(bf + j * 128 + 8 * ng + 4);
;     q.C0 = *(const f4v*)(bf + 2048 + j * 128 + 8 * ng); q.C1 = *(const f4v*)(bf + 2048 + j * 128 + 8 * ng + 4);
;     q.xq = bf[4096 + j * 16 + prow]; q.ds = bf[4096 + 256 + j * 16 + prow];
;     q.sc = *(const float4*)(bf + 4096 + 512 + j * 4);
;     return q;
;     ...
;   auto run_chunk = [&](int c, const float* bf, float* sy) {
;     flush(max(c - 1, 0));
;     MStep cur = lds_step(bf, 0);
; #pragma unroll
;     for (int j = 0; j < 16; ++j) {
;       MStep nxt = cur;
;       if (j + 1 < 16) nxt = lds_step(bf, j + 1);
;       f2v ya = M0 * cur.C0.xy + M1 * cur.C0.zw, yb = M2 * cur.C1.xy + M3 * cur.C1.zw;
;       ya += yb;
;       float yp = row16_sum(ya.x + ya.y);
;       float y = cur.sc.x * yp + cur.xq * cur.sc.y + cur.ds;
;       const float dA = cur.sc.x, xq = cur.xq;
;       M0 = M0 * dA + xq * cur.B0.xy; M1 = M1 * dA + xq * cur.B0.zw;
;       M2 = M2 * dA + xq * cur.B1.xy; M3 = M3 * dA + xq * cur.B1.zw;
;       sy[(ng == 0 ? j * 16 : 0) + ysel] = y;
;       cur = nxt;
;     }
;   };
	v_pk_mul_f32 v[94:95], v[46:47], v[102:103]
	s_nop 0
	v_pk_fma_f32 v[94:95], v[108:109], v[100:101], v[94:95]
	s_nop 0
	v_pk_add_f32 v[92:93], v[92:93], v[94:95]
	s_nop 0
	v_add_f32_e32 v92, v92, v93
	s_nop 1
	v_add_f32_dpp v92, v92, v92 quad_perm:[1,0,3,2] row_mask:0xf bank_mask:0xf bound_ctrl:1
	s_nop 1
	v_add_f32_dpp v92, v92, v92 quad_perm:[2,3,0,1] row_mask:0xf bank_mask:0xf bound_ctrl:1
	s_nop 1
	v_add_f32_dpp v92, v92, v92 row_half_mirror row_mask:0xf bank_mask:0xf bound_ctrl:1
	s_nop 1
	v_add_f32_dpp v92, v92, v92 row_mirror row_mask:0xf bank_mask:0xf bound_ctrl:1
	s_waitcnt lgkmcnt(8)
	v_mul_f32_e32 v92, v112, v92
	v_fmac_f32_e32 v92, v16, v113
	v_add_f32_e32 v94, v115, v92
	v_pk_mul_f32 v[92:93], v[104:105], v[112:113] op_sel_hi:[1,0]
	ds_write_b32 v73, v94 offset:38400
	v_pk_fma_f32 v[104:105], v[26:27], v[16:17], v[92:93] op_sel_hi:[1,0,1]
	v_pk_mul_f32 v[26:27], v[106:107], v[112:113] op_sel_hi:[1,0]
	s_nop 0
	v_pk_fma_f32 v[106:107], v[28:29], v[16:17], v[26:27] op_sel_hi:[1,0,1]
	v_pk_mul_f32 v[26:27], v[108:109], v[112:113] op_sel_hi:[1,0]
	s_waitcnt lgkmcnt(5)
	v_pk_mul_f32 v[90:91], v[106:107], v[90:91]
	v_pk_fma_f32 v[108:109], v[42:43], v[16:17], v[26:27] op_sel_hi:[1,0,1]
	v_pk_mul_f32 v[26:27], v[46:47], v[112:113] op_sel_hi:[1,0]
	v_pk_fma_f32 v[88:89], v[104:105], v[88:89], v[90:91]
	v_pk_fma_f32 v[46:47], v[44:45], v[16:17], v[26:27] op_sel_hi:[1,0,1]
	ds_read_b128 v[26:29], v59 offset:24320
	ds_read_b128 v[42:45], v59 offset:24336
	ds_read_b128 v[92:95], v59 offset:32512
	ds_read_b128 v[100:103], v59 offset:32528
	ds_read_b32 v16, v60 offset:35776
	ds_read_b32 v115, v60 offset:36800
	ds_read_b64 v[112:113], v157 offset:37296
	s_waitcnt lgkmcnt(11)
	v_pk_mul_f32 v[90:91], v[46:47], v[98:99]
	s_nop 0
	v_pk_fma_f32 v[90:91], v[108:109], v[96:97], v[90:91]
	s_nop 0
	v_pk_add_f32 v[88:89], v[88:89], v[90:91]
	s_nop 0
	v_add_f32_e32 v88, v88, v89
	s_nop 1
	v_add_f32_dpp v88, v88, v88 quad_perm:[1,0,3,2] row_mask:0xf bank_mask:0xf bound_ctrl:1
	s_nop 1
	v_add_f32_dpp v88, v88, v88 quad_perm:[2,3,0,1] row_mask:0xf bank_mask:0xf bound_ctrl:1
	s_nop 1
	v_add_f32_dpp v88, v88, v88 row_half_mirror row_mask:0xf bank_mask:0xf bound_ctrl:1
	s_nop 1
	v_add_f32_dpp v88, v88, v88 row_mirror row_mask:0xf bank_mask:0xf bound_ctrl:1
	s_waitcnt lgkmcnt(8)
	v_mul_f32_e32 v88, v110, v88
	v_fmac_f32_e32 v88, v8, v111
	v_add_f32_e32 v90, v114, v88
	v_pk_mul_f32 v[88:89], v[104:105], v[110:111] op_sel_hi:[1,0]
	ds_write_b32 v74, v90 offset:38400
	v_pk_fma_f32 v[104:105], v[22:23], v[8:9], v[88:89] op_sel_hi:[1,0,1]
	v_pk_mul_f32 v[22:23], v[106:107], v[110:111] op_sel_hi:[1,0]
	s_nop 0
	v_pk_fma_f32 v[106:107], v[24:25], v[8:9], v[22:23] op_sel_hi:[1,0,1]
	v_pk_mul_f32 v[22:23], v[108:109], v[110:111] op_sel_hi:[1,0]
	s_waitcnt lgkmcnt(5)
	v_pk_mul_f32 v[94:95], v[106:107], v[94:95]
	v_pk_fma_f32 v[108:109], v[38:39], v[8:9], v[22:23] op_sel_hi:[1,0,1]
	v_pk_mul_f32 v[22:23], v[46:47], v[110:111] op_sel_hi:[1,0]
	v_pk_fma_f32 v[92:93], v[104:105], v[92:93], v[94:95]
	v_pk_fma_f32 v[46:47], v[40:41], v[8:9], v[22:23] op_sel_hi:[1,0,1]
	ds_read_b128 v[22:25], v59 offset:24832
	ds_read_b128 v[38:41], v59 offset:24848
	ds_read_b128 v[88:91], v59 offset:33024
	ds_read_b128 v[96:99], v59 offset:33040
	ds_read_b32 v8, v60 offset:35840
	ds_read_b32 v114, v60 offset:36864
	ds_read_b64 v[110:111], v157 offset:37312
	s_waitcnt lgkmcnt(11)
	v_pk_mul_f32 v[94:95], v[46:47], v[102:103]
	s_nop 0
	v_pk_fma_f32 v[94:95], v[108:109], v[100:101], v[94:95]
	s_nop 0
	v_pk_add_f32 v[92:93], v[92:93], v[94:95]
	s_nop 0
	v_add_f32_e32 v92, v92, v93
	s_nop 1
	v_add_f32_dpp v92, v92, v92 quad_perm:[1,0,3,2] row_mask:0xf bank_mask:0xf bound_ctrl:1
	s_nop 1
	v_add_f32_dpp v92, v92, v92 quad_perm:[2,3,0,1] row_mask:0xf bank_mask:0xf bound_ctrl:1
	s_nop 1
	v_add_f32_dpp v92, v92, v92 row_half_mirror row_mask:0xf bank_mask:0xf bound_ctrl:1
	s_nop 1
	v_add_f32_dpp v92, v92, v92 row_mirror row_mask:0xf bank_mask:0xf bound_ctrl:1
	s_waitcnt lgkmcnt(8)
	v_mul_f32_e32 v92, v112, v92
	v_fmac_f32_e32 v92, v16, v113
	v_add_f32_e32 v94, v115, v92
	v_pk_mul_f32 v[92:93], v[104:105], v[112:113] op_sel_hi:[1,0]
	ds_write_b32 v75, v94 offset:38400
	v_pk_fma_f32 v[104:105], v[26:27], v[16:17], v[92:93] op_sel_hi:[1,0,1]
	v_pk_mul_f32 v[26:27], v[106:107], v[112:113] op_sel_hi:[1,0]
	s_nop 0
	v_pk_fma_f32 v[106:107], v[28:29], v[16:17], v[26:27] op_sel_hi:[1,0,1]
	v_pk_mul_f32 v[26:27], v[108:109], v[112:113] op_sel_hi:[1,0]
	s_waitcnt lgkmcnt(5)
	v_pk_mul_f32 v[90:91], v[106:107], v[90:91]
	v_pk_fma_f32 v[108:109], v[42:43], v[16:17], v[26:27] op_sel_hi:[1,0,1]
	v_pk_mul_f32 v[26:27], v[46:47], v[112:113] op_sel_hi:[1,0]
	v_pk_fma_f32 v[88:89], v[104:105], v[88:89], v[90:91]
	v_pk_fma_f32 v[46:47], v[44:45], v[16:17], v[26:27] op_sel_hi:[1,0,1]
	ds_read_b128 v[26:29], v59 offset:25344
	ds_read_b128 v[42:45], v59 offset:25360
	ds_read_b128 v[92:95], v59 offset:33536
	ds_read_b128 v[100:103], v59 offset:33552
	ds_read_b32 v16, v60 offset:35904
	ds_read_b32 v116, v60 offset:36928
	ds_read_b64 v[112:113], v157 offset:37328
	s_waitcnt lgkmcnt(11)
	v_pk_mul_f32 v[90:91], v[46:47], v[98:99]
	s_waitcnt lgkmcnt(8)
; DI float bf2f(bf16_t h) { return __uint_as_float(((unsigned)h) << 16); }
; DI float siluf(float x) { return x * sigmf(x); }
; DI float row16_sum(float v) { v += dppf(v, 0); v += dppf(v, 1); v += dppf(v, 2); v += dppf(v, 3); return v; }
; DI void mamba_scan(CP p, const Ptrs& w, int l, int item, float* sm) {
;     ...
;   auto stage = [&](const MPre& P, float* bufp) {
; #pragma unroll
;     for (int i = 0; i < 2; ++i) {
;       int idx = tid + 256 * i, j = idx >> 5, q = idx & 31;
;       float f[8];
;       unpack8(P.pbq[i], f);
;       float* d = bufp + (q < 16 ? 0 : 2048) + j * 128 + (q & 15) * 8;
;       *(float4*)d = make_float4(f[0], f[1], f[2], f[3]);
;       *(float4*)(d + 4) = make_float4(f[4], f[5], f[6], f[7]);
;     }
;     {
;       float xs = siluf(wX0 * P.pxm[0] * bf2f(P.px[0]) + wX1 * bf2f(P.px[1]) + wX2 * P.pxm[1] * bf2f(P.px[2]) + bX);
;       bufp[4096 + xj * 16 + xp] = xs * P.pdt[0];
;       bufp[4096 + 256 + xj * 16 + xp] = Dsk * xs;
;       if (xp == 0) *(float4*)(bufp + 4096 + 512 + xj * 4) = make_float4(P.pdt[1], P.pdt[2], 0.f, 0.f);
;     }
;   };
;     ...
;   auto run_chunk = [&](int c, const float* bf, float* sy) {
;     flush(max(c - 1, 0));
;     MStep cur = lds_step(bf, 0);
; #pragma unroll
;     for (int j = 0; j < 16; ++j) {
;       MStep nxt = cur;
;       if (j + 1 < 16) nxt = lds_step(bf, j + 1);
;       f2v ya = M0 * cur.C0.xy + M1 * cur.C0.zw, yb = M2 * cur.C1.xy + M3 * cur.C1.zw;
;       ya += yb;
;       float yp = row16_sum(ya.x + ya.y);
;       float y = cur.sc.x * yp + cur.xq * cur.sc.y + cur.ds;
;       const float dA = cur.sc.x, xq = cur.xq;
;       M0 = M0 * dA + xq * cur.B0.xy; M1 = M1 * dA + xq * cur.B0.zw;
;       M2 = M2 * dA + xq * cur.B1.xy; M3 = M3 * dA + xq * cur.B1.zw;
;       sy[(ng == 0 ? j * 16 : 0) + ysel] = y;
;       cur = nxt;
;     }
;   };
	v_pk_mul_f32 v[46:47], v[46:47], v[110:111] op_sel_hi:[1,0]
	v_pk_fma_f32 v[90:91], v[108:109], v[96:97], v[90:91]
	v_pk_fma_f32 v[40:41], v[40:41], v[8:9], v[46:47] op_sel_hi:[1,0,1]
	v_pk_add_f32 v[88:89], v[88:89], v[90:91]
	s_nop 0
	v_add_f32_e32 v88, v88, v89
	s_nop 1
	v_add_f32_dpp v88, v88, v88 quad_perm:[1,0,3,2] row_mask:0xf bank_mask:0xf bound_ctrl:1
	s_nop 1
	v_add_f32_dpp v88, v88, v88 quad_perm:[2,3,0,1] row_mask:0xf bank_mask:0xf bound_ctrl:1
	s_nop 1
	v_add_f32_dpp v88, v88, v88 row_half_mirror row_mask:0xf bank_mask:0xf bound_ctrl:1
	s_nop 1
	v_add_f32_dpp v88, v88, v88 row_mirror row_mask:0xf bank_mask:0xf bound_ctrl:1
	v_mul_f32_e32 v88, v110, v88
	v_fmac_f32_e32 v88, v8, v111
	v_add_f32_e32 v90, v114, v88
	v_pk_mul_f32 v[88:89], v[104:105], v[110:111] op_sel_hi:[1,0]
	ds_write_b32 v76, v90 offset:38400
	v_pk_fma_f32 v[22:23], v[22:23], v[8:9], v[88:89] op_sel_hi:[1,0,1]
	v_pk_mul_f32 v[88:89], v[106:107], v[110:111] op_sel_hi:[1,0]
	s_nop 0
	v_pk_fma_f32 v[24:25], v[24:25], v[8:9], v[88:89] op_sel_hi:[1,0,1]
	v_pk_mul_f32 v[88:89], v[108:109], v[110:111] op_sel_hi:[1,0]
	s_waitcnt lgkmcnt(5)
	v_pk_mul_f32 v[94:95], v[24:25], v[94:95]
	v_pk_fma_f32 v[38:39], v[38:39], v[8:9], v[88:89] op_sel_hi:[1,0,1]
	v_pk_fma_f32 v[92:93], v[22:23], v[92:93], v[94:95]
	s_waitcnt lgkmcnt(4)
	v_pk_mul_f32 v[94:95], v[40:41], v[102:103]
	s_waitcnt lgkmcnt(1)
	v_pk_mul_f32 v[22:23], v[22:23], v[112:113] op_sel_hi:[1,0]
	v_pk_fma_f32 v[94:95], v[38:39], v[100:101], v[94:95]
	ds_read_b128 v[88:91], v59 offset:25856
	ds_read_b128 v[96:99], v59 offset:25872
	ds_read_b128 v[104:107], v59 offset:34048
	ds_read_b128 v[108:111], v59 offset:34064
	ds_read_b32 v46, v60 offset:35968
	ds_read_b32 v47, v60 offset:36992
	ds_read_b64 v[114:115], v157 offset:37344
	v_pk_add_f32 v[92:93], v[92:93], v[94:95]
	s_nop 0
	v_add_f32_e32 v8, v92, v93
	s_nop 1
	v_add_f32_dpp v8, v8, v8 quad_perm:[1,0,3,2] row_mask:0xf bank_mask:0xf bound_ctrl:1
	s_nop 1
	v_add_f32_dpp v8, v8, v8 quad_perm:[2,3,0,1] row_mask:0xf bank_mask:0xf bound_ctrl:1
	s_nop 1
	v_add_f32_dpp v8, v8, v8 row_half_mirror row_mask:0xf bank_mask:0xf bound_ctrl:1
	s_nop 1
	v_add_f32_dpp v8, v8, v8 row_mirror row_mask:0xf bank_mask:0xf bound_ctrl:1
	v_mul_f32_e32 v8, v112, v8
	v_fmac_f32_e32 v8, v16, v113
	v_add_f32_e32 v8, v116, v8
	v_pk_fma_f32 v[116:117], v[26:27], v[16:17], v[22:23] op_sel_hi:[1,0,1]
	v_pk_mul_f32 v[22:23], v[24:25], v[112:113] op_sel_hi:[1,0]
	ds_write_b32 v77, v8 offset:38400
	v_pk_fma_f32 v[118:119], v[28:29], v[16:17], v[22:23] op_sel_hi:[1,0,1]
	v_pk_mul_f32 v[22:23], v[38:39], v[112:113] op_sel_hi:[1,0]
	s_nop 0
	v_pk_fma_f32 v[120:121], v[42:43], v[16:17], v[22:23] op_sel_hi:[1,0,1]
	v_pk_mul_f32 v[22:23], v[40:41], v[112:113] op_sel_hi:[1,0]
	s_waitcnt lgkmcnt(5)
	v_pk_mul_f32 v[40:41], v[118:119], v[106:107]
	v_pk_fma_f32 v[112:113], v[44:45], v[16:17], v[22:23] op_sel_hi:[1,0,1]
	v_pk_fma_f32 v[40:41], v[116:117], v[104:105], v[40:41]
	s_waitcnt lgkmcnt(4)
	v_pk_mul_f32 v[42:43], v[112:113], v[110:111]
	ds_read_b128 v[26:29], v59 offset:26368
	ds_read_b128 v[22:25], v59 offset:26384
	ds_read_b128 v[92:95], v59 offset:34560
	ds_read_b128 v[100:103], v59 offset:34576
	ds_read_b32 v8, v60 offset:36032
	ds_read_b32 v16, v60 offset:37056
	ds_read_b64 v[38:39], v157 offset:37360
	v_pk_fma_f32 v[42:43], v[120:121], v[108:109], v[42:43]
	s_nop 0
	v_pk_add_f32 v[40:41], v[40:41], v[42:43]
	s_nop 0
	v_add_f32_e32 v40, v40, v41
	s_nop 1
	v_add_f32_dpp v40, v40, v40 quad_perm:[1,0,3,2] row_mask:0xf bank_mask:0xf bound_ctrl:1
	s_nop 1
	v_add_f32_dpp v40, v40, v40 quad_perm:[2,3,0,1] row_mask:0xf bank_mask:0xf bound_ctrl:1
	s_nop 1
	v_add_f32_dpp v40, v40, v40 row_half_mirror row_mask:0xf bank_mask:0xf bound_ctrl:1
	s_nop 1
	v_add_f32_dpp v40, v40, v40 row_mirror row_mask:0xf bank_mask:0xf bound_ctrl:1
	s_waitcnt lgkmcnt(8)
	v_mul_f32_e32 v40, v114, v40
	v_fmac_f32_e32 v40, v46, v115
	v_add_f32_e32 v104, v47, v40
	v_pk_mul_f32 v[40:41], v[116:117], v[114:115] op_sel_hi:[1,0]
	ds_write_b32 v78, v104 offset:38400
	v_pk_fma_f32 v[42:43], v[88:89], v[46:47], v[40:41] op_sel_hi:[1,0,1]
	v_pk_mul_f32 v[40:41], v[118:119], v[114:115] op_sel_hi:[1,0]
	v_pk_mul_f32 v[88:89], v[112:113], v[114:115] op_sel_hi:[1,0]
	v_pk_fma_f32 v[44:45], v[90:91], v[46:47], v[40:41] op_sel_hi:[1,0,1]
	v_pk_mul_f32 v[40:41], v[120:121], v[114:115] op_sel_hi:[1,0]
	s_nop 0
	v_pk_fma_f32 v[40:41], v[96:97], v[46:47], v[40:41] op_sel_hi:[1,0,1]
	v_pk_fma_f32 v[46:47], v[98:99], v[46:47], v[88:89] op_sel_hi:[1,0,1]
	s_waitcnt lgkmcnt(5)
	v_pk_mul_f32 v[88:89], v[44:45], v[94:95]
	s_waitcnt lgkmcnt(4)
	v_pk_mul_f32 v[90:91], v[46:47], v[102:103]
	v_pk_fma_f32 v[88:89], v[42:43], v[92:93], v[88:89]
	v_pk_fma_f32 v[90:91], v[40:41], v[100:101], v[90:91]
	v_lshlrev_b32_e32 v94, 16, v21
	v_pk_add_f32 v[88:89], v[88:89], v[90:91]
	v_and_b32_e32 v95, 0xffff0000, v21
	v_add_f32_e32 v88, v88, v89
	v_lshlrev_b32_e32 v21, 16, v85
	v_lshlrev_b32_e32 v90, 16, v19
	v_add_f32_dpp v88, v88, v88 quad_perm:[1,0,3,2] row_mask:0xf bank_mask:0xf bound_ctrl:1
	v_and_b32_e32 v91, 0xffff0000, v19
	v_lshlrev_b32_e32 v19, 16, v84
	v_add_f32_dpp v88, v88, v88 quad_perm:[2,3,0,1] row_mask:0xf bank_mask:0xf bound_ctrl:1
	v_mul_f32_e32 v21, v50, v21
	v_and_b32_e32 v89, 0xffff0000, v18
	v_add_f32_dpp v88, v88, v88 row_half_mirror row_mask:0xf bank_mask:0xf bound_ctrl:1
	v_lshlrev_b32_e32 v92, 16, v20
	v_and_b32_e32 v93, 0xffff0000, v20
	v_add_f32_dpp v88, v88, v88 row_mirror row_mask:0xf bank_mask:0xf bound_ctrl:1
	s_waitcnt lgkmcnt(1)
	v_mul_f32_e32 v88, v38, v88
	v_fmac_f32_e32 v88, v8, v39
	v_add_f32_e32 v16, v16, v88
	ds_write_b32 v80, v16 offset:38400
	v_mul_f32_e32 v16, v49, v87
	v_fmac_f32_e32 v21, v16, v19
	v_mul_f32_e32 v16, v51, v86
	v_lshlrev_b32_e32 v19, 16, v83
	v_fmac_f32_e32 v21, v16, v19
	v_add_f32_e32 v16, v52, v21
	v_mul_f32_e32 v19, 0xbfb8aa3b, v16
	v_exp_f32_e32 v39, v19
	v_lshlrev_b32_e32 v88, 16, v18
	v_lshlrev_b32_e32 v18, 16, v12
	v_and_b32_e32 v19, 0xffff0000, v12
	v_add_f32_e32 v12, 1.0, v39
	v_rcp_f32_e32 v12, v12
	ds_write_b128 v58, v[92:95] offset:16
	ds_write_b128 v58, v[88:91]
	v_lshlrev_b32_e32 v20, 16, v13
	v_lshlrev_b32_e32 v90, 16, v15
	v_mul_f32_e32 v12, v16, v12
	v_lshlrev_b32_e32 v88, 16, v14
	v_and_b32_e32 v21, 0xffff0000, v13
	v_and_b32_e32 v91, 0xffff0000, v15
	v_and_b32_e32 v89, 0xffff0000, v14
	v_mul_f32_e32 v13, v36, v12
	v_mul_f32_e32 v12, v53, v12
	ds_write_b128 v58, v[88:91] offset:4112
	ds_write_b128 v58, v[18:21] offset:4096
	ds_write2st64_b32 v57, v13, v12 offset0:64 offset1:68
	s_and_saveexec_b64 s[4:5], vcc
	s_cbranch_execz .LBB0_700
	v_mov_b32_e32 v16, v37
	v_mov_b32_e32 v18, v157
	v_mov_b32_e32 v19, v157
	ds_write_b128 v72, v[16:19] offset:18432
	s_branch .LBB0_700

; #define TIDX ltid()
; DI void rwkv_scan(CP p, const Ptrs& w, int l, int item, float* sm) {
;   const int tid = TIDX, lane = tid & 63, wid = tid >> 6;
;   const int chain = item >> 2, rq = item & 3, b = chain >> 4, hd = (chain >> 1) & 7, dir = chain & 1;
;   const int sj = tid >> 4, skq = (tid & 15) * 4, sc_ = hd * 64 + skq;
;   float mu_r[4], mu_k[4], mu_v[4], kk_c[4], ka_c[4];
; #pragma unroll
;   for (int j = 0; j < 4; ++j) {
;     mu_r[j] = p.in[11][l * 1792 + sc_ + j]; mu_k[j] = p.in[11][l * 1792 + 512 + sc_ + j]; mu_v[j] = p.in[11][l * 1792 + 1024 + sc_ + j];
;     kk_c[j] = p.in[16][l * 512 + sc_ + j]; ka_c[j] = p.in[17][l * 512 + sc_ + j];
;   }
;   const bf16_t* Wd = w.R1 + (size_t)(0 * 2 + dir) * T * 512;
;   const bf16_t* Ad = w.R1 + (size_t)(1 * 2 + dir) * T * 512;
;   bf16_t* yout = w.R2 + (size_t)dir * T * 512;
;   constexpr int BUF = 6 * 1024 + 32;
;   const int kg = lane & 15, rs = lane >> 4, row = rq * 16 + wid * 4 + rs;
;   f2v SA = {0.f, 0.f}, SB = {0.f, 0.f};
;   struct RPre { uint2 pq[3][3], pwd, pad_; float psc[3], pmk[2]; };
;   RPre PA, PB;
;   auto load = [&](int c, RPre& P) {
;     int ii = pos2i(c * 16 + sj, dir);
;     size_t tok = (size_t)b * TPB + ii;
;     const bf16_t* prow = w.pB + tok * SPB + sc_;
;     bool hp = (ii != 0) && (ii != CTXL), hn = (ii != CTXL - 1) && (ii != TPB - 1);
;     const int op = hp ? -SPB : 0, on = hn ? SPB : 0;
;     P.pmk[0] = hp ? 0.5f : 0.f; P.pmk[1] = hn ? 0.5f : 0.f;
; #pragma unroll
;     for (int q = 0; q < 3; ++q) {
;       P.pq[q][0] = *(const uint2*)(prow + q * 512);
;       P.pq[q][1] = *(const uint2*)(prow + q * 512 + op);
;       P.pq[q][2] = *(const uint2*)(prow + q * 512 + on);
;     }
;     P.pwd = *(const uint2*)(Wd + tok * 512 + sc_);
;     P.pad_ = *(const uint2*)(Ad + tok * 512 + sc_);
.LBB0_706:
	s_and_b64 vcc, exec, s[4:5]
	s_cbranch_vccz .LBB0_687
	v_mov_b32_e32 v57, v214
	s_bfe_u32 s6, s70, 0x30003
	v_lshlrev_b32_e32 v83, 2, v57
	s_waitcnt vmcnt(2)
	v_and_b32_e32 v23, 60, v83
	s_lshl_b32 s66, s6, 6
	v_readlane_b32 s4, v254, 58
	v_or_b32_e32 v22, s66, v23
	s_mulk_i32 s4, 0x700
	s_bfe_u32 s10, s70, 0x10002
	v_add_u32_e32 v156, s4, v22
	v_lshl_add_u64 v[8:9], v[156:157], 2, s[62:63]
	s_movk_i32 s4, 0x1000
	s_ashr_i32 s7, s70, 6
	s_mul_i32 s11, s10, 0x1080000
	v_add_co_u32_e32 v4, vcc, s4, v8
	s_add_u32 s42, s78, s11
	v_readlane_b32 s4, v255, 1
	s_addc_u32 s43, s4, 0
	v_ashrrev_i32_e32 v97, 4, v57
	s_add_u32 s44, s42, 0x2100000
	s_addc_u32 s45, s43, 0
	v_cmp_lt_i32_e64 s[4:5], s37, v97
	v_addc_co_u32_e32 v5, vcc, 0, v9, vcc
	s_cmp_eq_u32 s10, 0
	v_cndmask_b32_e64 v20, v231, v232, s[4:5]
	s_cselect_b64 vcc, -1, 0
	v_sub_u32_e32 v20, v20, v97
	v_cndmask_b32_e32 v46, v20, v97, vcc
	v_ashrrev_i32_e32 v47, 31, v46
	v_mov_b32_e32 v20, 0x2100
	v_mad_i64_i32 v[20:21], s[4:5], s7, v20, v[46:47]
	s_waitcnt vmcnt(1)
	v_mov_b64_e32 v[24:25], s[50:51]
	v_or_b32_e32 v0, s79, v22
	v_mov_b32_e32 v1, v157
	v_mad_u64_u32 v[24:25], s[4:5], v20, s20, v[24:25]
	s_waitcnt vmcnt(0)
	v_lshlrev_b64 v[30:31], 10, v[20:21]
	v_lshlrev_b64 v[0:1], 2, v[0:1]
	v_mad_i32_i24 v25, v21, s20, v25
	v_lshlrev_b32_e32 v156, 1, v22
	s_waitcnt vmcnt(0)
	v_lshl_add_u64 v[32:33], s[42:43], 0, v[30:31]
	v_lshl_add_u64 v[30:31], s[44:45], 0, v[30:31]
	v_lshl_add_u64 v[12:13], s[12:13], 0, v[0:1]
	v_lshl_add_u64 v[16:17], s[14:15], 0, v[0:1]
	v_lshl_add_u64 v[48:49], v[24:25], 0, v[156:157]
	v_lshl_add_u64 v[32:33], v[32:33], 0, v[156:157]
	v_lshl_add_u64 v[30:31], v[30:31], 0, v[156:157]
	global_load_dwordx4 v[0:3], v[8:9], off
	s_nop 0
	global_load_dwordx4 v[4:7], v[4:5], off
	s_nop 0
	global_load_dwordx4 v[8:11], v[8:9], off offset:2048
	s_nop 0
	global_load_dwordx4 v[12:15], v[12:13], off
	s_nop 0
	global_load_dwordx4 v[16:19], v[16:17], off
	s_barrier
; DI void rwkv_scan(CP p, const Ptrs& w, int l, int item, float* sm) {
;     ...
;   auto load = [&](int c, RPre& P) {
;     int ii = pos2i(c * 16 + sj, dir);
;     size_t tok = (size_t)b * TPB + ii;
;     const bf16_t* prow = w.pB + tok * SPB + sc_;
;     bool hp = (ii != 0) && (ii != CTXL), hn = (ii != CTXL - 1) && (ii != TPB - 1);
;     const int op = hp ? -SPB : 0, on = hn ? SPB : 0;
;     P.pmk[0] = hp ? 0.5f : 0.f; P.pmk[1] = hn ? 0.5f : 0.f;
; #pragma unroll
;     for (int q = 0; q < 3; ++q) {
;       P.pq[q][0] = *(const uint2*)(prow + q * 512);
;       P.pq[q][1] = *(const uint2*)(prow + q * 512 + op);
;       P.pq[q][2] = *(const uint2*)(prow + q * 512 + on);
;     }
;     P.pwd = *(const uint2*)(Wd + tok * 512 + sc_);
;     P.pad_ = *(const uint2*)(Ad + tok * 512 + sc_);
;     const float* sc = w.bonus + (tok * 8 + hd) * 8;
;     P.psc[0] = sc[0]; P.psc[1] = sc[1 + 3 * dir]; P.psc[2] = sc[2 + 3 * dir];
;   };
;   auto up4 = [](uint2 u, float* f) { f[0] = __uint_as_float(u.x << 16); f[1] = __uint_as_float(u.x & 0xffff0000u); f[2] = __uint_as_float(u.y << 16); f[3] = __uint_as_float(u.y & 0xffff0000u); };
;   auto stage = [&](const RPre& P, float* bufp) {
;     float rc[4], rp[4], rn[4], kc[4], kp[4], kn[4], vc[4], vp[4], vn[4], wd4[4], ad4[4];
;     up4(P.pq[0][0], rc); up4(P.pq[0][1], rp); up4(P.pq[0][2], rn);
;     up4(P.pq[1][0], kc); up4(P.pq[1][1], kp); up4(P.pq[1][2], kn);
;     up4(P.pq[2][0], vc); up4(P.pq[2][1], vp); up4(P.pq[2][2], vn);
;     up4(P.pwd, wd4); up4(P.pad_, ad4);
;     float o0[4], o1[4], o2[4], o3[4], o4[4], o5[4];
; #pragma unroll
;     for (int j = 0; j < 4; ++j) {
;       float r_s = rc[j] + ((P.pmk[0] * rp[j] + P.pmk[1] * rn[j]) - rc[j]) * mu_r[j];
;       float k_s = kc[j] + ((P.pmk[0] * kp[j] + P.pmk[1] * kn[j]) - kc[j]) * mu_k[j];
;       float v_s = vc[j] + ((P.pmk[0] * vp[j] + P.pmk[1] * vn[j]) - vc[j]) * mu_v[j];
;       float kk = k_s * kk_c[j] * P.psc[0];
;       float a = ad4[j], wv = 1.f - wd4[j];
;       o0[j] = -kk; o1[j] = wv * r_s; o2[j] = wv; o3[j] = kk * a; o4[j] = k_s * (1.f + (a - 1.f) * ka_c[j]); o5[j] = v_s;
;     }
;     float* d = bufp + sj * 64 + skq;
;     *(float4*)(d + 0 * 1024) = make_float4(o0[0], o0[1], o0[2], o0[3]);
;     *(float4*)(d + 1 * 1024) = make_float4(o1[0], o1[1], o1[2], o1[3]);
;     *(float4*)(d + 2 * 1024) = make_float4(o2[0], o2[1], o2[2], o2[3]);
	global_load_dwordx2 v[24:25], v[48:49], off
	global_load_dwordx2 v[26:27], v[48:49], off offset:1024
	global_load_dwordx2 v[28:29], v[48:49], off offset:2048
	global_load_dwordx2 v[36:37], v[32:33], off
	global_load_dwordx2 v[50:51], v[30:31], off
	v_lshlrev_b64 v[20:21], 8, v[20:21]
	v_lshl_add_u64 v[20:21], s[2:3], 0, v[20:21]
	s_lshl_b32 s72, s6, 5
	s_mov_b32 s73, s91
	v_and_b32_e32 v39, 0xfffffeff, v46
	v_and_b32_e32 v46, 0xffffdfff, v46
	s_mul_hi_i32 s69, s7, 0x2100
	s_mul_i32 s68, s7, 0x2100
	v_lshl_add_u64 v[20:21], v[20:21], 0, s[72:73]
	v_cmp_eq_u32_e64 s[4:5], s37, v46
	v_cmp_eq_u32_e64 s[6:7], 0, v39
	global_load_dword v38, v[20:21], off
	v_cndmask_b32_e64 v52, v237, 0, s[4:5]
	v_mov_b32_e32 v53, v157
	v_lshl_add_u64 v[52:53], v[48:49], 0, v[52:53]
	v_cndmask_b32_e64 v46, 0.5, 0, s[4:5]
	v_cndmask_b32_e64 v47, 0.5, 0, s[6:7]
	v_lshlrev_b32_e32 v22, 8, v97
	v_lshl_or_b32 v103, v23, 2, v22
	s_mul_i32 s10, s10, 3
	v_cmp_eq_u32_e64 s[40:41], 0, v23
	s_waitcnt vmcnt(5)
	v_lshlrev_b32_e32 v34, 16, v24
	v_and_b32_e32 v35, 0xffff0000, v24
	v_lshlrev_b32_e32 v32, 16, v25
	v_and_b32_e32 v33, 0xffff0000, v25
	s_waitcnt vmcnt(4)
	v_lshlrev_b32_e32 v44, 16, v26
	v_and_b32_e32 v45, 0xffff0000, v26
	v_lshlrev_b32_e32 v42, 16, v27
	v_and_b32_e32 v43, 0xffff0000, v27
	s_waitcnt vmcnt(3)
	v_lshlrev_b32_e32 v26, 16, v28
	v_and_b32_e32 v27, 0xffff0000, v28
	v_lshlrev_b32_e32 v24, 16, v29
	v_and_b32_e32 v25, 0xffff0000, v29
	s_waitcnt vmcnt(1)
	v_lshlrev_b32_e32 v30, 16, v50
	v_and_b32_e32 v31, 0xffff0000, v50
	v_lshlrev_b32_e32 v28, 16, v51
	v_and_b32_e32 v29, 0xffff0000, v51
	v_cndmask_b32_e64 v51, -1, 0, s[6:7]
	v_cndmask_b32_e64 v50, v236, 0, s[6:7]
	v_lshl_add_u64 v[50:51], v[48:49], 0, v[50:51]
	global_load_dwordx2 v[54:55], v[50:51], off
	global_load_dwordx2 v[58:59], v[52:53], off
	global_load_dwordx2 v[60:61], v[50:51], off offset:1024
	global_load_dwordx2 v[62:63], v[52:53], off offset:1024
	global_load_dwordx2 v[48:49], v[50:51], off offset:2048
	global_load_dwordx2 v[64:65], v[52:53], off offset:2048
	v_lshlrev_b32_e32 v40, 16, v36
	v_and_b32_e32 v41, 0xffff0000, v36
	v_lshlrev_b32_e32 v36, 16, v37
	v_and_b32_e32 v37, 0xffff0000, v37
	s_waitcnt vmcnt(3)
	v_lshlrev_b32_e32 v52, 16, v60
	s_waitcnt vmcnt(2)
	v_and_b32_e32 v53, 0xffff0000, v62
	v_lshlrev_b32_e32 v50, 16, v62
	v_and_b32_e32 v51, 0xffff0000, v60
	v_pk_mul_f32 v[52:53], v[46:47], v[52:53] op_sel:[1,0] op_sel_hi:[0,1]
	v_pk_fma_f32 v[50:51], v[46:47], v[50:51], v[52:53]
	v_and_b32_e32 v53, 0xffff0000, v61
	v_lshlrev_b32_e32 v60, 16, v61
	v_and_b32_e32 v61, 0xffff0000, v63
	v_lshlrev_b32_e32 v52, 16, v63
	v_pk_mul_f32 v[60:61], v[46:47], v[60:61] op_sel:[1,0] op_sel_hi:[0,1]
	v_pk_fma_f32 v[52:53], v[46:47], v[52:53], v[60:61]
	v_pk_add_f32 v[50:51], v[50:51], v[44:45] neg_lo:[0,1] neg_hi:[0,1]
	v_pk_add_f32 v[52:53], v[52:53], v[42:43] neg_lo:[0,1] neg_hi:[0,1]
	v_pk_fma_f32 v[44:45], v[8:9], v[50:51], v[44:45]
	v_pk_fma_f32 v[42:43], v[10:11], v[52:53], v[42:43]
	v_pk_mul_f32 v[50:51], v[12:13], v[44:45]
	v_pk_mul_f32 v[52:53], v[14:15], v[42:43]
	v_pk_mul_f32 v[66:67], v[38:39], v[50:51] op_sel_hi:[0,1]
	v_pk_mul_f32 v[60:61], v[38:39], v[52:53] op_sel_hi:[0,1]
	v_xor_b32_e32 v51, 0x80000000, v67
	v_xor_b32_e32 v50, 0x80000000, v66
	v_xor_b32_e32 v53, 0x80000000, v61
	v_xor_b32_e32 v52, 0x80000000, v60
	ds_write_b128 v103, v[50:53]
	v_lshlrev_b32_e32 v50, 16, v54
	v_and_b32_e32 v51, 0xffff0000, v58
	v_pk_add_f32 v[38:39], v[40:41], 1.0 op_sel_hi:[1,0] neg_lo:[1,0] neg_hi:[1,0]
	v_lshlrev_b32_e32 v40, 16, v58
	v_and_b32_e32 v41, 0xffff0000, v54
	v_pk_mul_f32 v[50:51], v[46:47], v[50:51] op_sel:[1,0] op_sel_hi:[0,1]
	v_pk_fma_f32 v[40:41], v[46:47], v[40:41], v[50:51]
	v_lshlrev_b32_e32 v51, 16, v55
	v_and_b32_e32 v53, s0, v55
	v_and_b32_e32 v52, 0xffff0000, v59
	v_pk_add_f32 v[40:41], v[40:41], v[34:35] neg_lo:[0,1] neg_hi:[0,1]
	v_pk_mov_b32 v[50:51], v[50:51], v[52:53] op_sel:[1,0]
	v_pk_fma_f32 v[34:35], v[0:1], v[40:41], v[34:35]
	v_pk_add_f32 v[40:41], v[36:37], 1.0 op_sel_hi:[1,0] neg_lo:[1,0] neg_hi:[1,0]
	v_lshlrev_b32_e32 v36, 16, v59
	v_and_b32_e32 v37, 0xffff0000, v55
	v_pk_mul_f32 v[50:51], v[46:47], v[50:51] op_sel:[1,0] op_sel_hi:[0,1]
	v_pk_fma_f32 v[36:37], v[46:47], v[36:37], v[50:51]
	v_pk_mul_f32 v[34:35], v[34:35], v[38:39]
	v_pk_add_f32 v[36:37], v[36:37], v[32:33] neg_lo:[0,1] neg_hi:[0,1]
	s_nop 0
	v_pk_fma_f32 v[32:33], v[2:3], v[36:37], v[32:33]
	s_nop 0
	v_pk_mul_f32 v[36:37], v[32:33], v[40:41]
	ds_write_b128 v103, v[34:37] offset:4096
	ds_write_b128 v103, v[38:41] offset:8192
	v_pk_mul_f32 v[32:33], v[66:67], v[30:31]
	v_pk_mul_f32 v[34:35], v[60:61], v[28:29]
	v_pk_add_f32 v[30:31], v[30:31], -1.0 op_sel_hi:[1,0]
	v_pk_add_f32 v[28:29], v[28:29], -1.0 op_sel_hi:[1,0]
	v_pk_fma_f32 v[30:31], v[16:17], v[30:31], 1.0 op_sel_hi:[1,1,0]
	v_pk_fma_f32 v[28:29], v[18:19], v[28:29], 1.0 op_sel_hi:[1,1,0]
	ds_write_b128 v103, v[32:35] offset:12288
	v_pk_mul_f32 v[30:31], v[44:45], v[30:31]
	v_pk_mul_f32 v[32:33], v[42:43], v[28:29]
	ds_write_b128 v103, v[30:33] offset:16384
	s_waitcnt vmcnt(1)
	v_lshlrev_b32_e32 v30, 16, v48
	s_waitcnt vmcnt(0)
	v_and_b32_e32 v31, 0xffff0000, v64
	v_lshlrev_b32_e32 v28, 16, v64
	v_and_b32_e32 v29, 0xffff0000, v48
	v_pk_mul_f32 v[30:31], v[46:47], v[30:31] op_sel:[1,0] op_sel_hi:[0,1]
	v_pk_fma_f32 v[28:29], v[46:47], v[28:29], v[30:31]
	v_lshlrev_b32_e32 v31, 16, v49
	v_and_b32_e32 v33, s0, v49
	v_and_b32_e32 v32, 0xffff0000, v65
	v_pk_add_f32 v[28:29], v[28:29], v[26:27] neg_lo:[0,1] neg_hi:[0,1]
	v_pk_mov_b32 v[30:31], v[30:31], v[32:33] op_sel:[1,0]
	v_pk_fma_f32 v[26:27], v[4:5], v[28:29], v[26:27]
	v_lshlrev_b32_e32 v28, 16, v65
	v_and_b32_e32 v29, 0xffff0000, v49
	v_pk_mul_f32 v[30:31], v[46:47], v[30:31] op_sel:[1,0] op_sel_hi:[0,1]
	v_pk_fma_f32 v[28:29], v[46:47], v[28:29], v[30:31]
	s_nop 0
	v_pk_add_f32 v[28:29], v[28:29], v[24:25] neg_lo:[0,1] neg_hi:[0,1]
	s_nop 0
	v_pk_fma_f32 v[28:29], v[6:7], v[28:29], v[24:25]
	ds_write_b128 v103, v[26:29] offset:20480
	s_and_saveexec_b64 s[4:5], s[40:41]
	s_cbranch_execz .LBB0_709
	s_lshl_b32 s90, s10, 2
	v_lshl_add_u64 v[20:21], v[20:21], 0, s[90:91]
	global_load_dwordx2 v[20:21], v[20:21], off offset:4
	s_movk_i32 s6, 0xff08
	v_mad_u64_u32 v[22:23], s[6:7], v97, s6, v[22:23]
	s_waitcnt vmcnt(0)
	ds_write_b64 v22, v[20:21] offset:24576

; DI float row16_sum(float v) { v += dppf(v, 0); v += dppf(v, 1); v += dppf(v, 2); v += dppf(v, 3); return v; }
; DI void rwkv_scan(CP p, const Ptrs& w, int l, int item, float* sm) {
;     ...
;   auto load = [&](int c, RPre& P) {
;     int ii = pos2i(c * 16 + sj, dir);
;     size_t tok = (size_t)b * TPB + ii;
;     const bf16_t* prow = w.pB + tok * SPB + sc_;
;     bool hp = (ii != 0) && (ii != CTXL), hn = (ii != CTXL - 1) && (ii != TPB - 1);
;     const int op = hp ? -SPB : 0, on = hn ? SPB : 0;
;     P.pmk[0] = hp ? 0.5f : 0.f; P.pmk[1] = hn ? 0.5f : 0.f;
; #pragma unroll
;     for (int q = 0; q < 3; ++q) {
;       P.pq[q][0] = *(const uint2*)(prow + q * 512);
;       P.pq[q][1] = *(const uint2*)(prow + q * 512 + op);
;       P.pq[q][2] = *(const uint2*)(prow + q * 512 + on);
;     }
;     P.pwd = *(const uint2*)(Wd + tok * 512 + sc_);
;     P.pad_ = *(const uint2*)(Ad + tok * 512 + sc_);
;     const float* sc = w.bonus + (tok * 8 + hd) * 8;
;     P.psc[0] = sc[0]; P.psc[1] = sc[1 + 3 * dir]; P.psc[2] = sc[2 + 3 * dir];
;   };
;     ...
;   auto flush = [&](int c) {
;     {
;       int j = tid >> 4, rr = tid & 15;
;       int ii = pos2i(c * 16 + j, dir);
;       yout[((size_t)b * TPB + ii) * 512 + hd * 64 + rq * 16 + rr] = f2bf(sY[(c & 1) * 256 + j * 16 + rr]);
;     }
;   };
;   __syncthreads();
;   load(0, PA);
;   stage(PA, sm);
;   load(1, PB);
;   __syncthreads();
;   const int NCH = TPB / 16;
;   auto run_chunk = [&](int c, const float* bf, float* sy) {
;     flush(max(c - 1, 0));
;     RStep cur = lds_step(bf, 0);
; #pragma unroll
;     for (int j = 0; j < 16; ++j) {
;       RStep nxt = cur;
;       if (j + 1 < 16) nxt = lds_step(bf, j + 1);
;       f2v sa2 = SA * cur.a4.xy + SB * cur.a4.zw;
;       f2v yp2 = SA * cur.wr4.xy + SB * cur.wr4.zw;
;       float sa = sa2.x + sa2.y, yp = yp2.x + yp2.y;
;       sa = row16_sum(sa); yp = row16_sum(yp);
;       float y = yp + sa * cur.sc.x + cur.vv * cur.sc.y;
;       SA = SA * cur.w4.xy + (sa * cur.b4.xy + cur.vv * cur.k4.xy);
;       SB = SB * cur.w4.zw + (sa * cur.b4.zw + cur.vv * cur.k4.zw);
;       sy[(kg == 0 ? j * 16 : 0) + ysel - (c & 1) * 0] = y;
;       cur = nxt;
;     }
;   };
.LBB0_710:
	s_or_b64 exec, exec, s[4:5]
	v_pk_mul_f32 v[28:29], v[28:29], v[102:103] op_sel_hi:[1,0]
	s_addk_i32 s73, 0x200
	v_pk_fma_f32 v[24:25], v[24:25], v[96:97], v[28:29] op_sel_hi:[1,0,1]
	s_add_i32 s11, s11, 2
	v_pk_fma_f32 v[20:21], v[20:21], v[98:99], v[24:25]
	v_pk_mul_f32 v[24:25], v[30:31], v[102:103] op_sel_hi:[1,0]
	v_cndmask_b32_e64 v94, 0.5, 0, s[44:45]
	v_pk_fma_f32 v[24:25], v[26:27], v[96:97], v[24:25] op_sel_hi:[1,0,1]
	v_cndmask_b32_e64 v95, 0.5, 0, s[42:43]
	v_pk_fma_f32 v[22:23], v[22:23], v[100:101], v[24:25]
	v_add_u32_e32 v125, 32, v125
	s_cmpk_lt_u32 s10, 0x20e
	v_subrev_u32_e32 v124, 32, v124
	s_waitcnt lgkmcnt(0)
	s_barrier
	s_cbranch_scc0 .LBB0_686
.LBB0_711:
	s_min_u32 s4, s11, 1
	s_lshl_b32 s5, s4, 8
	s_lshl_b32 s17, s4, 4
	s_add_i32 s4, s10, 4
	s_min_u32 s4, s4, 0x20f
	v_lshl_add_u32 v24, s4, 4, v97
	s_sub_i32 s16, s73, s5
	v_cmp_lt_i32_e64 s[4:5], s37, v24
	s_nop 1
	v_cndmask_b32_e64 v25, v231, v232, s[4:5]
	v_sub_u32_e32 v25, v25, v24
	v_cndmask_b32_e32 v24, v25, v24, vcc
	v_ashrrev_i32_e32 v25, 31, v24
	v_lshl_add_u64 v[26:27], s[68:69], 0, v[24:25]
	v_mad_u64_u32 v[28:29], s[4:5], v26, s20, v[42:43]
	v_mov_b32_e32 v30, v29
	v_mad_u64_u32 v[30:31], s[4:5], v27, s20, v[30:31]
	v_and_b32_e32 v25, 0xfffffeff, v24
	v_mov_b32_e32 v29, v30
	v_and_b32_e32 v30, 0xffffdfff, v24
	v_cmp_eq_u32_e64 s[42:43], 0, v25
	v_cmp_eq_u32_e64 s[44:45], s37, v30
	s_and_b32 s4, s16, 0x100
	v_cndmask_b32_e64 v25, -1, 0, s[42:43]
	v_cndmask_b32_e64 v24, v236, 0, s[42:43]
	v_cndmask_b32_e64 v156, v237, 0, s[44:45]
	v_lshl_add_u64 v[24:25], v[28:29], 0, v[24:25]
	v_lshl_add_u64 v[30:31], v[28:29], 0, v[156:157]
	global_load_dwordx2 v[88:89], v[28:29], off
	global_load_dwordx2 v[86:87], v[28:29], off offset:1024
	global_load_dwordx2 v[84:85], v[28:29], off offset:2048
	global_load_dwordx2 v[74:75], v[24:25], off
	global_load_dwordx2 v[76:77], v[30:31], off
	global_load_dwordx2 v[78:79], v[24:25], off offset:1024
	global_load_dwordx2 v[70:71], v[24:25], off offset:2048
	v_lshlrev_b64 v[24:25], 10, v[26:27]
	v_lshl_add_u64 v[28:29], v[34:35], 0, v[24:25]
	v_lshl_add_u64 v[24:25], v[36:37], 0, v[24:25]
	global_load_dwordx2 v[80:81], v[30:31], off offset:1024
	global_load_dwordx2 v[72:73], v[30:31], off offset:2048
	global_load_dwordx2 v[92:93], v[28:29], off
	global_load_dwordx2 v[90:91], v[24:25], off
	v_lshlrev_b64 v[24:25], 8, v[26:27]
	v_lshl_add_u64 v[24:25], s[6:7], 0, v[24:25]
	v_lshl_add_u64 v[26:27], v[24:25], 0, s[90:91]
	global_load_dword v82, v[24:25], off
	global_load_dwordx2 v[68:69], v[26:27], off offset:4
	v_lshl_add_u32 v25, s4, 2, v83
	v_subrev_u32_e32 v24, s17, v125
	ds_read_b32 v25, v25 offset:49408
	v_cmp_lt_i32_e64 s[4:5], s37, v24
	ds_read2st64_b32 v[154:155], v106 offset0:80 offset1:81
	s_nop 0
	v_cndmask_b32_e64 v26, v231, v232, s[4:5]
	v_add3_u32 v26, v26, v124, s17
	v_cndmask_b32_e32 v24, v26, v24, vcc
	s_waitcnt lgkmcnt(1)
	v_cvt_pk_bf16_f32 v26, v25, s0
	v_ashrrev_i32_e32 v25, 31, v24
	v_lshl_add_u64 v[24:25], s[68:69], 0, v[24:25]
	v_lshlrev_b64 v[24:25], 10, v[24:25]
	v_lshl_add_u64 v[24:25], v[38:39], 0, v[24:25]
	global_store_short v[24:25], v26, off
	v_add_u32_e64 v24, s21, 0
	ds_read2_b64 v[24:27], v24 offset1:1
	ds_read_b128 v[28:31], v105
	ds_read_b128 v[98:101], v105 offset:256
	ds_read_b128 v[126:129], v105 offset:4096
	ds_read_b128 v[130:133], v105 offset:4352
	ds_read_b128 v[134:137], v105 offset:8192
	ds_read_b128 v[138:141], v105 offset:8448
	ds_read_b128 v[142:145], v105 offset:12288
	ds_read_b128 v[146:149], v105 offset:12544
	ds_read_b128 v[150:153], v105 offset:16384
	ds_read_b128 v[168:171], v105 offset:16640
	s_waitcnt lgkmcnt(9)
	v_pk_mul_f32 v[30:31], v[22:23], v[30:31]
	s_nop 0
	v_pk_fma_f32 v[28:29], v[20:21], v[28:29], v[30:31]
	s_waitcnt lgkmcnt(7)
	v_pk_mul_f32 v[30:31], v[22:23], v[128:129]
	v_add_f32_e32 v28, v28, v29
	v_pk_fma_f32 v[30:31], v[20:21], v[126:127], v[30:31]
	s_nop 0
	v_add_f32_e32 v29, v30, v31
	v_add_f32_dpp v28, v28, v28 quad_perm:[1,0,3,2] row_mask:0xf bank_mask:0xf bound_ctrl:1
	s_nop 0
	v_add_f32_dpp v29, v29, v29 quad_perm:[1,0,3,2] row_mask:0xf bank_mask:0xf bound_ctrl:1
	v_add_f32_dpp v28, v28, v28 quad_perm:[2,3,0,1] row_mask:0xf bank_mask:0xf bound_ctrl:1
	s_nop 0
	v_add_f32_dpp v29, v29, v29 quad_perm:[2,3,0,1] row_mask:0xf bank_mask:0xf bound_ctrl:1
	v_add_f32_dpp v28, v28, v28 row_half_mirror row_mask:0xf bank_mask:0xf bound_ctrl:1
	s_nop 0
	v_add_f32_dpp v29, v29, v29 row_half_mirror row_mask:0xf bank_mask:0xf bound_ctrl:1
	v_add_f32_dpp v28, v28, v28 row_mirror row_mask:0xf bank_mask:0xf bound_ctrl:1
	s_nop 0
	v_add_f32_dpp v29, v29, v29 row_mirror row_mask:0xf bank_mask:0xf bound_ctrl:1
	v_fmac_f32_e32 v29, v24, v28
	v_fmac_f32_e32 v29, v154, v25
	s_waitcnt lgkmcnt(3)
	v_pk_mul_f32 v[24:25], v[142:143], v[28:29] op_sel_hi:[1,0]
	ds_write_b32 v107, v29 offset:49408
	s_waitcnt lgkmcnt(2)
; DI float row16_sum(float v) { v += dppf(v, 0); v += dppf(v, 1); v += dppf(v, 2); v += dppf(v, 3); return v; }
; DI void rwkv_scan(CP p, const Ptrs& w, int l, int item, float* sm) {
;     ...
;   auto lds_step = [&](const float* bf, int j) {
;     RStep q;
;     q.a4 = *(const f4v*)(bf + 0 * 1024 + j * 64 + 4 * kg);
;     q.wr4 = *(const f4v*)(bf + 1 * 1024 + j * 64 + 4 * kg);
;     q.w4 = *(const f4v*)(bf + 2 * 1024 + j * 64 + 4 * kg);
;     q.b4 = *(const f4v*)(bf + 3 * 1024 + j * 64 + 4 * kg);
;     q.k4 = *(const f4v*)(bf + 4 * 1024 + j * 64 + 4 * kg);
;     q.vv = bf[5 * 1024 + j * 64 + row];
;     q.sc = *(const float2*)(bf + 6 * 1024 + j * 2);
;     return q;
;   };
;   auto flush = [&](int c) {
;     {
;       int j = tid >> 4, rr = tid & 15;
;       int ii = pos2i(c * 16 + j, dir);
;       yout[((size_t)b * TPB + ii) * 512 + hd * 64 + rq * 16 + rr] = f2bf(sY[(c & 1) * 256 + j * 16 + rr]);
;     }
;   };
;   __syncthreads();
;   load(0, PA);
;   stage(PA, sm);
;   load(1, PB);
;   __syncthreads();
;   const int NCH = TPB / 16;
;   auto run_chunk = [&](int c, const float* bf, float* sy) {
;     flush(max(c - 1, 0));
;     RStep cur = lds_step(bf, 0);
; #pragma unroll
;     for (int j = 0; j < 16; ++j) {
;       RStep nxt = cur;
;       if (j + 1 < 16) nxt = lds_step(bf, j + 1);
;       f2v sa2 = SA * cur.a4.xy + SB * cur.a4.zw;
;       f2v yp2 = SA * cur.wr4.xy + SB * cur.wr4.zw;
;       float sa = sa2.x + sa2.y, yp = yp2.x + yp2.y;
;       sa = row16_sum(sa); yp = row16_sum(yp);
;       float y = yp + sa * cur.sc.x + cur.vv * cur.sc.y;
;       SA = SA * cur.w4.xy + (sa * cur.b4.xy + cur.vv * cur.k4.xy);
;       SB = SB * cur.w4.zw + (sa * cur.b4.zw + cur.vv * cur.k4.zw);
;       sy[(kg == 0 ? j * 16 : 0) + ysel - (c & 1) * 0] = y;
;       cur = nxt;
;     }
	v_pk_fma_f32 v[24:25], v[150:151], v[154:155], v[24:25] op_sel_hi:[1,0,1]
	s_nop 0
	v_pk_fma_f32 v[24:25], v[20:21], v[134:135], v[24:25]
	v_pk_mul_f32 v[20:21], v[144:145], v[28:29] op_sel_hi:[1,0]
	s_nop 0
	v_pk_fma_f32 v[20:21], v[152:153], v[154:155], v[20:21] op_sel_hi:[1,0,1]
	s_nop 0
	v_pk_fma_f32 v[150:151], v[22:23], v[136:137], v[20:21]
	ds_read_b128 v[20:23], v105 offset:512
	ds_read_b128 v[28:31], v105 offset:4608
	ds_read_b128 v[126:129], v105 offset:8704
	ds_read_b128 v[134:137], v105 offset:12800
	ds_read_b128 v[142:145], v105 offset:16896
	ds_read_b32 v96, v106 offset:20992
	ds_read_b64 v[152:153], v157 offset:24592
	v_pk_mul_f32 v[100:101], v[100:101], v[150:151]
	s_nop 0
	v_pk_fma_f32 v[98:99], v[98:99], v[24:25], v[100:101]
	v_pk_mul_f32 v[100:101], v[132:133], v[150:151]
	v_add_f32_e32 v98, v98, v99
	v_pk_fma_f32 v[100:101], v[130:131], v[24:25], v[100:101]
	s_nop 0
	v_add_f32_e32 v99, v100, v101
	v_add_f32_dpp v98, v98, v98 quad_perm:[1,0,3,2] row_mask:0xf bank_mask:0xf bound_ctrl:1
	v_mov_b32_e32 v100, v155
	v_add_f32_dpp v99, v99, v99 quad_perm:[1,0,3,2] row_mask:0xf bank_mask:0xf bound_ctrl:1
	v_add_f32_dpp v98, v98, v98 quad_perm:[2,3,0,1] row_mask:0xf bank_mask:0xf bound_ctrl:1
	s_nop 0
	v_add_f32_dpp v99, v99, v99 quad_perm:[2,3,0,1] row_mask:0xf bank_mask:0xf bound_ctrl:1
	v_add_f32_dpp v98, v98, v98 row_half_mirror row_mask:0xf bank_mask:0xf bound_ctrl:1
	s_nop 0
	v_add_f32_dpp v99, v99, v99 row_half_mirror row_mask:0xf bank_mask:0xf bound_ctrl:1
	v_add_f32_dpp v98, v98, v98 row_mirror row_mask:0xf bank_mask:0xf bound_ctrl:1
	s_nop 0
	v_add_f32_dpp v99, v99, v99 row_mirror row_mask:0xf bank_mask:0xf bound_ctrl:1
	v_fmac_f32_e32 v99, v98, v26
	v_fmac_f32_e32 v99, v155, v27
	v_pk_mul_f32 v[26:27], v[146:147], v[98:99] op_sel_hi:[1,0]
	ds_write_b32 v108, v99 offset:49408
	s_waitcnt lgkmcnt(9)
	v_pk_fma_f32 v[26:27], v[168:169], v[100:101], v[26:27] op_sel_hi:[1,0,1]
	s_nop 0
	v_pk_fma_f32 v[154:155], v[138:139], v[24:25], v[26:27]
	v_pk_mul_f32 v[24:25], v[148:149], v[98:99] op_sel_hi:[1,0]
	s_nop 0
	v_pk_fma_f32 v[24:25], v[170:171], v[100:101], v[24:25] op_sel_hi:[1,0,1]
	s_nop 0
	v_pk_fma_f32 v[150:151], v[140:141], v[150:151], v[24:25]
	ds_read_b128 v[24:27], v105 offset:768
	ds_read_b128 v[98:101], v105 offset:4864
	ds_read_b128 v[130:133], v105 offset:8960
	ds_read_b128 v[138:141], v105 offset:13056
	ds_read_b128 v[146:149], v105 offset:17152
	ds_read_b32 v102, v106 offset:21248
	ds_read_b64 v[168:169], v157 offset:24600
	s_waitcnt lgkmcnt(14)
	v_pk_mul_f32 v[22:23], v[22:23], v[150:151]
	s_nop 0
	v_pk_fma_f32 v[20:21], v[20:21], v[154:155], v[22:23]
	s_waitcnt lgkmcnt(13)
	v_pk_mul_f32 v[22:23], v[30:31], v[150:151]
	v_add_f32_e32 v20, v20, v21
	v_pk_fma_f32 v[22:23], v[28:29], v[154:155], v[22:23]
	s_nop 0
	v_add_f32_e32 v21, v22, v23
	v_add_f32_dpp v20, v20, v20 quad_perm:[1,0,3,2] row_mask:0xf bank_mask:0xf bound_ctrl:1
	s_nop 0
	v_add_f32_dpp v21, v21, v21 quad_perm:[1,0,3,2] row_mask:0xf bank_mask:0xf bound_ctrl:1
	v_add_f32_dpp v20, v20, v20 quad_perm:[2,3,0,1] row_mask:0xf bank_mask:0xf bound_ctrl:1
	s_nop 0
	v_add_f32_dpp v21, v21, v21 quad_perm:[2,3,0,1] row_mask:0xf bank_mask:0xf bound_ctrl:1
	v_add_f32_dpp v20, v20, v20 row_half_mirror row_mask:0xf bank_mask:0xf bound_ctrl:1
	s_nop 0
	v_add_f32_dpp v21, v21, v21 row_half_mirror row_mask:0xf bank_mask:0xf bound_ctrl:1
	v_add_f32_dpp v20, v20, v20 row_mirror row_mask:0xf bank_mask:0xf bound_ctrl:1
	s_waitcnt lgkmcnt(11)
	v_pk_mul_f32 v[22:23], v[134:135], v[20:21] op_sel_hi:[1,0]
	v_add_f32_dpp v28, v21, v21 row_mirror row_mask:0xf bank_mask:0xf bound_ctrl:1
	s_waitcnt lgkmcnt(8)
	v_fmac_f32_e32 v28, v20, v152
	v_pk_mul_f32 v[20:21], v[136:137], v[20:21] op_sel_hi:[1,0]
	v_pk_fma_f32 v[22:23], v[142:143], v[96:97], v[22:23] op_sel_hi:[1,0,1]
	v_pk_fma_f32 v[20:21], v[144:145], v[96:97], v[20:21] op_sel_hi:[1,0,1]
	v_fmac_f32_e32 v28, v96, v153
	v_pk_fma_f32 v[150:151], v[128:129], v[150:151], v[20:21]
	v_pk_fma_f32 v[152:153], v[126:127], v[154:155], v[22:23]
	s_waitcnt lgkmcnt(6)
	v_pk_mul_f32 v[26:27], v[26:27], v[150:151]
	ds_write_b32 v109, v28 offset:49408
	v_pk_fma_f32 v[24:25], v[24:25], v[152:153], v[26:27]
	s_waitcnt lgkmcnt(6)
	v_pk_mul_f32 v[26:27], v[100:101], v[150:151]
	v_add_f32_e32 v24, v24, v25
	v_pk_fma_f32 v[26:27], v[98:99], v[152:153], v[26:27]
	ds_read_b128 v[20:23], v105 offset:1024
	ds_read_b128 v[28:31], v105 offset:5120
	ds_read_b128 v[126:129], v105 offset:9216
	ds_read_b128 v[134:137], v105 offset:13312
	ds_read_b128 v[142:145], v105 offset:17408
	ds_read_b32 v96, v106 offset:21504
	ds_read_b64 v[154:155], v157 offset:24608
	v_add_f32_e32 v25, v26, v27
	v_add_f32_dpp v24, v24, v24 quad_perm:[1,0,3,2] row_mask:0xf bank_mask:0xf bound_ctrl:1
	s_nop 0
	v_add_f32_dpp v25, v25, v25 quad_perm:[1,0,3,2] row_mask:0xf bank_mask:0xf bound_ctrl:1
	v_add_f32_dpp v24, v24, v24 quad_perm:[2,3,0,1] row_mask:0xf bank_mask:0xf bound_ctrl:1
	s_nop 0
	v_add_f32_dpp v25, v25, v25 quad_perm:[2,3,0,1] row_mask:0xf bank_mask:0xf bound_ctrl:1
	v_add_f32_dpp v24, v24, v24 row_half_mirror row_mask:0xf bank_mask:0xf bound_ctrl:1
	s_nop 0
	v_add_f32_dpp v25, v25, v25 row_half_mirror row_mask:0xf bank_mask:0xf bound_ctrl:1
	v_add_f32_dpp v24, v24, v24 row_mirror row_mask:0xf bank_mask:0xf bound_ctrl:1
	s_waitcnt lgkmcnt(11)
	v_pk_mul_f32 v[26:27], v[138:139], v[24:25] op_sel_hi:[1,0]
	v_add_f32_dpp v98, v25, v25 row_mirror row_mask:0xf bank_mask:0xf bound_ctrl:1
	s_waitcnt lgkmcnt(8)
; DI float row16_sum(float v) { v += dppf(v, 0); v += dppf(v, 1); v += dppf(v, 2); v += dppf(v, 3); return v; }
; DI void rwkv_scan(CP p, const Ptrs& w, int l, int item, float* sm) {
;     ...
;   auto lds_step = [&](const float* bf, int j) {
;     RStep q;
;     q.a4 = *(const f4v*)(bf + 0 * 1024 + j * 64 + 4 * kg);
;     q.wr4 = *(const f4v*)(bf + 1 * 1024 + j * 64 + 4 * kg);
;     q.w4 = *(const f4v*)(bf + 2 * 1024 + j * 64 + 4 * kg);
;     q.b4 = *(const f4v*)(bf + 3 * 1024 + j * 64 + 4 * kg);
;     q.k4 = *(const f4v*)(bf + 4 * 1024 + j * 64 + 4 * kg);
;     q.vv = bf[5 * 1024 + j * 64 + row];
;     q.sc = *(const float2*)(bf + 6 * 1024 + j * 2);
;     return q;
;   };
;   auto flush = [&](int c) {
;     {
;       int j = tid >> 4, rr = tid & 15;
;       int ii = pos2i(c * 16 + j, dir);
;       yout[((size_t)b * TPB + ii) * 512 + hd * 64 + rq * 16 + rr] = f2bf(sY[(c & 1) * 256 + j * 16 + rr]);
;     }
;   };
;   __syncthreads();
;   load(0, PA);
;   stage(PA, sm);
;   load(1, PB);
;   __syncthreads();
;   const int NCH = TPB / 16;
;   auto run_chunk = [&](int c, const float* bf, float* sy) {
;     flush(max(c - 1, 0));
;     RStep cur = lds_step(bf, 0);
; #pragma unroll
;     for (int j = 0; j < 16; ++j) {
;       RStep nxt = cur;
;       if (j + 1 < 16) nxt = lds_step(bf, j + 1);
;       f2v sa2 = SA * cur.a4.xy + SB * cur.a4.zw;
;       f2v yp2 = SA * cur.wr4.xy + SB * cur.wr4.zw;
;       float sa = sa2.x + sa2.y, yp = yp2.x + yp2.y;
;       sa = row16_sum(sa); yp = row16_sum(yp);
;       float y = yp + sa * cur.sc.x + cur.vv * cur.sc.y;
;       SA = SA * cur.w4.xy + (sa * cur.b4.xy + cur.vv * cur.k4.xy);
;       SB = SB * cur.w4.zw + (sa * cur.b4.zw + cur.vv * cur.k4.zw);
;       sy[(kg == 0 ? j * 16 : 0) + ysel - (c & 1) * 0] = y;
;       cur = nxt;
;     }
	v_fmac_f32_e32 v98, v24, v168
	v_pk_mul_f32 v[24:25], v[140:141], v[24:25] op_sel_hi:[1,0]
	v_pk_fma_f32 v[26:27], v[146:147], v[102:103], v[26:27] op_sel_hi:[1,0,1]
	v_pk_fma_f32 v[24:25], v[148:149], v[102:103], v[24:25] op_sel_hi:[1,0,1]
	v_pk_fma_f32 v[152:153], v[130:131], v[152:153], v[26:27]
	v_pk_fma_f32 v[150:151], v[132:133], v[150:151], v[24:25]
	v_fmac_f32_e32 v98, v102, v169
	s_waitcnt lgkmcnt(6)
	v_pk_mul_f32 v[22:23], v[22:23], v[150:151]
	ds_write_b32 v110, v98 offset:49408
	v_pk_fma_f32 v[20:21], v[20:21], v[152:153], v[22:23]
	s_waitcnt lgkmcnt(6)
	v_pk_mul_f32 v[22:23], v[30:31], v[150:151]
	v_add_f32_e32 v20, v20, v21
	v_pk_fma_f32 v[22:23], v[28:29], v[152:153], v[22:23]
	ds_read_b128 v[24:27], v105 offset:1280
	ds_read_b128 v[98:101], v105 offset:5376
	ds_read_b128 v[130:133], v105 offset:9472
	ds_read_b128 v[138:141], v105 offset:13568
	ds_read_b128 v[146:149], v105 offset:17664
	ds_read_b32 v102, v106 offset:21760
	ds_read_b64 v[168:169], v157 offset:24616
	v_add_f32_e32 v21, v22, v23
	v_add_f32_dpp v20, v20, v20 quad_perm:[1,0,3,2] row_mask:0xf bank_mask:0xf bound_ctrl:1
	s_nop 0
	v_add_f32_dpp v21, v21, v21 quad_perm:[1,0,3,2] row_mask:0xf bank_mask:0xf bound_ctrl:1
	v_add_f32_dpp v20, v20, v20 quad_perm:[2,3,0,1] row_mask:0xf bank_mask:0xf bound_ctrl:1
	s_nop 0
	v_add_f32_dpp v21, v21, v21 quad_perm:[2,3,0,1] row_mask:0xf bank_mask:0xf bound_ctrl:1
	v_add_f32_dpp v20, v20, v20 row_half_mirror row_mask:0xf bank_mask:0xf bound_ctrl:1
	s_nop 0
	v_add_f32_dpp v21, v21, v21 row_half_mirror row_mask:0xf bank_mask:0xf bound_ctrl:1
	v_add_f32_dpp v20, v20, v20 row_mirror row_mask:0xf bank_mask:0xf bound_ctrl:1
	s_waitcnt lgkmcnt(11)
	v_pk_mul_f32 v[22:23], v[134:135], v[20:21] op_sel_hi:[1,0]
	v_add_f32_dpp v28, v21, v21 row_mirror row_mask:0xf bank_mask:0xf bound_ctrl:1
	s_waitcnt lgkmcnt(8)
	v_fmac_f32_e32 v28, v20, v154
	v_pk_mul_f32 v[20:21], v[136:137], v[20:21] op_sel_hi:[1,0]
	v_pk_fma_f32 v[22:23], v[142:143], v[96:97], v[22:23] op_sel_hi:[1,0,1]
	v_pk_fma_f32 v[20:21], v[144:145], v[96:97], v[20:21] op_sel_hi:[1,0,1]
	v_pk_fma_f32 v[152:153], v[126:127], v[152:153], v[22:23]
	v_pk_fma_f32 v[150:151], v[128:129], v[150:151], v[20:21]
	v_fmac_f32_e32 v28, v96, v155
	s_waitcnt lgkmcnt(6)
	v_pk_mul_f32 v[26:27], v[26:27], v[150:151]
	ds_write_b32 v111, v28 offset:49408
	v_pk_fma_f32 v[24:25], v[24:25], v[152:153], v[26:27]
	s_waitcnt lgkmcnt(6)
	v_pk_mul_f32 v[26:27], v[100:101], v[150:151]
	v_add_f32_e32 v24, v24, v25
	v_pk_fma_f32 v[26:27], v[98:99], v[152:153], v[26:27]
	ds_read_b128 v[20:23], v105 offset:1536
	ds_read_b128 v[28:31], v105 offset:5632
	ds_read_b128 v[126:129], v105 offset:9728
	ds_read_b128 v[134:137], v105 offset:13824
	ds_read_b128 v[142:145], v105 offset:17920
	ds_read_b32 v96, v106 offset:22016
	ds_read_b64 v[154:155], v157 offset:24624
	v_add_f32_e32 v25, v26, v27
	v_add_f32_dpp v24, v24, v24 quad_perm:[1,0,3,2] row_mask:0xf bank_mask:0xf bound_ctrl:1
	s_nop 0
	v_add_f32_dpp v25, v25, v25 quad_perm:[1,0,3,2] row_mask:0xf bank_mask:0xf bound_ctrl:1
	v_add_f32_dpp v24, v24, v24 quad_perm:[2,3,0,1] row_mask:0xf bank_mask:0xf bound_ctrl:1
	s_nop 0
	v_add_f32_dpp v25, v25, v25 quad_perm:[2,3,0,1] row_mask:0xf bank_mask:0xf bound_ctrl:1
	v_add_f32_dpp v24, v24, v24 row_half_mirror row_mask:0xf bank_mask:0xf bound_ctrl:1
	s_nop 0
	v_add_f32_dpp v25, v25, v25 row_half_mirror row_mask:0xf bank_mask:0xf bound_ctrl:1
	v_add_f32_dpp v24, v24, v24 row_mirror row_mask:0xf bank_mask:0xf bound_ctrl:1
	s_waitcnt lgkmcnt(11)
	v_pk_mul_f32 v[26:27], v[138:139], v[24:25] op_sel_hi:[1,0]
	v_add_f32_dpp v98, v25, v25 row_mirror row_mask:0xf bank_mask:0xf bound_ctrl:1
	s_waitcnt lgkmcnt(8)
	v_fmac_f32_e32 v98, v24, v168
	v_pk_mul_f32 v[24:25], v[140:141], v[24:25] op_sel_hi:[1,0]
	v_pk_fma_f32 v[26:27], v[146:147], v[102:103], v[26:27] op_sel_hi:[1,0,1]
	v_pk_fma_f32 v[24:25], v[148:149], v[102:103], v[24:25] op_sel_hi:[1,0,1]
	v_pk_fma_f32 v[152:153], v[130:131], v[152:153], v[26:27]
	v_pk_fma_f32 v[150:151], v[132:133], v[150:151], v[24:25]
	v_fmac_f32_e32 v98, v102, v169
	s_waitcnt lgkmcnt(6)
	v_pk_mul_f32 v[22:23], v[22:23], v[150:151]
	ds_write_b32 v112, v98 offset:49408
	v_pk_fma_f32 v[20:21], v[20:21], v[152:153], v[22:23]
	s_waitcnt lgkmcnt(6)
	v_pk_mul_f32 v[22:23], v[30:31], v[150:151]
	v_add_f32_e32 v20, v20, v21
	v_pk_fma_f32 v[22:23], v[28:29], v[152:153], v[22:23]
	ds_read_b128 v[24:27], v105 offset:1792
	ds_read_b128 v[98:101], v105 offset:5888
	ds_read_b128 v[130:133], v105 offset:9984
	ds_read_b128 v[138:141], v105 offset:14080
	ds_read_b128 v[146:149], v105 offset:18176
	ds_read_b32 v102, v106 offset:22272
	ds_read_b64 v[168:169], v157 offset:24632
	v_add_f32_e32 v21, v22, v23
	v_add_f32_dpp v20, v20, v20 quad_perm:[1,0,3,2] row_mask:0xf bank_mask:0xf bound_ctrl:1
	s_nop 0
	v_add_f32_dpp v21, v21, v21 quad_perm:[1,0,3,2] row_mask:0xf bank_mask:0xf bound_ctrl:1
	v_add_f32_dpp v20, v20, v20 quad_perm:[2,3,0,1] row_mask:0xf bank_mask:0xf bound_ctrl:1
	s_nop 0
	v_add_f32_dpp v21, v21, v21 quad_perm:[2,3,0,1] row_mask:0xf bank_mask:0xf bound_ctrl:1
	v_add_f32_dpp v20, v20, v20 row_half_mirror row_mask:0xf bank_mask:0xf bound_ctrl:1
	s_nop 0
	v_add_f32_dpp v21, v21, v21 row_half_mirror row_mask:0xf bank_mask:0xf bound_ctrl:1
	v_add_f32_dpp v20, v20, v20 row_mirror row_mask:0xf bank_mask:0xf bound_ctrl:1
	s_waitcnt lgkmcnt(11)
	v_pk_mul_f32 v[22:23], v[134:135], v[20:21] op_sel_hi:[1,0]
	v_add_f32_dpp v28, v21, v21 row_mirror row_mask:0xf bank_mask:0xf bound_ctrl:1
	s_waitcnt lgkmcnt(8)
; DI float row16_sum(float v) { v += dppf(v, 0); v += dppf(v, 1); v += dppf(v, 2); v += dppf(v, 3); return v; }
; DI void rwkv_scan(CP p, const Ptrs& w, int l, int item, float* sm) {
;     ...
;   auto lds_step = [&](const float* bf, int j) {
;     RStep q;
;     q.a4 = *(const f4v*)(bf + 0 * 1024 + j * 64 + 4 * kg);
;     q.wr4 = *(const f4v*)(bf + 1 * 1024 + j * 64 + 4 * kg);
;     q.w4 = *(const f4v*)(bf + 2 * 1024 + j * 64 + 4 * kg);
;     q.b4 = *(const f4v*)(bf + 3 * 1024 + j * 64 + 4 * kg);
;     q.k4 = *(const f4v*)(bf + 4 * 1024 + j * 64 + 4 * kg);
;     q.vv = bf[5 * 1024 + j * 64 + row];
;     q.sc = *(const float2*)(bf + 6 * 1024 + j * 2);
;     return q;
;   };
;   auto flush = [&](int c) {
;     {
;       int j = tid >> 4, rr = tid & 15;
;       int ii = pos2i(c * 16 + j, dir);
;       yout[((size_t)b * TPB + ii) * 512 + hd * 64 + rq * 16 + rr] = f2bf(sY[(c & 1) * 256 + j * 16 + rr]);
;     }
;   };
;   __syncthreads();
;   load(0, PA);
;   stage(PA, sm);
;   load(1, PB);
;   __syncthreads();
;   const int NCH = TPB / 16;
;   auto run_chunk = [&](int c, const float* bf, float* sy) {
;     flush(max(c - 1, 0));
;     RStep cur = lds_step(bf, 0);
; #pragma unroll
;     for (int j = 0; j < 16; ++j) {
;       RStep nxt = cur;
;       if (j + 1 < 16) nxt = lds_step(bf, j + 1);
;       f2v sa2 = SA * cur.a4.xy + SB * cur.a4.zw;
;       f2v yp2 = SA * cur.wr4.xy + SB * cur.wr4.zw;
;       float sa = sa2.x + sa2.y, yp = yp2.x + yp2.y;
;       sa = row16_sum(sa); yp = row16_sum(yp);
;       float y = yp + sa * cur.sc.x + cur.vv * cur.sc.y;
;       SA = SA * cur.w4.xy + (sa * cur.b4.xy + cur.vv * cur.k4.xy);
;       SB = SB * cur.w4.zw + (sa * cur.b4.zw + cur.vv * cur.k4.zw);
;       sy[(kg == 0 ? j * 16 : 0) + ysel - (c & 1) * 0] = y;
;       cur = nxt;
;     }
	v_fmac_f32_e32 v28, v20, v154
	v_pk_mul_f32 v[20:21], v[136:137], v[20:21] op_sel_hi:[1,0]
	v_pk_fma_f32 v[22:23], v[142:143], v[96:97], v[22:23] op_sel_hi:[1,0,1]
	v_pk_fma_f32 v[20:21], v[144:145], v[96:97], v[20:21] op_sel_hi:[1,0,1]
	v_pk_fma_f32 v[152:153], v[126:127], v[152:153], v[22:23]
	v_pk_fma_f32 v[150:151], v[128:129], v[150:151], v[20:21]
	v_fmac_f32_e32 v28, v96, v155
	s_waitcnt lgkmcnt(6)
	v_pk_mul_f32 v[26:27], v[26:27], v[150:151]
	ds_write_b32 v113, v28 offset:49408
	v_pk_fma_f32 v[24:25], v[24:25], v[152:153], v[26:27]
	s_waitcnt lgkmcnt(6)
	v_pk_mul_f32 v[26:27], v[100:101], v[150:151]
	v_add_f32_e32 v24, v24, v25
	v_pk_fma_f32 v[26:27], v[98:99], v[152:153], v[26:27]
	ds_read_b128 v[20:23], v105 offset:2048
	ds_read_b128 v[28:31], v105 offset:6144
	ds_read_b128 v[126:129], v105 offset:10240
	ds_read_b128 v[134:137], v105 offset:14336
	ds_read_b128 v[142:145], v105 offset:18432
	ds_read_b32 v96, v106 offset:22528
	ds_read_b64 v[154:155], v157 offset:24640
	v_add_f32_e32 v25, v26, v27
	v_add_f32_dpp v24, v24, v24 quad_perm:[1,0,3,2] row_mask:0xf bank_mask:0xf bound_ctrl:1
	s_nop 0
	v_add_f32_dpp v25, v25, v25 quad_perm:[1,0,3,2] row_mask:0xf bank_mask:0xf bound_ctrl:1
	v_add_f32_dpp v24, v24, v24 quad_perm:[2,3,0,1] row_mask:0xf bank_mask:0xf bound_ctrl:1
	s_nop 0
	v_add_f32_dpp v25, v25, v25 quad_perm:[2,3,0,1] row_mask:0xf bank_mask:0xf bound_ctrl:1
	v_add_f32_dpp v24, v24, v24 row_half_mirror row_mask:0xf bank_mask:0xf bound_ctrl:1
	s_nop 0
	v_add_f32_dpp v25, v25, v25 row_half_mirror row_mask:0xf bank_mask:0xf bound_ctrl:1
	v_add_f32_dpp v24, v24, v24 row_mirror row_mask:0xf bank_mask:0xf bound_ctrl:1
	s_waitcnt lgkmcnt(11)
	v_pk_mul_f32 v[26:27], v[138:139], v[24:25] op_sel_hi:[1,0]
	v_add_f32_dpp v98, v25, v25 row_mirror row_mask:0xf bank_mask:0xf bound_ctrl:1
	s_waitcnt lgkmcnt(8)
	v_fmac_f32_e32 v98, v24, v168
	v_pk_mul_f32 v[24:25], v[140:141], v[24:25] op_sel_hi:[1,0]
	v_pk_fma_f32 v[26:27], v[146:147], v[102:103], v[26:27] op_sel_hi:[1,0,1]
	v_pk_fma_f32 v[24:25], v[148:149], v[102:103], v[24:25] op_sel_hi:[1,0,1]
	v_pk_fma_f32 v[152:153], v[130:131], v[152:153], v[26:27]
	v_pk_fma_f32 v[150:151], v[132:133], v[150:151], v[24:25]
	v_fmac_f32_e32 v98, v102, v169
	s_waitcnt lgkmcnt(6)
	v_pk_mul_f32 v[22:23], v[22:23], v[150:151]
	ds_write_b32 v114, v98 offset:49408
	v_pk_fma_f32 v[20:21], v[20:21], v[152:153], v[22:23]
	s_waitcnt lgkmcnt(6)
	v_pk_mul_f32 v[22:23], v[30:31], v[150:151]
	v_add_f32_e32 v20, v20, v21
	v_pk_fma_f32 v[22:23], v[28:29], v[152:153], v[22:23]
	ds_read_b128 v[24:27], v105 offset:2304
	ds_read_b128 v[98:101], v105 offset:6400
	ds_read_b128 v[130:133], v105 offset:10496
	ds_read_b128 v[138:141], v105 offset:14592
	ds_read_b128 v[146:149], v105 offset:18688
	ds_read_b32 v102, v106 offset:22784
	ds_read_b64 v[168:169], v157 offset:24648
	v_add_f32_e32 v21, v22, v23
	v_add_f32_dpp v20, v20, v20 quad_perm:[1,0,3,2] row_mask:0xf bank_mask:0xf bound_ctrl:1
	s_nop 0
	v_add_f32_dpp v21, v21, v21 quad_perm:[1,0,3,2] row_mask:0xf bank_mask:0xf bound_ctrl:1
	v_add_f32_dpp v20, v20, v20 quad_perm:[2,3,0,1] row_mask:0xf bank_mask:0xf bound_ctrl:1
	s_nop 0
	v_add_f32_dpp v21, v21, v21 quad_perm:[2,3,0,1] row_mask:0xf bank_mask:0xf bound_ctrl:1
	v_add_f32_dpp v20, v20, v20 row_half_mirror row_mask:0xf bank_mask:0xf bound_ctrl:1
	s_nop 0
	v_add_f32_dpp v21, v21, v21 row_half_mirror row_mask:0xf bank_mask:0xf bound_ctrl:1
	v_add_f32_dpp v20, v20, v20 row_mirror row_mask:0xf bank_mask:0xf bound_ctrl:1
	s_waitcnt lgkmcnt(11)
	v_pk_mul_f32 v[22:23], v[134:135], v[20:21] op_sel_hi:[1,0]
	v_add_f32_dpp v28, v21, v21 row_mirror row_mask:0xf bank_mask:0xf bound_ctrl:1
	s_waitcnt lgkmcnt(8)
	v_fmac_f32_e32 v28, v20, v154
	v_pk_mul_f32 v[20:21], v[136:137], v[20:21] op_sel_hi:[1,0]
	v_pk_fma_f32 v[22:23], v[142:143], v[96:97], v[22:23] op_sel_hi:[1,0,1]
	v_pk_fma_f32 v[20:21], v[144:145], v[96:97], v[20:21] op_sel_hi:[1,0,1]
	v_pk_fma_f32 v[152:153], v[126:127], v[152:153], v[22:23]
	v_pk_fma_f32 v[150:151], v[128:129], v[150:151], v[20:21]
	v_fmac_f32_e32 v28, v96, v155
	s_waitcnt lgkmcnt(6)
	v_pk_mul_f32 v[26:27], v[26:27], v[150:151]
	ds_write_b32 v115, v28 offset:49408
	v_pk_fma_f32 v[24:25], v[24:25], v[152:153], v[26:27]
	s_waitcnt lgkmcnt(6)
	v_pk_mul_f32 v[26:27], v[100:101], v[150:151]
	v_add_f32_e32 v24, v24, v25
	v_pk_fma_f32 v[26:27], v[98:99], v[152:153], v[26:27]
	ds_read_b128 v[20:23], v105 offset:2560
	ds_read_b128 v[28:31], v105 offset:6656
	ds_read_b128 v[126:129], v105 offset:10752
	ds_read_b128 v[134:137], v105 offset:14848
	ds_read_b128 v[142:145], v105 offset:18944
	ds_read_b32 v96, v106 offset:23040
	ds_read_b64 v[154:155], v157 offset:24656
	v_add_f32_e32 v25, v26, v27
	v_add_f32_dpp v24, v24, v24 quad_perm:[1,0,3,2] row_mask:0xf bank_mask:0xf bound_ctrl:1
	s_nop 0
	v_add_f32_dpp v25, v25, v25 quad_perm:[1,0,3,2] row_mask:0xf bank_mask:0xf bound_ctrl:1
	v_add_f32_dpp v24, v24, v24 quad_perm:[2,3,0,1] row_mask:0xf bank_mask:0xf bound_ctrl:1
	s_nop 0
	v_add_f32_dpp v25, v25, v25 quad_perm:[2,3,0,1] row_mask:0xf bank_mask:0xf bound_ctrl:1
	v_add_f32_dpp v24, v24, v24 row_half_mirror row_mask:0xf bank_mask:0xf bound_ctrl:1
	s_nop 0
	v_add_f32_dpp v25, v25, v25 row_half_mirror row_mask:0xf bank_mask:0xf bound_ctrl:1
	v_add_f32_dpp v24, v24, v24 row_mirror row_mask:0xf bank_mask:0xf bound_ctrl:1
	s_waitcnt lgkmcnt(11)
	v_pk_mul_f32 v[26:27], v[138:139], v[24:25] op_sel_hi:[1,0]
	v_add_f32_dpp v98, v25, v25 row_mirror row_mask:0xf bank_mask:0xf bound_ctrl:1
	s_waitcnt lgkmcnt(8)
; DI float row16_sum(float v) { v += dppf(v, 0); v += dppf(v, 1); v += dppf(v, 2); v += dppf(v, 3); return v; }
; DI void rwkv_scan(CP p, const Ptrs& w, int l, int item, float* sm) {
;     ...
;   auto lds_step = [&](const float* bf, int j) {
;     RStep q;
;     q.a4 = *(const f4v*)(bf + 0 * 1024 + j * 64 + 4 * kg);
;     q.wr4 = *(const f4v*)(bf + 1 * 1024 + j * 64 + 4 * kg);
;     q.w4 = *(const f4v*)(bf + 2 * 1024 + j * 64 + 4 * kg);
;     q.b4 = *(const f4v*)(bf + 3 * 1024 + j * 64 + 4 * kg);
;     q.k4 = *(const f4v*)(bf + 4 * 1024 + j * 64 + 4 * kg);
;     q.vv = bf[5 * 1024 + j * 64 + row];
;     q.sc = *(const float2*)(bf + 6 * 1024 + j * 2);
;     return q;
;   };
;   auto flush = [&](int c) {
;     {
;       int j = tid >> 4, rr = tid & 15;
;       int ii = pos2i(c * 16 + j, dir);
;       yout[((size_t)b * TPB + ii) * 512 + hd * 64 + rq * 16 + rr] = f2bf(sY[(c & 1) * 256 + j * 16 + rr]);
;     }
;   };
;   __syncthreads();
;   load(0, PA);
;   stage(PA, sm);
;   load(1, PB);
;   __syncthreads();
;   const int NCH = TPB / 16;
;   auto run_chunk = [&](int c, const float* bf, float* sy) {
;     flush(max(c - 1, 0));
;     RStep cur = lds_step(bf, 0);
; #pragma unroll
;     for (int j = 0; j < 16; ++j) {
;       RStep nxt = cur;
;       if (j + 1 < 16) nxt = lds_step(bf, j + 1);
;       f2v sa2 = SA * cur.a4.xy + SB * cur.a4.zw;
;       f2v yp2 = SA * cur.wr4.xy + SB * cur.wr4.zw;
;       float sa = sa2.x + sa2.y, yp = yp2.x + yp2.y;
;       sa = row16_sum(sa); yp = row16_sum(yp);
;       float y = yp + sa * cur.sc.x + cur.vv * cur.sc.y;
;       SA = SA * cur.w4.xy + (sa * cur.b4.xy + cur.vv * cur.k4.xy);
;       SB = SB * cur.w4.zw + (sa * cur.b4.zw + cur.vv * cur.k4.zw);
;       sy[(kg == 0 ? j * 16 : 0) + ysel - (c & 1) * 0] = y;
;       cur = nxt;
;     }
	v_fmac_f32_e32 v98, v24, v168
	v_pk_mul_f32 v[24:25], v[140:141], v[24:25] op_sel_hi:[1,0]
	v_pk_fma_f32 v[26:27], v[146:147], v[102:103], v[26:27] op_sel_hi:[1,0,1]
	v_pk_fma_f32 v[24:25], v[148:149], v[102:103], v[24:25] op_sel_hi:[1,0,1]
	v_pk_fma_f32 v[152:153], v[130:131], v[152:153], v[26:27]
	v_pk_fma_f32 v[150:151], v[132:133], v[150:151], v[24:25]
	v_fmac_f32_e32 v98, v102, v169
	s_waitcnt lgkmcnt(6)
	v_pk_mul_f32 v[22:23], v[22:23], v[150:151]
	ds_write_b32 v116, v98 offset:49408
	v_pk_fma_f32 v[20:21], v[20:21], v[152:153], v[22:23]
	s_waitcnt lgkmcnt(6)
	v_pk_mul_f32 v[22:23], v[30:31], v[150:151]
	v_add_f32_e32 v20, v20, v21
	v_pk_fma_f32 v[22:23], v[28:29], v[152:153], v[22:23]
	ds_read_b128 v[24:27], v105 offset:2816
	ds_read_b128 v[98:101], v105 offset:6912
	ds_read_b128 v[130:133], v105 offset:11008
	ds_read_b128 v[138:141], v105 offset:15104
	ds_read_b128 v[146:149], v105 offset:19200
	ds_read_b32 v102, v106 offset:23296
	ds_read_b64 v[168:169], v157 offset:24664
	v_add_f32_e32 v21, v22, v23
	v_add_f32_dpp v20, v20, v20 quad_perm:[1,0,3,2] row_mask:0xf bank_mask:0xf bound_ctrl:1
	s_nop 0
	v_add_f32_dpp v21, v21, v21 quad_perm:[1,0,3,2] row_mask:0xf bank_mask:0xf bound_ctrl:1
	v_add_f32_dpp v20, v20, v20 quad_perm:[2,3,0,1] row_mask:0xf bank_mask:0xf bound_ctrl:1
	s_nop 0
	v_add_f32_dpp v21, v21, v21 quad_perm:[2,3,0,1] row_mask:0xf bank_mask:0xf bound_ctrl:1
	v_add_f32_dpp v20, v20, v20 row_half_mirror row_mask:0xf bank_mask:0xf bound_ctrl:1
	s_nop 0
	v_add_f32_dpp v21, v21, v21 row_half_mirror row_mask:0xf bank_mask:0xf bound_ctrl:1
	v_add_f32_dpp v20, v20, v20 row_mirror row_mask:0xf bank_mask:0xf bound_ctrl:1
	s_waitcnt lgkmcnt(11)
	v_pk_mul_f32 v[22:23], v[134:135], v[20:21] op_sel_hi:[1,0]
	v_add_f32_dpp v28, v21, v21 row_mirror row_mask:0xf bank_mask:0xf bound_ctrl:1
	s_waitcnt lgkmcnt(8)
	v_fmac_f32_e32 v28, v20, v154
	v_pk_mul_f32 v[20:21], v[136:137], v[20:21] op_sel_hi:[1,0]
	v_pk_fma_f32 v[22:23], v[142:143], v[96:97], v[22:23] op_sel_hi:[1,0,1]
	v_pk_fma_f32 v[20:21], v[144:145], v[96:97], v[20:21] op_sel_hi:[1,0,1]
	v_pk_fma_f32 v[152:153], v[126:127], v[152:153], v[22:23]
	v_pk_fma_f32 v[150:151], v[128:129], v[150:151], v[20:21]
	v_fmac_f32_e32 v28, v96, v155
	s_waitcnt lgkmcnt(6)
	v_pk_mul_f32 v[26:27], v[26:27], v[150:151]
	ds_write_b32 v117, v28 offset:49408
	v_pk_fma_f32 v[24:25], v[24:25], v[152:153], v[26:27]
	s_waitcnt lgkmcnt(6)
	v_pk_mul_f32 v[26:27], v[100:101], v[150:151]
	v_add_f32_e32 v24, v24, v25
	v_pk_fma_f32 v[26:27], v[98:99], v[152:153], v[26:27]
	ds_read_b128 v[20:23], v105 offset:3072
	ds_read_b128 v[28:31], v105 offset:7168
	ds_read_b128 v[126:129], v105 offset:11264
	ds_read_b128 v[134:137], v105 offset:15360
	ds_read_b128 v[142:145], v105 offset:19456
	ds_read_b32 v96, v106 offset:23552
	ds_read_b64 v[154:155], v157 offset:24672
	v_add_f32_e32 v25, v26, v27
	v_add_f32_dpp v24, v24, v24 quad_perm:[1,0,3,2] row_mask:0xf bank_mask:0xf bound_ctrl:1
	s_nop 0
	v_add_f32_dpp v25, v25, v25 quad_perm:[1,0,3,2] row_mask:0xf bank_mask:0xf bound_ctrl:1
	v_add_f32_dpp v24, v24, v24 quad_perm:[2,3,0,1] row_mask:0xf bank_mask:0xf bound_ctrl:1
	s_nop 0
	v_add_f32_dpp v25, v25, v25 quad_perm:[2,3,0,1] row_mask:0xf bank_mask:0xf bound_ctrl:1
	v_add_f32_dpp v24, v24, v24 row_half_mirror row_mask:0xf bank_mask:0xf bound_ctrl:1
	s_nop 0
	v_add_f32_dpp v25, v25, v25 row_half_mirror row_mask:0xf bank_mask:0xf bound_ctrl:1
	v_add_f32_dpp v24, v24, v24 row_mirror row_mask:0xf bank_mask:0xf bound_ctrl:1
	s_waitcnt lgkmcnt(11)
	v_pk_mul_f32 v[26:27], v[138:139], v[24:25] op_sel_hi:[1,0]
	v_add_f32_dpp v98, v25, v25 row_mirror row_mask:0xf bank_mask:0xf bound_ctrl:1
	s_waitcnt lgkmcnt(8)
	v_fmac_f32_e32 v98, v24, v168
	v_pk_mul_f32 v[24:25], v[140:141], v[24:25] op_sel_hi:[1,0]
	v_pk_fma_f32 v[26:27], v[146:147], v[102:103], v[26:27] op_sel_hi:[1,0,1]
	v_pk_fma_f32 v[24:25], v[148:149], v[102:103], v[24:25] op_sel_hi:[1,0,1]
	v_pk_fma_f32 v[152:153], v[130:131], v[152:153], v[26:27]
	v_pk_fma_f32 v[150:151], v[132:133], v[150:151], v[24:25]
	v_fmac_f32_e32 v98, v102, v169
	s_waitcnt lgkmcnt(6)
	v_pk_mul_f32 v[22:23], v[22:23], v[150:151]
	ds_write_b32 v118, v98 offset:49408
	v_pk_fma_f32 v[20:21], v[20:21], v[152:153], v[22:23]
	s_waitcnt lgkmcnt(6)
	v_pk_mul_f32 v[22:23], v[30:31], v[150:151]
	v_add_f32_e32 v20, v20, v21
	v_pk_fma_f32 v[22:23], v[28:29], v[152:153], v[22:23]
	ds_read_b128 v[24:27], v105 offset:3328
	ds_read_b128 v[98:101], v105 offset:7424
	ds_read_b128 v[130:133], v105 offset:11520
	ds_read_b128 v[138:141], v105 offset:15616
	ds_read_b128 v[146:149], v105 offset:19712
	ds_read_b32 v102, v106 offset:23808
	ds_read_b64 v[172:173], v157 offset:24680
	v_add_f32_e32 v21, v22, v23
	v_add_f32_dpp v20, v20, v20 quad_perm:[1,0,3,2] row_mask:0xf bank_mask:0xf bound_ctrl:1
	s_nop 0
	v_add_f32_dpp v21, v21, v21 quad_perm:[1,0,3,2] row_mask:0xf bank_mask:0xf bound_ctrl:1
	v_add_f32_dpp v20, v20, v20 quad_perm:[2,3,0,1] row_mask:0xf bank_mask:0xf bound_ctrl:1
	s_nop 0
	v_add_f32_dpp v21, v21, v21 quad_perm:[2,3,0,1] row_mask:0xf bank_mask:0xf bound_ctrl:1
	v_add_f32_dpp v20, v20, v20 row_half_mirror row_mask:0xf bank_mask:0xf bound_ctrl:1
	s_nop 0
	v_add_f32_dpp v21, v21, v21 row_half_mirror row_mask:0xf bank_mask:0xf bound_ctrl:1
	v_add_f32_dpp v20, v20, v20 row_mirror row_mask:0xf bank_mask:0xf bound_ctrl:1
	s_waitcnt lgkmcnt(11)
	v_pk_mul_f32 v[22:23], v[134:135], v[20:21] op_sel_hi:[1,0]
	v_add_f32_dpp v28, v21, v21 row_mirror row_mask:0xf bank_mask:0xf bound_ctrl:1
	s_waitcnt lgkmcnt(8)
; DI float row16_sum(float v) { v += dppf(v, 0); v += dppf(v, 1); v += dppf(v, 2); v += dppf(v, 3); return v; }
; DI void rwkv_scan(CP p, const Ptrs& w, int l, int item, float* sm) {
;     ...
;     up4(P.pq[0][0], rc); up4(P.pq[0][1], rp); up4(P.pq[0][2], rn);
;     up4(P.pq[1][0], kc); up4(P.pq[1][1], kp); up4(P.pq[1][2], kn);
;     up4(P.pq[2][0], vc); up4(P.pq[2][1], vp); up4(P.pq[2][2], vn);
;     up4(P.pwd, wd4); up4(P.pad_, ad4);
;     float o0[4], o1[4], o2[4], o3[4], o4[4], o5[4];
; #pragma unroll
;     for (int j = 0; j < 4; ++j) {
;       float r_s = rc[j] + ((P.pmk[0] * rp[j] + P.pmk[1] * rn[j]) - rc[j]) * mu_r[j];
;       float k_s = kc[j] + ((P.pmk[0] * kp[j] + P.pmk[1] * kn[j]) - kc[j]) * mu_k[j];
;       float v_s = vc[j] + ((P.pmk[0] * vp[j] + P.pmk[1] * vn[j]) - vc[j]) * mu_v[j];
;       float kk = k_s * kk_c[j] * P.psc[0];
;       float a = ad4[j], wv = 1.f - wd4[j];
;       o0[j] = -kk; o1[j] = wv * r_s; o2[j] = wv; o3[j] = kk * a; o4[j] = k_s * (1.f + (a - 1.f) * ka_c[j]); o5[j] = v_s;
;     ...
;     for (int j = 0; j < 16; ++j) {
;       RStep nxt = cur;
;       if (j + 1 < 16) nxt = lds_step(bf, j + 1);
;       f2v sa2 = SA * cur.a4.xy + SB * cur.a4.zw;
;       f2v yp2 = SA * cur.wr4.xy + SB * cur.wr4.zw;
;       float sa = sa2.x + sa2.y, yp = yp2.x + yp2.y;
;       sa = row16_sum(sa); yp = row16_sum(yp);
;       float y = yp + sa * cur.sc.x + cur.vv * cur.sc.y;
;       SA = SA * cur.w4.xy + (sa * cur.b4.xy + cur.vv * cur.k4.xy);
;       SB = SB * cur.w4.zw + (sa * cur.b4.zw + cur.vv * cur.k4.zw);
;       sy[(kg == 0 ? j * 16 : 0) + ysel - (c & 1) * 0] = y;
;       cur = nxt;
;     }
	v_fmac_f32_e32 v28, v20, v154
	v_pk_mul_f32 v[20:21], v[136:137], v[20:21] op_sel_hi:[1,0]
	v_pk_fma_f32 v[22:23], v[142:143], v[96:97], v[22:23] op_sel_hi:[1,0,1]
	v_pk_fma_f32 v[20:21], v[144:145], v[96:97], v[20:21] op_sel_hi:[1,0,1]
	v_pk_fma_f32 v[22:23], v[126:127], v[152:153], v[22:23]
	v_pk_fma_f32 v[20:21], v[128:129], v[150:151], v[20:21]
	v_fmac_f32_e32 v28, v96, v155
	s_waitcnt lgkmcnt(6)
	v_pk_mul_f32 v[26:27], v[26:27], v[20:21]
	ds_write_b32 v119, v28 offset:49408
	v_pk_fma_f32 v[24:25], v[24:25], v[22:23], v[26:27]
	s_waitcnt lgkmcnt(6)
	v_pk_mul_f32 v[26:27], v[100:101], v[20:21]
	v_add_f32_e32 v24, v24, v25
	v_pk_fma_f32 v[26:27], v[98:99], v[22:23], v[26:27]
	ds_read_b128 v[126:129], v105 offset:3584
	ds_read_b128 v[134:137], v105 offset:7680
	ds_read_b128 v[142:145], v105 offset:11776
	ds_read_b128 v[150:153], v105 offset:15872
	ds_read_b128 v[168:171], v105 offset:19968
	ds_read_b32 v154, v106 offset:24064
	ds_read_b64 v[174:175], v157 offset:24688
	v_add_f32_e32 v25, v26, v27
	v_add_f32_dpp v24, v24, v24 quad_perm:[1,0,3,2] row_mask:0xf bank_mask:0xf bound_ctrl:1
	s_nop 0
	v_add_f32_dpp v25, v25, v25 quad_perm:[1,0,3,2] row_mask:0xf bank_mask:0xf bound_ctrl:1
	v_add_f32_dpp v24, v24, v24 quad_perm:[2,3,0,1] row_mask:0xf bank_mask:0xf bound_ctrl:1
	s_nop 0
	v_add_f32_dpp v25, v25, v25 quad_perm:[2,3,0,1] row_mask:0xf bank_mask:0xf bound_ctrl:1
	v_add_f32_dpp v24, v24, v24 row_half_mirror row_mask:0xf bank_mask:0xf bound_ctrl:1
	s_nop 0
	v_add_f32_dpp v25, v25, v25 row_half_mirror row_mask:0xf bank_mask:0xf bound_ctrl:1
	v_add_f32_dpp v24, v24, v24 row_mirror row_mask:0xf bank_mask:0xf bound_ctrl:1
	s_nop 0
	v_add_f32_dpp v25, v25, v25 row_mirror row_mask:0xf bank_mask:0xf bound_ctrl:1
	s_waitcnt lgkmcnt(8)
	v_fmac_f32_e32 v25, v24, v172
	v_fmac_f32_e32 v25, v102, v173
	v_pk_mul_f32 v[26:27], v[138:139], v[24:25] op_sel_hi:[1,0]
	ds_write_b32 v120, v25 offset:49408
	v_pk_fma_f32 v[26:27], v[146:147], v[102:103], v[26:27] op_sel_hi:[1,0,1]
	s_nop 0
	v_pk_fma_f32 v[98:99], v[130:131], v[22:23], v[26:27]
	v_pk_mul_f32 v[22:23], v[140:141], v[24:25] op_sel_hi:[1,0]
	s_nop 0
	v_pk_fma_f32 v[22:23], v[148:149], v[102:103], v[22:23] op_sel_hi:[1,0,1]
	s_nop 0
	v_pk_fma_f32 v[100:101], v[132:133], v[20:21], v[22:23]
	ds_read_b128 v[130:133], v105 offset:3840
	ds_read_b128 v[138:141], v105 offset:7936
	ds_read_b128 v[20:23], v105 offset:12032
	ds_read_b128 v[28:31], v105 offset:16128
	ds_read_b128 v[24:27], v105 offset:20224
	ds_read_b32 v96, v106 offset:24320
	ds_read_b64 v[146:147], v157 offset:24696
	s_waitcnt lgkmcnt(14)
	v_pk_mul_f32 v[128:129], v[128:129], v[100:101]
	s_nop 0
	v_pk_fma_f32 v[126:127], v[126:127], v[98:99], v[128:129]
	s_waitcnt lgkmcnt(13)
	v_pk_mul_f32 v[128:129], v[136:137], v[100:101]
	v_add_f32_e32 v102, v126, v127
	v_pk_fma_f32 v[128:129], v[134:135], v[98:99], v[128:129]
	s_waitcnt vmcnt(21)
	v_and_b32_e32 v137, 0xffff0000, v52
	v_add_f32_e32 v126, v128, v129
	v_add_f32_dpp v102, v102, v102 quad_perm:[1,0,3,2] row_mask:0xf bank_mask:0xf bound_ctrl:1
	s_waitcnt vmcnt(20)
	v_lshlrev_b32_e32 v136, 16, v54
	v_add_f32_dpp v126, v126, v126 quad_perm:[1,0,3,2] row_mask:0xf bank_mask:0xf bound_ctrl:1
	v_add_f32_dpp v102, v102, v102 quad_perm:[2,3,0,1] row_mask:0xf bank_mask:0xf bound_ctrl:1
	s_waitcnt vmcnt(16)
	v_lshlrev_b32_e32 v134, 16, v64
	v_add_f32_dpp v126, v126, v126 quad_perm:[2,3,0,1] row_mask:0xf bank_mask:0xf bound_ctrl:1
	v_add_f32_dpp v102, v102, v102 row_half_mirror row_mask:0xf bank_mask:0xf bound_ctrl:1
	v_and_b32_e32 v135, 0xffff0000, v64
	v_add_f32_dpp v126, v126, v126 row_half_mirror row_mask:0xf bank_mask:0xf bound_ctrl:1
	v_add_f32_dpp v102, v102, v102 row_mirror row_mask:0xf bank_mask:0xf bound_ctrl:1
	v_lshlrev_b32_e32 v64, 16, v65
	v_add_f32_dpp v128, v126, v126 row_mirror row_mask:0xf bank_mask:0xf bound_ctrl:1
	s_waitcnt lgkmcnt(11)
	v_pk_mul_f32 v[126:127], v[150:151], v[102:103] op_sel_hi:[1,0]
	s_waitcnt lgkmcnt(8)
	v_fmac_f32_e32 v128, v102, v174
	v_pk_fma_f32 v[126:127], v[168:169], v[154:155], v[126:127] op_sel_hi:[1,0,1]
	v_fmac_f32_e32 v128, v154, v175
	v_pk_fma_f32 v[98:99], v[142:143], v[98:99], v[126:127]
	v_pk_mul_f32 v[126:127], v[152:153], v[102:103] op_sel_hi:[1,0]
	ds_write_b32 v121, v128 offset:49408
	v_pk_fma_f32 v[126:127], v[170:171], v[154:155], v[126:127] op_sel_hi:[1,0,1]
	v_and_b32_e32 v65, 0xffff0000, v65
	v_pk_fma_f32 v[100:101], v[144:145], v[100:101], v[126:127]
	s_waitcnt lgkmcnt(7)
	v_pk_mul_f32 v[126:127], v[132:133], v[100:101]
	s_waitcnt lgkmcnt(6)
	v_pk_mul_f32 v[128:129], v[140:141], v[100:101]
	v_pk_fma_f32 v[126:127], v[130:131], v[98:99], v[126:127]
	v_pk_fma_f32 v[128:129], v[138:139], v[98:99], v[128:129]
	v_add_f32_e32 v102, v126, v127
	v_add_f32_e32 v126, v128, v129
	v_lshlrev_b32_e32 v138, 16, v52
	v_add_f32_dpp v102, v102, v102 quad_perm:[1,0,3,2] row_mask:0xf bank_mask:0xf bound_ctrl:1
	v_add_f32_dpp v126, v126, v126 quad_perm:[1,0,3,2] row_mask:0xf bank_mask:0xf bound_ctrl:1
	v_and_b32_e32 v139, 0xffff0000, v54
	v_add_f32_dpp v102, v102, v102 quad_perm:[2,3,0,1] row_mask:0xf bank_mask:0xf bound_ctrl:1
	v_add_f32_dpp v126, v126, v126 quad_perm:[2,3,0,1] row_mask:0xf bank_mask:0xf bound_ctrl:1
	v_and_b32_e32 v141, 0xffff0000, v53
	v_add_f32_dpp v102, v102, v102 row_half_mirror row_mask:0xf bank_mask:0xf bound_ctrl:1
	v_add_f32_dpp v126, v126, v126 row_half_mirror row_mask:0xf bank_mask:0xf bound_ctrl:1
	v_lshlrev_b32_e32 v52, 16, v53
	v_add_f32_dpp v102, v102, v102 row_mirror row_mask:0xf bank_mask:0xf bound_ctrl:1
	v_add_f32_dpp v126, v126, v126 row_mirror row_mask:0xf bank_mask:0xf bound_ctrl:1
	s_waitcnt lgkmcnt(1)
; DI void rwkv_scan(CP p, const Ptrs& w, int l, int item, float* sm) {
;     ...
;     up4(P.pq[0][0], rc); up4(P.pq[0][1], rp); up4(P.pq[0][2], rn);
;     up4(P.pq[1][0], kc); up4(P.pq[1][1], kp); up4(P.pq[1][2], kn);
;     up4(P.pq[2][0], vc); up4(P.pq[2][1], vp); up4(P.pq[2][2], vn);
;     up4(P.pwd, wd4); up4(P.pad_, ad4);
;     float o0[4], o1[4], o2[4], o3[4], o4[4], o5[4];
; #pragma unroll
;     for (int j = 0; j < 4; ++j) {
;       float r_s = rc[j] + ((P.pmk[0] * rp[j] + P.pmk[1] * rn[j]) - rc[j]) * mu_r[j];
;       float k_s = kc[j] + ((P.pmk[0] * kp[j] + P.pmk[1] * kn[j]) - kc[j]) * mu_k[j];
;       float v_s = vc[j] + ((P.pmk[0] * vp[j] + P.pmk[1] * vn[j]) - vc[j]) * mu_v[j];
;       float kk = k_s * kk_c[j] * P.psc[0];
;       float a = ad4[j], wv = 1.f - wd4[j];
;       o0[j] = -kk; o1[j] = wv * r_s; o2[j] = wv; o3[j] = kk * a; o4[j] = k_s * (1.f + (a - 1.f) * ka_c[j]); o5[j] = v_s;
;     }
;     float* d = bufp + sj * 64 + skq;
;     *(float4*)(d + 0 * 1024) = make_float4(o0[0], o0[1], o0[2], o0[3]);
;     *(float4*)(d + 1 * 1024) = make_float4(o1[0], o1[1], o1[2], o1[3]);
;     *(float4*)(d + 2 * 1024) = make_float4(o2[0], o2[1], o2[2], o2[3]);
;     *(float4*)(d + 3 * 1024) = make_float4(o3[0], o3[1], o3[2], o3[3]);
;     *(float4*)(d + 4 * 1024) = make_float4(o4[0], o4[1], o4[2], o4[3]);
;     *(float4*)(d + 5 * 1024) = make_float4(o5[0], o5[1], o5[2], o5[3]);
;     if (skq == 0) *(float2*)(bufp + 6 * 1024 + sj * 2) = make_float2(P.psc[1], P.psc[2]);
	v_fmac_f32_e32 v126, v102, v146
	v_and_b32_e32 v53, 0xffff0000, v55
	v_fmac_f32_e32 v126, v96, v147
	v_pk_mul_f32 v[138:139], v[94:95], v[138:139] op_sel:[1,0] op_sel_hi:[0,1]
	v_lshlrev_b32_e32 v140, 16, v55
	v_pk_mul_f32 v[52:53], v[94:95], v[52:53] op_sel:[1,0] op_sel_hi:[0,1]
	ds_write_b32 v122, v126 offset:49408
	v_lshlrev_b32_e32 v126, 16, v58
	v_and_b32_e32 v127, 0xffff0000, v58
	v_lshlrev_b32_e32 v128, 16, v59
	v_and_b32_e32 v129, 0xffff0000, v59
	v_lshlrev_b32_e32 v58, 16, v60
	v_and_b32_e32 v59, 0xffff0000, v60
	v_lshlrev_b32_e32 v60, 16, v61
	v_and_b32_e32 v61, 0xffff0000, v61
	v_pk_fma_f32 v[136:137], v[94:95], v[136:137], v[138:139]
	v_pk_fma_f32 v[52:53], v[94:95], v[140:141], v[52:53]
	v_pk_add_f32 v[136:137], v[136:137], v[58:59] neg_lo:[0,1] neg_hi:[0,1]
	v_pk_add_f32 v[52:53], v[52:53], v[60:61] neg_lo:[0,1] neg_hi:[0,1]
	v_pk_fma_f32 v[136:137], v[8:9], v[136:137], v[58:59]
	v_pk_fma_f32 v[140:141], v[10:11], v[52:53], v[60:61]
	v_pk_mul_f32 v[58:59], v[12:13], v[136:137]
	v_pk_mul_f32 v[52:53], v[14:15], v[140:141]
	s_waitcnt vmcnt(15)
	v_pk_mul_f32 v[138:139], v[56:57], v[58:59] op_sel_hi:[0,1]
	v_pk_mul_f32 v[142:143], v[56:57], v[52:53] op_sel_hi:[0,1]
	v_xor_b32_e32 v59, 0x80000000, v139
	v_xor_b32_e32 v58, 0x80000000, v138
	v_xor_b32_e32 v61, 0x80000000, v143
	v_xor_b32_e32 v60, 0x80000000, v142
	ds_write_b128 v103, v[58:61] offset:24704
	v_lshlrev_b32_e32 v59, 16, v48
	v_and_b32_e32 v61, s0, v48
	v_and_b32_e32 v60, 0xffff0000, v50
	v_pk_mov_b32 v[58:59], v[58:59], v[60:61] op_sel:[1,0]
	v_lshlrev_b32_e32 v54, 16, v50
	v_and_b32_e32 v55, 0xffff0000, v48
	v_pk_mul_f32 v[58:59], v[94:95], v[58:59] op_sel:[1,0] op_sel_hi:[0,1]
	v_pk_fma_f32 v[54:55], v[94:95], v[54:55], v[58:59]
	v_lshlrev_b32_e32 v132, 16, v66
	v_and_b32_e32 v133, 0xffff0000, v66
	v_pk_add_f32 v[54:55], v[54:55], v[126:127] neg_lo:[0,1] neg_hi:[0,1]
	v_lshlrev_b32_e32 v66, 16, v67
	v_and_b32_e32 v67, 0xffff0000, v67
	v_pk_add_f32 v[52:53], v[132:133], 1.0 op_sel_hi:[1,0] neg_lo:[1,0] neg_hi:[1,0]
	v_pk_fma_f32 v[54:55], v[0:1], v[54:55], v[126:127]
	v_and_b32_e32 v61, 0xffff0000, v49
	v_pk_mul_f32 v[58:59], v[54:55], v[52:53]
	v_pk_add_f32 v[54:55], v[66:67], 1.0 op_sel_hi:[1,0] neg_lo:[1,0] neg_hi:[1,0]
	v_lshlrev_b32_e32 v67, 16, v49
	v_and_b32_e32 v49, s0, v49
	v_and_b32_e32 v48, 0xffff0000, v51
	v_pk_mov_b32 v[48:49], v[66:67], v[48:49] op_sel:[1,0]
	v_lshlrev_b32_e32 v60, 16, v51
	v_pk_mul_f32 v[48:49], v[94:95], v[48:49] op_sel:[1,0] op_sel_hi:[0,1]
	v_pk_fma_f32 v[48:49], v[94:95], v[60:61], v[48:49]
	v_pk_mul_f32 v[50:51], v[142:143], v[64:65]
	v_pk_add_f32 v[48:49], v[48:49], v[128:129] neg_lo:[0,1] neg_hi:[0,1]
	v_lshlrev_b32_e32 v130, 16, v62
	v_pk_fma_f32 v[48:49], v[2:3], v[48:49], v[128:129]
	v_and_b32_e32 v131, 0xffff0000, v62
	v_pk_mul_f32 v[60:61], v[48:49], v[54:55]
	v_pk_mul_f32 v[48:49], v[138:139], v[134:135]
	ds_write_b128 v103, v[58:61] offset:28800
	ds_write_b128 v103, v[52:55] offset:32896
	ds_write_b128 v103, v[48:51] offset:36992
	v_pk_add_f32 v[48:49], v[134:135], -1.0 op_sel_hi:[1,0]
	v_pk_add_f32 v[50:51], v[64:65], -1.0 op_sel_hi:[1,0]
	v_pk_fma_f32 v[48:49], v[16:17], v[48:49], 1.0 op_sel_hi:[1,1,0]
	v_pk_fma_f32 v[50:51], v[18:19], v[50:51], 1.0 op_sel_hi:[1,1,0]
	v_pk_mul_f32 v[48:49], v[48:49], v[136:137]
	v_pk_mul_f32 v[50:51], v[50:51], v[140:141]
	ds_write_b128 v103, v[48:51] offset:41088
	v_lshlrev_b32_e32 v51, 16, v40
	v_and_b32_e32 v53, s0, v40
	v_and_b32_e32 v52, 0xffff0000, v46
	v_pk_mov_b32 v[50:51], v[50:51], v[52:53] op_sel:[1,0]
	v_lshlrev_b32_e32 v48, 16, v46
	v_and_b32_e32 v49, 0xffff0000, v40
	v_pk_mul_f32 v[50:51], v[94:95], v[50:51] op_sel:[1,0] op_sel_hi:[0,1]
	v_pk_fma_f32 v[48:49], v[94:95], v[48:49], v[50:51]
	v_and_b32_e32 v51, 0xffff0000, v41
	v_lshlrev_b32_e32 v53, 16, v41
	v_and_b32_e32 v41, s0, v41
	v_and_b32_e32 v40, 0xffff0000, v47
	v_pk_mov_b32 v[40:41], v[52:53], v[40:41] op_sel:[1,0]
	v_lshlrev_b32_e32 v50, 16, v47
	v_pk_mul_f32 v[40:41], v[94:95], v[40:41] op_sel:[1,0] op_sel_hi:[0,1]
	v_lshlrev_b32_e32 v62, 16, v63
	v_and_b32_e32 v63, 0xffff0000, v63
	v_pk_fma_f32 v[40:41], v[94:95], v[50:51], v[40:41]
	v_pk_add_f32 v[48:49], v[48:49], v[130:131] neg_lo:[0,1] neg_hi:[0,1]
	v_pk_add_f32 v[40:41], v[40:41], v[62:63] neg_lo:[0,1] neg_hi:[0,1]
	v_pk_fma_f32 v[48:49], v[4:5], v[48:49], v[130:131]
	v_pk_fma_f32 v[50:51], v[6:7], v[40:41], v[62:63]
	ds_write_b128 v103, v[48:51] offset:45184
	s_and_saveexec_b64 s[4:5], s[40:41]
	s_cbranch_execz .LBB0_713
	s_waitcnt vmcnt(14)
	ds_write_b64 v104, v[44:45] offset:49280
; DI float row16_sum(float v) { v += dppf(v, 0); v += dppf(v, 1); v += dppf(v, 2); v += dppf(v, 3); return v; }
; DI void rwkv_scan(CP p, const Ptrs& w, int l, int item, float* sm) {
;     ...
;   auto load = [&](int c, RPre& P) {
;     int ii = pos2i(c * 16 + sj, dir);
;     size_t tok = (size_t)b * TPB + ii;
;     const bf16_t* prow = w.pB + tok * SPB + sc_;
;     bool hp = (ii != 0) && (ii != CTXL), hn = (ii != CTXL - 1) && (ii != TPB - 1);
;     const int op = hp ? -SPB : 0, on = hn ? SPB : 0;
;     P.pmk[0] = hp ? 0.5f : 0.f; P.pmk[1] = hn ? 0.5f : 0.f;
; #pragma unroll
;     for (int q = 0; q < 3; ++q) {
;       P.pq[q][0] = *(const uint2*)(prow + q * 512);
;       P.pq[q][1] = *(const uint2*)(prow + q * 512 + op);
;       P.pq[q][2] = *(const uint2*)(prow + q * 512 + on);
;     }
;     P.pwd = *(const uint2*)(Wd + tok * 512 + sc_);
;     P.pad_ = *(const uint2*)(Ad + tok * 512 + sc_);
;     const float* sc = w.bonus + (tok * 8 + hd) * 8;
;     P.psc[0] = sc[0]; P.psc[1] = sc[1 + 3 * dir]; P.psc[2] = sc[2 + 3 * dir];
;   };
;     ...
;     for (int j = 0; j < 16; ++j) {
;       RStep nxt = cur;
;       if (j + 1 < 16) nxt = lds_step(bf, j + 1);
;       f2v sa2 = SA * cur.a4.xy + SB * cur.a4.zw;
;       f2v yp2 = SA * cur.wr4.xy + SB * cur.wr4.zw;
;       float sa = sa2.x + sa2.y, yp = yp2.x + yp2.y;
;       sa = row16_sum(sa); yp = row16_sum(yp);
;       float y = yp + sa * cur.sc.x + cur.vv * cur.sc.y;
;       SA = SA * cur.w4.xy + (sa * cur.b4.xy + cur.vv * cur.k4.xy);
;       SB = SB * cur.w4.zw + (sa * cur.b4.zw + cur.vv * cur.k4.zw);
;       sy[(kg == 0 ? j * 16 : 0) + ysel - (c & 1) * 0] = y;
;       cur = nxt;
;     }
.LBB0_713:
	s_or_b64 exec, exec, s[4:5]
	v_pk_mul_f32 v[28:29], v[28:29], v[102:103] op_sel_hi:[1,0]
	s_add_i32 s10, s10, 2
	v_pk_fma_f32 v[24:25], v[24:25], v[96:97], v[28:29] op_sel_hi:[1,0,1]
	s_min_u32 s4, s10, 0x20c
	v_pk_fma_f32 v[154:155], v[20:21], v[98:99], v[24:25]
	v_pk_mul_f32 v[20:21], v[30:31], v[102:103] op_sel_hi:[1,0]
	v_cndmask_b32_e64 v95, 0.5, 0, s[42:43]
	v_pk_fma_f32 v[20:21], v[26:27], v[96:97], v[20:21] op_sel_hi:[1,0,1]
	v_cndmask_b32_e64 v94, 0.5, 0, s[44:45]
	v_pk_fma_f32 v[168:169], v[22:23], v[100:101], v[20:21]
	v_lshl_add_u32 v20, s4, 4, v123
	v_cmp_lt_i32_e64 s[4:5], s37, v20
	s_waitcnt lgkmcnt(0)
	s_barrier
	v_cndmask_b32_e64 v21, v231, v232, s[4:5]
	v_sub_u32_e32 v21, v21, v20
	v_cndmask_b32_e32 v20, v21, v20, vcc
	v_ashrrev_i32_e32 v21, 31, v20
	v_lshl_add_u64 v[22:23], s[68:69], 0, v[20:21]
	v_mad_u64_u32 v[24:25], s[4:5], v22, s20, v[42:43]
	v_mov_b32_e32 v26, v25
	v_mad_u64_u32 v[26:27], s[4:5], v23, s20, v[26:27]
	v_and_b32_e32 v21, 0xfffffeff, v20
	v_mov_b32_e32 v25, v26
	v_and_b32_e32 v26, 0xffffdfff, v20
	v_cmp_eq_u32_e64 s[42:43], 0, v21
	v_cmp_eq_u32_e64 s[44:45], s37, v26
	s_nop 0
	v_cndmask_b32_e64 v21, -1, 0, s[42:43]
	v_cndmask_b32_e64 v20, v236, 0, s[42:43]
	v_cndmask_b32_e64 v156, v237, 0, s[44:45]
	v_lshl_add_u64 v[20:21], v[24:25], 0, v[20:21]
	v_lshl_add_u64 v[26:27], v[24:25], 0, v[156:157]
	global_load_dwordx2 v[58:59], v[24:25], off
	global_load_dwordx2 v[60:61], v[24:25], off offset:1024
	global_load_dwordx2 v[62:63], v[24:25], off offset:2048
	global_load_dwordx2 v[48:49], v[20:21], off
	global_load_dwordx2 v[50:51], v[26:27], off
	global_load_dwordx2 v[52:53], v[20:21], off offset:1024
	global_load_dwordx2 v[40:41], v[20:21], off offset:2048
	v_lshlrev_b64 v[20:21], 10, v[22:23]
	v_lshl_add_u64 v[24:25], v[34:35], 0, v[20:21]
	v_lshl_add_u64 v[20:21], v[36:37], 0, v[20:21]
	global_load_dwordx2 v[54:55], v[26:27], off offset:1024
	global_load_dwordx2 v[46:47], v[26:27], off offset:2048
	global_load_dwordx2 v[66:67], v[24:25], off
	global_load_dwordx2 v[64:65], v[20:21], off
	v_lshlrev_b64 v[20:21], 8, v[22:23]
	v_lshl_add_u64 v[20:21], s[6:7], 0, v[20:21]
	v_lshl_add_u64 v[22:23], v[20:21], 0, s[90:91]
	global_load_dword v56, v[20:21], off
	global_load_dwordx2 v[44:45], v[22:23], off offset:4
	ds_read_b32 v21, v83 offset:49408
	v_cmp_lt_i32_e64 s[4:5], s37, v125
	s_waitcnt lgkmcnt(0)
	v_cvt_pk_bf16_f32 v22, v21, s0
	v_cndmask_b32_e64 v20, v231, v232, s[4:5]
	v_add_u32_e32 v20, v20, v124
	v_cndmask_b32_e32 v20, v20, v125, vcc
	v_ashrrev_i32_e32 v21, 31, v20
	v_lshl_add_u64 v[20:21], s[68:69], 0, v[20:21]
	v_lshlrev_b64 v[20:21], 10, v[20:21]
	v_lshl_add_u64 v[20:21], v[38:39], 0, v[20:21]
	global_store_short v[20:21], v22, off
	v_add_u32_e32 v20, 0x80, v106
	ds_read2st64_b32 v[170:171], v20 offset0:176 offset1:177
	v_add_u32_e64 v20, s22, 0
	ds_read2_b64 v[20:23], v20 offset0:16 offset1:17
	ds_read_b128 v[24:27], v105 offset:24704
	ds_read_b128 v[28:31], v105 offset:24960
	ds_read_b128 v[98:101], v105 offset:28800
	ds_read_b128 v[126:129], v105 offset:29056
	ds_read_b128 v[130:133], v105 offset:32896
	ds_read_b128 v[134:137], v105 offset:33152
	ds_read_b128 v[138:141], v105 offset:36992
	ds_read_b128 v[142:145], v105 offset:37248
	ds_read_b128 v[146:149], v105 offset:41088
	ds_read_b128 v[150:153], v105 offset:41344
	s_waitcnt lgkmcnt(9)
	v_pk_mul_f32 v[26:27], v[168:169], v[26:27]
	s_nop 0
	v_pk_fma_f32 v[24:25], v[154:155], v[24:25], v[26:27]
	s_waitcnt lgkmcnt(7)
	v_pk_mul_f32 v[26:27], v[168:169], v[100:101]
	v_add_f32_e32 v24, v24, v25
	v_pk_fma_f32 v[26:27], v[154:155], v[98:99], v[26:27]
	s_nop 0
	v_add_f32_e32 v25, v26, v27
	v_add_f32_dpp v24, v24, v24 quad_perm:[1,0,3,2] row_mask:0xf bank_mask:0xf bound_ctrl:1
	s_nop 0
	v_add_f32_dpp v25, v25, v25 quad_perm:[1,0,3,2] row_mask:0xf bank_mask:0xf bound_ctrl:1
	v_add_f32_dpp v24, v24, v24 quad_perm:[2,3,0,1] row_mask:0xf bank_mask:0xf bound_ctrl:1
	s_nop 0
	v_add_f32_dpp v25, v25, v25 quad_perm:[2,3,0,1] row_mask:0xf bank_mask:0xf bound_ctrl:1
	v_add_f32_dpp v24, v24, v24 row_half_mirror row_mask:0xf bank_mask:0xf bound_ctrl:1
	s_nop 0
	v_add_f32_dpp v25, v25, v25 row_half_mirror row_mask:0xf bank_mask:0xf bound_ctrl:1
	v_add_f32_dpp v24, v24, v24 row_mirror row_mask:0xf bank_mask:0xf bound_ctrl:1
	s_nop 0
	v_add_f32_dpp v26, v25, v25 row_mirror row_mask:0xf bank_mask:0xf bound_ctrl:1
	v_fmac_f32_e32 v26, v20, v24
	v_fmac_f32_e32 v26, v170, v21
	s_waitcnt lgkmcnt(3)
	v_pk_mul_f32 v[20:21], v[138:139], v[24:25] op_sel_hi:[1,0]
	v_pk_mul_f32 v[24:25], v[140:141], v[24:25] op_sel_hi:[1,0]
	s_waitcnt lgkmcnt(1)
	v_pk_fma_f32 v[20:21], v[146:147], v[170:171], v[20:21] op_sel_hi:[1,0,1]
	v_pk_fma_f32 v[24:25], v[148:149], v[170:171], v[24:25] op_sel_hi:[1,0,1]
	v_pk_fma_f32 v[20:21], v[154:155], v[130:131], v[20:21]
	v_pk_fma_f32 v[154:155], v[168:169], v[132:133], v[24:25]
	ds_write_b32 v107, v26 offset:50432
	v_pk_mul_f32 v[30:31], v[30:31], v[154:155]
	ds_read_b128 v[24:27], v105 offset:33408
	ds_read_b128 v[98:101], v105 offset:37504
	ds_read_b128 v[130:133], v105 offset:25216
	ds_read_b128 v[138:141], v105 offset:41600
	ds_read_b128 v[146:149], v105 offset:29312
	ds_read_b32 v96, v106 offset:45696
	ds_read_b64 v[168:169], v157 offset:49296
	v_pk_fma_f32 v[28:29], v[28:29], v[20:21], v[30:31]
	v_pk_mul_f32 v[30:31], v[128:129], v[154:155]
	v_add_f32_e32 v28, v28, v29
	v_pk_fma_f32 v[30:31], v[126:127], v[20:21], v[30:31]
	s_nop 0
	v_add_f32_e32 v29, v30, v31
	v_add_f32_dpp v28, v28, v28 quad_perm:[1,0,3,2] row_mask:0xf bank_mask:0xf bound_ctrl:1
	v_mov_b32_e32 v30, v171
	v_add_f32_dpp v29, v29, v29 quad_perm:[1,0,3,2] row_mask:0xf bank_mask:0xf bound_ctrl:1
	v_add_f32_dpp v28, v28, v28 quad_perm:[2,3,0,1] row_mask:0xf bank_mask:0xf bound_ctrl:1
	s_nop 0
	v_add_f32_dpp v29, v29, v29 quad_perm:[2,3,0,1] row_mask:0xf bank_mask:0xf bound_ctrl:1
	v_add_f32_dpp v28, v28, v28 row_half_mirror row_mask:0xf bank_mask:0xf bound_ctrl:1
	s_nop 0
	v_add_f32_dpp v29, v29, v29 row_half_mirror row_mask:0xf bank_mask:0xf bound_ctrl:1
	v_add_f32_dpp v28, v28, v28 row_mirror row_mask:0xf bank_mask:0xf bound_ctrl:1
	s_nop 0
	v_add_f32_dpp v29, v29, v29 row_mirror row_mask:0xf bank_mask:0xf bound_ctrl:1
	v_fmac_f32_e32 v29, v28, v22
	v_fmac_f32_e32 v29, v171, v23
	v_pk_mul_f32 v[22:23], v[142:143], v[28:29] op_sel_hi:[1,0]
	ds_write_b32 v108, v29 offset:50432
	s_waitcnt lgkmcnt(9)
; DI float row16_sum(float v) { v += dppf(v, 0); v += dppf(v, 1); v += dppf(v, 2); v += dppf(v, 3); return v; }
; DI void rwkv_scan(CP p, const Ptrs& w, int l, int item, float* sm) {
;     ...
;     for (int j = 0; j < 16; ++j) {
;       RStep nxt = cur;
;       if (j + 1 < 16) nxt = lds_step(bf, j + 1);
;       f2v sa2 = SA * cur.a4.xy + SB * cur.a4.zw;
;       f2v yp2 = SA * cur.wr4.xy + SB * cur.wr4.zw;
;       float sa = sa2.x + sa2.y, yp = yp2.x + yp2.y;
;       sa = row16_sum(sa); yp = row16_sum(yp);
;       float y = yp + sa * cur.sc.x + cur.vv * cur.sc.y;
;       SA = SA * cur.w4.xy + (sa * cur.b4.xy + cur.vv * cur.k4.xy);
;       SB = SB * cur.w4.zw + (sa * cur.b4.zw + cur.vv * cur.k4.zw);
;       sy[(kg == 0 ? j * 16 : 0) + ysel - (c & 1) * 0] = y;
;       cur = nxt;
;     }
	v_pk_fma_f32 v[22:23], v[150:151], v[30:31], v[22:23] op_sel_hi:[1,0,1]
	s_nop 0
	v_pk_fma_f32 v[150:151], v[134:135], v[20:21], v[22:23]
	v_pk_mul_f32 v[20:21], v[144:145], v[28:29] op_sel_hi:[1,0]
	s_nop 0
	v_pk_fma_f32 v[20:21], v[152:153], v[30:31], v[20:21] op_sel_hi:[1,0,1]
	s_nop 0
	v_pk_fma_f32 v[152:153], v[136:137], v[154:155], v[20:21]
	ds_read_b128 v[20:23], v105 offset:33664
	ds_read_b128 v[28:31], v105 offset:37760
	ds_read_b128 v[126:129], v105 offset:25472
	ds_read_b128 v[134:137], v105 offset:41856
	ds_read_b128 v[142:145], v105 offset:29568
	ds_read_b32 v102, v106 offset:45952
	ds_read_b64 v[154:155], v157 offset:49304
	s_waitcnt lgkmcnt(12)
	v_pk_mul_f32 v[132:133], v[132:133], v[152:153]
	s_nop 0
	v_pk_fma_f32 v[130:131], v[130:131], v[150:151], v[132:133]
	s_waitcnt lgkmcnt(10)
	v_pk_mul_f32 v[132:133], v[148:149], v[152:153]
	v_add_f32_e32 v130, v130, v131
	v_pk_fma_f32 v[132:133], v[146:147], v[150:151], v[132:133]
	s_nop 0
	v_add_f32_e32 v131, v132, v133
	v_add_f32_dpp v130, v130, v130 quad_perm:[1,0,3,2] row_mask:0xf bank_mask:0xf bound_ctrl:1
	s_nop 0
	v_add_f32_dpp v131, v131, v131 quad_perm:[1,0,3,2] row_mask:0xf bank_mask:0xf bound_ctrl:1
	v_add_f32_dpp v130, v130, v130 quad_perm:[2,3,0,1] row_mask:0xf bank_mask:0xf bound_ctrl:1
	s_nop 0
	v_add_f32_dpp v131, v131, v131 quad_perm:[2,3,0,1] row_mask:0xf bank_mask:0xf bound_ctrl:1
	v_add_f32_dpp v130, v130, v130 row_half_mirror row_mask:0xf bank_mask:0xf bound_ctrl:1
	s_nop 0
	v_add_f32_dpp v131, v131, v131 row_half_mirror row_mask:0xf bank_mask:0xf bound_ctrl:1
	v_add_f32_dpp v130, v130, v130 row_mirror row_mask:0xf bank_mask:0xf bound_ctrl:1
	s_nop 0
	v_add_f32_dpp v131, v131, v131 row_mirror row_mask:0xf bank_mask:0xf bound_ctrl:1
	s_waitcnt lgkmcnt(8)
	v_fmac_f32_e32 v131, v130, v168
	v_fmac_f32_e32 v131, v96, v169
	v_pk_mul_f32 v[98:99], v[98:99], v[130:131] op_sel_hi:[1,0]
	ds_write_b32 v109, v131 offset:50432
	v_pk_fma_f32 v[98:99], v[138:139], v[96:97], v[98:99] op_sel_hi:[1,0,1]
	s_nop 0
	v_pk_fma_f32 v[150:151], v[24:25], v[150:151], v[98:99]
	v_pk_mul_f32 v[24:25], v[100:101], v[130:131] op_sel_hi:[1,0]
	s_nop 0
	v_pk_fma_f32 v[24:25], v[140:141], v[96:97], v[24:25] op_sel_hi:[1,0,1]
	s_nop 0
	v_pk_fma_f32 v[152:153], v[26:27], v[152:153], v[24:25]
	ds_read_b128 v[24:27], v105 offset:33920
	ds_read_b128 v[98:101], v105 offset:38016
	ds_read_b128 v[130:133], v105 offset:25728
	ds_read_b128 v[138:141], v105 offset:42112
	ds_read_b128 v[146:149], v105 offset:29824
	ds_read_b32 v96, v106 offset:46208
	ds_read_b64 v[168:169], v157 offset:49312
	s_waitcnt lgkmcnt(12)
	v_pk_mul_f32 v[128:129], v[128:129], v[152:153]
	s_nop 0
	v_pk_fma_f32 v[126:127], v[126:127], v[150:151], v[128:129]
	s_waitcnt lgkmcnt(10)
	v_pk_mul_f32 v[128:129], v[144:145], v[152:153]
	v_add_f32_e32 v126, v126, v127
	v_pk_fma_f32 v[128:129], v[142:143], v[150:151], v[128:129]
	s_nop 0
	v_add_f32_e32 v127, v128, v129
	v_add_f32_dpp v126, v126, v126 quad_perm:[1,0,3,2] row_mask:0xf bank_mask:0xf bound_ctrl:1
	s_nop 0
	v_add_f32_dpp v127, v127, v127 quad_perm:[1,0,3,2] row_mask:0xf bank_mask:0xf bound_ctrl:1
	v_add_f32_dpp v126, v126, v126 quad_perm:[2,3,0,1] row_mask:0xf bank_mask:0xf bound_ctrl:1
	s_nop 0
	v_add_f32_dpp v127, v127, v127 quad_perm:[2,3,0,1] row_mask:0xf bank_mask:0xf bound_ctrl:1
	v_add_f32_dpp v126, v126, v126 row_half_mirror row_mask:0xf bank_mask:0xf bound_ctrl:1
	s_nop 0
	v_add_f32_dpp v127, v127, v127 row_half_mirror row_mask:0xf bank_mask:0xf bound_ctrl:1
	v_add_f32_dpp v126, v126, v126 row_mirror row_mask:0xf bank_mask:0xf bound_ctrl:1
	s_nop 0
	v_add_f32_dpp v127, v127, v127 row_mirror row_mask:0xf bank_mask:0xf bound_ctrl:1
	s_waitcnt lgkmcnt(8)
	v_fmac_f32_e32 v127, v126, v154
	v_fmac_f32_e32 v127, v102, v155
	v_pk_mul_f32 v[28:29], v[28:29], v[126:127] op_sel_hi:[1,0]
	ds_write_b32 v110, v127 offset:50432
	v_pk_fma_f32 v[28:29], v[134:135], v[102:103], v[28:29] op_sel_hi:[1,0,1]
	s_nop 0
	v_pk_fma_f32 v[150:151], v[20:21], v[150:151], v[28:29]
	v_pk_mul_f32 v[20:21], v[30:31], v[126:127] op_sel_hi:[1,0]
	s_nop 0
	v_pk_fma_f32 v[20:21], v[136:137], v[102:103], v[20:21] op_sel_hi:[1,0,1]
	s_nop 0
	v_pk_fma_f32 v[152:153], v[22:23], v[152:153], v[20:21]
	ds_read_b128 v[20:23], v105 offset:34176
	ds_read_b128 v[28:31], v105 offset:38272
	ds_read_b128 v[126:129], v105 offset:25984
	ds_read_b128 v[134:137], v105 offset:42368
	ds_read_b128 v[142:145], v105 offset:30080
	ds_read_b32 v102, v106 offset:46464
	ds_read_b64 v[154:155], v157 offset:49320
	s_waitcnt lgkmcnt(12)
	v_pk_mul_f32 v[132:133], v[132:133], v[152:153]
	s_nop 0
	v_pk_fma_f32 v[130:131], v[130:131], v[150:151], v[132:133]
	s_waitcnt lgkmcnt(10)
	v_pk_mul_f32 v[132:133], v[148:149], v[152:153]
	v_add_f32_e32 v130, v130, v131
	v_pk_fma_f32 v[132:133], v[146:147], v[150:151], v[132:133]
	s_nop 0
	v_add_f32_e32 v131, v132, v133
	v_add_f32_dpp v130, v130, v130 quad_perm:[1,0,3,2] row_mask:0xf bank_mask:0xf bound_ctrl:1
	s_nop 0
	v_add_f32_dpp v131, v131, v131 quad_perm:[1,0,3,2] row_mask:0xf bank_mask:0xf bound_ctrl:1
	v_add_f32_dpp v130, v130, v130 quad_perm:[2,3,0,1] row_mask:0xf bank_mask:0xf bound_ctrl:1
	s_nop 0
	v_add_f32_dpp v131, v131, v131 quad_perm:[2,3,0,1] row_mask:0xf bank_mask:0xf bound_ctrl:1
	v_add_f32_dpp v130, v130, v130 row_half_mirror row_mask:0xf bank_mask:0xf bound_ctrl:1
	s_nop 0
	v_add_f32_dpp v131, v131, v131 row_half_mirror row_mask:0xf bank_mask:0xf bound_ctrl:1
	v_add_f32_dpp v130, v130, v130 row_mirror row_mask:0xf bank_mask:0xf bound_ctrl:1
	s_nop 0
	v_add_f32_dpp v131, v131, v131 row_mirror row_mask:0xf bank_mask:0xf bound_ctrl:1
	s_waitcnt lgkmcnt(8)
; DI float row16_sum(float v) { v += dppf(v, 0); v += dppf(v, 1); v += dppf(v, 2); v += dppf(v, 3); return v; }
; DI void rwkv_scan(CP p, const Ptrs& w, int l, int item, float* sm) {
;     ...
;     for (int j = 0; j < 16; ++j) {
;       RStep nxt = cur;
;       if (j + 1 < 16) nxt = lds_step(bf, j + 1);
;       f2v sa2 = SA * cur.a4.xy + SB * cur.a4.zw;
;       f2v yp2 = SA * cur.wr4.xy + SB * cur.wr4.zw;
;       float sa = sa2.x + sa2.y, yp = yp2.x + yp2.y;
;       sa = row16_sum(sa); yp = row16_sum(yp);
;       float y = yp + sa * cur.sc.x + cur.vv * cur.sc.y;
;       SA = SA * cur.w4.xy + (sa * cur.b4.xy + cur.vv * cur.k4.xy);
;       SB = SB * cur.w4.zw + (sa * cur.b4.zw + cur.vv * cur.k4.zw);
;       sy[(kg == 0 ? j * 16 : 0) + ysel - (c & 1) * 0] = y;
;       cur = nxt;
;     }
	v_fmac_f32_e32 v131, v130, v168
	v_fmac_f32_e32 v131, v96, v169
	v_pk_mul_f32 v[98:99], v[98:99], v[130:131] op_sel_hi:[1,0]
	ds_write_b32 v111, v131 offset:50432
	v_pk_fma_f32 v[98:99], v[138:139], v[96:97], v[98:99] op_sel_hi:[1,0,1]
	s_nop 0
	v_pk_fma_f32 v[150:151], v[24:25], v[150:151], v[98:99]
	v_pk_mul_f32 v[24:25], v[100:101], v[130:131] op_sel_hi:[1,0]
	s_nop 0
	v_pk_fma_f32 v[24:25], v[140:141], v[96:97], v[24:25] op_sel_hi:[1,0,1]
	s_nop 0
	v_pk_fma_f32 v[152:153], v[26:27], v[152:153], v[24:25]
	ds_read_b128 v[24:27], v105 offset:34432
	ds_read_b128 v[98:101], v105 offset:38528
	ds_read_b128 v[130:133], v105 offset:26240
	ds_read_b128 v[138:141], v105 offset:42624
	ds_read_b128 v[146:149], v105 offset:30336
	ds_read_b32 v96, v106 offset:46720
	ds_read_b64 v[168:169], v157 offset:49328
	s_waitcnt lgkmcnt(12)
	v_pk_mul_f32 v[128:129], v[128:129], v[152:153]
	s_nop 0
	v_pk_fma_f32 v[126:127], v[126:127], v[150:151], v[128:129]
	s_waitcnt lgkmcnt(10)
	v_pk_mul_f32 v[128:129], v[144:145], v[152:153]
	v_add_f32_e32 v126, v126, v127
	v_pk_fma_f32 v[128:129], v[142:143], v[150:151], v[128:129]
	s_nop 0
	v_add_f32_e32 v127, v128, v129
	v_add_f32_dpp v126, v126, v126 quad_perm:[1,0,3,2] row_mask:0xf bank_mask:0xf bound_ctrl:1
	s_nop 0
	v_add_f32_dpp v127, v127, v127 quad_perm:[1,0,3,2] row_mask:0xf bank_mask:0xf bound_ctrl:1
	v_add_f32_dpp v126, v126, v126 quad_perm:[2,3,0,1] row_mask:0xf bank_mask:0xf bound_ctrl:1
	s_nop 0
	v_add_f32_dpp v127, v127, v127 quad_perm:[2,3,0,1] row_mask:0xf bank_mask:0xf bound_ctrl:1
	v_add_f32_dpp v126, v126, v126 row_half_mirror row_mask:0xf bank_mask:0xf bound_ctrl:1
	s_nop 0
	v_add_f32_dpp v127, v127, v127 row_half_mirror row_mask:0xf bank_mask:0xf bound_ctrl:1
	v_add_f32_dpp v126, v126, v126 row_mirror row_mask:0xf bank_mask:0xf bound_ctrl:1
	s_nop 0
	v_add_f32_dpp v127, v127, v127 row_mirror row_mask:0xf bank_mask:0xf bound_ctrl:1
	s_waitcnt lgkmcnt(8)
	v_fmac_f32_e32 v127, v126, v154
	v_fmac_f32_e32 v127, v102, v155
	v_pk_mul_f32 v[28:29], v[28:29], v[126:127] op_sel_hi:[1,0]
	ds_write_b32 v112, v127 offset:50432
	v_pk_fma_f32 v[28:29], v[134:135], v[102:103], v[28:29] op_sel_hi:[1,0,1]
	s_nop 0
	v_pk_fma_f32 v[150:151], v[20:21], v[150:151], v[28:29]
	v_pk_mul_f32 v[20:21], v[30:31], v[126:127] op_sel_hi:[1,0]
	s_nop 0
	v_pk_fma_f32 v[20:21], v[136:137], v[102:103], v[20:21] op_sel_hi:[1,0,1]
	s_nop 0
	v_pk_fma_f32 v[152:153], v[22:23], v[152:153], v[20:21]
	ds_read_b128 v[20:23], v105 offset:34688
	ds_read_b128 v[28:31], v105 offset:38784
	ds_read_b128 v[126:129], v105 offset:26496
	ds_read_b128 v[134:137], v105 offset:42880
	ds_read_b128 v[142:145], v105 offset:30592
	ds_read_b32 v102, v106 offset:46976
	ds_read_b64 v[154:155], v157 offset:49336
	s_waitcnt lgkmcnt(12)
	v_pk_mul_f32 v[132:133], v[132:133], v[152:153]
	s_nop 0
	v_pk_fma_f32 v[130:131], v[130:131], v[150:151], v[132:133]
	s_waitcnt lgkmcnt(10)
	v_pk_mul_f32 v[132:133], v[148:149], v[152:153]
	v_add_f32_e32 v130, v130, v131
	v_pk_fma_f32 v[132:133], v[146:147], v[150:151], v[132:133]
	s_nop 0
	v_add_f32_e32 v131, v132, v133
	v_add_f32_dpp v130, v130, v130 quad_perm:[1,0,3,2] row_mask:0xf bank_mask:0xf bound_ctrl:1
	s_nop 0
	v_add_f32_dpp v131, v131, v131 quad_perm:[1,0,3,2] row_mask:0xf bank_mask:0xf bound_ctrl:1
	v_add_f32_dpp v130, v130, v130 quad_perm:[2,3,0,1] row_mask:0xf bank_mask:0xf bound_ctrl:1
	s_nop 0
	v_add_f32_dpp v131, v131, v131 quad_perm:[2,3,0,1] row_mask:0xf bank_mask:0xf bound_ctrl:1
	v_add_f32_dpp v130, v130, v130 row_half_mirror row_mask:0xf bank_mask:0xf bound_ctrl:1
	s_nop 0
	v_add_f32_dpp v131, v131, v131 row_half_mirror row_mask:0xf bank_mask:0xf bound_ctrl:1
	v_add_f32_dpp v130, v130, v130 row_mirror row_mask:0xf bank_mask:0xf bound_ctrl:1
	s_nop 0
	v_add_f32_dpp v131, v131, v131 row_mirror row_mask:0xf bank_mask:0xf bound_ctrl:1
	s_waitcnt lgkmcnt(8)
	v_fmac_f32_e32 v131, v130, v168
	v_fmac_f32_e32 v131, v96, v169
	v_pk_mul_f32 v[98:99], v[98:99], v[130:131] op_sel_hi:[1,0]
	ds_write_b32 v113, v131 offset:50432
	v_pk_fma_f32 v[98:99], v[138:139], v[96:97], v[98:99] op_sel_hi:[1,0,1]
	s_nop 0
	v_pk_fma_f32 v[150:151], v[24:25], v[150:151], v[98:99]
	v_pk_mul_f32 v[24:25], v[100:101], v[130:131] op_sel_hi:[1,0]
	s_nop 0
	v_pk_fma_f32 v[24:25], v[140:141], v[96:97], v[24:25] op_sel_hi:[1,0,1]
	s_nop 0
	v_pk_fma_f32 v[152:153], v[26:27], v[152:153], v[24:25]
	ds_read_b128 v[24:27], v105 offset:34944
	ds_read_b128 v[98:101], v105 offset:39040
	ds_read_b128 v[130:133], v105 offset:26752
	ds_read_b128 v[138:141], v105 offset:43136
	ds_read_b128 v[146:149], v105 offset:30848
	ds_read_b32 v96, v106 offset:47232
	ds_read_b64 v[168:169], v157 offset:49344
	s_waitcnt lgkmcnt(12)
	v_pk_mul_f32 v[128:129], v[128:129], v[152:153]
	s_nop 0
	v_pk_fma_f32 v[126:127], v[126:127], v[150:151], v[128:129]
	s_waitcnt lgkmcnt(10)
	v_pk_mul_f32 v[128:129], v[144:145], v[152:153]
	v_add_f32_e32 v126, v126, v127
	v_pk_fma_f32 v[128:129], v[142:143], v[150:151], v[128:129]
	s_nop 0
	v_add_f32_e32 v127, v128, v129
	v_add_f32_dpp v126, v126, v126 quad_perm:[1,0,3,2] row_mask:0xf bank_mask:0xf bound_ctrl:1
	s_nop 0
	v_add_f32_dpp v127, v127, v127 quad_perm:[1,0,3,2] row_mask:0xf bank_mask:0xf bound_ctrl:1
	v_add_f32_dpp v126, v126, v126 quad_perm:[2,3,0,1] row_mask:0xf bank_mask:0xf bound_ctrl:1
	s_nop 0
	v_add_f32_dpp v127, v127, v127 quad_perm:[2,3,0,1] row_mask:0xf bank_mask:0xf bound_ctrl:1
	v_add_f32_dpp v126, v126, v126 row_half_mirror row_mask:0xf bank_mask:0xf bound_ctrl:1
	s_nop 0
	v_add_f32_dpp v127, v127, v127 row_half_mirror row_mask:0xf bank_mask:0xf bound_ctrl:1
	v_add_f32_dpp v126, v126, v126 row_mirror row_mask:0xf bank_mask:0xf bound_ctrl:1
	s_nop 0
	v_add_f32_dpp v127, v127, v127 row_mirror row_mask:0xf bank_mask:0xf bound_ctrl:1
	s_waitcnt lgkmcnt(8)
; DI float row16_sum(float v) { v += dppf(v, 0); v += dppf(v, 1); v += dppf(v, 2); v += dppf(v, 3); return v; }
; DI void rwkv_scan(CP p, const Ptrs& w, int l, int item, float* sm) {
;     ...
;     for (int j = 0; j < 16; ++j) {
;       RStep nxt = cur;
;       if (j + 1 < 16) nxt = lds_step(bf, j + 1);
;       f2v sa2 = SA * cur.a4.xy + SB * cur.a4.zw;
;       f2v yp2 = SA * cur.wr4.xy + SB * cur.wr4.zw;
;       float sa = sa2.x + sa2.y, yp = yp2.x + yp2.y;
;       sa = row16_sum(sa); yp = row16_sum(yp);
;       float y = yp + sa * cur.sc.x + cur.vv * cur.sc.y;
;       SA = SA * cur.w4.xy + (sa * cur.b4.xy + cur.vv * cur.k4.xy);
;       SB = SB * cur.w4.zw + (sa * cur.b4.zw + cur.vv * cur.k4.zw);
;       sy[(kg == 0 ? j * 16 : 0) + ysel - (c & 1) * 0] = y;
;       cur = nxt;
;     }
	v_fmac_f32_e32 v127, v126, v154
	v_fmac_f32_e32 v127, v102, v155
	v_pk_mul_f32 v[28:29], v[28:29], v[126:127] op_sel_hi:[1,0]
	ds_write_b32 v114, v127 offset:50432
	v_pk_fma_f32 v[28:29], v[134:135], v[102:103], v[28:29] op_sel_hi:[1,0,1]
	s_nop 0
	v_pk_fma_f32 v[150:151], v[20:21], v[150:151], v[28:29]
	v_pk_mul_f32 v[20:21], v[30:31], v[126:127] op_sel_hi:[1,0]
	s_nop 0
	v_pk_fma_f32 v[20:21], v[136:137], v[102:103], v[20:21] op_sel_hi:[1,0,1]
	s_nop 0
	v_pk_fma_f32 v[152:153], v[22:23], v[152:153], v[20:21]
	ds_read_b128 v[20:23], v105 offset:35200
	ds_read_b128 v[28:31], v105 offset:39296
	ds_read_b128 v[126:129], v105 offset:27008
	ds_read_b128 v[134:137], v105 offset:43392
	ds_read_b128 v[142:145], v105 offset:31104
	ds_read_b32 v102, v106 offset:47488
	ds_read_b64 v[154:155], v157 offset:49352
	s_waitcnt lgkmcnt(12)
	v_pk_mul_f32 v[132:133], v[132:133], v[152:153]
	s_nop 0
	v_pk_fma_f32 v[130:131], v[130:131], v[150:151], v[132:133]
	s_waitcnt lgkmcnt(10)
	v_pk_mul_f32 v[132:133], v[148:149], v[152:153]
	v_add_f32_e32 v130, v130, v131
	v_pk_fma_f32 v[132:133], v[146:147], v[150:151], v[132:133]
	s_nop 0
	v_add_f32_e32 v131, v132, v133
	v_add_f32_dpp v130, v130, v130 quad_perm:[1,0,3,2] row_mask:0xf bank_mask:0xf bound_ctrl:1
	s_nop 0
	v_add_f32_dpp v131, v131, v131 quad_perm:[1,0,3,2] row_mask:0xf bank_mask:0xf bound_ctrl:1
	v_add_f32_dpp v130, v130, v130 quad_perm:[2,3,0,1] row_mask:0xf bank_mask:0xf bound_ctrl:1
	s_nop 0
	v_add_f32_dpp v131, v131, v131 quad_perm:[2,3,0,1] row_mask:0xf bank_mask:0xf bound_ctrl:1
	v_add_f32_dpp v130, v130, v130 row_half_mirror row_mask:0xf bank_mask:0xf bound_ctrl:1
	s_nop 0
	v_add_f32_dpp v131, v131, v131 row_half_mirror row_mask:0xf bank_mask:0xf bound_ctrl:1
	v_add_f32_dpp v130, v130, v130 row_mirror row_mask:0xf bank_mask:0xf bound_ctrl:1
	s_nop 0
	v_add_f32_dpp v131, v131, v131 row_mirror row_mask:0xf bank_mask:0xf bound_ctrl:1
	s_waitcnt lgkmcnt(8)
	v_fmac_f32_e32 v131, v130, v168
	v_fmac_f32_e32 v131, v96, v169
	v_pk_mul_f32 v[98:99], v[98:99], v[130:131] op_sel_hi:[1,0]
	ds_write_b32 v115, v131 offset:50432
	v_pk_fma_f32 v[98:99], v[138:139], v[96:97], v[98:99] op_sel_hi:[1,0,1]
	s_nop 0
	v_pk_fma_f32 v[150:151], v[24:25], v[150:151], v[98:99]
	v_pk_mul_f32 v[24:25], v[100:101], v[130:131] op_sel_hi:[1,0]
	s_nop 0
	v_pk_fma_f32 v[24:25], v[140:141], v[96:97], v[24:25] op_sel_hi:[1,0,1]
	s_nop 0
	v_pk_fma_f32 v[152:153], v[26:27], v[152:153], v[24:25]
	ds_read_b128 v[24:27], v105 offset:35456
	ds_read_b128 v[98:101], v105 offset:39552
	ds_read_b128 v[130:133], v105 offset:27264
	ds_read_b128 v[138:141], v105 offset:43648
	ds_read_b128 v[146:149], v105 offset:31360
	ds_read_b32 v96, v106 offset:47744
	ds_read_b64 v[168:169], v157 offset:49360
	s_waitcnt lgkmcnt(12)
	v_pk_mul_f32 v[128:129], v[128:129], v[152:153]
	s_nop 0
	v_pk_fma_f32 v[126:127], v[126:127], v[150:151], v[128:129]
	s_waitcnt lgkmcnt(10)
	v_pk_mul_f32 v[128:129], v[144:145], v[152:153]
	v_add_f32_e32 v126, v126, v127
	v_pk_fma_f32 v[128:129], v[142:143], v[150:151], v[128:129]
	s_nop 0
	v_add_f32_e32 v127, v128, v129
	v_add_f32_dpp v126, v126, v126 quad_perm:[1,0,3,2] row_mask:0xf bank_mask:0xf bound_ctrl:1
	s_nop 0
	v_add_f32_dpp v127, v127, v127 quad_perm:[1,0,3,2] row_mask:0xf bank_mask:0xf bound_ctrl:1
	v_add_f32_dpp v126, v126, v126 quad_perm:[2,3,0,1] row_mask:0xf bank_mask:0xf bound_ctrl:1
	s_nop 0
	v_add_f32_dpp v127, v127, v127 quad_perm:[2,3,0,1] row_mask:0xf bank_mask:0xf bound_ctrl:1
	v_add_f32_dpp v126, v126, v126 row_half_mirror row_mask:0xf bank_mask:0xf bound_ctrl:1
	s_nop 0
	v_add_f32_dpp v127, v127, v127 row_half_mirror row_mask:0xf bank_mask:0xf bound_ctrl:1
	v_add_f32_dpp v126, v126, v126 row_mirror row_mask:0xf bank_mask:0xf bound_ctrl:1
	s_nop 0
	v_add_f32_dpp v127, v127, v127 row_mirror row_mask:0xf bank_mask:0xf bound_ctrl:1
	s_waitcnt lgkmcnt(8)
	v_fmac_f32_e32 v127, v126, v154
	v_fmac_f32_e32 v127, v102, v155
	v_pk_mul_f32 v[28:29], v[28:29], v[126:127] op_sel_hi:[1,0]
	ds_write_b32 v116, v127 offset:50432
	v_pk_fma_f32 v[28:29], v[134:135], v[102:103], v[28:29] op_sel_hi:[1,0,1]
	s_nop 0
	v_pk_fma_f32 v[150:151], v[20:21], v[150:151], v[28:29]
	v_pk_mul_f32 v[20:21], v[30:31], v[126:127] op_sel_hi:[1,0]
	s_nop 0
	v_pk_fma_f32 v[20:21], v[136:137], v[102:103], v[20:21] op_sel_hi:[1,0,1]
	s_nop 0
	v_pk_fma_f32 v[152:153], v[22:23], v[152:153], v[20:21]
	ds_read_b128 v[20:23], v105 offset:35712
	ds_read_b128 v[28:31], v105 offset:39808
	ds_read_b128 v[126:129], v105 offset:27520
	ds_read_b128 v[134:137], v105 offset:43904
	ds_read_b128 v[142:145], v105 offset:31616
	ds_read_b32 v102, v106 offset:48000
	ds_read_b64 v[154:155], v157 offset:49368
	s_waitcnt lgkmcnt(12)
	v_pk_mul_f32 v[132:133], v[132:133], v[152:153]
	s_nop 0
	v_pk_fma_f32 v[130:131], v[130:131], v[150:151], v[132:133]
	s_waitcnt lgkmcnt(10)
	v_pk_mul_f32 v[132:133], v[148:149], v[152:153]
	v_add_f32_e32 v130, v130, v131
	v_pk_fma_f32 v[132:133], v[146:147], v[150:151], v[132:133]
	s_nop 0
	v_add_f32_e32 v131, v132, v133
	v_add_f32_dpp v130, v130, v130 quad_perm:[1,0,3,2] row_mask:0xf bank_mask:0xf bound_ctrl:1
	s_nop 0
	v_add_f32_dpp v131, v131, v131 quad_perm:[1,0,3,2] row_mask:0xf bank_mask:0xf bound_ctrl:1
	v_add_f32_dpp v130, v130, v130 quad_perm:[2,3,0,1] row_mask:0xf bank_mask:0xf bound_ctrl:1
	s_nop 0
	v_add_f32_dpp v131, v131, v131 quad_perm:[2,3,0,1] row_mask:0xf bank_mask:0xf bound_ctrl:1
	v_add_f32_dpp v130, v130, v130 row_half_mirror row_mask:0xf bank_mask:0xf bound_ctrl:1
	s_nop 0
	v_add_f32_dpp v131, v131, v131 row_half_mirror row_mask:0xf bank_mask:0xf bound_ctrl:1
	v_add_f32_dpp v130, v130, v130 row_mirror row_mask:0xf bank_mask:0xf bound_ctrl:1
	s_nop 0
	v_add_f32_dpp v131, v131, v131 row_mirror row_mask:0xf bank_mask:0xf bound_ctrl:1
	s_waitcnt lgkmcnt(8)
; DI float row16_sum(float v) { v += dppf(v, 0); v += dppf(v, 1); v += dppf(v, 2); v += dppf(v, 3); return v; }
; DI void rwkv_scan(CP p, const Ptrs& w, int l, int item, float* sm) {
;     ...
;     for (int j = 0; j < 16; ++j) {
;       RStep nxt = cur;
;       if (j + 1 < 16) nxt = lds_step(bf, j + 1);
;       f2v sa2 = SA * cur.a4.xy + SB * cur.a4.zw;
;       f2v yp2 = SA * cur.wr4.xy + SB * cur.wr4.zw;
;       float sa = sa2.x + sa2.y, yp = yp2.x + yp2.y;
;       sa = row16_sum(sa); yp = row16_sum(yp);
;       float y = yp + sa * cur.sc.x + cur.vv * cur.sc.y;
;       SA = SA * cur.w4.xy + (sa * cur.b4.xy + cur.vv * cur.k4.xy);
;       SB = SB * cur.w4.zw + (sa * cur.b4.zw + cur.vv * cur.k4.zw);
;       sy[(kg == 0 ? j * 16 : 0) + ysel - (c & 1) * 0] = y;
;       cur = nxt;
;     }
	v_fmac_f32_e32 v131, v130, v168
	v_fmac_f32_e32 v131, v96, v169
	v_pk_mul_f32 v[98:99], v[98:99], v[130:131] op_sel_hi:[1,0]
	ds_write_b32 v117, v131 offset:50432
	v_pk_fma_f32 v[98:99], v[138:139], v[96:97], v[98:99] op_sel_hi:[1,0,1]
	s_nop 0
	v_pk_fma_f32 v[150:151], v[24:25], v[150:151], v[98:99]
	v_pk_mul_f32 v[24:25], v[100:101], v[130:131] op_sel_hi:[1,0]
	s_nop 0
	v_pk_fma_f32 v[24:25], v[140:141], v[96:97], v[24:25] op_sel_hi:[1,0,1]
	s_nop 0
	v_pk_fma_f32 v[152:153], v[26:27], v[152:153], v[24:25]
	ds_read_b128 v[24:27], v105 offset:35968
	ds_read_b128 v[98:101], v105 offset:40064
	ds_read_b128 v[130:133], v105 offset:27776
	ds_read_b128 v[138:141], v105 offset:44160
	ds_read_b128 v[146:149], v105 offset:31872
	ds_read_b32 v96, v106 offset:48256
	ds_read_b64 v[168:169], v157 offset:49376
	s_waitcnt lgkmcnt(12)
	v_pk_mul_f32 v[128:129], v[128:129], v[152:153]
	s_nop 0
	v_pk_fma_f32 v[126:127], v[126:127], v[150:151], v[128:129]
	s_waitcnt lgkmcnt(10)
	v_pk_mul_f32 v[128:129], v[144:145], v[152:153]
	v_add_f32_e32 v126, v126, v127
	v_pk_fma_f32 v[128:129], v[142:143], v[150:151], v[128:129]
	s_nop 0
	v_add_f32_e32 v127, v128, v129
	v_add_f32_dpp v126, v126, v126 quad_perm:[1,0,3,2] row_mask:0xf bank_mask:0xf bound_ctrl:1
	s_nop 0
	v_add_f32_dpp v127, v127, v127 quad_perm:[1,0,3,2] row_mask:0xf bank_mask:0xf bound_ctrl:1
	v_add_f32_dpp v126, v126, v126 quad_perm:[2,3,0,1] row_mask:0xf bank_mask:0xf bound_ctrl:1
	s_nop 0
	v_add_f32_dpp v127, v127, v127 quad_perm:[2,3,0,1] row_mask:0xf bank_mask:0xf bound_ctrl:1
	v_add_f32_dpp v126, v126, v126 row_half_mirror row_mask:0xf bank_mask:0xf bound_ctrl:1
	s_nop 0
	v_add_f32_dpp v127, v127, v127 row_half_mirror row_mask:0xf bank_mask:0xf bound_ctrl:1
	v_add_f32_dpp v126, v126, v126 row_mirror row_mask:0xf bank_mask:0xf bound_ctrl:1
	s_nop 0
	v_add_f32_dpp v127, v127, v127 row_mirror row_mask:0xf bank_mask:0xf bound_ctrl:1
	s_waitcnt lgkmcnt(8)
	v_fmac_f32_e32 v127, v126, v154
	v_fmac_f32_e32 v127, v102, v155
	v_pk_mul_f32 v[28:29], v[28:29], v[126:127] op_sel_hi:[1,0]
	ds_write_b32 v118, v127 offset:50432
	v_pk_fma_f32 v[28:29], v[134:135], v[102:103], v[28:29] op_sel_hi:[1,0,1]
	s_nop 0
	v_pk_fma_f32 v[150:151], v[20:21], v[150:151], v[28:29]
	v_pk_mul_f32 v[20:21], v[30:31], v[126:127] op_sel_hi:[1,0]
	s_nop 0
	v_pk_fma_f32 v[20:21], v[136:137], v[102:103], v[20:21] op_sel_hi:[1,0,1]
	s_nop 0
	v_pk_fma_f32 v[152:153], v[22:23], v[152:153], v[20:21]
	ds_read_b128 v[20:23], v105 offset:36224
	ds_read_b128 v[28:31], v105 offset:40320
	ds_read_b128 v[126:129], v105 offset:28032
	ds_read_b128 v[134:137], v105 offset:44416
	ds_read_b128 v[142:145], v105 offset:32128
	ds_read_b32 v102, v106 offset:48512
	ds_read_b64 v[154:155], v157 offset:49384
	s_waitcnt lgkmcnt(12)
	v_pk_mul_f32 v[132:133], v[132:133], v[152:153]
	s_nop 0
	v_pk_fma_f32 v[130:131], v[130:131], v[150:151], v[132:133]
	s_waitcnt lgkmcnt(10)
	v_pk_mul_f32 v[132:133], v[148:149], v[152:153]
	v_add_f32_e32 v130, v130, v131
	v_pk_fma_f32 v[132:133], v[146:147], v[150:151], v[132:133]
	s_nop 0
	v_add_f32_e32 v131, v132, v133
	v_add_f32_dpp v130, v130, v130 quad_perm:[1,0,3,2] row_mask:0xf bank_mask:0xf bound_ctrl:1
	s_nop 0
	v_add_f32_dpp v131, v131, v131 quad_perm:[1,0,3,2] row_mask:0xf bank_mask:0xf bound_ctrl:1
	v_add_f32_dpp v130, v130, v130 quad_perm:[2,3,0,1] row_mask:0xf bank_mask:0xf bound_ctrl:1
	s_nop 0
	v_add_f32_dpp v131, v131, v131 quad_perm:[2,3,0,1] row_mask:0xf bank_mask:0xf bound_ctrl:1
	v_add_f32_dpp v130, v130, v130 row_half_mirror row_mask:0xf bank_mask:0xf bound_ctrl:1
	s_nop 0
	v_add_f32_dpp v131, v131, v131 row_half_mirror row_mask:0xf bank_mask:0xf bound_ctrl:1
	v_add_f32_dpp v130, v130, v130 row_mirror row_mask:0xf bank_mask:0xf bound_ctrl:1
	s_nop 0
	v_add_f32_dpp v131, v131, v131 row_mirror row_mask:0xf bank_mask:0xf bound_ctrl:1
	s_waitcnt lgkmcnt(8)
	v_fmac_f32_e32 v131, v130, v168
	v_fmac_f32_e32 v131, v96, v169
	v_pk_mul_f32 v[98:99], v[98:99], v[130:131] op_sel_hi:[1,0]
	ds_write_b32 v119, v131 offset:50432
	v_pk_fma_f32 v[98:99], v[138:139], v[96:97], v[98:99] op_sel_hi:[1,0,1]
	s_nop 0
	v_pk_fma_f32 v[24:25], v[24:25], v[150:151], v[98:99]
	v_pk_mul_f32 v[98:99], v[100:101], v[130:131] op_sel_hi:[1,0]
	s_nop 0
	v_pk_fma_f32 v[98:99], v[140:141], v[96:97], v[98:99] op_sel_hi:[1,0,1]
	s_nop 0
	v_pk_fma_f32 v[26:27], v[26:27], v[152:153], v[98:99]
	ds_read_b128 v[98:101], v105 offset:36480
	ds_read_b128 v[130:133], v105 offset:40576
	ds_read_b128 v[138:141], v105 offset:28288
	ds_read_b128 v[146:149], v105 offset:44672
	ds_read_b128 v[150:153], v105 offset:32384
	ds_read_b32 v156, v106 offset:48768
	ds_read_b64 v[168:169], v157 offset:49392
	s_waitcnt lgkmcnt(12)
	v_pk_mul_f32 v[128:129], v[128:129], v[26:27]
	s_nop 0
	v_pk_fma_f32 v[126:127], v[126:127], v[24:25], v[128:129]
	s_waitcnt lgkmcnt(10)
	v_pk_mul_f32 v[128:129], v[144:145], v[26:27]
	v_add_f32_e32 v96, v126, v127
	v_pk_fma_f32 v[128:129], v[142:143], v[24:25], v[128:129]
	s_nop 0
	v_add_f32_dpp v96, v96, v96 quad_perm:[1,0,3,2] row_mask:0xf bank_mask:0xf bound_ctrl:1
	v_add_f32_e32 v126, v128, v129
	s_nop 0
	v_add_f32_dpp v96, v96, v96 quad_perm:[2,3,0,1] row_mask:0xf bank_mask:0xf bound_ctrl:1
	v_add_f32_dpp v126, v126, v126 quad_perm:[1,0,3,2] row_mask:0xf bank_mask:0xf bound_ctrl:1
	s_nop 0
	v_add_f32_dpp v96, v96, v96 row_half_mirror row_mask:0xf bank_mask:0xf bound_ctrl:1
	v_add_f32_dpp v126, v126, v126 quad_perm:[2,3,0,1] row_mask:0xf bank_mask:0xf bound_ctrl:1
	s_nop 0
	v_add_f32_dpp v96, v96, v96 row_mirror row_mask:0xf bank_mask:0xf bound_ctrl:1
	v_pk_mul_f32 v[28:29], v[28:29], v[96:97] op_sel_hi:[1,0]
	v_add_f32_dpp v126, v126, v126 row_half_mirror row_mask:0xf bank_mask:0xf bound_ctrl:1
	s_waitcnt lgkmcnt(9)
; DI float row16_sum(float v) { v += dppf(v, 0); v += dppf(v, 1); v += dppf(v, 2); v += dppf(v, 3); return v; }
; DI void rwkv_scan(CP p, const Ptrs& w, int l, int item, float* sm) {
;     ...
;     up4(P.pq[0][0], rc); up4(P.pq[0][1], rp); up4(P.pq[0][2], rn);
;     up4(P.pq[1][0], kc); up4(P.pq[1][1], kp); up4(P.pq[1][2], kn);
;     up4(P.pq[2][0], vc); up4(P.pq[2][1], vp); up4(P.pq[2][2], vn);
;     up4(P.pwd, wd4); up4(P.pad_, ad4);
;     float o0[4], o1[4], o2[4], o3[4], o4[4], o5[4];
; #pragma unroll
;     for (int j = 0; j < 4; ++j) {
;       float r_s = rc[j] + ((P.pmk[0] * rp[j] + P.pmk[1] * rn[j]) - rc[j]) * mu_r[j];
;       float k_s = kc[j] + ((P.pmk[0] * kp[j] + P.pmk[1] * kn[j]) - kc[j]) * mu_k[j];
;       float v_s = vc[j] + ((P.pmk[0] * vp[j] + P.pmk[1] * vn[j]) - vc[j]) * mu_v[j];
;       float kk = k_s * kk_c[j] * P.psc[0];
;       float a = ad4[j], wv = 1.f - wd4[j];
;       o0[j] = -kk; o1[j] = wv * r_s; o2[j] = wv; o3[j] = kk * a; o4[j] = k_s * (1.f + (a - 1.f) * ka_c[j]); o5[j] = v_s;
;     ...
;     for (int j = 0; j < 16; ++j) {
;       RStep nxt = cur;
;       if (j + 1 < 16) nxt = lds_step(bf, j + 1);
;       f2v sa2 = SA * cur.a4.xy + SB * cur.a4.zw;
;       f2v yp2 = SA * cur.wr4.xy + SB * cur.wr4.zw;
;       float sa = sa2.x + sa2.y, yp = yp2.x + yp2.y;
;       sa = row16_sum(sa); yp = row16_sum(yp);
;       float y = yp + sa * cur.sc.x + cur.vv * cur.sc.y;
;       SA = SA * cur.w4.xy + (sa * cur.b4.xy + cur.vv * cur.k4.xy);
;       SB = SB * cur.w4.zw + (sa * cur.b4.zw + cur.vv * cur.k4.zw);
;       sy[(kg == 0 ? j * 16 : 0) + ysel - (c & 1) * 0] = y;
;       cur = nxt;
;     }
	v_pk_fma_f32 v[28:29], v[134:135], v[102:103], v[28:29] op_sel_hi:[1,0,1]
	s_nop 0
	v_pk_fma_f32 v[142:143], v[20:21], v[24:25], v[28:29]
	v_pk_mul_f32 v[20:21], v[30:31], v[96:97] op_sel_hi:[1,0]
	v_add_f32_dpp v126, v126, v126 row_mirror row_mask:0xf bank_mask:0xf bound_ctrl:1
	v_pk_fma_f32 v[20:21], v[136:137], v[102:103], v[20:21] op_sel_hi:[1,0,1]
	s_waitcnt lgkmcnt(8)
	v_fmac_f32_e32 v126, v96, v154
	v_pk_fma_f32 v[144:145], v[22:23], v[26:27], v[20:21]
	v_fmac_f32_e32 v126, v102, v155
	s_waitcnt lgkmcnt(4)
	v_pk_mul_f32 v[140:141], v[140:141], v[144:145]
	ds_write_b32 v120, v126 offset:50432
	v_pk_fma_f32 v[138:139], v[138:139], v[142:143], v[140:141]
	s_waitcnt lgkmcnt(3)
	v_pk_mul_f32 v[140:141], v[152:153], v[144:145]
	v_add_f32_e32 v102, v138, v139
	v_pk_fma_f32 v[140:141], v[150:151], v[142:143], v[140:141]
	ds_read_b128 v[20:23], v105 offset:36736
	ds_read_b128 v[28:31], v105 offset:40832
	ds_read_b128 v[126:129], v105 offset:28544
	ds_read_b128 v[24:27], v105 offset:44928
	ds_read_b128 v[134:137], v105 offset:32640
	ds_read_b32 v96, v106 offset:49024
	ds_read_b64 v[154:155], v157 offset:49400
	v_add_f32_dpp v102, v102, v102 quad_perm:[1,0,3,2] row_mask:0xf bank_mask:0xf bound_ctrl:1
	v_add_f32_e32 v138, v140, v141
	s_waitcnt vmcnt(20)
	v_and_b32_e32 v139, 0xffff0000, v80
	v_add_f32_dpp v102, v102, v102 quad_perm:[2,3,0,1] row_mask:0xf bank_mask:0xf bound_ctrl:1
	v_add_f32_dpp v138, v138, v138 quad_perm:[1,0,3,2] row_mask:0xf bank_mask:0xf bound_ctrl:1
	v_and_b32_e32 v141, 0xffff0000, v79
	v_add_f32_dpp v102, v102, v102 row_half_mirror row_mask:0xf bank_mask:0xf bound_ctrl:1
	v_add_f32_dpp v138, v138, v138 quad_perm:[2,3,0,1] row_mask:0xf bank_mask:0xf bound_ctrl:1
	v_lshlrev_b32_e32 v140, 16, v81
	v_add_f32_dpp v102, v102, v102 row_mirror row_mask:0xf bank_mask:0xf bound_ctrl:1
	v_pk_mul_f32 v[130:131], v[130:131], v[102:103] op_sel_hi:[1,0]
	v_add_f32_dpp v138, v138, v138 row_half_mirror row_mask:0xf bank_mask:0xf bound_ctrl:1
	s_waitcnt lgkmcnt(9)
	v_pk_fma_f32 v[130:131], v[146:147], v[156:157], v[130:131] op_sel_hi:[1,0,1]
	s_nop 0
	v_pk_fma_f32 v[98:99], v[98:99], v[142:143], v[130:131]
	v_pk_mul_f32 v[130:131], v[132:133], v[102:103] op_sel_hi:[1,0]
	v_add_f32_dpp v138, v138, v138 row_mirror row_mask:0xf bank_mask:0xf bound_ctrl:1
	v_pk_fma_f32 v[130:131], v[148:149], v[156:157], v[130:131] op_sel_hi:[1,0,1]
	s_waitcnt lgkmcnt(8)
	v_fmac_f32_e32 v138, v102, v168
	v_pk_fma_f32 v[100:101], v[100:101], v[144:145], v[130:131]
	v_fmac_f32_e32 v138, v156, v169
	s_waitcnt lgkmcnt(4)
	v_pk_mul_f32 v[128:129], v[128:129], v[100:101]
	ds_write_b32 v121, v138 offset:50432
	v_pk_fma_f32 v[126:127], v[126:127], v[98:99], v[128:129]
	s_waitcnt lgkmcnt(3)
	v_pk_mul_f32 v[128:129], v[136:137], v[100:101]
	v_lshlrev_b32_e32 v132, 16, v85
	v_pk_fma_f32 v[128:129], v[134:135], v[98:99], v[128:129]
	v_and_b32_e32 v133, 0xffff0000, v85
	v_and_b32_e32 v85, 0xffff0000, v78
	v_lshlrev_b32_e32 v138, 16, v78
	v_lshlrev_b32_e32 v78, 16, v79
	v_and_b32_e32 v79, 0xffff0000, v81
	v_add_f32_e32 v102, v126, v127
	v_add_f32_e32 v126, v128, v129
	v_lshlrev_b32_e32 v130, 16, v84
	v_and_b32_e32 v131, 0xffff0000, v84
	v_lshlrev_b32_e32 v84, 16, v80
	v_pk_mul_f32 v[138:139], v[94:95], v[138:139] op_sel:[1,0] op_sel_hi:[0,1]
	v_pk_mul_f32 v[78:79], v[94:95], v[78:79] op_sel:[1,0] op_sel_hi:[0,1]
	v_add_f32_dpp v102, v102, v102 quad_perm:[1,0,3,2] row_mask:0xf bank_mask:0xf bound_ctrl:1
	v_add_f32_dpp v126, v126, v126 quad_perm:[1,0,3,2] row_mask:0xf bank_mask:0xf bound_ctrl:1
	v_lshlrev_b32_e32 v128, 16, v86
	v_and_b32_e32 v129, 0xffff0000, v86
	v_lshlrev_b32_e32 v86, 16, v87
	v_and_b32_e32 v87, 0xffff0000, v87
	v_pk_fma_f32 v[84:85], v[94:95], v[84:85], v[138:139]
	v_pk_fma_f32 v[78:79], v[94:95], v[140:141], v[78:79]
	v_add_f32_dpp v102, v102, v102 quad_perm:[2,3,0,1] row_mask:0xf bank_mask:0xf bound_ctrl:1
	v_add_f32_dpp v126, v126, v126 quad_perm:[2,3,0,1] row_mask:0xf bank_mask:0xf bound_ctrl:1
	v_pk_add_f32 v[84:85], v[84:85], v[128:129] neg_lo:[0,1] neg_hi:[0,1]
	v_pk_add_f32 v[78:79], v[78:79], v[86:87] neg_lo:[0,1] neg_hi:[0,1]
	v_add_f32_dpp v102, v102, v102 row_half_mirror row_mask:0xf bank_mask:0xf bound_ctrl:1
	v_add_f32_dpp v126, v126, v126 row_half_mirror row_mask:0xf bank_mask:0xf bound_ctrl:1
	v_pk_fma_f32 v[128:129], v[8:9], v[84:85], v[128:129]
	v_pk_fma_f32 v[140:141], v[10:11], v[78:79], v[86:87]
	v_add_f32_dpp v102, v102, v102 row_mirror row_mask:0xf bank_mask:0xf bound_ctrl:1
	v_add_f32_dpp v126, v126, v126 row_mirror row_mask:0xf bank_mask:0xf bound_ctrl:1
	v_pk_mul_f32 v[84:85], v[12:13], v[128:129]
	v_pk_mul_f32 v[78:79], v[14:15], v[140:141]
	s_waitcnt lgkmcnt(1)
; DI void rwkv_scan(CP p, const Ptrs& w, int l, int item, float* sm) {
;     ...
;     up4(P.pq[0][0], rc); up4(P.pq[0][1], rp); up4(P.pq[0][2], rn);
;     up4(P.pq[1][0], kc); up4(P.pq[1][1], kp); up4(P.pq[1][2], kn);
;     up4(P.pq[2][0], vc); up4(P.pq[2][1], vp); up4(P.pq[2][2], vn);
;     up4(P.pwd, wd4); up4(P.pad_, ad4);
;     float o0[4], o1[4], o2[4], o3[4], o4[4], o5[4];
; #pragma unroll
;     for (int j = 0; j < 4; ++j) {
;       float r_s = rc[j] + ((P.pmk[0] * rp[j] + P.pmk[1] * rn[j]) - rc[j]) * mu_r[j];
;       float k_s = kc[j] + ((P.pmk[0] * kp[j] + P.pmk[1] * kn[j]) - kc[j]) * mu_k[j];
;       float v_s = vc[j] + ((P.pmk[0] * vp[j] + P.pmk[1] * vn[j]) - vc[j]) * mu_v[j];
;       float kk = k_s * kk_c[j] * P.psc[0];
;       float a = ad4[j], wv = 1.f - wd4[j];
;       o0[j] = -kk; o1[j] = wv * r_s; o2[j] = wv; o3[j] = kk * a; o4[j] = k_s * (1.f + (a - 1.f) * ka_c[j]); o5[j] = v_s;
;     }
;     float* d = bufp + sj * 64 + skq;
;     *(float4*)(d + 0 * 1024) = make_float4(o0[0], o0[1], o0[2], o0[3]);
;     *(float4*)(d + 1 * 1024) = make_float4(o1[0], o1[1], o1[2], o1[3]);
;     *(float4*)(d + 2 * 1024) = make_float4(o2[0], o2[1], o2[2], o2[3]);
;     *(float4*)(d + 3 * 1024) = make_float4(o3[0], o3[1], o3[2], o3[3]);
;     *(float4*)(d + 4 * 1024) = make_float4(o4[0], o4[1], o4[2], o4[3]);
;     *(float4*)(d + 5 * 1024) = make_float4(o5[0], o5[1], o5[2], o5[3]);
;     if (skq == 0) *(float2*)(bufp + 6 * 1024 + sj * 2) = make_float2(P.psc[1], P.psc[2]);
	v_fmac_f32_e32 v126, v102, v154
	s_waitcnt vmcnt(16)
	v_pk_mul_f32 v[138:139], v[82:83], v[84:85] op_sel_hi:[0,1]
	v_pk_mul_f32 v[142:143], v[82:83], v[78:79] op_sel_hi:[0,1]
	v_fmac_f32_e32 v126, v96, v155
	v_xor_b32_e32 v85, 0x80000000, v139
	v_xor_b32_e32 v84, 0x80000000, v138
	v_xor_b32_e32 v87, 0x80000000, v143
	v_xor_b32_e32 v86, 0x80000000, v142
	ds_write_b32 v122, v126 offset:50432
	ds_write_b128 v103, v[84:87]
	v_lshlrev_b32_e32 v84, 16, v74
	v_and_b32_e32 v85, 0xffff0000, v76
	v_lshlrev_b32_e32 v80, 16, v76
	v_and_b32_e32 v81, 0xffff0000, v74
	v_pk_mul_f32 v[84:85], v[94:95], v[84:85] op_sel:[1,0] op_sel_hi:[0,1]
	v_lshlrev_b32_e32 v126, 16, v88
	v_and_b32_e32 v127, 0xffff0000, v88
	v_pk_fma_f32 v[80:81], v[94:95], v[80:81], v[84:85]
	v_lshlrev_b32_e32 v134, 16, v92
	v_and_b32_e32 v135, 0xffff0000, v92
	v_pk_add_f32 v[80:81], v[80:81], v[126:127] neg_lo:[0,1] neg_hi:[0,1]
	v_lshlrev_b32_e32 v92, 16, v93
	v_and_b32_e32 v93, 0xffff0000, v93
	v_pk_add_f32 v[78:79], v[134:135], 1.0 op_sel_hi:[1,0] neg_lo:[1,0] neg_hi:[1,0]
	v_pk_fma_f32 v[80:81], v[0:1], v[80:81], v[126:127]
	v_and_b32_e32 v87, 0xffff0000, v75
	v_pk_mul_f32 v[84:85], v[80:81], v[78:79]
	v_pk_add_f32 v[80:81], v[92:93], 1.0 op_sel_hi:[1,0] neg_lo:[1,0] neg_hi:[1,0]
	v_lshlrev_b32_e32 v93, 16, v75
	v_and_b32_e32 v75, s0, v75
	v_and_b32_e32 v74, 0xffff0000, v77
	v_pk_mov_b32 v[74:75], v[92:93], v[74:75] op_sel:[1,0]
	v_lshlrev_b32_e32 v86, 16, v77
	v_pk_mul_f32 v[74:75], v[94:95], v[74:75] op_sel:[1,0] op_sel_hi:[0,1]
	v_lshlrev_b32_e32 v88, 16, v89
	v_and_b32_e32 v89, 0xffff0000, v89
	v_pk_fma_f32 v[74:75], v[94:95], v[86:87], v[74:75]
	v_lshlrev_b32_e32 v136, 16, v90
	v_pk_add_f32 v[74:75], v[74:75], v[88:89] neg_lo:[0,1] neg_hi:[0,1]
	v_and_b32_e32 v137, 0xffff0000, v90
	v_lshlrev_b32_e32 v90, 16, v91
	v_and_b32_e32 v91, 0xffff0000, v91
	v_pk_fma_f32 v[74:75], v[2:3], v[74:75], v[88:89]
	v_pk_mul_f32 v[76:77], v[142:143], v[90:91]
	v_pk_mul_f32 v[86:87], v[74:75], v[80:81]
	v_pk_mul_f32 v[74:75], v[138:139], v[136:137]
	ds_write_b128 v103, v[84:87] offset:4096
	ds_write_b128 v103, v[78:81] offset:8192
	ds_write_b128 v103, v[74:77] offset:12288
	v_pk_add_f32 v[74:75], v[136:137], -1.0 op_sel_hi:[1,0]
	v_pk_add_f32 v[76:77], v[90:91], -1.0 op_sel_hi:[1,0]
	v_pk_fma_f32 v[74:75], v[16:17], v[74:75], 1.0 op_sel_hi:[1,1,0]
	v_pk_fma_f32 v[76:77], v[18:19], v[76:77], 1.0 op_sel_hi:[1,1,0]
	v_pk_mul_f32 v[74:75], v[128:129], v[74:75]
	v_pk_mul_f32 v[76:77], v[140:141], v[76:77]
	ds_write_b128 v103, v[74:77] offset:16384
	v_lshlrev_b32_e32 v76, 16, v70
	v_and_b32_e32 v77, 0xffff0000, v72
	v_lshlrev_b32_e32 v74, 16, v72
	v_and_b32_e32 v75, 0xffff0000, v70
	v_pk_mul_f32 v[76:77], v[94:95], v[76:77] op_sel:[1,0] op_sel_hi:[0,1]
	v_pk_fma_f32 v[74:75], v[94:95], v[74:75], v[76:77]
	v_and_b32_e32 v77, 0xffff0000, v71
	v_lshlrev_b32_e32 v79, 16, v71
	v_and_b32_e32 v71, s0, v71
	v_and_b32_e32 v70, 0xffff0000, v73
	v_pk_mov_b32 v[70:71], v[78:79], v[70:71] op_sel:[1,0]
	v_lshlrev_b32_e32 v76, 16, v73
	v_pk_mul_f32 v[70:71], v[94:95], v[70:71] op_sel:[1,0] op_sel_hi:[0,1]
	v_pk_fma_f32 v[70:71], v[94:95], v[76:77], v[70:71]
	v_pk_add_f32 v[74:75], v[74:75], v[130:131] neg_lo:[0,1] neg_hi:[0,1]
	v_pk_add_f32 v[70:71], v[70:71], v[132:133] neg_lo:[0,1] neg_hi:[0,1]
	v_pk_fma_f32 v[74:75], v[4:5], v[74:75], v[130:131]
	v_pk_fma_f32 v[76:77], v[6:7], v[70:71], v[132:133]
	ds_write_b128 v103, v[74:77] offset:20480
	s_and_saveexec_b64 s[4:5], s[40:41]
	s_cbranch_execz .LBB0_710
	s_waitcnt vmcnt(15)
	ds_write_b64 v104, v[68:69] offset:24576
	s_branch .LBB0_710
